# GEMM K-loop tweaks (A1 hoist, DMA spread) + hand-written phase C residual epilogue with batched loads
# speedup vs baseline: 1.1402x; 1.0303x over previous
.LBB0_94:
	s_ashr_i32 s0, s2, 31
	s_lshr_b32 s0, s0, 29
	s_add_i32 s0, s2, s0
	v_mov_b32_e32 v78, v133
	s_and_b32 s1, s0, 0x1fffff8
	s_lshl_b32 s0, s0, 5
	s_and_b32 s22, s0, 0xffffff00
	v_ashrrev_i32_e32 v6, 6, v78
	v_bfe_u32 v7, v78, 3, 3
	v_lshl_or_b32 v8, v6, 5, v7
	v_add_u32_e32 v0, s22, v8
	s_waitcnt lgkmcnt(0)
	v_ashrrev_i32_e32 v1, 31, v0
	v_lshlrev_b64 v[2:3], 11, v[0:1]
	v_bfe_u32 v1, v78, 4, 2
	v_readlane_b32 s20, v214, 4
	v_xor_b32_e32 v1, v1, v78
	v_readlane_b32 s21, v214, 5
	v_lshlrev_b32_e32 v1, 4, v1
	v_and_b32_e32 v64, 0x70, v1
	v_lshl_add_u64 v[2:3], s[20:21], 0, v[2:3]
	v_or_b32_e32 v1, 8, v8
	v_lshl_add_u64 v[66:67], v[2:3], 0, v[64:65]
	v_add_u32_e32 v2, s22, v1
	v_lshrrev_b32_e32 v1, 1, v1
	v_xor_b32_e32 v1, v1, v78
	v_ashrrev_i32_e32 v3, 31, v2
	v_lshlrev_b32_e32 v1, 4, v1
	v_or_b32_e32 v0, 16, v0
	v_lshlrev_b64 v[2:3], 11, v[2:3]
	v_and_b32_e32 v4, 0x70, v1
	v_ashrrev_i32_e32 v1, 31, v0
	v_lshl_add_u64 v[2:3], s[20:21], 0, v[2:3]
	v_mov_b32_e32 v5, v65
	v_lshlrev_b64 v[0:1], 11, v[0:1]
	v_lshl_add_u64 v[68:69], v[2:3], 0, v[4:5]
	v_lshl_add_u64 v[0:1], s[20:21], 0, v[0:1]
	v_or_b32_e32 v2, 24, v8
	v_lshl_add_u64 v[70:71], v[0:1], 0, v[64:65]
	v_add_u32_e32 v0, s22, v2
	v_lshrrev_b32_e32 v2, 1, v2
	v_ashrrev_i32_e32 v1, 31, v0
	v_xor_b32_e32 v2, v2, v78
	v_lshlrev_b64 v[0:1], 11, v[0:1]
	v_lshlrev_b32_e32 v2, 4, v2
	s_sub_i32 s1, s2, s1
	v_lshl_add_u64 v[0:1], s[20:21], 0, v[0:1]
	v_and_b32_e32 v2, 0x70, v2
	v_mov_b32_e32 v3, v65
	s_lshl_b32 s0, s1, 7
	v_lshl_add_u64 v[72:73], v[0:1], 0, v[2:3]
	v_lshl_or_b32 v2, v6, 4, v7
	v_add_u32_e32 v0, s0, v2
	v_lshlrev_b32_e32 v3, 12, v6
	v_ashrrev_i32_e32 v1, 31, v0
	v_add_u32_e32 v126, 0, v3
	v_lshlrev_b64 v[0:1], 11, v[0:1]
	s_waitcnt vmcnt(0)
	v_readfirstlane_b32 s38, v126
	v_add_u32_e32 v127, 0x400, v126
	v_lshl_add_u64 v[0:1], s[40:41], 0, v[0:1]
	v_or_b32_e32 v2, 8, v2
	s_waitcnt lgkmcnt(0)
	s_barrier
	s_mov_b32 m0, s38
	v_readfirstlane_b32 s39, v127
	v_add_u32_e32 v128, 0x800, v126
	v_lshlrev_b32_e32 v5, 11, v6
	v_and_b32_e32 v80, 1, v6
	v_lshl_add_u64 v[74:75], v[0:1], 0, v[64:65]
	v_add_u32_e32 v0, s0, v2
	v_lshrrev_b32_e32 v2, 1, v2
	global_load_lds_dwordx4 v[66:67], off
	s_mov_b32 m0, s39
	v_readfirstlane_b32 s48, v128
	v_add_u32_e32 v129, 0xc00, v126
	v_add_u32_e32 v6, 0, v5
	v_ashrrev_i32_e32 v1, 31, v0
	v_xor_b32_e32 v2, v2, v78
	global_load_lds_dwordx4 v[68:69], off
	s_mov_b32 m0, s48
	v_readfirstlane_b32 s49, v129
	v_add_u32_e32 v131, 0x8000, v6
	v_lshlrev_b64 v[0:1], 11, v[0:1]
	v_lshlrev_b32_e32 v2, 4, v2
	global_load_lds_dwordx4 v[70:71], off
	s_mov_b32 m0, s49
	v_readfirstlane_b32 s53, v131
	v_add_u32_e32 v130, 0x8400, v6
	v_lshl_add_u64 v[0:1], s[40:41], 0, v[0:1]
	v_and_b32_e32 v64, 0x70, v2
	global_load_lds_dwordx4 v[72:73], off
	s_mov_b32 m0, s53
	v_readfirstlane_b32 s54, v130
	v_add_u32_e32 v120, 0xc000, v126
	v_lshl_add_u64 v[76:77], v[0:1], 0, v[64:65]
	global_load_lds_dwordx4 v[74:75], off
	s_mov_b32 m0, s54
	s_mov_b64 s[20:21], 0x80
	v_readfirstlane_b32 s29, v120
	v_add_u32_e32 v121, 0xc400, v126
	global_load_lds_dwordx4 v[76:77], off
	v_lshl_add_u64 v[0:1], v[66:67], 0, s[20:21]
	s_mov_b32 m0, s29
	v_readfirstlane_b32 s33, v121
	v_add_u32_e32 v122, 0xc800, v126
	global_load_lds_dwordx4 v[0:1], off
	v_lshl_add_u64 v[0:1], v[68:69], 0, s[20:21]
	s_mov_b32 m0, s33
	v_readfirstlane_b32 s34, v122
	v_add_u32_e32 v123, 0xcc00, v126
	global_load_lds_dwordx4 v[0:1], off
	v_lshl_add_u64 v[0:1], v[70:71], 0, s[20:21]
	s_mov_b32 m0, s34
	v_readfirstlane_b32 s35, v123
	v_add_u32_e32 v124, s85, v5
	global_load_lds_dwordx4 v[0:1], off
	v_lshl_add_u64 v[0:1], v[72:73], 0, s[20:21]
	s_mov_b32 m0, s35
	v_readfirstlane_b32 s36, v124
	v_add_u32_e32 v125, 0x14400, v6
	global_load_lds_dwordx4 v[0:1], off
	v_lshl_add_u64 v[0:1], v[74:75], 0, s[20:21]
	s_mov_b32 m0, s36
	v_readfirstlane_b32 s37, v125
	global_load_lds_dwordx4 v[0:1], off
	v_lshl_add_u64 v[0:1], v[76:77], 0, s[20:21]
	s_mov_b32 m0, s37
	v_lshrrev_b32_e32 v2, 1, v78
	v_bfe_u32 v64, v78, 5, 1
	global_load_lds_dwordx4 v[0:1], off
	v_add_u32_e32 v114, s3, v3
	v_bitop3_b32 v0, v2, v64, 7 bitop3:0x6c
	s_waitcnt vmcnt(6)
	s_mov_b64 s[30:31], 0x100
	v_readfirstlane_b32 s1, v114
	v_add_u32_e32 v115, 0x400, v114
	v_lshlrev_b32_e32 v132, 4, v0
	s_waitcnt lgkmcnt(0)
	s_barrier
	v_lshl_add_u64 v[0:1], v[66:67], 0, s[30:31]
	s_mov_b32 m0, s1
	v_readfirstlane_b32 s20, v115
	v_add_u32_e32 v116, 0x800, v114
	global_load_lds_dwordx4 v[0:1], off
	v_lshl_add_u64 v[0:1], v[68:69], 0, s[30:31]
	s_mov_b32 m0, s20
	v_readfirstlane_b32 s21, v116
	v_add_u32_e32 v117, 0xc00, v114
	v_readlane_b32 s24, v212, 31
	v_and_b32_e32 v79, 31, v78
	global_load_lds_dwordx4 v[0:1], off
	v_lshl_add_u64 v[0:1], v[70:71], 0, s[30:31]
	s_mov_b32 m0, s21
	v_readfirstlane_b32 s23, v117
	v_add_u32_e32 v118, s24, v5
	v_add_u32_e32 v2, s3, v5
	v_lshlrev_b32_e32 v4, 7, v79
	global_load_lds_dwordx4 v[0:1], off
	v_lshl_add_u64 v[0:1], v[72:73], 0, s[30:31]
	s_mov_b32 m0, s23
	v_readfirstlane_b32 s24, v118
	v_add_u32_e32 v119, 0x8400, v2
	v_lshl_or_b32 v102, v80, 13, v4
	global_load_lds_dwordx4 v[0:1], off
	v_lshl_add_u64 v[0:1], v[74:75], 0, s[30:31]
	s_mov_b32 m0, s24
	v_readfirstlane_b32 s28, v119
	global_load_lds_dwordx4 v[0:1], off
	v_lshl_add_u64 v[0:1], v[76:77], 0, s[30:31]
	s_mov_b32 m0, s28
	v_add_u32_e32 v100, 0, v102
	global_load_lds_dwordx4 v[0:1], off
	v_add_u32_e32 v83, v100, v132
	v_ashrrev_i32_e32 v81, 7, v78
	ds_read_b128 v[0:3], v83 offset:32768
	ds_read_b128 v[8:11], v83 offset:36864
	v_lshl_or_b32 v134, v81, 13, v4
	v_add_u32_e32 v101, 0, v134
	v_add_u32_e32 v82, v101, v132
	ds_read_b128 v[4:7], v82
	ds_read_b128 v[150:153], v82 offset:4096
	s_waitcnt lgkmcnt(1)
	v_lshrrev_b32_e32 v182, 6, v133
	s_nop 0
	v_readfirstlane_b32 s32, v182
	v_mfma_f32_32x32x16_bf16 v[48:63], v[0:3], v[4:7], 0
	v_bfe_u32 v103, v78, 1, 3
	s_mov_b64 s[30:31], 0x180
	s_nop 0
	v_or_b32_e32 v143, 0x8000, v102
	v_or_b32_e32 v144, 0x9000, v102
	v_add_u32_e32 v145, s3, v134
	v_lshl_or_b32 v81, v81, 6, v79
	s_waitcnt vmcnt(12)
	v_mfma_f32_32x32x16_bf16 v[32:47], v[8:11], v[4:7], 0
	v_mul_lo_u32 v81, v81, s26
	s_mov_b64 s[80:81], 0x200
	s_waitcnt lgkmcnt(0)
	v_mfma_f32_32x32x16_bf16 v[16:31], v[0:3], v[150:153], 0
	v_bitop3_b32 v0, v64, v103, 2 bitop3:0x36
	v_lshlrev_b32_e32 v138, 4, v0
	v_add_u32_e32 v85, v100, v138
	ds_read_b128 v[86:89], v85 offset:32768
	ds_read_b128 v[94:97], v85 offset:36864
	v_add_u32_e32 v84, v101, v138
	ds_read_b128 v[90:93], v84
	v_mfma_f32_32x32x16_bf16 v[0:15], v[8:11], v[150:153], 0
	ds_read_b128 v[154:157], v84 offset:4096
	s_waitcnt lgkmcnt(1)
	v_mfma_f32_32x32x16_bf16 v[48:63], v[86:89], v[90:93], v[48:63]
	v_mfma_f32_32x32x16_bf16 v[32:47], v[94:97], v[90:93], v[32:47]
	s_waitcnt lgkmcnt(0)
	v_mfma_f32_32x32x16_bf16 v[16:31], v[86:89], v[154:157], v[16:31]
	v_bitop3_b32 v86, v64, v103, 4 bitop3:0x36
	v_lshlrev_b32_e32 v139, 4, v86
	v_add_u32_e32 v87, v100, v139
	v_add_u32_e32 v86, v101, v139
	v_mfma_f32_32x32x16_bf16 v[0:15], v[94:97], v[154:157], v[0:15]
	ds_read_b128 v[88:91], v87 offset:32768
	ds_read_b128 v[92:95], v86
	ds_read_b128 v[96:99], v87 offset:36864
	ds_read_b128 v[150:153], v86 offset:4096
	s_waitcnt lgkmcnt(1)
	v_mfma_f32_32x32x16_bf16 v[48:63], v[88:91], v[92:95], v[48:63]
	v_mfma_f32_32x32x16_bf16 v[32:47], v[96:99], v[92:95], v[32:47]
	s_waitcnt lgkmcnt(0)
	v_mfma_f32_32x32x16_bf16 v[16:31], v[88:91], v[150:153], v[16:31]
	v_bitop3_b32 v88, v64, v103, 6 bitop3:0x36
	v_lshlrev_b32_e32 v142, 4, v88
	v_add_u32_e32 v89, v100, v142
	v_add_u32_e32 v88, v101, v142
	v_lshlrev_b32_e32 v64, 4, v64
	v_lshl_or_b32 v64, v80, 8, v64
	v_add3_u32 v64, 0, v81, v64
	v_mfma_f32_32x32x16_bf16 v[0:15], v[96:99], v[150:153], v[0:15]
	ds_read_b128 v[90:93], v89 offset:32768
	ds_read_b128 v[94:97], v88
	ds_read_b128 v[98:101], v89 offset:36864
	ds_read_b128 v[154:157], v88 offset:4096
	s_waitcnt lgkmcnt(1)
	v_mfma_f32_32x32x16_bf16 v[48:63], v[90:93], v[94:97], v[48:63]
	v_mfma_f32_32x32x16_bf16 v[32:47], v[98:101], v[94:97], v[32:47]
	s_waitcnt vmcnt(6)
	s_waitcnt lgkmcnt(0)
	s_barrier
	s_waitcnt lgkmcnt(0)
	v_mfma_f32_32x32x16_bf16 v[16:31], v[90:93], v[154:157], v[16:31]
	v_lshl_add_u64 v[158:159], v[66:67], 0, s[30:31]
	s_nop 0
	v_lshl_add_u64 v[160:161], v[68:69], 0, s[30:31]
	s_nop 0
	s_nop 0
	s_nop 0
	v_lshl_add_u64 v[162:163], v[70:71], 0, s[30:31]
	s_nop 0
	v_mfma_f32_32x32x16_bf16 v[0:15], v[98:101], v[154:157], v[0:15]
	s_and_b32 m0, s32, 7
	s_lshl_b32 m0, m0, 12
	s_add_i32 m0, m0, 0x0
	s_nop 0
	global_load_lds_dwordx4 v[158:159], off
	s_nop 0
	v_lshl_add_u64 v[164:165], v[72:73], 0, s[30:31]
	s_nop 0
	s_nop 0
	s_nop 0
	v_lshl_add_u64 v[166:167], v[74:75], 0, s[30:31]
	s_nop 0
	s_nop 0
	s_nop 0
	v_lshl_add_u64 v[168:169], v[76:77], 0, s[30:31]
	s_nop 0
	s_add_i32 s30, 0, 0xc000
	s_nop 0
	v_add_u32_e32 v90, s30, v132
	v_add_u32_e32 v92, v90, v143
	v_add_u32_e32 v90, v90, v144
	ds_read_b128 v[94:97], v92
	ds_read_b128 v[98:101], v82 offset:49152
	ds_read_b128 v[102:105], v90
	ds_read_b128 v[150:153], v82 offset:53248
	s_waitcnt lgkmcnt(1)
	v_mfma_f32_32x32x16_bf16 v[48:63], v[94:97], v[98:101], v[48:63]
	v_add_u32_e32 v91, s30, v138
	v_add_u32_e32 v93, v91, v143
	v_add_u32_e32 v91, v91, v144
	s_nop 0
	v_mfma_f32_32x32x16_bf16 v[32:47], v[102:105], v[98:101], v[32:47]
	s_and_b32 m0, s32, 7
	s_lshl_b32 m0, m0, 12
	s_add_i32 m0, m0, 0x400
	s_nop 0
	global_load_lds_dwordx4 v[160:161], off
	s_waitcnt lgkmcnt(0)
	v_mfma_f32_32x32x16_bf16 v[16:31], v[94:97], v[150:153], v[16:31]
	v_mfma_f32_32x32x16_bf16 v[0:15], v[102:105], v[150:153], v[0:15]
	s_and_b32 m0, s32, 7
	s_lshl_b32 m0, m0, 12
	s_add_i32 m0, m0, 0x800
	s_nop 0
	global_load_lds_dwordx4 v[162:163], off
	ds_read_b128 v[94:97], v93
	ds_read_b128 v[98:101], v84 offset:49152
	ds_read_b128 v[102:105], v91
	ds_read_b128 v[154:157], v84 offset:53248
	s_waitcnt lgkmcnt(1)
	v_mfma_f32_32x32x16_bf16 v[48:63], v[94:97], v[98:101], v[48:63]
	v_mfma_f32_32x32x16_bf16 v[32:47], v[102:105], v[98:101], v[32:47]
	s_and_b32 m0, s32, 7
	s_lshl_b32 m0, m0, 12
	s_add_i32 m0, m0, 0xc00
	s_nop 0
	global_load_lds_dwordx4 v[164:165], off
	s_waitcnt lgkmcnt(0)
	v_mfma_f32_32x32x16_bf16 v[16:31], v[94:97], v[154:157], v[16:31]
	v_add_u32_e32 v94, s30, v139
	v_add_u32_e32 v95, v94, v143
	v_add_u32_e32 v94, v94, v144
	v_mfma_f32_32x32x16_bf16 v[0:15], v[102:105], v[154:157], v[0:15]
	s_and_b32 m0, s32, 7
	s_lshl_b32 m0, m0, 11
	s_add_i32 m0, m0, 0x8000
	s_nop 0
	global_load_lds_dwordx4 v[166:167], off
	ds_read_b128 v[96:99], v95
	ds_read_b128 v[100:103], v86 offset:49152
	ds_read_b128 v[104:107], v94
	ds_read_b128 v[150:153], v86 offset:53248
	s_waitcnt lgkmcnt(1)
	v_mfma_f32_32x32x16_bf16 v[48:63], v[96:99], v[100:103], v[48:63]
	v_mfma_f32_32x32x16_bf16 v[32:47], v[104:107], v[100:103], v[32:47]
	s_and_b32 m0, s32, 7
	s_lshl_b32 m0, m0, 11
	s_add_i32 m0, m0, 0x8400
	s_nop 0
	global_load_lds_dwordx4 v[168:169], off
	s_waitcnt lgkmcnt(0)
	v_mfma_f32_32x32x16_bf16 v[16:31], v[96:99], v[150:153], v[16:31]
	v_add_u32_e32 v96, s30, v142
	v_add_u32_e32 v97, v96, v143
	v_add_u32_e32 v96, v96, v144
	s_mov_b64 s[30:31], 0x200
	v_mfma_f32_32x32x16_bf16 v[0:15], v[104:107], v[150:153], v[0:15]
	ds_read_b128 v[98:101], v97
	ds_read_b128 v[102:105], v88 offset:49152
	ds_read_b128 v[106:109], v96
	ds_read_b128 v[154:157], v88 offset:53248
	s_waitcnt lgkmcnt(1)
	v_mfma_f32_32x32x16_bf16 v[48:63], v[98:101], v[102:105], v[48:63]
	v_mfma_f32_32x32x16_bf16 v[32:47], v[106:109], v[102:105], v[32:47]
	s_waitcnt vmcnt(6)
	s_waitcnt lgkmcnt(0)
	s_barrier
	s_waitcnt lgkmcnt(0)
	v_mfma_f32_32x32x16_bf16 v[16:31], v[98:101], v[154:157], v[16:31]
	v_lshl_add_u64 v[170:171], v[66:67], 0, s[30:31]
	s_nop 0
	v_lshl_add_u64 v[172:173], v[68:69], 0, s[30:31]
	s_nop 0
	v_add_u32_e32 v101, s3, v132
	s_nop 0
	v_lshl_add_u64 v[174:175], v[70:71], 0, s[30:31]
	s_nop 0
	v_mfma_f32_32x32x16_bf16 v[0:15], v[106:109], v[154:157], v[0:15]
	s_and_b32 m0, s32, 7
	s_lshl_b32 m0, m0, 12
	s_add_i32 m0, m0, 0xc000
	s_nop 0
	global_load_lds_dwordx4 v[170:171], off
	s_nop 0
	v_lshl_add_u64 v[176:177], v[72:73], 0, s[30:31]
	s_nop 0
	v_add_u32_e32 v100, v145, v132
	s_nop 0
	v_lshl_add_u64 v[178:179], v[74:75], 0, s[30:31]
	s_nop 0
	v_or_b32_e32 v132, 0x1000, v134
	s_nop 0
	v_lshl_add_u64 v[180:181], v[76:77], 0, s[30:31]
	s_nop 0
	s_mov_b64 s[30:31], 0x280
	s_nop 0
	v_add_u32_e32 v98, v101, v143
	v_add_u32_e32 v99, v101, v144
	ds_read_b128 v[110:113], v98
	ds_read_b128 v[106:109], v99
	ds_read_b128 v[102:105], v100
	v_add_u32_e32 v101, v101, v132
	ds_read_b128 v[134:137], v101
	s_waitcnt lgkmcnt(0)
	v_mfma_f32_32x32x16_bf16 v[48:63], v[110:113], v[102:105], v[48:63]
	s_nop 0
	v_mfma_f32_32x32x16_bf16 v[32:47], v[106:109], v[102:105], v[32:47]
	s_and_b32 m0, s32, 7
	s_lshl_b32 m0, m0, 12
	s_add_i32 m0, m0, 0xc400
	s_nop 0
	global_load_lds_dwordx4 v[172:173], off
	v_add_u32_e32 v105, s3, v138
	v_add_u32_e32 v102, v105, v143
	v_add_u32_e32 v103, v105, v144
	v_add_u32_e32 v104, v145, v138
	v_add_u32_e32 v105, v105, v132
	v_mfma_f32_32x32x16_bf16 v[16:31], v[110:113], v[134:137], v[16:31]
	ds_read_b128 v[110:113], v104
	v_mfma_f32_32x32x16_bf16 v[0:15], v[106:109], v[134:137], v[0:15]
	s_and_b32 m0, s32, 7
	s_lshl_b32 m0, m0, 12
	s_add_i32 m0, m0, 0xc800
	s_nop 0
	global_load_lds_dwordx4 v[174:175], off
	ds_read_b128 v[106:109], v102
	ds_read_b128 v[134:137], v103
	ds_read_b128 v[150:153], v105
	s_waitcnt lgkmcnt(1)
	v_mfma_f32_32x32x16_bf16 v[48:63], v[106:109], v[110:113], v[48:63]
	v_mfma_f32_32x32x16_bf16 v[32:47], v[134:137], v[110:113], v[32:47]
	s_and_b32 m0, s32, 7
	s_lshl_b32 m0, m0, 12
	s_add_i32 m0, m0, 0xcc00
	s_nop 0
	global_load_lds_dwordx4 v[176:177], off
	s_waitcnt lgkmcnt(0)
	v_mfma_f32_32x32x16_bf16 v[16:31], v[106:109], v[150:153], v[16:31]
	v_add_u32_e32 v109, s3, v139
	v_add_u32_e32 v106, v109, v143
	v_add_u32_e32 v107, v109, v144
	v_add_u32_e32 v108, v145, v139
	ds_read_b128 v[138:141], v107
	v_add_u32_e32 v109, v109, v132
	v_mfma_f32_32x32x16_bf16 v[0:15], v[134:137], v[150:153], v[0:15]
	s_and_b32 m0, s32, 7
	s_lshl_b32 m0, m0, 11
	s_add_i32 m0, m0, 0x14000
	s_nop 0
	global_load_lds_dwordx4 v[178:179], off
	ds_read_b128 v[110:113], v106
	ds_read_b128 v[134:137], v108
	ds_read_b128 v[154:157], v109
	s_waitcnt lgkmcnt(1)
	v_mfma_f32_32x32x16_bf16 v[48:63], v[110:113], v[134:137], v[48:63]
	v_mfma_f32_32x32x16_bf16 v[32:47], v[138:141], v[134:137], v[32:47]
	s_and_b32 m0, s32, 7
	s_lshl_b32 m0, m0, 11
	s_add_i32 m0, m0, 0x14400
	s_nop 0
	global_load_lds_dwordx4 v[180:181], off
	s_waitcnt lgkmcnt(0)
	v_mfma_f32_32x32x16_bf16 v[16:31], v[110:113], v[154:157], v[16:31]
	v_add_u32_e32 v113, s3, v142
	v_add_u32_e32 v110, v113, v143
	v_add_u32_e32 v111, v113, v144
	v_add_u32_e32 v112, v145, v142
	ds_read_b128 v[142:145], v111
	v_add_u32_e32 v113, v113, v132
	v_mfma_f32_32x32x16_bf16 v[0:15], v[138:141], v[154:157], v[0:15]
	ds_read_b128 v[134:137], v110
	ds_read_b128 v[138:141], v112
	ds_read_b128 v[150:153], v113
	s_waitcnt lgkmcnt(1)
	v_mfma_f32_32x32x16_bf16 v[48:63], v[134:137], v[138:141], v[48:63]
	v_mfma_f32_32x32x16_bf16 v[32:47], v[142:145], v[138:141], v[32:47]
	s_waitcnt vmcnt(6)
	s_waitcnt lgkmcnt(0)
	s_barrier
	s_waitcnt lgkmcnt(0)
	v_mfma_f32_32x32x16_bf16 v[16:31], v[134:137], v[150:153], v[16:31]
	v_lshl_add_u64 v[158:159], v[66:67], 0, s[30:31]
	s_nop 0
	v_lshl_add_u64 v[160:161], v[68:69], 0, s[30:31]
	s_nop 0
	s_nop 0
	s_nop 0
	v_lshl_add_u64 v[162:163], v[70:71], 0, s[30:31]
	s_nop 0
	v_mfma_f32_32x32x16_bf16 v[0:15], v[142:145], v[150:153], v[0:15]
	s_and_b32 m0, s32, 7
	s_lshl_b32 m0, m0, 12
	s_add_i32 m0, m0, 0x18000
	s_nop 0
	global_load_lds_dwordx4 v[158:159], off
	s_nop 0
	v_lshl_add_u64 v[164:165], v[72:73], 0, s[30:31]
	s_nop 0
	s_nop 0
	s_nop 0
	v_lshl_add_u64 v[166:167], v[74:75], 0, s[30:31]
	s_nop 0
	s_nop 0
	s_nop 0
	v_lshl_add_u64 v[168:169], v[76:77], 0, s[30:31]
	s_nop 0
	s_mov_b64 s[30:31], 0x300
	s_nop 0
	ds_read_b128 v[134:137], v83 offset:32768
	ds_read_b128 v[138:141], v82
	ds_read_b128 v[142:145], v83 offset:36864
	ds_read_b128 v[154:157], v82 offset:4096
	s_waitcnt lgkmcnt(1)
	v_mfma_f32_32x32x16_bf16 v[48:63], v[134:137], v[138:141], v[48:63]
	s_nop 0
	v_readfirstlane_b32 s38, v114
	v_mfma_f32_32x32x16_bf16 v[32:47], v[142:145], v[138:141], v[32:47]
	s_and_b32 m0, s32, 7
	s_lshl_b32 m0, m0, 12
	s_add_i32 m0, m0, 0x18400
	s_nop 0
	global_load_lds_dwordx4 v[160:161], off
	s_waitcnt lgkmcnt(0)
	v_mfma_f32_32x32x16_bf16 v[16:31], v[134:137], v[154:157], v[16:31]
	v_mfma_f32_32x32x16_bf16 v[0:15], v[142:145], v[154:157], v[0:15]
	s_and_b32 m0, s32, 7
	s_lshl_b32 m0, m0, 12
	s_add_i32 m0, m0, 0x18800
	s_nop 0
	global_load_lds_dwordx4 v[162:163], off
	ds_read_b128 v[134:137], v85 offset:32768
	ds_read_b128 v[138:141], v84
	ds_read_b128 v[142:145], v85 offset:36864
	ds_read_b128 v[150:153], v84 offset:4096
	s_waitcnt lgkmcnt(1)
	v_mfma_f32_32x32x16_bf16 v[48:63], v[134:137], v[138:141], v[48:63]
	v_mfma_f32_32x32x16_bf16 v[32:47], v[142:145], v[138:141], v[32:47]
	s_and_b32 m0, s32, 7
	s_lshl_b32 m0, m0, 12
	s_add_i32 m0, m0, 0x18c00
	s_nop 0
	global_load_lds_dwordx4 v[164:165], off
	s_waitcnt lgkmcnt(0)
	v_mfma_f32_32x32x16_bf16 v[16:31], v[134:137], v[150:153], v[16:31]
	v_mfma_f32_32x32x16_bf16 v[0:15], v[142:145], v[150:153], v[0:15]
	s_and_b32 m0, s32, 7
	s_lshl_b32 m0, m0, 11
	s_add_i32 m0, m0, 0x20000
	s_nop 0
	global_load_lds_dwordx4 v[166:167], off
	ds_read_b128 v[134:137], v87 offset:32768
	ds_read_b128 v[138:141], v86
	ds_read_b128 v[142:145], v87 offset:36864
	ds_read_b128 v[154:157], v86 offset:4096
	s_waitcnt lgkmcnt(1)
	v_mfma_f32_32x32x16_bf16 v[48:63], v[134:137], v[138:141], v[48:63]
	v_mfma_f32_32x32x16_bf16 v[32:47], v[142:145], v[138:141], v[32:47]
	s_and_b32 m0, s32, 7
	s_lshl_b32 m0, m0, 11
	s_add_i32 m0, m0, 0x20400
	s_nop 0
	global_load_lds_dwordx4 v[168:169], off
	s_waitcnt lgkmcnt(0)
	v_mfma_f32_32x32x16_bf16 v[16:31], v[134:137], v[154:157], v[16:31]
	v_mfma_f32_32x32x16_bf16 v[0:15], v[142:145], v[154:157], v[0:15]
	ds_read_b128 v[134:137], v89 offset:32768
	ds_read_b128 v[138:141], v88
	ds_read_b128 v[142:145], v89 offset:36864
	ds_read_b128 v[150:153], v88 offset:4096
	s_waitcnt lgkmcnt(1)
	v_mfma_f32_32x32x16_bf16 v[48:63], v[134:137], v[138:141], v[48:63]
	v_mfma_f32_32x32x16_bf16 v[32:47], v[142:145], v[138:141], v[32:47]
	s_waitcnt vmcnt(6)
	s_waitcnt lgkmcnt(0)
	s_barrier
	s_waitcnt lgkmcnt(0)
	v_mfma_f32_32x32x16_bf16 v[16:31], v[134:137], v[150:153], v[16:31]
	v_lshl_add_u64 v[170:171], v[66:67], 0, s[30:31]
	s_nop 0
	v_lshl_add_u64 v[172:173], v[68:69], 0, s[30:31]
	s_nop 0
	v_readfirstlane_b32 s39, v115
	s_nop 0
	v_lshl_add_u64 v[174:175], v[70:71], 0, s[30:31]
	s_nop 0
	v_mfma_f32_32x32x16_bf16 v[0:15], v[142:145], v[150:153], v[0:15]
	s_and_b32 m0, s32, 7
	s_lshl_b32 m0, m0, 12
	s_add_i32 m0, m0, 0x0
	s_nop 0
	global_load_lds_dwordx4 v[170:171], off
	s_nop 0
	v_lshl_add_u64 v[176:177], v[72:73], 0, s[30:31]
	s_nop 0
	v_readfirstlane_b32 s48, v116
	s_nop 0
	v_lshl_add_u64 v[178:179], v[74:75], 0, s[30:31]
	s_nop 0
	v_readfirstlane_b32 s49, v117
	s_nop 0
	v_lshl_add_u64 v[180:181], v[76:77], 0, s[30:31]
	s_nop 0
	s_mov_b64 s[30:31], 0x380
	s_nop 0
	ds_read_b128 v[134:137], v92
	ds_read_b128 v[138:141], v82 offset:49152
	ds_read_b128 v[142:145], v90
	ds_read_b128 v[154:157], v82 offset:53248
	s_waitcnt lgkmcnt(1)
	v_mfma_f32_32x32x16_bf16 v[48:63], v[134:137], v[138:141], v[48:63]
	s_nop 0
	v_readfirstlane_b32 s53, v118
	v_readfirstlane_b32 s54, v119
	v_mfma_f32_32x32x16_bf16 v[32:47], v[142:145], v[138:141], v[32:47]
	s_and_b32 m0, s32, 7
	s_lshl_b32 m0, m0, 12
	s_add_i32 m0, m0, 0x400
	s_nop 0
	global_load_lds_dwordx4 v[172:173], off
	s_waitcnt lgkmcnt(0)
	v_mfma_f32_32x32x16_bf16 v[16:31], v[134:137], v[154:157], v[16:31]
	v_mfma_f32_32x32x16_bf16 v[0:15], v[142:145], v[154:157], v[0:15]
	s_and_b32 m0, s32, 7
	s_lshl_b32 m0, m0, 12
	s_add_i32 m0, m0, 0x800
	s_nop 0
	global_load_lds_dwordx4 v[174:175], off
	ds_read_b128 v[134:137], v93
	ds_read_b128 v[138:141], v84 offset:49152
	ds_read_b128 v[142:145], v91
	ds_read_b128 v[150:153], v84 offset:53248
	s_waitcnt lgkmcnt(1)
	v_mfma_f32_32x32x16_bf16 v[48:63], v[134:137], v[138:141], v[48:63]
	v_mfma_f32_32x32x16_bf16 v[32:47], v[142:145], v[138:141], v[32:47]
	s_and_b32 m0, s32, 7
	s_lshl_b32 m0, m0, 12
	s_add_i32 m0, m0, 0xc00
	s_nop 0
	global_load_lds_dwordx4 v[176:177], off
	s_waitcnt lgkmcnt(0)
	v_mfma_f32_32x32x16_bf16 v[16:31], v[134:137], v[150:153], v[16:31]
	v_mfma_f32_32x32x16_bf16 v[0:15], v[142:145], v[150:153], v[0:15]
	s_and_b32 m0, s32, 7
	s_lshl_b32 m0, m0, 11
	s_add_i32 m0, m0, 0x8000
	s_nop 0
	global_load_lds_dwordx4 v[178:179], off
	ds_read_b128 v[134:137], v95
	ds_read_b128 v[138:141], v86 offset:49152
	ds_read_b128 v[142:145], v94
	ds_read_b128 v[154:157], v86 offset:53248
	s_waitcnt lgkmcnt(1)
	v_mfma_f32_32x32x16_bf16 v[48:63], v[134:137], v[138:141], v[48:63]
	v_mfma_f32_32x32x16_bf16 v[32:47], v[142:145], v[138:141], v[32:47]
	s_and_b32 m0, s32, 7
	s_lshl_b32 m0, m0, 11
	s_add_i32 m0, m0, 0x8400
	s_nop 0
	global_load_lds_dwordx4 v[180:181], off
	s_waitcnt lgkmcnt(0)
	v_mfma_f32_32x32x16_bf16 v[16:31], v[134:137], v[154:157], v[16:31]
	v_mfma_f32_32x32x16_bf16 v[0:15], v[142:145], v[154:157], v[0:15]
	ds_read_b128 v[134:137], v97
	ds_read_b128 v[138:141], v88 offset:49152
	ds_read_b128 v[142:145], v96
	ds_read_b128 v[150:153], v88 offset:53248
	s_waitcnt lgkmcnt(1)
	v_mfma_f32_32x32x16_bf16 v[48:63], v[134:137], v[138:141], v[48:63]
	v_mfma_f32_32x32x16_bf16 v[32:47], v[142:145], v[138:141], v[32:47]
	s_waitcnt vmcnt(6)
	s_waitcnt lgkmcnt(0)
	s_barrier
	s_waitcnt lgkmcnt(0)
	v_mfma_f32_32x32x16_bf16 v[16:31], v[134:137], v[150:153], v[16:31]
	v_lshl_add_u64 v[158:159], v[66:67], 0, s[30:31]
	s_nop 0
	v_lshl_add_u64 v[160:161], v[68:69], 0, s[30:31]
	s_nop 0
	v_readfirstlane_b32 s33, v121
	s_nop 0
	v_lshl_add_u64 v[162:163], v[70:71], 0, s[30:31]
	s_nop 0
	v_mfma_f32_32x32x16_bf16 v[0:15], v[142:145], v[150:153], v[0:15]
	s_and_b32 m0, s32, 7
	s_lshl_b32 m0, m0, 12
	s_add_i32 m0, m0, 0xc000
	s_nop 0
	global_load_lds_dwordx4 v[158:159], off
	s_nop 0
	v_lshl_add_u64 v[164:165], v[72:73], 0, s[30:31]
	s_nop 0
	v_readfirstlane_b32 s34, v122
	s_nop 0
	v_lshl_add_u64 v[166:167], v[74:75], 0, s[30:31]
	s_nop 0
	v_readfirstlane_b32 s35, v123
	s_nop 0
	v_lshl_add_u64 v[168:169], v[76:77], 0, s[30:31]
	s_nop 0
	s_mov_b64 s[30:31], 0x400
	s_nop 0
	ds_read_b128 v[134:137], v98
	ds_read_b128 v[138:141], v100
	ds_read_b128 v[142:145], v99
	ds_read_b128 v[154:157], v101
	s_waitcnt lgkmcnt(1)
	v_mfma_f32_32x32x16_bf16 v[48:63], v[134:137], v[138:141], v[48:63]
	s_nop 0
	v_readfirstlane_b32 s1, v126
	v_readfirstlane_b32 s36, v124
	v_readfirstlane_b32 s37, v125
	v_mfma_f32_32x32x16_bf16 v[32:47], v[142:145], v[138:141], v[32:47]
	s_and_b32 m0, s32, 7
	s_lshl_b32 m0, m0, 12
	s_add_i32 m0, m0, 0xc400
	s_nop 0
	global_load_lds_dwordx4 v[160:161], off
	s_waitcnt lgkmcnt(0)
	v_mfma_f32_32x32x16_bf16 v[16:31], v[134:137], v[154:157], v[16:31]
	v_mfma_f32_32x32x16_bf16 v[0:15], v[142:145], v[154:157], v[0:15]
	s_and_b32 m0, s32, 7
	s_lshl_b32 m0, m0, 12
	s_add_i32 m0, m0, 0xc800
	s_nop 0
	global_load_lds_dwordx4 v[162:163], off
	ds_read_b128 v[134:137], v102
	ds_read_b128 v[138:141], v104
	ds_read_b128 v[142:145], v103
	ds_read_b128 v[150:153], v105
	s_waitcnt lgkmcnt(1)
	v_mfma_f32_32x32x16_bf16 v[48:63], v[134:137], v[138:141], v[48:63]
	v_mfma_f32_32x32x16_bf16 v[32:47], v[142:145], v[138:141], v[32:47]
	s_and_b32 m0, s32, 7
	s_lshl_b32 m0, m0, 12
	s_add_i32 m0, m0, 0xcc00
	s_nop 0
	global_load_lds_dwordx4 v[164:165], off
	s_waitcnt lgkmcnt(0)
	v_mfma_f32_32x32x16_bf16 v[16:31], v[134:137], v[150:153], v[16:31]
	v_mfma_f32_32x32x16_bf16 v[0:15], v[142:145], v[150:153], v[0:15]
	s_and_b32 m0, s32, 7
	s_lshl_b32 m0, m0, 11
	s_add_i32 m0, m0, 0x14000
	s_nop 0
	global_load_lds_dwordx4 v[166:167], off
	ds_read_b128 v[134:137], v106
	ds_read_b128 v[138:141], v108
	ds_read_b128 v[142:145], v107
	ds_read_b128 v[154:157], v109
	s_waitcnt lgkmcnt(1)
	v_mfma_f32_32x32x16_bf16 v[48:63], v[134:137], v[138:141], v[48:63]
	v_mfma_f32_32x32x16_bf16 v[32:47], v[142:145], v[138:141], v[32:47]
	s_and_b32 m0, s32, 7
	s_lshl_b32 m0, m0, 11
	s_add_i32 m0, m0, 0x14400
	s_nop 0
	global_load_lds_dwordx4 v[168:169], off
	s_waitcnt lgkmcnt(0)
	v_mfma_f32_32x32x16_bf16 v[16:31], v[134:137], v[154:157], v[16:31]
	v_mfma_f32_32x32x16_bf16 v[0:15], v[142:145], v[154:157], v[0:15]
	ds_read_b128 v[134:137], v110
	ds_read_b128 v[138:141], v112
	ds_read_b128 v[142:145], v111
	ds_read_b128 v[150:153], v113
	s_waitcnt lgkmcnt(1)
	v_mfma_f32_32x32x16_bf16 v[48:63], v[134:137], v[138:141], v[48:63]
	v_mfma_f32_32x32x16_bf16 v[32:47], v[142:145], v[138:141], v[32:47]
	s_waitcnt vmcnt(6)
	s_waitcnt lgkmcnt(0)
	s_barrier
	s_waitcnt lgkmcnt(0)
	v_mfma_f32_32x32x16_bf16 v[16:31], v[134:137], v[150:153], v[16:31]
	v_lshl_add_u64 v[170:171], v[66:67], 0, s[30:31]
	s_nop 0
	v_lshl_add_u64 v[172:173], v[68:69], 0, s[30:31]
	s_nop 0
	v_readfirstlane_b32 s20, v127
	s_nop 0
	v_lshl_add_u64 v[174:175], v[70:71], 0, s[30:31]
	s_nop 0
	v_mfma_f32_32x32x16_bf16 v[0:15], v[142:145], v[150:153], v[0:15]
	s_and_b32 m0, s32, 7
	s_lshl_b32 m0, m0, 12
	s_add_i32 m0, m0, 0x18000
	s_nop 0
	global_load_lds_dwordx4 v[170:171], off
	s_nop 0
	v_lshl_add_u64 v[176:177], v[72:73], 0, s[30:31]
	s_nop 0
	v_readfirstlane_b32 s21, v128
	s_nop 0
	v_lshl_add_u64 v[178:179], v[74:75], 0, s[30:31]
	s_nop 0
	v_readfirstlane_b32 s23, v129
	s_nop 0
	v_lshl_add_u64 v[180:181], v[76:77], 0, s[30:31]
	s_nop 0
	s_mov_b64 s[28:29], 0x480
	s_nop 0
	ds_read_b128 v[134:137], v83 offset:32768
	ds_read_b128 v[138:141], v82
	ds_read_b128 v[142:145], v83 offset:36864
	ds_read_b128 v[154:157], v82 offset:4096
	s_waitcnt lgkmcnt(1)
	v_mfma_f32_32x32x16_bf16 v[48:63], v[134:137], v[138:141], v[48:63]
	s_nop 0
	v_lshl_add_u64 v[162:163], v[70:71], 0, s[28:29]
	v_readfirstlane_b32 s24, v131
	s_mov_b64 s[30:31], 0x500
	v_mfma_f32_32x32x16_bf16 v[32:47], v[142:145], v[138:141], v[32:47]
	s_and_b32 m0, s32, 7
	s_lshl_b32 m0, m0, 12
	s_add_i32 m0, m0, 0x18400
	s_nop 0
	global_load_lds_dwordx4 v[172:173], off
	s_waitcnt lgkmcnt(0)
	v_mfma_f32_32x32x16_bf16 v[16:31], v[134:137], v[154:157], v[16:31]
	v_mfma_f32_32x32x16_bf16 v[0:15], v[142:145], v[154:157], v[0:15]
	s_and_b32 m0, s32, 7
	s_lshl_b32 m0, m0, 12
	s_add_i32 m0, m0, 0x18800
	s_nop 0
	global_load_lds_dwordx4 v[174:175], off
	ds_read_b128 v[134:137], v85 offset:32768
	ds_read_b128 v[138:141], v84
	ds_read_b128 v[142:145], v85 offset:36864
	ds_read_b128 v[150:153], v84 offset:4096
	s_waitcnt lgkmcnt(1)
	v_mfma_f32_32x32x16_bf16 v[48:63], v[134:137], v[138:141], v[48:63]
	v_mfma_f32_32x32x16_bf16 v[32:47], v[142:145], v[138:141], v[32:47]
	s_and_b32 m0, s32, 7
	s_lshl_b32 m0, m0, 12
	s_add_i32 m0, m0, 0x18c00
	s_nop 0
	global_load_lds_dwordx4 v[176:177], off
	s_waitcnt lgkmcnt(0)
	v_mfma_f32_32x32x16_bf16 v[16:31], v[134:137], v[150:153], v[16:31]
	v_mfma_f32_32x32x16_bf16 v[0:15], v[142:145], v[150:153], v[0:15]
	s_and_b32 m0, s32, 7
	s_lshl_b32 m0, m0, 11
	s_add_i32 m0, m0, 0x20000
	s_nop 0
	global_load_lds_dwordx4 v[178:179], off
	ds_read_b128 v[134:137], v87 offset:32768
	ds_read_b128 v[138:141], v86
	ds_read_b128 v[142:145], v87 offset:36864
	ds_read_b128 v[154:157], v86 offset:4096
	s_waitcnt lgkmcnt(1)
	v_mfma_f32_32x32x16_bf16 v[48:63], v[134:137], v[138:141], v[48:63]
	v_mfma_f32_32x32x16_bf16 v[32:47], v[142:145], v[138:141], v[32:47]
	s_and_b32 m0, s32, 7
	s_lshl_b32 m0, m0, 11
	s_add_i32 m0, m0, 0x20400
	s_nop 0
	global_load_lds_dwordx4 v[180:181], off
	s_waitcnt lgkmcnt(0)
	v_mfma_f32_32x32x16_bf16 v[16:31], v[134:137], v[154:157], v[16:31]
	v_mfma_f32_32x32x16_bf16 v[0:15], v[142:145], v[154:157], v[0:15]
	ds_read_b128 v[134:137], v89 offset:32768
	ds_read_b128 v[138:141], v88
	ds_read_b128 v[142:145], v89 offset:36864
	ds_read_b128 v[150:153], v88 offset:4096
	s_waitcnt lgkmcnt(1)
	v_mfma_f32_32x32x16_bf16 v[48:63], v[134:137], v[138:141], v[48:63]
	v_mfma_f32_32x32x16_bf16 v[32:47], v[142:145], v[138:141], v[32:47]
	s_waitcnt vmcnt(6)
	s_waitcnt lgkmcnt(0)
	s_barrier
	s_waitcnt lgkmcnt(0)
	v_mfma_f32_32x32x16_bf16 v[16:31], v[134:137], v[150:153], v[16:31]
	v_lshl_add_u64 v[158:159], v[66:67], 0, s[28:29]
	s_nop 0
	v_lshl_add_u64 v[160:161], v[68:69], 0, s[28:29]
	s_nop 0
	s_nop 0
	s_nop 0
	s_nop 0
	v_mfma_f32_32x32x16_bf16 v[0:15], v[142:145], v[150:153], v[0:15]
	s_and_b32 m0, s32, 7
	s_lshl_b32 m0, m0, 12
	s_add_i32 m0, m0, 0x0
	s_nop 0
	global_load_lds_dwordx4 v[158:159], off
	s_nop 0
	v_lshl_add_u64 v[164:165], v[72:73], 0, s[28:29]
	s_nop 0
	s_nop 0
	s_nop 0
	v_lshl_add_u64 v[166:167], v[74:75], 0, s[28:29]
	s_nop 0
	s_nop 0
	s_nop 0
	v_lshl_add_u64 v[168:169], v[76:77], 0, s[28:29]
	v_readfirstlane_b32 s28, v130
	s_nop 0
	v_readfirstlane_b32 s29, v120
	s_nop 0
	ds_read_b128 v[126:129], v92
	ds_read_b128 v[134:137], v82 offset:49152
	ds_read_b128 v[138:141], v90
	ds_read_b128 v[154:157], v82 offset:53248
	s_waitcnt lgkmcnt(1)
	v_mfma_f32_32x32x16_bf16 v[48:63], v[126:129], v[134:137], v[48:63]
	s_nop 0
	v_lshl_add_u64 v[174:175], v[70:71], 0, s[30:31]
	v_mfma_f32_32x32x16_bf16 v[32:47], v[138:141], v[134:137], v[32:47]
	s_and_b32 m0, s32, 7
	s_lshl_b32 m0, m0, 12
	s_add_i32 m0, m0, 0x400
	s_nop 0
	global_load_lds_dwordx4 v[160:161], off
	s_waitcnt lgkmcnt(0)
	v_mfma_f32_32x32x16_bf16 v[16:31], v[126:129], v[154:157], v[16:31]
	v_mfma_f32_32x32x16_bf16 v[0:15], v[138:141], v[154:157], v[0:15]
	s_and_b32 m0, s32, 7
	s_lshl_b32 m0, m0, 12
	s_add_i32 m0, m0, 0x800
	s_nop 0
	global_load_lds_dwordx4 v[162:163], off
	ds_read_b128 v[126:129], v93
	ds_read_b128 v[134:137], v84 offset:49152
	ds_read_b128 v[138:141], v91
	ds_read_b128 v[150:153], v84 offset:53248
	s_waitcnt lgkmcnt(1)
	v_mfma_f32_32x32x16_bf16 v[48:63], v[126:129], v[134:137], v[48:63]
	v_mfma_f32_32x32x16_bf16 v[32:47], v[138:141], v[134:137], v[32:47]
	s_and_b32 m0, s32, 7
	s_lshl_b32 m0, m0, 12
	s_add_i32 m0, m0, 0xc00
	s_nop 0
	global_load_lds_dwordx4 v[164:165], off
	s_waitcnt lgkmcnt(0)
	v_mfma_f32_32x32x16_bf16 v[16:31], v[126:129], v[150:153], v[16:31]
	v_mfma_f32_32x32x16_bf16 v[0:15], v[138:141], v[150:153], v[0:15]
	s_and_b32 m0, s32, 7
	s_lshl_b32 m0, m0, 11
	s_add_i32 m0, m0, 0x8000
	s_nop 0
	global_load_lds_dwordx4 v[166:167], off
	ds_read_b128 v[126:129], v95
	ds_read_b128 v[134:137], v86 offset:49152
	ds_read_b128 v[138:141], v94
	ds_read_b128 v[154:157], v86 offset:53248
	s_waitcnt lgkmcnt(1)
	v_mfma_f32_32x32x16_bf16 v[48:63], v[126:129], v[134:137], v[48:63]
	v_mfma_f32_32x32x16_bf16 v[32:47], v[138:141], v[134:137], v[32:47]
	s_and_b32 m0, s32, 7
	s_lshl_b32 m0, m0, 11
	s_add_i32 m0, m0, 0x8400
	s_nop 0
	global_load_lds_dwordx4 v[168:169], off
	s_waitcnt lgkmcnt(0)
	v_mfma_f32_32x32x16_bf16 v[16:31], v[126:129], v[154:157], v[16:31]
	v_mfma_f32_32x32x16_bf16 v[0:15], v[138:141], v[154:157], v[0:15]
	ds_read_b128 v[126:129], v97
	ds_read_b128 v[134:137], v88 offset:49152
	ds_read_b128 v[138:141], v96
	ds_read_b128 v[150:153], v88 offset:53248
	s_waitcnt lgkmcnt(1)
	v_mfma_f32_32x32x16_bf16 v[48:63], v[126:129], v[134:137], v[48:63]
	v_mfma_f32_32x32x16_bf16 v[32:47], v[138:141], v[134:137], v[32:47]
	s_waitcnt vmcnt(6)
	s_waitcnt lgkmcnt(0)
	s_barrier
	s_waitcnt lgkmcnt(0)
	v_mfma_f32_32x32x16_bf16 v[16:31], v[126:129], v[150:153], v[16:31]
	v_lshl_add_u64 v[170:171], v[66:67], 0, s[30:31]
	s_nop 0
	v_lshl_add_u64 v[172:173], v[68:69], 0, s[30:31]
	s_nop 0
	s_nop 0
	s_nop 0
	s_nop 0
	v_mfma_f32_32x32x16_bf16 v[0:15], v[138:141], v[150:153], v[0:15]
	s_and_b32 m0, s32, 7
	s_lshl_b32 m0, m0, 12
	s_add_i32 m0, m0, 0xc000
	s_nop 0
	global_load_lds_dwordx4 v[170:171], off
	s_nop 0
	v_lshl_add_u64 v[176:177], v[72:73], 0, s[30:31]
	s_nop 0
	s_nop 0
	s_nop 0
	v_lshl_add_u64 v[178:179], v[74:75], 0, s[30:31]
	s_nop 0
	s_nop 0
	s_nop 0
	v_lshl_add_u64 v[180:181], v[76:77], 0, s[30:31]
	s_nop 0
	s_mov_b64 s[30:31], 0x580
	s_nop 0
	ds_read_b128 v[120:123], v98
	ds_read_b128 v[124:127], v100
	ds_read_b128 v[128:131], v99
	ds_read_b128 v[154:157], v101
	s_waitcnt lgkmcnt(1)
	v_mfma_f32_32x32x16_bf16 v[48:63], v[120:123], v[124:127], v[48:63]
	s_nop 0
	v_lshl_add_u64 v[162:163], v[70:71], 0, s[30:31]
	v_mfma_f32_32x32x16_bf16 v[32:47], v[128:131], v[124:127], v[32:47]
	s_and_b32 m0, s32, 7
	s_lshl_b32 m0, m0, 12
	s_add_i32 m0, m0, 0xc400
	s_nop 0
	global_load_lds_dwordx4 v[172:173], off
	s_waitcnt lgkmcnt(0)
	v_mfma_f32_32x32x16_bf16 v[16:31], v[120:123], v[154:157], v[16:31]
	v_mfma_f32_32x32x16_bf16 v[0:15], v[128:131], v[154:157], v[0:15]
	s_and_b32 m0, s32, 7
	s_lshl_b32 m0, m0, 12
	s_add_i32 m0, m0, 0xc800
	s_nop 0
	global_load_lds_dwordx4 v[174:175], off
	ds_read_b128 v[120:123], v102
	ds_read_b128 v[124:127], v104
	ds_read_b128 v[128:131], v103
	ds_read_b128 v[150:153], v105
	s_waitcnt lgkmcnt(1)
	v_mfma_f32_32x32x16_bf16 v[48:63], v[120:123], v[124:127], v[48:63]
	v_mfma_f32_32x32x16_bf16 v[32:47], v[128:131], v[124:127], v[32:47]
	s_and_b32 m0, s32, 7
	s_lshl_b32 m0, m0, 12
	s_add_i32 m0, m0, 0xcc00
	s_nop 0
	global_load_lds_dwordx4 v[176:177], off
	s_waitcnt lgkmcnt(0)
	v_mfma_f32_32x32x16_bf16 v[16:31], v[120:123], v[150:153], v[16:31]
	v_mfma_f32_32x32x16_bf16 v[0:15], v[128:131], v[150:153], v[0:15]
	s_and_b32 m0, s32, 7
	s_lshl_b32 m0, m0, 11
	s_add_i32 m0, m0, 0x14000
	s_nop 0
	global_load_lds_dwordx4 v[178:179], off
	ds_read_b128 v[120:123], v106
	ds_read_b128 v[124:127], v108
	ds_read_b128 v[128:131], v107
	ds_read_b128 v[154:157], v109
	s_waitcnt lgkmcnt(1)
	v_mfma_f32_32x32x16_bf16 v[48:63], v[120:123], v[124:127], v[48:63]
	v_mfma_f32_32x32x16_bf16 v[32:47], v[128:131], v[124:127], v[32:47]
	s_and_b32 m0, s32, 7
	s_lshl_b32 m0, m0, 11
	s_add_i32 m0, m0, 0x14400
	s_nop 0
	global_load_lds_dwordx4 v[180:181], off
	s_waitcnt lgkmcnt(0)
	v_mfma_f32_32x32x16_bf16 v[16:31], v[120:123], v[154:157], v[16:31]
	v_mfma_f32_32x32x16_bf16 v[0:15], v[128:131], v[154:157], v[0:15]
	ds_read_b128 v[120:123], v110
	ds_read_b128 v[124:127], v112
	ds_read_b128 v[128:131], v111
	ds_read_b128 v[150:153], v113
	s_waitcnt lgkmcnt(1)
	v_mfma_f32_32x32x16_bf16 v[48:63], v[120:123], v[124:127], v[48:63]
	v_mfma_f32_32x32x16_bf16 v[32:47], v[128:131], v[124:127], v[32:47]
	s_waitcnt vmcnt(6)
	s_waitcnt lgkmcnt(0)
	s_barrier
	s_waitcnt lgkmcnt(0)
	v_mfma_f32_32x32x16_bf16 v[16:31], v[120:123], v[150:153], v[16:31]
	v_lshl_add_u64 v[158:159], v[66:67], 0, s[30:31]
	s_nop 0
	v_lshl_add_u64 v[160:161], v[68:69], 0, s[30:31]
	s_nop 0
	s_nop 0
	s_nop 0
	s_nop 0
	v_mfma_f32_32x32x16_bf16 v[0:15], v[128:131], v[150:153], v[0:15]
	s_and_b32 m0, s32, 7
	s_lshl_b32 m0, m0, 12
	s_add_i32 m0, m0, 0x18000
	s_nop 0
	global_load_lds_dwordx4 v[158:159], off
	s_nop 0
	v_lshl_add_u64 v[164:165], v[72:73], 0, s[30:31]
	s_nop 0
	s_nop 0
	s_nop 0
	v_lshl_add_u64 v[166:167], v[74:75], 0, s[30:31]
	s_nop 0
	s_nop 0
	s_nop 0
	v_lshl_add_u64 v[168:169], v[76:77], 0, s[30:31]
	s_nop 0
	s_mov_b64 s[30:31], 0x600
	s_nop 0
	ds_read_b128 v[114:117], v83 offset:32768
	ds_read_b128 v[118:121], v82
	ds_read_b128 v[122:125], v83 offset:36864
	ds_read_b128 v[154:157], v82 offset:4096
	s_waitcnt lgkmcnt(1)
	v_mfma_f32_32x32x16_bf16 v[48:63], v[114:117], v[118:121], v[48:63]
	s_nop 0
	v_mfma_f32_32x32x16_bf16 v[32:47], v[122:125], v[118:121], v[32:47]
	s_and_b32 m0, s32, 7
	s_lshl_b32 m0, m0, 12
	s_add_i32 m0, m0, 0x18400
	s_nop 0
	global_load_lds_dwordx4 v[160:161], off
	s_waitcnt lgkmcnt(0)
	v_mfma_f32_32x32x16_bf16 v[16:31], v[114:117], v[154:157], v[16:31]
	v_mfma_f32_32x32x16_bf16 v[0:15], v[122:125], v[154:157], v[0:15]
	s_and_b32 m0, s32, 7
	s_lshl_b32 m0, m0, 12
	s_add_i32 m0, m0, 0x18800
	s_nop 0
	global_load_lds_dwordx4 v[162:163], off
	ds_read_b128 v[114:117], v85 offset:32768
	ds_read_b128 v[118:121], v84
	ds_read_b128 v[122:125], v85 offset:36864
	ds_read_b128 v[150:153], v84 offset:4096
	s_waitcnt lgkmcnt(1)
	v_mfma_f32_32x32x16_bf16 v[48:63], v[114:117], v[118:121], v[48:63]
	v_mfma_f32_32x32x16_bf16 v[32:47], v[122:125], v[118:121], v[32:47]
	s_and_b32 m0, s32, 7
	s_lshl_b32 m0, m0, 12
	s_add_i32 m0, m0, 0x18c00
	s_nop 0
	global_load_lds_dwordx4 v[164:165], off
	s_waitcnt lgkmcnt(0)
	v_mfma_f32_32x32x16_bf16 v[16:31], v[114:117], v[150:153], v[16:31]
	v_mfma_f32_32x32x16_bf16 v[0:15], v[122:125], v[150:153], v[0:15]
	s_and_b32 m0, s32, 7
	s_lshl_b32 m0, m0, 11
	s_add_i32 m0, m0, 0x20000
	s_nop 0
	global_load_lds_dwordx4 v[166:167], off
	ds_read_b128 v[114:117], v87 offset:32768
	ds_read_b128 v[118:121], v86
	ds_read_b128 v[122:125], v87 offset:36864
	ds_read_b128 v[154:157], v86 offset:4096
	s_waitcnt lgkmcnt(1)
	v_mfma_f32_32x32x16_bf16 v[48:63], v[114:117], v[118:121], v[48:63]
	v_mfma_f32_32x32x16_bf16 v[32:47], v[122:125], v[118:121], v[32:47]
	s_and_b32 m0, s32, 7
	s_lshl_b32 m0, m0, 11
	s_add_i32 m0, m0, 0x20400
	s_nop 0
	global_load_lds_dwordx4 v[168:169], off
	s_waitcnt lgkmcnt(0)
	v_mfma_f32_32x32x16_bf16 v[16:31], v[114:117], v[154:157], v[16:31]
	v_mfma_f32_32x32x16_bf16 v[0:15], v[122:125], v[154:157], v[0:15]
	ds_read_b128 v[114:117], v89 offset:32768
	ds_read_b128 v[118:121], v88
	ds_read_b128 v[122:125], v89 offset:36864
	ds_read_b128 v[150:153], v88 offset:4096
	s_waitcnt lgkmcnt(1)
	v_mfma_f32_32x32x16_bf16 v[48:63], v[114:117], v[118:121], v[48:63]
	v_mfma_f32_32x32x16_bf16 v[32:47], v[122:125], v[118:121], v[32:47]
	s_waitcnt vmcnt(6)
	s_waitcnt lgkmcnt(0)
	s_barrier
	s_waitcnt lgkmcnt(0)
	v_mfma_f32_32x32x16_bf16 v[16:31], v[114:117], v[150:153], v[16:31]
	v_lshl_add_u64 v[170:171], v[66:67], 0, s[30:31]
	s_nop 0
	v_lshl_add_u64 v[172:173], v[68:69], 0, s[30:31]
	s_nop 0
	s_nop 0
	s_nop 0
	v_lshl_add_u64 v[174:175], v[70:71], 0, s[30:31]
	s_nop 0
	v_mfma_f32_32x32x16_bf16 v[0:15], v[122:125], v[150:153], v[0:15]
	s_and_b32 m0, s32, 7
	s_lshl_b32 m0, m0, 12
	s_add_i32 m0, m0, 0x0
	s_nop 0
	global_load_lds_dwordx4 v[170:171], off
	s_nop 0
	v_lshl_add_u64 v[176:177], v[72:73], 0, s[30:31]
	s_nop 0
	s_nop 0
	s_nop 0
	v_lshl_add_u64 v[178:179], v[74:75], 0, s[30:31]
	s_nop 0
	s_nop 0
	s_nop 0
	v_lshl_add_u64 v[180:181], v[76:77], 0, s[30:31]
	s_nop 0
	s_mov_b64 s[30:31], 0x680
	s_nop 0
	ds_read_b128 v[114:117], v92
	ds_read_b128 v[118:121], v82 offset:49152
	ds_read_b128 v[122:125], v90
	ds_read_b128 v[154:157], v82 offset:53248
	s_waitcnt lgkmcnt(1)
	v_mfma_f32_32x32x16_bf16 v[48:63], v[114:117], v[118:121], v[48:63]
	s_nop 0
	v_mfma_f32_32x32x16_bf16 v[32:47], v[122:125], v[118:121], v[32:47]
	s_and_b32 m0, s32, 7
	s_lshl_b32 m0, m0, 12
	s_add_i32 m0, m0, 0x400
	s_nop 0
	global_load_lds_dwordx4 v[172:173], off
	s_waitcnt lgkmcnt(0)
	v_mfma_f32_32x32x16_bf16 v[16:31], v[114:117], v[154:157], v[16:31]
	v_mfma_f32_32x32x16_bf16 v[0:15], v[122:125], v[154:157], v[0:15]
	s_and_b32 m0, s32, 7
	s_lshl_b32 m0, m0, 12
	s_add_i32 m0, m0, 0x800
	s_nop 0
	global_load_lds_dwordx4 v[174:175], off
	ds_read_b128 v[114:117], v93
	ds_read_b128 v[118:121], v84 offset:49152
	ds_read_b128 v[122:125], v91
	ds_read_b128 v[150:153], v84 offset:53248
	s_waitcnt lgkmcnt(1)
	v_mfma_f32_32x32x16_bf16 v[48:63], v[114:117], v[118:121], v[48:63]
	v_mfma_f32_32x32x16_bf16 v[32:47], v[122:125], v[118:121], v[32:47]
	s_and_b32 m0, s32, 7
	s_lshl_b32 m0, m0, 12
	s_add_i32 m0, m0, 0xc00
	s_nop 0
	global_load_lds_dwordx4 v[176:177], off
	s_waitcnt lgkmcnt(0)
	v_mfma_f32_32x32x16_bf16 v[16:31], v[114:117], v[150:153], v[16:31]
	v_mfma_f32_32x32x16_bf16 v[0:15], v[122:125], v[150:153], v[0:15]
	s_and_b32 m0, s32, 7
	s_lshl_b32 m0, m0, 11
	s_add_i32 m0, m0, 0x8000
	s_nop 0
	global_load_lds_dwordx4 v[178:179], off
	ds_read_b128 v[114:117], v95
	ds_read_b128 v[118:121], v86 offset:49152
	ds_read_b128 v[122:125], v94
	ds_read_b128 v[154:157], v86 offset:53248
	s_waitcnt lgkmcnt(1)
	v_mfma_f32_32x32x16_bf16 v[48:63], v[114:117], v[118:121], v[48:63]
	v_mfma_f32_32x32x16_bf16 v[32:47], v[122:125], v[118:121], v[32:47]
	s_and_b32 m0, s32, 7
	s_lshl_b32 m0, m0, 11
	s_add_i32 m0, m0, 0x8400
	s_nop 0
	global_load_lds_dwordx4 v[180:181], off
	s_waitcnt lgkmcnt(0)
	v_mfma_f32_32x32x16_bf16 v[16:31], v[114:117], v[154:157], v[16:31]
	v_mfma_f32_32x32x16_bf16 v[0:15], v[122:125], v[154:157], v[0:15]
	ds_read_b128 v[114:117], v97
	ds_read_b128 v[118:121], v88 offset:49152
	ds_read_b128 v[122:125], v96
	ds_read_b128 v[150:153], v88 offset:53248
	s_waitcnt lgkmcnt(1)
	v_mfma_f32_32x32x16_bf16 v[48:63], v[114:117], v[118:121], v[48:63]
	v_mfma_f32_32x32x16_bf16 v[32:47], v[122:125], v[118:121], v[32:47]
	s_waitcnt vmcnt(6)
	s_waitcnt lgkmcnt(0)
	s_barrier
	s_waitcnt lgkmcnt(0)
	v_mfma_f32_32x32x16_bf16 v[16:31], v[114:117], v[150:153], v[16:31]
	v_lshl_add_u64 v[158:159], v[66:67], 0, s[30:31]
	s_nop 0
	v_lshl_add_u64 v[160:161], v[68:69], 0, s[30:31]
	s_nop 0
	s_nop 0
	s_nop 0
	v_lshl_add_u64 v[162:163], v[70:71], 0, s[30:31]
	s_nop 0
	v_mfma_f32_32x32x16_bf16 v[0:15], v[122:125], v[150:153], v[0:15]
	s_and_b32 m0, s32, 7
	s_lshl_b32 m0, m0, 12
	s_add_i32 m0, m0, 0xc000
	s_nop 0
	global_load_lds_dwordx4 v[158:159], off
	s_nop 0
	v_lshl_add_u64 v[164:165], v[72:73], 0, s[30:31]
	s_nop 0
	s_nop 0
	s_nop 0
	v_lshl_add_u64 v[166:167], v[74:75], 0, s[30:31]
	s_nop 0
	s_nop 0
	s_nop 0
	v_lshl_add_u64 v[168:169], v[76:77], 0, s[30:31]
	s_nop 0
	s_mov_b64 s[30:31], 0x700
	s_nop 0
	ds_read_b128 v[114:117], v98
	ds_read_b128 v[118:121], v100
	ds_read_b128 v[122:125], v99
	ds_read_b128 v[154:157], v101
	s_waitcnt lgkmcnt(1)
	v_mfma_f32_32x32x16_bf16 v[48:63], v[114:117], v[118:121], v[48:63]
	s_nop 0
	v_mfma_f32_32x32x16_bf16 v[32:47], v[122:125], v[118:121], v[32:47]
	s_and_b32 m0, s32, 7
	s_lshl_b32 m0, m0, 12
	s_add_i32 m0, m0, 0xc400
	s_nop 0
	global_load_lds_dwordx4 v[160:161], off
	s_waitcnt lgkmcnt(0)
	v_mfma_f32_32x32x16_bf16 v[16:31], v[114:117], v[154:157], v[16:31]
	v_mfma_f32_32x32x16_bf16 v[0:15], v[122:125], v[154:157], v[0:15]
	s_and_b32 m0, s32, 7
	s_lshl_b32 m0, m0, 12
	s_add_i32 m0, m0, 0xc800
	s_nop 0
	global_load_lds_dwordx4 v[162:163], off
	ds_read_b128 v[114:117], v102
	ds_read_b128 v[118:121], v104
	ds_read_b128 v[122:125], v103
	ds_read_b128 v[150:153], v105
	s_waitcnt lgkmcnt(1)
	v_mfma_f32_32x32x16_bf16 v[48:63], v[114:117], v[118:121], v[48:63]
	v_mfma_f32_32x32x16_bf16 v[32:47], v[122:125], v[118:121], v[32:47]
	s_and_b32 m0, s32, 7
	s_lshl_b32 m0, m0, 12
	s_add_i32 m0, m0, 0xcc00
	s_nop 0
	global_load_lds_dwordx4 v[164:165], off
	s_waitcnt lgkmcnt(0)
	v_mfma_f32_32x32x16_bf16 v[16:31], v[114:117], v[150:153], v[16:31]
	v_mfma_f32_32x32x16_bf16 v[0:15], v[122:125], v[150:153], v[0:15]
	s_and_b32 m0, s32, 7
	s_lshl_b32 m0, m0, 11
	s_add_i32 m0, m0, 0x14000
	s_nop 0
	global_load_lds_dwordx4 v[166:167], off
	ds_read_b128 v[114:117], v106
	ds_read_b128 v[118:121], v108
	ds_read_b128 v[122:125], v107
	ds_read_b128 v[154:157], v109
	s_waitcnt lgkmcnt(1)
	v_mfma_f32_32x32x16_bf16 v[48:63], v[114:117], v[118:121], v[48:63]
	v_mfma_f32_32x32x16_bf16 v[32:47], v[122:125], v[118:121], v[32:47]
	s_and_b32 m0, s32, 7
	s_lshl_b32 m0, m0, 11
	s_add_i32 m0, m0, 0x14400
	s_nop 0
	global_load_lds_dwordx4 v[168:169], off
	s_waitcnt lgkmcnt(0)
	v_mfma_f32_32x32x16_bf16 v[16:31], v[114:117], v[154:157], v[16:31]
	v_mfma_f32_32x32x16_bf16 v[0:15], v[122:125], v[154:157], v[0:15]
	ds_read_b128 v[114:117], v110
	ds_read_b128 v[118:121], v112
	ds_read_b128 v[122:125], v111
	ds_read_b128 v[150:153], v113
	s_waitcnt lgkmcnt(1)
	v_mfma_f32_32x32x16_bf16 v[48:63], v[114:117], v[118:121], v[48:63]
	v_mfma_f32_32x32x16_bf16 v[32:47], v[122:125], v[118:121], v[32:47]
	s_waitcnt vmcnt(6)
	s_waitcnt lgkmcnt(0)
	s_barrier
	s_waitcnt lgkmcnt(0)
	v_mfma_f32_32x32x16_bf16 v[16:31], v[114:117], v[150:153], v[16:31]
	v_lshl_add_u64 v[170:171], v[66:67], 0, s[30:31]
	s_nop 0
	v_lshl_add_u64 v[172:173], v[68:69], 0, s[30:31]
	s_nop 0
	s_nop 0
	s_nop 0
	v_lshl_add_u64 v[174:175], v[70:71], 0, s[30:31]
	s_nop 0
	v_mfma_f32_32x32x16_bf16 v[0:15], v[122:125], v[150:153], v[0:15]
	s_and_b32 m0, s32, 7
	s_lshl_b32 m0, m0, 12
	s_add_i32 m0, m0, 0x18000
	s_nop 0
	global_load_lds_dwordx4 v[170:171], off
	s_nop 0
	v_lshl_add_u64 v[176:177], v[72:73], 0, s[30:31]
	s_nop 0
	s_nop 0
	s_nop 0
	v_lshl_add_u64 v[178:179], v[74:75], 0, s[30:31]
	s_nop 0
	s_nop 0
	s_nop 0
	v_lshl_add_u64 v[180:181], v[76:77], 0, s[30:31]
	s_nop 0
	s_mov_b64 s[30:31], 0x780
	s_nop 0
	ds_read_b128 v[114:117], v83 offset:32768
	ds_read_b128 v[118:121], v82
	ds_read_b128 v[122:125], v83 offset:36864
	ds_read_b128 v[154:157], v82 offset:4096
	s_waitcnt lgkmcnt(1)
	v_mfma_f32_32x32x16_bf16 v[48:63], v[114:117], v[118:121], v[48:63]
	v_lshl_add_u64 v[158:159], v[66:67], 0, s[30:31]
	s_nop 0
	v_mfma_f32_32x32x16_bf16 v[32:47], v[122:125], v[118:121], v[32:47]
	s_and_b32 m0, s32, 7
	s_lshl_b32 m0, m0, 12
	s_add_i32 m0, m0, 0x18400
	s_nop 0
	global_load_lds_dwordx4 v[172:173], off
	s_waitcnt lgkmcnt(0)
	v_mfma_f32_32x32x16_bf16 v[16:31], v[114:117], v[154:157], v[16:31]
	v_mfma_f32_32x32x16_bf16 v[0:15], v[122:125], v[154:157], v[0:15]
	s_and_b32 m0, s32, 7
	s_lshl_b32 m0, m0, 12
	s_add_i32 m0, m0, 0x18800
	s_nop 0
	global_load_lds_dwordx4 v[174:175], off
	ds_read_b128 v[114:117], v85 offset:32768
	ds_read_b128 v[118:121], v84
	ds_read_b128 v[122:125], v85 offset:36864
	ds_read_b128 v[150:153], v84 offset:4096
	s_waitcnt lgkmcnt(1)
	v_mfma_f32_32x32x16_bf16 v[48:63], v[114:117], v[118:121], v[48:63]
	v_mfma_f32_32x32x16_bf16 v[32:47], v[122:125], v[118:121], v[32:47]
	s_and_b32 m0, s32, 7
	s_lshl_b32 m0, m0, 12
	s_add_i32 m0, m0, 0x18c00
	s_nop 0
	global_load_lds_dwordx4 v[176:177], off
	s_waitcnt lgkmcnt(0)
	v_mfma_f32_32x32x16_bf16 v[16:31], v[114:117], v[150:153], v[16:31]
	v_mfma_f32_32x32x16_bf16 v[0:15], v[122:125], v[150:153], v[0:15]
	s_and_b32 m0, s32, 7
	s_lshl_b32 m0, m0, 11
	s_add_i32 m0, m0, 0x20000
	s_nop 0
	global_load_lds_dwordx4 v[178:179], off
	ds_read_b128 v[114:117], v87 offset:32768
	ds_read_b128 v[118:121], v86
	ds_read_b128 v[122:125], v87 offset:36864
	ds_read_b128 v[154:157], v86 offset:4096
	s_waitcnt lgkmcnt(1)
	v_mfma_f32_32x32x16_bf16 v[48:63], v[114:117], v[118:121], v[48:63]
	v_mfma_f32_32x32x16_bf16 v[32:47], v[122:125], v[118:121], v[32:47]
	s_and_b32 m0, s32, 7
	s_lshl_b32 m0, m0, 11
	s_add_i32 m0, m0, 0x20400
	s_nop 0
	global_load_lds_dwordx4 v[180:181], off
	s_waitcnt lgkmcnt(0)
	v_mfma_f32_32x32x16_bf16 v[16:31], v[114:117], v[154:157], v[16:31]
	v_mfma_f32_32x32x16_bf16 v[0:15], v[122:125], v[154:157], v[0:15]
	ds_read_b128 v[114:117], v89 offset:32768
	ds_read_b128 v[118:121], v88
	ds_read_b128 v[122:125], v89 offset:36864
	ds_read_b128 v[150:153], v88 offset:4096
	s_waitcnt lgkmcnt(1)
	v_mfma_f32_32x32x16_bf16 v[48:63], v[114:117], v[118:121], v[48:63]
	v_mfma_f32_32x32x16_bf16 v[32:47], v[122:125], v[118:121], v[32:47]
	s_waitcnt vmcnt(6)
	s_waitcnt lgkmcnt(0)
	s_barrier
	s_nop 0
	v_lshl_add_u64 v[160:161], v[68:69], 0, s[30:31]
	s_nop 0
	s_waitcnt lgkmcnt(0)
	v_mfma_f32_32x32x16_bf16 v[16:31], v[114:117], v[150:153], v[16:31]
	s_nop 0
	v_lshl_add_u64 v[162:163], v[70:71], 0, s[30:31]
	s_nop 0
	v_readlane_b32 s20, v215, 52
	s_nop 0
	v_lshl_add_u64 v[164:165], v[72:73], 0, s[30:31]
	s_nop 0
	v_mfma_f32_32x32x16_bf16 v[0:15], v[122:125], v[150:153], v[0:15]
	s_and_b32 m0, s32, 7
	s_lshl_b32 m0, m0, 12
	s_add_i32 m0, m0, 0x0
	s_nop 0
	global_load_lds_dwordx4 v[158:159], off
	s_nop 0
	v_lshl_add_u64 v[166:167], v[74:75], 0, s[30:31]
	s_nop 0
	v_readlane_b32 s21, v215, 53
	s_nop 0
	v_lshl_add_u64 v[168:169], v[76:77], 0, s[30:31]
	s_nop 0
	s_mov_b32 s23, 0
	s_nop 0
	ds_read_b128 v[66:69], v92
	ds_read_b128 v[70:73], v82 offset:49152
	ds_read_b128 v[74:77], v90
	ds_read_b128 v[154:157], v82 offset:53248
	s_waitcnt lgkmcnt(1)
	v_mfma_f32_32x32x16_bf16 v[48:63], v[66:69], v[70:73], v[48:63]
	v_mfma_f32_32x32x16_bf16 v[32:47], v[74:77], v[70:73], v[32:47]
	s_and_b32 m0, s32, 7
	s_lshl_b32 m0, m0, 12
	s_add_i32 m0, m0, 0x400
	s_nop 0
	global_load_lds_dwordx4 v[160:161], off
	s_waitcnt lgkmcnt(0)
	v_mfma_f32_32x32x16_bf16 v[16:31], v[66:69], v[154:157], v[16:31]
	v_mfma_f32_32x32x16_bf16 v[0:15], v[74:77], v[154:157], v[0:15]
	s_and_b32 m0, s32, 7
	s_lshl_b32 m0, m0, 12
	s_add_i32 m0, m0, 0x800
	s_nop 0
	global_load_lds_dwordx4 v[162:163], off
	ds_read_b128 v[66:69], v93
	ds_read_b128 v[70:73], v84 offset:49152
	ds_read_b128 v[74:77], v91
	ds_read_b128 v[150:153], v84 offset:53248
	s_waitcnt lgkmcnt(1)
	v_mfma_f32_32x32x16_bf16 v[48:63], v[66:69], v[70:73], v[48:63]
	v_mfma_f32_32x32x16_bf16 v[32:47], v[74:77], v[70:73], v[32:47]
	s_and_b32 m0, s32, 7
	s_lshl_b32 m0, m0, 12
	s_add_i32 m0, m0, 0xc00
	s_nop 0
	global_load_lds_dwordx4 v[164:165], off
	s_waitcnt lgkmcnt(0)
	v_mfma_f32_32x32x16_bf16 v[16:31], v[66:69], v[150:153], v[16:31]
	v_mfma_f32_32x32x16_bf16 v[0:15], v[74:77], v[150:153], v[0:15]
	s_and_b32 m0, s32, 7
	s_lshl_b32 m0, m0, 11
	s_add_i32 m0, m0, 0x8000
	s_nop 0
	global_load_lds_dwordx4 v[166:167], off
	ds_read_b128 v[66:69], v95
	ds_read_b128 v[70:73], v86 offset:49152
	ds_read_b128 v[74:77], v94
	ds_read_b128 v[154:157], v86 offset:53248
	s_waitcnt lgkmcnt(1)
	v_mfma_f32_32x32x16_bf16 v[48:63], v[66:69], v[70:73], v[48:63]
	v_mfma_f32_32x32x16_bf16 v[32:47], v[74:77], v[70:73], v[32:47]
	s_and_b32 m0, s32, 7
	s_lshl_b32 m0, m0, 11
	s_add_i32 m0, m0, 0x8400
	s_nop 0
	global_load_lds_dwordx4 v[168:169], off
	s_waitcnt lgkmcnt(0)
	v_mfma_f32_32x32x16_bf16 v[16:31], v[66:69], v[154:157], v[16:31]
	v_mfma_f32_32x32x16_bf16 v[0:15], v[74:77], v[154:157], v[0:15]
	ds_read_b128 v[66:69], v97
	ds_read_b128 v[70:73], v88 offset:49152
	ds_read_b128 v[74:77], v96
	ds_read_b128 v[150:153], v88 offset:53248
	s_waitcnt lgkmcnt(1)
	v_mfma_f32_32x32x16_bf16 v[48:63], v[66:69], v[70:73], v[48:63]
	v_mfma_f32_32x32x16_bf16 v[32:47], v[74:77], v[70:73], v[32:47]
	s_waitcnt vmcnt(6)
	s_waitcnt lgkmcnt(0)
	s_barrier
	s_waitcnt lgkmcnt(0)
	v_mfma_f32_32x32x16_bf16 v[16:31], v[66:69], v[150:153], v[16:31]
	v_mfma_f32_32x32x16_bf16 v[0:15], v[74:77], v[150:153], v[0:15]
	ds_read_b128 v[66:69], v98
	ds_read_b128 v[70:73], v100
	ds_read_b128 v[74:77], v99
	ds_read_b128 v[154:157], v101
	s_waitcnt lgkmcnt(1)
	v_mfma_f32_32x32x16_bf16 v[48:63], v[66:69], v[70:73], v[48:63]
	v_mfma_f32_32x32x16_bf16 v[32:47], v[74:77], v[70:73], v[32:47]
	s_waitcnt lgkmcnt(0)
	v_mfma_f32_32x32x16_bf16 v[16:31], v[66:69], v[154:157], v[16:31]
	v_mfma_f32_32x32x16_bf16 v[0:15], v[74:77], v[154:157], v[0:15]
	ds_read_b128 v[66:69], v102
	ds_read_b128 v[70:73], v104
	ds_read_b128 v[74:77], v103
	ds_read_b128 v[150:153], v105
	s_waitcnt lgkmcnt(1)
	v_mfma_f32_32x32x16_bf16 v[48:63], v[66:69], v[70:73], v[48:63]
	v_mfma_f32_32x32x16_bf16 v[32:47], v[74:77], v[70:73], v[32:47]
	s_waitcnt lgkmcnt(0)
	v_mfma_f32_32x32x16_bf16 v[16:31], v[66:69], v[150:153], v[16:31]
	v_mfma_f32_32x32x16_bf16 v[0:15], v[74:77], v[150:153], v[0:15]
	ds_read_b128 v[66:69], v106
	ds_read_b128 v[70:73], v108
	ds_read_b128 v[74:77], v107
	ds_read_b128 v[154:157], v109
	s_waitcnt lgkmcnt(1)
	v_mfma_f32_32x32x16_bf16 v[48:63], v[66:69], v[70:73], v[48:63]
	v_mfma_f32_32x32x16_bf16 v[32:47], v[74:77], v[70:73], v[32:47]
	s_waitcnt lgkmcnt(0)
	v_mfma_f32_32x32x16_bf16 v[16:31], v[66:69], v[154:157], v[16:31]
	v_mfma_f32_32x32x16_bf16 v[0:15], v[74:77], v[154:157], v[0:15]
	ds_read_b128 v[66:69], v110
	ds_read_b128 v[70:73], v112
	ds_read_b128 v[74:77], v111
	ds_read_b128 v[150:153], v113
	s_waitcnt lgkmcnt(1)
	v_mfma_f32_32x32x16_bf16 v[48:63], v[66:69], v[70:73], v[48:63]
	v_mfma_f32_32x32x16_bf16 v[32:47], v[74:77], v[70:73], v[32:47]
	s_waitcnt vmcnt(0)
	s_waitcnt lgkmcnt(0)
	s_barrier
	s_waitcnt lgkmcnt(0)
	v_mfma_f32_32x32x16_bf16 v[16:31], v[66:69], v[150:153], v[16:31]
	v_mfma_f32_32x32x16_bf16 v[0:15], v[74:77], v[150:153], v[0:15]
	ds_read_b128 v[66:69], v83 offset:32768
	ds_read_b128 v[70:73], v82
	ds_read_b128 v[74:77], v83 offset:36864
	ds_read_b128 v[154:157], v82 offset:4096
	s_waitcnt lgkmcnt(1)
	v_mfma_f32_32x32x16_bf16 v[48:63], v[66:69], v[70:73], v[48:63]
	v_mfma_f32_32x32x16_bf16 v[32:47], v[74:77], v[70:73], v[32:47]
	s_waitcnt lgkmcnt(0)
	v_mfma_f32_32x32x16_bf16 v[16:31], v[66:69], v[154:157], v[16:31]
	v_mfma_f32_32x32x16_bf16 v[0:15], v[74:77], v[154:157], v[0:15]
	ds_read_b128 v[66:69], v85 offset:32768
	ds_read_b128 v[70:73], v84
	ds_read_b128 v[74:77], v85 offset:36864
	ds_read_b128 v[150:153], v84 offset:4096
	s_waitcnt lgkmcnt(1)
	v_mfma_f32_32x32x16_bf16 v[48:63], v[66:69], v[70:73], v[48:63]
	v_mfma_f32_32x32x16_bf16 v[32:47], v[74:77], v[70:73], v[32:47]
	s_waitcnt lgkmcnt(0)
	v_mfma_f32_32x32x16_bf16 v[16:31], v[66:69], v[150:153], v[16:31]
	v_mfma_f32_32x32x16_bf16 v[0:15], v[74:77], v[150:153], v[0:15]
	ds_read_b128 v[66:69], v87 offset:32768
	ds_read_b128 v[70:73], v86
	ds_read_b128 v[74:77], v87 offset:36864
	s_waitcnt lgkmcnt(0)
	v_mfma_f32_32x32x16_bf16 v[48:63], v[66:69], v[70:73], v[48:63]
	v_mfma_f32_32x32x16_bf16 v[32:47], v[74:77], v[70:73], v[32:47]
	ds_read_b128 v[70:73], v86 offset:4096
	s_waitcnt lgkmcnt(0)
	v_mfma_f32_32x32x16_bf16 v[0:15], v[74:77], v[70:73], v[0:15]
	v_mfma_f32_32x32x16_bf16 v[16:31], v[66:69], v[70:73], v[16:31]
	ds_read_b128 v[66:69], v89 offset:32768
	ds_read_b128 v[70:73], v88
	ds_read_b128 v[74:77], v89 offset:36864
	ds_read_b128 v[82:85], v88 offset:4096
	s_waitcnt lgkmcnt(0)
	s_barrier
	s_waitcnt lgkmcnt(0)
	v_mfma_f32_32x32x16_bf16 v[48:63], v[66:69], v[70:73], v[48:63]
	v_mfma_f32_32x32x16_bf16 v[32:47], v[74:77], v[70:73], v[32:47]
	s_nop 10
	ds_write_b128 v64, v[48:51]
	ds_write_b128 v64, v[52:55] offset:32
	ds_write_b128 v64, v[56:59] offset:64
	ds_write_b128 v64, v[60:63] offset:96
	ds_write_b128 v64, v[32:35] offset:128
	v_mfma_f32_32x32x16_bf16 v[0:15], v[74:77], v[82:85], v[0:15]
	v_mfma_f32_32x32x16_bf16 v[16:31], v[66:69], v[82:85], v[16:31]
	ds_write_b128 v64, v[36:39] offset:160
	ds_write_b128 v64, v[40:43] offset:192
	ds_write_b128 v64, v[44:47] offset:224
	s_nop 8
	ds_write_b128 v64, v[16:19] offset:16896
	ds_write_b128 v64, v[20:23] offset:16928
	ds_write_b128 v64, v[24:27] offset:16960
	ds_write_b128 v64, v[28:31] offset:16992
	ds_write_b128 v64, v[0:3] offset:17024
	ds_write_b128 v64, v[4:7] offset:17056
	ds_write_b128 v64, v[8:11] offset:17088
	ds_write_b128 v64, v[12:15] offset:17120
	s_waitcnt lgkmcnt(0)
	s_barrier
	v_lshl_or_b32 v0, v79, 2, s0
	v_ashrrev_i32_e32 v1, 31, v0
	v_lshl_add_u32 v4, v79, 4, 0
	v_cmp_eq_u32_e64 s[0:1], 0, v79
	v_lshl_add_u64 v[6:7], v[0:1], 2, s[92:93]
	v_lshl_add_u64 v[8:9], v[0:1], 1, s[20:21]
	s_branch .LBB0_96

.LBB0_159:
	v_mov_b32_e32 v78, v133
	s_lshl_b32 s22, s2, 8
	v_ashrrev_i32_e32 v6, 6, v78
	v_bfe_u32 v7, v78, 3, 3
	v_lshl_or_b32 v8, v6, 5, v7
	v_add_u32_e32 v0, s22, v8
	s_waitcnt lgkmcnt(0)
	v_ashrrev_i32_e32 v1, 31, v0
	v_lshlrev_b64 v[2:3], 11, v[0:1]
	v_bfe_u32 v1, v78, 4, 2
	v_readlane_b32 s0, v214, 4
	v_xor_b32_e32 v1, v1, v78
	v_readlane_b32 s1, v214, 5
	v_lshlrev_b32_e32 v1, 4, v1
	v_and_b32_e32 v64, 0x70, v1
	v_lshl_add_u64 v[2:3], s[0:1], 0, v[2:3]
	v_or_b32_e32 v1, 8, v8
	v_lshl_add_u64 v[66:67], v[2:3], 0, v[64:65]
	v_add_u32_e32 v2, s22, v1
	v_lshrrev_b32_e32 v1, 1, v1
	v_xor_b32_e32 v1, v1, v78
	v_ashrrev_i32_e32 v3, 31, v2
	v_lshlrev_b32_e32 v1, 4, v1
	v_or_b32_e32 v0, 16, v0
	v_lshlrev_b64 v[2:3], 11, v[2:3]
	v_and_b32_e32 v4, 0x70, v1
	v_ashrrev_i32_e32 v1, 31, v0
	v_lshl_add_u64 v[2:3], s[0:1], 0, v[2:3]
	v_mov_b32_e32 v5, v65
	v_lshlrev_b64 v[0:1], 11, v[0:1]
	v_lshl_add_u64 v[68:69], v[2:3], 0, v[4:5]
	v_lshl_add_u64 v[0:1], s[0:1], 0, v[0:1]
	v_or_b32_e32 v2, 24, v8
	v_lshl_add_u64 v[70:71], v[0:1], 0, v[64:65]
	v_add_u32_e32 v0, s22, v2
	v_lshrrev_b32_e32 v2, 1, v2
	v_ashrrev_i32_e32 v1, 31, v0
	v_xor_b32_e32 v2, v2, v78
	v_lshlrev_b64 v[0:1], 11, v[0:1]
	v_lshlrev_b32_e32 v2, 4, v2
	v_lshl_add_u64 v[0:1], s[0:1], 0, v[0:1]
	v_and_b32_e32 v2, 0x70, v2
	v_mov_b32_e32 v3, v65
	v_lshl_add_u64 v[72:73], v[0:1], 0, v[2:3]
	v_lshl_or_b32 v2, v6, 4, v7
	v_readlane_b32 s31, v214, 58
	v_lshlrev_b32_e32 v3, 12, v6
	v_add_u32_e32 v126, 0, v3
	v_add_u32_e32 v0, s31, v2
	v_ashrrev_i32_e32 v1, 31, v0
	v_lshlrev_b64 v[0:1], 11, v[0:1]
	s_waitcnt vmcnt(0)
	v_readfirstlane_b32 s37, v126
	v_add_u32_e32 v127, 0x400, v126
	v_lshl_add_u64 v[0:1], s[40:41], 0, v[0:1]
	v_or_b32_e32 v2, 8, v2
	s_waitcnt lgkmcnt(0)
	s_barrier
	s_mov_b32 m0, s37
	v_readfirstlane_b32 s38, v127
	v_add_u32_e32 v128, 0x800, v126
	v_lshlrev_b32_e32 v5, 11, v6
	v_and_b32_e32 v80, 1, v6
	v_lshl_add_u64 v[74:75], v[0:1], 0, v[64:65]
	v_add_u32_e32 v0, s31, v2
	v_lshrrev_b32_e32 v2, 1, v2
	global_load_lds_dwordx4 v[66:67], off
	s_mov_b32 m0, s38
	v_readfirstlane_b32 s39, v128
	v_add_u32_e32 v129, 0xc00, v126
	v_add_u32_e32 v6, 0, v5
	v_ashrrev_i32_e32 v1, 31, v0
	v_xor_b32_e32 v2, v2, v78
	global_load_lds_dwordx4 v[68:69], off
	s_mov_b32 m0, s39
	v_readfirstlane_b32 s48, v129
	v_add_u32_e32 v131, 0x8000, v6
	v_lshlrev_b64 v[0:1], 11, v[0:1]
	v_lshlrev_b32_e32 v2, 4, v2
	global_load_lds_dwordx4 v[70:71], off
	s_mov_b32 m0, s48
	v_readfirstlane_b32 s49, v131
	v_add_u32_e32 v130, 0x8400, v6
	v_lshl_add_u64 v[0:1], s[40:41], 0, v[0:1]
	v_and_b32_e32 v64, 0x70, v2
	global_load_lds_dwordx4 v[72:73], off
	s_mov_b32 m0, s49
	v_readfirstlane_b32 s53, v130
	v_add_u32_e32 v120, 0xc000, v126
	v_lshl_add_u64 v[76:77], v[0:1], 0, v[64:65]
	global_load_lds_dwordx4 v[74:75], off
	s_mov_b32 m0, s53
	s_mov_b64 s[0:1], 0x80
	v_readfirstlane_b32 s28, v120
	v_add_u32_e32 v121, 0xc400, v126
	global_load_lds_dwordx4 v[76:77], off
	v_lshl_add_u64 v[0:1], v[66:67], 0, s[0:1]
	s_mov_b32 m0, s28
	v_readfirstlane_b32 s29, v121
	v_add_u32_e32 v122, 0xc800, v126
	global_load_lds_dwordx4 v[0:1], off
	v_lshl_add_u64 v[0:1], v[68:69], 0, s[0:1]
	s_mov_b32 m0, s29
	v_readfirstlane_b32 s33, v122
	v_add_u32_e32 v123, 0xcc00, v126
	global_load_lds_dwordx4 v[0:1], off
	v_lshl_add_u64 v[0:1], v[70:71], 0, s[0:1]
	s_mov_b32 m0, s33
	v_readfirstlane_b32 s34, v123
	v_add_u32_e32 v124, s85, v5
	global_load_lds_dwordx4 v[0:1], off
	v_lshl_add_u64 v[0:1], v[72:73], 0, s[0:1]
	s_mov_b32 m0, s34
	v_readfirstlane_b32 s35, v124
	v_add_u32_e32 v125, 0x14400, v6
	global_load_lds_dwordx4 v[0:1], off
	v_lshl_add_u64 v[0:1], v[74:75], 0, s[0:1]
	s_mov_b32 m0, s35
	v_readfirstlane_b32 s36, v125
	global_load_lds_dwordx4 v[0:1], off
	v_lshl_add_u64 v[0:1], v[76:77], 0, s[0:1]
	s_mov_b32 m0, s36
	v_lshrrev_b32_e32 v2, 1, v78
	v_bfe_u32 v64, v78, 5, 1
	global_load_lds_dwordx4 v[0:1], off
	v_add_u32_e32 v114, s3, v3
	v_bitop3_b32 v0, v2, v64, 7 bitop3:0x6c
	s_waitcnt vmcnt(6)
	s_mov_b64 s[46:47], 0x100
	v_readfirstlane_b32 s0, v114
	v_add_u32_e32 v115, 0x400, v114
	v_lshlrev_b32_e32 v132, 4, v0
	s_waitcnt lgkmcnt(0)
	s_barrier
	v_lshl_add_u64 v[0:1], v[66:67], 0, s[46:47]
	s_mov_b32 m0, s0
	v_readfirstlane_b32 s1, v115
	v_add_u32_e32 v116, 0x800, v114
	global_load_lds_dwordx4 v[0:1], off
	v_lshl_add_u64 v[0:1], v[68:69], 0, s[46:47]
	s_mov_b32 m0, s1
	v_readfirstlane_b32 s20, v116
	v_add_u32_e32 v117, 0xc00, v114
	v_readlane_b32 s23, v212, 31
	v_and_b32_e32 v79, 31, v78
	global_load_lds_dwordx4 v[0:1], off
	v_lshl_add_u64 v[0:1], v[70:71], 0, s[46:47]
	s_mov_b32 m0, s20
	v_readfirstlane_b32 s21, v117
	v_add_u32_e32 v118, s23, v5
	v_add_u32_e32 v2, s3, v5
	v_lshlrev_b32_e32 v4, 7, v79
	global_load_lds_dwordx4 v[0:1], off
	v_lshl_add_u64 v[0:1], v[72:73], 0, s[46:47]
	s_mov_b32 m0, s21
	v_readfirstlane_b32 s23, v118
	v_add_u32_e32 v119, 0x8400, v2
	v_lshl_or_b32 v102, v80, 13, v4
	global_load_lds_dwordx4 v[0:1], off
	v_lshl_add_u64 v[0:1], v[74:75], 0, s[46:47]
	s_mov_b32 m0, s23
	v_readfirstlane_b32 s24, v119
	global_load_lds_dwordx4 v[0:1], off
	v_lshl_add_u64 v[0:1], v[76:77], 0, s[46:47]
	s_mov_b32 m0, s24
	v_add_u32_e32 v100, 0, v102
	global_load_lds_dwordx4 v[0:1], off
	v_add_u32_e32 v83, v100, v132
	v_ashrrev_i32_e32 v81, 7, v78
	ds_read_b128 v[0:3], v83 offset:32768
	ds_read_b128 v[8:11], v83 offset:36864
	v_lshl_or_b32 v134, v81, 13, v4
	v_add_u32_e32 v101, 0, v134
	v_add_u32_e32 v82, v101, v132
	ds_read_b128 v[4:7], v82
	ds_read_b128 v[154:157], v82 offset:4096
	s_waitcnt lgkmcnt(1)
	v_lshrrev_b32_e32 v182, 6, v133
	s_nop 0
	v_readfirstlane_b32 s32, v182
	v_mfma_f32_32x32x16_bf16 v[48:63], v[0:3], v[4:7], 0
	v_bfe_u32 v103, v78, 1, 3
	s_mov_b64 s[46:47], 0x180
	s_nop 0
	s_add_i32 s30, 0, 0xc000
	v_or_b32_e32 v143, 0x8000, v102
	v_or_b32_e32 v144, 0x9000, v102
	v_add_u32_e32 v145, s3, v134
	s_waitcnt vmcnt(12)
	v_mfma_f32_32x32x16_bf16 v[32:47], v[8:11], v[4:7], 0
	v_lshl_or_b32 v81, v81, 6, v79
	v_mul_lo_u32 v81, v81, s26
	s_mov_b64 s[80:81], 0x200
	s_waitcnt lgkmcnt(0)
	v_mfma_f32_32x32x16_bf16 v[16:31], v[0:3], v[154:157], 0
	v_bitop3_b32 v0, v64, v103, 2 bitop3:0x36
	v_lshlrev_b32_e32 v138, 4, v0
	v_add_u32_e32 v85, v100, v138
	ds_read_b128 v[86:89], v85 offset:32768
	ds_read_b128 v[94:97], v85 offset:36864
	v_add_u32_e32 v84, v101, v138
	ds_read_b128 v[90:93], v84
	v_mfma_f32_32x32x16_bf16 v[0:15], v[8:11], v[154:157], 0
	ds_read_b128 v[150:153], v84 offset:4096
	s_waitcnt lgkmcnt(1)
	v_mfma_f32_32x32x16_bf16 v[48:63], v[86:89], v[90:93], v[48:63]
	v_mfma_f32_32x32x16_bf16 v[32:47], v[94:97], v[90:93], v[32:47]
	s_waitcnt lgkmcnt(0)
	v_mfma_f32_32x32x16_bf16 v[16:31], v[86:89], v[150:153], v[16:31]
	v_bitop3_b32 v86, v64, v103, 4 bitop3:0x36
	v_lshlrev_b32_e32 v139, 4, v86
	v_add_u32_e32 v87, v100, v139
	v_add_u32_e32 v86, v101, v139
	v_mfma_f32_32x32x16_bf16 v[0:15], v[94:97], v[150:153], v[0:15]
	ds_read_b128 v[88:91], v87 offset:32768
	ds_read_b128 v[92:95], v86
	ds_read_b128 v[96:99], v87 offset:36864
	ds_read_b128 v[154:157], v86 offset:4096
	s_waitcnt lgkmcnt(1)
	v_mfma_f32_32x32x16_bf16 v[48:63], v[88:91], v[92:95], v[48:63]
	v_mfma_f32_32x32x16_bf16 v[32:47], v[96:99], v[92:95], v[32:47]
	s_waitcnt lgkmcnt(0)
	v_mfma_f32_32x32x16_bf16 v[16:31], v[88:91], v[154:157], v[16:31]
	v_bitop3_b32 v88, v64, v103, 6 bitop3:0x36
	v_lshlrev_b32_e32 v142, 4, v88
	v_add_u32_e32 v89, v100, v142
	v_add_u32_e32 v88, v101, v142
	v_lshlrev_b32_e32 v64, 4, v64
	v_lshl_or_b32 v64, v80, 8, v64
	v_add3_u32 v64, 0, v81, v64
	v_mfma_f32_32x32x16_bf16 v[0:15], v[96:99], v[154:157], v[0:15]
	ds_read_b128 v[90:93], v89 offset:32768
	ds_read_b128 v[94:97], v88
	ds_read_b128 v[98:101], v89 offset:36864
	ds_read_b128 v[150:153], v88 offset:4096
	s_waitcnt lgkmcnt(1)
	v_mfma_f32_32x32x16_bf16 v[48:63], v[90:93], v[94:97], v[48:63]
	v_mfma_f32_32x32x16_bf16 v[32:47], v[98:101], v[94:97], v[32:47]
	s_waitcnt vmcnt(6)
	s_waitcnt lgkmcnt(0)
	s_barrier
	s_waitcnt lgkmcnt(0)
	v_mfma_f32_32x32x16_bf16 v[16:31], v[90:93], v[150:153], v[16:31]
	v_lshl_add_u64 v[158:159], v[66:67], 0, s[46:47]
	s_nop 0
	v_lshl_add_u64 v[160:161], v[68:69], 0, s[46:47]
	s_nop 0
	s_nop 0
	s_nop 0
	v_lshl_add_u64 v[162:163], v[70:71], 0, s[46:47]
	s_nop 0
	v_mfma_f32_32x32x16_bf16 v[0:15], v[98:101], v[150:153], v[0:15]
	s_and_b32 m0, s32, 7
	s_lshl_b32 m0, m0, 12
	s_add_i32 m0, m0, 0x0
	s_nop 0
	global_load_lds_dwordx4 v[158:159], off
	s_nop 0
	v_lshl_add_u64 v[164:165], v[72:73], 0, s[46:47]
	s_nop 0
	s_nop 0
	s_nop 0
	v_lshl_add_u64 v[166:167], v[74:75], 0, s[46:47]
	s_nop 0
	s_nop 0
	s_nop 0
	v_lshl_add_u64 v[168:169], v[76:77], 0, s[46:47]
	s_nop 0
	s_mov_b64 s[46:47], 0x200
	s_nop 0
	v_add_u32_e32 v90, s30, v132
	v_add_u32_e32 v92, v90, v143
	v_add_u32_e32 v90, v90, v144
	ds_read_b128 v[94:97], v92
	ds_read_b128 v[98:101], v82 offset:49152
	ds_read_b128 v[102:105], v90
	ds_read_b128 v[154:157], v82 offset:53248
	s_waitcnt lgkmcnt(1)
	v_mfma_f32_32x32x16_bf16 v[48:63], v[94:97], v[98:101], v[48:63]
	v_add_u32_e32 v91, s30, v138
	v_add_u32_e32 v93, v91, v143
	v_add_u32_e32 v91, v91, v144
	s_nop 0
	v_mfma_f32_32x32x16_bf16 v[32:47], v[102:105], v[98:101], v[32:47]
	s_and_b32 m0, s32, 7
	s_lshl_b32 m0, m0, 12
	s_add_i32 m0, m0, 0x400
	s_nop 0
	global_load_lds_dwordx4 v[160:161], off
	s_waitcnt lgkmcnt(0)
	v_mfma_f32_32x32x16_bf16 v[16:31], v[94:97], v[154:157], v[16:31]
	v_mfma_f32_32x32x16_bf16 v[0:15], v[102:105], v[154:157], v[0:15]
	s_and_b32 m0, s32, 7
	s_lshl_b32 m0, m0, 12
	s_add_i32 m0, m0, 0x800
	s_nop 0
	global_load_lds_dwordx4 v[162:163], off
	ds_read_b128 v[94:97], v93
	ds_read_b128 v[98:101], v84 offset:49152
	ds_read_b128 v[102:105], v91
	ds_read_b128 v[150:153], v84 offset:53248
	s_waitcnt lgkmcnt(1)
	v_mfma_f32_32x32x16_bf16 v[48:63], v[94:97], v[98:101], v[48:63]
	v_mfma_f32_32x32x16_bf16 v[32:47], v[102:105], v[98:101], v[32:47]
	s_and_b32 m0, s32, 7
	s_lshl_b32 m0, m0, 12
	s_add_i32 m0, m0, 0xc00
	s_nop 0
	global_load_lds_dwordx4 v[164:165], off
	s_waitcnt lgkmcnt(0)
	v_mfma_f32_32x32x16_bf16 v[16:31], v[94:97], v[150:153], v[16:31]
	v_add_u32_e32 v94, s30, v139
	v_add_u32_e32 v95, v94, v143
	v_add_u32_e32 v94, v94, v144
	v_mfma_f32_32x32x16_bf16 v[0:15], v[102:105], v[150:153], v[0:15]
	s_and_b32 m0, s32, 7
	s_lshl_b32 m0, m0, 11
	s_add_i32 m0, m0, 0x8000
	s_nop 0
	global_load_lds_dwordx4 v[166:167], off
	ds_read_b128 v[96:99], v95
	ds_read_b128 v[100:103], v86 offset:49152
	ds_read_b128 v[104:107], v94
	ds_read_b128 v[154:157], v86 offset:53248
	s_waitcnt lgkmcnt(1)
	v_mfma_f32_32x32x16_bf16 v[48:63], v[96:99], v[100:103], v[48:63]
	v_mfma_f32_32x32x16_bf16 v[32:47], v[104:107], v[100:103], v[32:47]
	s_and_b32 m0, s32, 7
	s_lshl_b32 m0, m0, 11
	s_add_i32 m0, m0, 0x8400
	s_nop 0
	global_load_lds_dwordx4 v[168:169], off
	s_waitcnt lgkmcnt(0)
	v_mfma_f32_32x32x16_bf16 v[16:31], v[96:99], v[154:157], v[16:31]
	v_add_u32_e32 v96, s30, v142
	v_add_u32_e32 v97, v96, v143
	v_add_u32_e32 v96, v96, v144
	v_mfma_f32_32x32x16_bf16 v[0:15], v[104:107], v[154:157], v[0:15]
	ds_read_b128 v[98:101], v97
	ds_read_b128 v[102:105], v88 offset:49152
	ds_read_b128 v[106:109], v96
	ds_read_b128 v[150:153], v88 offset:53248
	s_waitcnt lgkmcnt(1)
	v_mfma_f32_32x32x16_bf16 v[48:63], v[98:101], v[102:105], v[48:63]
	v_mfma_f32_32x32x16_bf16 v[32:47], v[106:109], v[102:105], v[32:47]
	s_waitcnt vmcnt(6)
	s_waitcnt lgkmcnt(0)
	s_barrier
	s_waitcnt lgkmcnt(0)
	v_mfma_f32_32x32x16_bf16 v[16:31], v[98:101], v[150:153], v[16:31]
	v_lshl_add_u64 v[170:171], v[66:67], 0, s[46:47]
	s_nop 0
	v_lshl_add_u64 v[172:173], v[68:69], 0, s[46:47]
	s_nop 0
	v_add_u32_e32 v101, s3, v132
	s_nop 0
	v_lshl_add_u64 v[174:175], v[70:71], 0, s[46:47]
	s_nop 0
	v_mfma_f32_32x32x16_bf16 v[0:15], v[106:109], v[150:153], v[0:15]
	s_and_b32 m0, s32, 7
	s_lshl_b32 m0, m0, 12
	s_add_i32 m0, m0, 0xc000
	s_nop 0
	global_load_lds_dwordx4 v[170:171], off
	s_nop 0
	v_lshl_add_u64 v[176:177], v[72:73], 0, s[46:47]
	s_nop 0
	v_add_u32_e32 v100, v145, v132
	s_nop 0
	v_lshl_add_u64 v[178:179], v[74:75], 0, s[46:47]
	s_nop 0
	v_or_b32_e32 v132, 0x1000, v134
	s_nop 0
	v_lshl_add_u64 v[180:181], v[76:77], 0, s[46:47]
	s_nop 0
	s_mov_b64 s[46:47], 0x280
	s_nop 0
	v_add_u32_e32 v98, v101, v143
	v_add_u32_e32 v99, v101, v144
	ds_read_b128 v[110:113], v98
	ds_read_b128 v[106:109], v99
	ds_read_b128 v[102:105], v100
	v_add_u32_e32 v101, v101, v132
	ds_read_b128 v[134:137], v101
	s_waitcnt lgkmcnt(0)
	v_mfma_f32_32x32x16_bf16 v[48:63], v[110:113], v[102:105], v[48:63]
	s_nop 0
	v_mfma_f32_32x32x16_bf16 v[32:47], v[106:109], v[102:105], v[32:47]
	s_and_b32 m0, s32, 7
	s_lshl_b32 m0, m0, 12
	s_add_i32 m0, m0, 0xc400
	s_nop 0
	global_load_lds_dwordx4 v[172:173], off
	v_add_u32_e32 v105, s3, v138
	v_add_u32_e32 v102, v105, v143
	v_add_u32_e32 v103, v105, v144
	v_add_u32_e32 v104, v145, v138
	v_add_u32_e32 v105, v105, v132
	v_mfma_f32_32x32x16_bf16 v[16:31], v[110:113], v[134:137], v[16:31]
	ds_read_b128 v[110:113], v104
	v_mfma_f32_32x32x16_bf16 v[0:15], v[106:109], v[134:137], v[0:15]
	s_and_b32 m0, s32, 7
	s_lshl_b32 m0, m0, 12
	s_add_i32 m0, m0, 0xc800
	s_nop 0
	global_load_lds_dwordx4 v[174:175], off
	ds_read_b128 v[106:109], v102
	ds_read_b128 v[134:137], v103
	ds_read_b128 v[154:157], v105
	s_waitcnt lgkmcnt(1)
	v_mfma_f32_32x32x16_bf16 v[48:63], v[106:109], v[110:113], v[48:63]
	v_mfma_f32_32x32x16_bf16 v[32:47], v[134:137], v[110:113], v[32:47]
	s_and_b32 m0, s32, 7
	s_lshl_b32 m0, m0, 12
	s_add_i32 m0, m0, 0xcc00
	s_nop 0
	global_load_lds_dwordx4 v[176:177], off
	s_waitcnt lgkmcnt(0)
	v_mfma_f32_32x32x16_bf16 v[16:31], v[106:109], v[154:157], v[16:31]
	v_add_u32_e32 v109, s3, v139
	v_add_u32_e32 v106, v109, v143
	v_add_u32_e32 v107, v109, v144
	v_add_u32_e32 v108, v145, v139
	ds_read_b128 v[138:141], v107
	v_add_u32_e32 v109, v109, v132
	v_mfma_f32_32x32x16_bf16 v[0:15], v[134:137], v[154:157], v[0:15]
	s_and_b32 m0, s32, 7
	s_lshl_b32 m0, m0, 11
	s_add_i32 m0, m0, 0x14000
	s_nop 0
	global_load_lds_dwordx4 v[178:179], off
	ds_read_b128 v[110:113], v106
	ds_read_b128 v[134:137], v108
	ds_read_b128 v[150:153], v109
	s_waitcnt lgkmcnt(1)
	v_mfma_f32_32x32x16_bf16 v[48:63], v[110:113], v[134:137], v[48:63]
	v_mfma_f32_32x32x16_bf16 v[32:47], v[138:141], v[134:137], v[32:47]
	s_and_b32 m0, s32, 7
	s_lshl_b32 m0, m0, 11
	s_add_i32 m0, m0, 0x14400
	s_nop 0
	global_load_lds_dwordx4 v[180:181], off
	s_waitcnt lgkmcnt(0)
	v_mfma_f32_32x32x16_bf16 v[16:31], v[110:113], v[150:153], v[16:31]
	v_add_u32_e32 v113, s3, v142
	v_add_u32_e32 v110, v113, v143
	v_add_u32_e32 v111, v113, v144
	v_add_u32_e32 v112, v145, v142
	ds_read_b128 v[142:145], v111
	v_add_u32_e32 v113, v113, v132
	v_mfma_f32_32x32x16_bf16 v[0:15], v[138:141], v[150:153], v[0:15]
	ds_read_b128 v[134:137], v110
	ds_read_b128 v[138:141], v112
	ds_read_b128 v[154:157], v113
	s_waitcnt lgkmcnt(1)
	v_mfma_f32_32x32x16_bf16 v[48:63], v[134:137], v[138:141], v[48:63]
	v_mfma_f32_32x32x16_bf16 v[32:47], v[142:145], v[138:141], v[32:47]
	s_waitcnt vmcnt(6)
	s_waitcnt lgkmcnt(0)
	s_barrier
	s_waitcnt lgkmcnt(0)
	v_mfma_f32_32x32x16_bf16 v[16:31], v[134:137], v[154:157], v[16:31]
	v_lshl_add_u64 v[158:159], v[66:67], 0, s[46:47]
	s_nop 0
	v_lshl_add_u64 v[160:161], v[68:69], 0, s[46:47]
	s_nop 0
	s_nop 0
	s_nop 0
	v_lshl_add_u64 v[162:163], v[70:71], 0, s[46:47]
	s_nop 0
	v_mfma_f32_32x32x16_bf16 v[0:15], v[142:145], v[154:157], v[0:15]
	s_and_b32 m0, s32, 7
	s_lshl_b32 m0, m0, 12
	s_add_i32 m0, m0, 0x18000
	s_nop 0
	global_load_lds_dwordx4 v[158:159], off
	s_nop 0
	v_lshl_add_u64 v[164:165], v[72:73], 0, s[46:47]
	s_nop 0
	s_nop 0
	s_nop 0
	v_lshl_add_u64 v[166:167], v[74:75], 0, s[46:47]
	s_nop 0
	s_nop 0
	s_nop 0
	v_lshl_add_u64 v[168:169], v[76:77], 0, s[46:47]
	s_nop 0
	s_mov_b64 s[46:47], 0x300
	s_nop 0
	ds_read_b128 v[134:137], v83 offset:32768
	ds_read_b128 v[138:141], v82
	ds_read_b128 v[142:145], v83 offset:36864
	ds_read_b128 v[150:153], v82 offset:4096
	s_waitcnt lgkmcnt(1)
	v_mfma_f32_32x32x16_bf16 v[48:63], v[134:137], v[138:141], v[48:63]
	s_nop 0
	v_mfma_f32_32x32x16_bf16 v[32:47], v[142:145], v[138:141], v[32:47]
	s_and_b32 m0, s32, 7
	s_lshl_b32 m0, m0, 12
	s_add_i32 m0, m0, 0x18400
	s_nop 0
	global_load_lds_dwordx4 v[160:161], off
	s_waitcnt lgkmcnt(0)
	v_mfma_f32_32x32x16_bf16 v[16:31], v[134:137], v[150:153], v[16:31]
	v_mfma_f32_32x32x16_bf16 v[0:15], v[142:145], v[150:153], v[0:15]
	s_and_b32 m0, s32, 7
	s_lshl_b32 m0, m0, 12
	s_add_i32 m0, m0, 0x18800
	s_nop 0
	global_load_lds_dwordx4 v[162:163], off
	ds_read_b128 v[134:137], v85 offset:32768
	ds_read_b128 v[138:141], v84
	ds_read_b128 v[142:145], v85 offset:36864
	ds_read_b128 v[154:157], v84 offset:4096
	s_waitcnt lgkmcnt(1)
	v_mfma_f32_32x32x16_bf16 v[48:63], v[134:137], v[138:141], v[48:63]
	v_mfma_f32_32x32x16_bf16 v[32:47], v[142:145], v[138:141], v[32:47]
	s_and_b32 m0, s32, 7
	s_lshl_b32 m0, m0, 12
	s_add_i32 m0, m0, 0x18c00
	s_nop 0
	global_load_lds_dwordx4 v[164:165], off
	s_waitcnt lgkmcnt(0)
	v_mfma_f32_32x32x16_bf16 v[16:31], v[134:137], v[154:157], v[16:31]
	v_mfma_f32_32x32x16_bf16 v[0:15], v[142:145], v[154:157], v[0:15]
	s_and_b32 m0, s32, 7
	s_lshl_b32 m0, m0, 11
	s_add_i32 m0, m0, 0x20000
	s_nop 0
	global_load_lds_dwordx4 v[166:167], off
	ds_read_b128 v[134:137], v87 offset:32768
	ds_read_b128 v[138:141], v86
	ds_read_b128 v[142:145], v87 offset:36864
	ds_read_b128 v[150:153], v86 offset:4096
	s_waitcnt lgkmcnt(1)
	v_mfma_f32_32x32x16_bf16 v[48:63], v[134:137], v[138:141], v[48:63]
	v_mfma_f32_32x32x16_bf16 v[32:47], v[142:145], v[138:141], v[32:47]
	s_and_b32 m0, s32, 7
	s_lshl_b32 m0, m0, 11
	s_add_i32 m0, m0, 0x20400
	s_nop 0
	global_load_lds_dwordx4 v[168:169], off
	s_waitcnt lgkmcnt(0)
	v_mfma_f32_32x32x16_bf16 v[16:31], v[134:137], v[150:153], v[16:31]
	v_mfma_f32_32x32x16_bf16 v[0:15], v[142:145], v[150:153], v[0:15]
	ds_read_b128 v[134:137], v89 offset:32768
	ds_read_b128 v[138:141], v88
	ds_read_b128 v[142:145], v89 offset:36864
	ds_read_b128 v[154:157], v88 offset:4096
	s_waitcnt lgkmcnt(1)
	v_mfma_f32_32x32x16_bf16 v[48:63], v[134:137], v[138:141], v[48:63]
	v_mfma_f32_32x32x16_bf16 v[32:47], v[142:145], v[138:141], v[32:47]
	s_waitcnt vmcnt(6)
	s_waitcnt lgkmcnt(0)
	s_barrier
	s_waitcnt lgkmcnt(0)
	v_mfma_f32_32x32x16_bf16 v[16:31], v[134:137], v[154:157], v[16:31]
	v_lshl_add_u64 v[170:171], v[66:67], 0, s[46:47]
	s_nop 0
	v_lshl_add_u64 v[172:173], v[68:69], 0, s[46:47]
	s_nop 0
	s_nop 0
	s_nop 0
	v_lshl_add_u64 v[174:175], v[70:71], 0, s[46:47]
	s_nop 0
	v_mfma_f32_32x32x16_bf16 v[0:15], v[142:145], v[154:157], v[0:15]
	s_and_b32 m0, s32, 7
	s_lshl_b32 m0, m0, 12
	s_add_i32 m0, m0, 0x0
	s_nop 0
	global_load_lds_dwordx4 v[170:171], off
	s_nop 0
	v_lshl_add_u64 v[176:177], v[72:73], 0, s[46:47]
	s_nop 0
	s_mov_b64 s[38:39], 0x380
	s_nop 0
	v_lshl_add_u64 v[178:179], v[74:75], 0, s[46:47]
	s_nop 0
	v_readfirstlane_b32 s48, v117
	s_nop 0
	v_lshl_add_u64 v[180:181], v[76:77], 0, s[46:47]
	s_nop 0
	s_mov_b64 s[46:47], 0x580
	s_nop 0
	ds_read_b128 v[134:137], v92
	ds_read_b128 v[138:141], v82 offset:49152
	ds_read_b128 v[142:145], v90
	ds_read_b128 v[150:153], v82 offset:53248
	s_waitcnt lgkmcnt(1)
	v_mfma_f32_32x32x16_bf16 v[48:63], v[134:137], v[138:141], v[48:63]
	s_nop 0
	v_readfirstlane_b32 s49, v118
	v_readfirstlane_b32 s53, v119
	v_mfma_f32_32x32x16_bf16 v[32:47], v[142:145], v[138:141], v[32:47]
	s_and_b32 m0, s32, 7
	s_lshl_b32 m0, m0, 12
	s_add_i32 m0, m0, 0x400
	s_nop 0
	global_load_lds_dwordx4 v[172:173], off
	s_waitcnt lgkmcnt(0)
	v_mfma_f32_32x32x16_bf16 v[16:31], v[134:137], v[150:153], v[16:31]
	v_mfma_f32_32x32x16_bf16 v[0:15], v[142:145], v[150:153], v[0:15]
	s_and_b32 m0, s32, 7
	s_lshl_b32 m0, m0, 12
	s_add_i32 m0, m0, 0x800
	s_nop 0
	global_load_lds_dwordx4 v[174:175], off
	ds_read_b128 v[134:137], v93
	ds_read_b128 v[138:141], v84 offset:49152
	ds_read_b128 v[142:145], v91
	ds_read_b128 v[154:157], v84 offset:53248
	s_waitcnt lgkmcnt(1)
	v_mfma_f32_32x32x16_bf16 v[48:63], v[134:137], v[138:141], v[48:63]
	v_mfma_f32_32x32x16_bf16 v[32:47], v[142:145], v[138:141], v[32:47]
	s_and_b32 m0, s32, 7
	s_lshl_b32 m0, m0, 12
	s_add_i32 m0, m0, 0xc00
	s_nop 0
	global_load_lds_dwordx4 v[176:177], off
	s_waitcnt lgkmcnt(0)
	v_mfma_f32_32x32x16_bf16 v[16:31], v[134:137], v[154:157], v[16:31]
	v_mfma_f32_32x32x16_bf16 v[0:15], v[142:145], v[154:157], v[0:15]
	s_and_b32 m0, s32, 7
	s_lshl_b32 m0, m0, 11
	s_add_i32 m0, m0, 0x8000
	s_nop 0
	global_load_lds_dwordx4 v[178:179], off
	ds_read_b128 v[134:137], v95
	ds_read_b128 v[138:141], v86 offset:49152
	ds_read_b128 v[142:145], v94
	ds_read_b128 v[150:153], v86 offset:53248
	s_waitcnt lgkmcnt(1)
	v_mfma_f32_32x32x16_bf16 v[48:63], v[134:137], v[138:141], v[48:63]
	v_mfma_f32_32x32x16_bf16 v[32:47], v[142:145], v[138:141], v[32:47]
	s_and_b32 m0, s32, 7
	s_lshl_b32 m0, m0, 11
	s_add_i32 m0, m0, 0x8400
	s_nop 0
	global_load_lds_dwordx4 v[180:181], off
	s_waitcnt lgkmcnt(0)
	v_mfma_f32_32x32x16_bf16 v[16:31], v[134:137], v[150:153], v[16:31]
	v_mfma_f32_32x32x16_bf16 v[0:15], v[142:145], v[150:153], v[0:15]
	ds_read_b128 v[134:137], v97
	ds_read_b128 v[138:141], v88 offset:49152
	ds_read_b128 v[142:145], v96
	ds_read_b128 v[154:157], v88 offset:53248
	s_waitcnt lgkmcnt(1)
	v_mfma_f32_32x32x16_bf16 v[48:63], v[134:137], v[138:141], v[48:63]
	v_mfma_f32_32x32x16_bf16 v[32:47], v[142:145], v[138:141], v[32:47]
	s_waitcnt vmcnt(6)
	s_waitcnt lgkmcnt(0)
	s_barrier
	s_waitcnt lgkmcnt(0)
	v_mfma_f32_32x32x16_bf16 v[16:31], v[134:137], v[154:157], v[16:31]
	v_lshl_add_u64 v[158:159], v[66:67], 0, s[38:39]
	s_nop 0
	v_lshl_add_u64 v[160:161], v[68:69], 0, s[38:39]
	s_nop 0
	s_mov_b64 s[28:29], 0x400
	s_nop 0
	v_lshl_add_u64 v[162:163], v[70:71], 0, s[38:39]
	s_nop 0
	v_mfma_f32_32x32x16_bf16 v[0:15], v[142:145], v[154:157], v[0:15]
	s_and_b32 m0, s32, 7
	s_lshl_b32 m0, m0, 12
	s_add_i32 m0, m0, 0xc000
	s_nop 0
	global_load_lds_dwordx4 v[158:159], off
	s_nop 0
	v_lshl_add_u64 v[164:165], v[72:73], 0, s[38:39]
	s_nop 0
	v_readfirstlane_b32 s33, v122
	s_nop 0
	v_lshl_add_u64 v[166:167], v[74:75], 0, s[38:39]
	s_nop 0
	v_readfirstlane_b32 s34, v123
	s_nop 0
	v_lshl_add_u64 v[168:169], v[76:77], 0, s[38:39]
	s_nop 0
	s_mov_b64 s[36:37], 0x500
	s_nop 0
	ds_read_b128 v[134:137], v98
	ds_read_b128 v[138:141], v100
	ds_read_b128 v[142:145], v99
	ds_read_b128 v[150:153], v101
	s_waitcnt lgkmcnt(1)
	v_mfma_f32_32x32x16_bf16 v[48:63], v[134:137], v[138:141], v[48:63]
	s_nop 0
	v_readfirstlane_b32 s0, v126
	v_readfirstlane_b32 s35, v124
	v_readfirstlane_b32 s38, v115
	v_readfirstlane_b32 s39, v116
	v_mfma_f32_32x32x16_bf16 v[32:47], v[142:145], v[138:141], v[32:47]
	s_and_b32 m0, s32, 7
	s_lshl_b32 m0, m0, 12
	s_add_i32 m0, m0, 0xc400
	s_nop 0
	global_load_lds_dwordx4 v[160:161], off
	s_waitcnt lgkmcnt(0)
	v_mfma_f32_32x32x16_bf16 v[16:31], v[134:137], v[150:153], v[16:31]
	v_mfma_f32_32x32x16_bf16 v[0:15], v[142:145], v[150:153], v[0:15]
	s_and_b32 m0, s32, 7
	s_lshl_b32 m0, m0, 12
	s_add_i32 m0, m0, 0xc800
	s_nop 0
	global_load_lds_dwordx4 v[162:163], off
	ds_read_b128 v[134:137], v102
	ds_read_b128 v[138:141], v104
	ds_read_b128 v[142:145], v103
	ds_read_b128 v[154:157], v105
	s_waitcnt lgkmcnt(1)
	v_mfma_f32_32x32x16_bf16 v[48:63], v[134:137], v[138:141], v[48:63]
	v_mfma_f32_32x32x16_bf16 v[32:47], v[142:145], v[138:141], v[32:47]
	s_and_b32 m0, s32, 7
	s_lshl_b32 m0, m0, 12
	s_add_i32 m0, m0, 0xcc00
	s_nop 0
	global_load_lds_dwordx4 v[164:165], off
	s_waitcnt lgkmcnt(0)
	v_mfma_f32_32x32x16_bf16 v[16:31], v[134:137], v[154:157], v[16:31]
	v_mfma_f32_32x32x16_bf16 v[0:15], v[142:145], v[154:157], v[0:15]
	s_and_b32 m0, s32, 7
	s_lshl_b32 m0, m0, 11
	s_add_i32 m0, m0, 0x14000
	s_nop 0
	global_load_lds_dwordx4 v[166:167], off
	ds_read_b128 v[134:137], v106
	ds_read_b128 v[138:141], v108
	ds_read_b128 v[142:145], v107
	ds_read_b128 v[150:153], v109
	s_waitcnt lgkmcnt(1)
	v_mfma_f32_32x32x16_bf16 v[48:63], v[134:137], v[138:141], v[48:63]
	v_mfma_f32_32x32x16_bf16 v[32:47], v[142:145], v[138:141], v[32:47]
	s_and_b32 m0, s32, 7
	s_lshl_b32 m0, m0, 11
	s_add_i32 m0, m0, 0x14400
	s_nop 0
	global_load_lds_dwordx4 v[168:169], off
	s_waitcnt lgkmcnt(0)
	v_mfma_f32_32x32x16_bf16 v[16:31], v[134:137], v[150:153], v[16:31]
	v_mfma_f32_32x32x16_bf16 v[0:15], v[142:145], v[150:153], v[0:15]
	ds_read_b128 v[134:137], v110
	ds_read_b128 v[138:141], v112
	ds_read_b128 v[142:145], v111
	ds_read_b128 v[154:157], v113
	s_waitcnt lgkmcnt(1)
	v_mfma_f32_32x32x16_bf16 v[48:63], v[134:137], v[138:141], v[48:63]
	v_mfma_f32_32x32x16_bf16 v[32:47], v[142:145], v[138:141], v[32:47]
	s_waitcnt vmcnt(6)
	s_waitcnt lgkmcnt(0)
	s_barrier
	s_waitcnt lgkmcnt(0)
	v_mfma_f32_32x32x16_bf16 v[16:31], v[134:137], v[154:157], v[16:31]
	v_lshl_add_u64 v[170:171], v[66:67], 0, s[28:29]
	s_nop 0
	v_lshl_add_u64 v[172:173], v[68:69], 0, s[28:29]
	s_nop 0
	v_readfirstlane_b32 s1, v127
	s_nop 0
	v_lshl_add_u64 v[174:175], v[70:71], 0, s[28:29]
	s_nop 0
	v_mfma_f32_32x32x16_bf16 v[0:15], v[142:145], v[154:157], v[0:15]
	s_and_b32 m0, s32, 7
	s_lshl_b32 m0, m0, 12
	s_add_i32 m0, m0, 0x18000
	s_nop 0
	global_load_lds_dwordx4 v[170:171], off
	s_nop 0
	v_lshl_add_u64 v[176:177], v[72:73], 0, s[28:29]
	s_nop 0
	v_readfirstlane_b32 s20, v128
	s_nop 0
	v_lshl_add_u64 v[178:179], v[74:75], 0, s[28:29]
	s_nop 0
	v_readfirstlane_b32 s21, v129
	s_nop 0
	v_lshl_add_u64 v[180:181], v[76:77], 0, s[28:29]
	s_nop 0
	s_mov_b64 s[28:29], 0x480
	s_nop 0
	ds_read_b128 v[134:137], v83 offset:32768
	ds_read_b128 v[138:141], v82
	ds_read_b128 v[142:145], v83 offset:36864
	ds_read_b128 v[150:153], v82 offset:4096
	s_waitcnt lgkmcnt(1)
	v_mfma_f32_32x32x16_bf16 v[48:63], v[134:137], v[138:141], v[48:63]
	s_nop 0
	v_lshl_add_u64 v[162:163], v[70:71], 0, s[28:29]
	v_readfirstlane_b32 s23, v131
	v_readfirstlane_b32 s24, v130
	v_mfma_f32_32x32x16_bf16 v[32:47], v[142:145], v[138:141], v[32:47]
	s_and_b32 m0, s32, 7
	s_lshl_b32 m0, m0, 12
	s_add_i32 m0, m0, 0x18400
	s_nop 0
	global_load_lds_dwordx4 v[172:173], off
	s_waitcnt lgkmcnt(0)
	v_mfma_f32_32x32x16_bf16 v[16:31], v[134:137], v[150:153], v[16:31]
	v_mfma_f32_32x32x16_bf16 v[0:15], v[142:145], v[150:153], v[0:15]
	s_and_b32 m0, s32, 7
	s_lshl_b32 m0, m0, 12
	s_add_i32 m0, m0, 0x18800
	s_nop 0
	global_load_lds_dwordx4 v[174:175], off
	ds_read_b128 v[134:137], v85 offset:32768
	ds_read_b128 v[138:141], v84
	ds_read_b128 v[142:145], v85 offset:36864
	ds_read_b128 v[154:157], v84 offset:4096
	s_waitcnt lgkmcnt(1)
	v_mfma_f32_32x32x16_bf16 v[48:63], v[134:137], v[138:141], v[48:63]
	v_mfma_f32_32x32x16_bf16 v[32:47], v[142:145], v[138:141], v[32:47]
	s_and_b32 m0, s32, 7
	s_lshl_b32 m0, m0, 12
	s_add_i32 m0, m0, 0x18c00
	s_nop 0
	global_load_lds_dwordx4 v[176:177], off
	s_waitcnt lgkmcnt(0)
	v_mfma_f32_32x32x16_bf16 v[16:31], v[134:137], v[154:157], v[16:31]
	v_mfma_f32_32x32x16_bf16 v[0:15], v[142:145], v[154:157], v[0:15]
	s_and_b32 m0, s32, 7
	s_lshl_b32 m0, m0, 11
	s_add_i32 m0, m0, 0x20000
	s_nop 0
	global_load_lds_dwordx4 v[178:179], off
	ds_read_b128 v[134:137], v87 offset:32768
	ds_read_b128 v[138:141], v86
	ds_read_b128 v[142:145], v87 offset:36864
	ds_read_b128 v[150:153], v86 offset:4096
	s_waitcnt lgkmcnt(1)
	v_mfma_f32_32x32x16_bf16 v[48:63], v[134:137], v[138:141], v[48:63]
	v_mfma_f32_32x32x16_bf16 v[32:47], v[142:145], v[138:141], v[32:47]
	s_and_b32 m0, s32, 7
	s_lshl_b32 m0, m0, 11
	s_add_i32 m0, m0, 0x20400
	s_nop 0
	global_load_lds_dwordx4 v[180:181], off
	s_waitcnt lgkmcnt(0)
	v_mfma_f32_32x32x16_bf16 v[16:31], v[134:137], v[150:153], v[16:31]
	v_mfma_f32_32x32x16_bf16 v[0:15], v[142:145], v[150:153], v[0:15]
	ds_read_b128 v[134:137], v89 offset:32768
	ds_read_b128 v[138:141], v88
	ds_read_b128 v[142:145], v89 offset:36864
	ds_read_b128 v[154:157], v88 offset:4096
	s_waitcnt lgkmcnt(1)
	v_mfma_f32_32x32x16_bf16 v[48:63], v[134:137], v[138:141], v[48:63]
	v_mfma_f32_32x32x16_bf16 v[32:47], v[142:145], v[138:141], v[32:47]
	s_waitcnt vmcnt(6)
	s_waitcnt lgkmcnt(0)
	s_barrier
	s_waitcnt lgkmcnt(0)
	v_mfma_f32_32x32x16_bf16 v[16:31], v[134:137], v[154:157], v[16:31]
	v_lshl_add_u64 v[158:159], v[66:67], 0, s[28:29]
	s_nop 0
	v_lshl_add_u64 v[160:161], v[68:69], 0, s[28:29]
	s_nop 0
	s_nop 0
	s_nop 0
	s_nop 0
	v_mfma_f32_32x32x16_bf16 v[0:15], v[142:145], v[154:157], v[0:15]
	s_and_b32 m0, s32, 7
	s_lshl_b32 m0, m0, 12
	s_add_i32 m0, m0, 0x0
	s_nop 0
	global_load_lds_dwordx4 v[158:159], off
	s_nop 0
	v_lshl_add_u64 v[164:165], v[72:73], 0, s[28:29]
	s_nop 0
	s_nop 0
	s_nop 0
	v_lshl_add_u64 v[166:167], v[74:75], 0, s[28:29]
	s_nop 0
	s_nop 0
	s_nop 0
	v_lshl_add_u64 v[168:169], v[76:77], 0, s[28:29]
	s_nop 0
	v_readfirstlane_b32 s28, v120
	s_nop 0
	ds_read_b128 v[126:129], v92
	ds_read_b128 v[134:137], v82 offset:49152
	ds_read_b128 v[138:141], v90
	ds_read_b128 v[150:153], v82 offset:53248
	s_waitcnt lgkmcnt(1)
	v_mfma_f32_32x32x16_bf16 v[48:63], v[126:129], v[134:137], v[48:63]
	s_nop 0
	v_readfirstlane_b32 s29, v121
	v_lshl_add_u64 v[174:175], v[70:71], 0, s[36:37]
	v_mfma_f32_32x32x16_bf16 v[32:47], v[138:141], v[134:137], v[32:47]
	s_and_b32 m0, s32, 7
	s_lshl_b32 m0, m0, 12
	s_add_i32 m0, m0, 0x400
	s_nop 0
	global_load_lds_dwordx4 v[160:161], off
	s_waitcnt lgkmcnt(0)
	v_mfma_f32_32x32x16_bf16 v[16:31], v[126:129], v[150:153], v[16:31]
	v_mfma_f32_32x32x16_bf16 v[0:15], v[138:141], v[150:153], v[0:15]
	s_and_b32 m0, s32, 7
	s_lshl_b32 m0, m0, 12
	s_add_i32 m0, m0, 0x800
	s_nop 0
	global_load_lds_dwordx4 v[162:163], off
	ds_read_b128 v[126:129], v93
	ds_read_b128 v[134:137], v84 offset:49152
	ds_read_b128 v[138:141], v91
	ds_read_b128 v[154:157], v84 offset:53248
	s_waitcnt lgkmcnt(1)
	v_mfma_f32_32x32x16_bf16 v[48:63], v[126:129], v[134:137], v[48:63]
	v_mfma_f32_32x32x16_bf16 v[32:47], v[138:141], v[134:137], v[32:47]
	s_and_b32 m0, s32, 7
	s_lshl_b32 m0, m0, 12
	s_add_i32 m0, m0, 0xc00
	s_nop 0
	global_load_lds_dwordx4 v[164:165], off
	s_waitcnt lgkmcnt(0)
	v_mfma_f32_32x32x16_bf16 v[16:31], v[126:129], v[154:157], v[16:31]
	v_mfma_f32_32x32x16_bf16 v[0:15], v[138:141], v[154:157], v[0:15]
	s_and_b32 m0, s32, 7
	s_lshl_b32 m0, m0, 11
	s_add_i32 m0, m0, 0x8000
	s_nop 0
	global_load_lds_dwordx4 v[166:167], off
	ds_read_b128 v[126:129], v95
	ds_read_b128 v[134:137], v86 offset:49152
	ds_read_b128 v[138:141], v94
	ds_read_b128 v[150:153], v86 offset:53248
	s_waitcnt lgkmcnt(1)
	v_mfma_f32_32x32x16_bf16 v[48:63], v[126:129], v[134:137], v[48:63]
	v_mfma_f32_32x32x16_bf16 v[32:47], v[138:141], v[134:137], v[32:47]
	s_and_b32 m0, s32, 7
	s_lshl_b32 m0, m0, 11
	s_add_i32 m0, m0, 0x8400
	s_nop 0
	global_load_lds_dwordx4 v[168:169], off
	s_waitcnt lgkmcnt(0)
	v_mfma_f32_32x32x16_bf16 v[16:31], v[126:129], v[150:153], v[16:31]
	v_mfma_f32_32x32x16_bf16 v[0:15], v[138:141], v[150:153], v[0:15]
	ds_read_b128 v[126:129], v97
	ds_read_b128 v[134:137], v88 offset:49152
	ds_read_b128 v[138:141], v96
	ds_read_b128 v[154:157], v88 offset:53248
	s_waitcnt lgkmcnt(1)
	v_mfma_f32_32x32x16_bf16 v[48:63], v[126:129], v[134:137], v[48:63]
	v_mfma_f32_32x32x16_bf16 v[32:47], v[138:141], v[134:137], v[32:47]
	s_waitcnt vmcnt(6)
	s_waitcnt lgkmcnt(0)
	s_barrier
	s_waitcnt lgkmcnt(0)
	v_mfma_f32_32x32x16_bf16 v[16:31], v[126:129], v[154:157], v[16:31]
	v_lshl_add_u64 v[170:171], v[66:67], 0, s[36:37]
	s_nop 0
	v_lshl_add_u64 v[172:173], v[68:69], 0, s[36:37]
	s_nop 0
	s_nop 0
	s_nop 0
	s_nop 0
	v_mfma_f32_32x32x16_bf16 v[0:15], v[138:141], v[154:157], v[0:15]
	s_and_b32 m0, s32, 7
	s_lshl_b32 m0, m0, 12
	s_add_i32 m0, m0, 0xc000
	s_nop 0
	global_load_lds_dwordx4 v[170:171], off
	s_nop 0
	v_lshl_add_u64 v[176:177], v[72:73], 0, s[36:37]
	s_nop 0
	s_nop 0
	s_nop 0
	v_lshl_add_u64 v[178:179], v[74:75], 0, s[36:37]
	s_nop 0
	s_nop 0
	s_nop 0
	v_lshl_add_u64 v[180:181], v[76:77], 0, s[36:37]
	v_readfirstlane_b32 s36, v125
	s_nop 0
	v_readfirstlane_b32 s37, v114
	s_nop 0
	ds_read_b128 v[120:123], v98
	ds_read_b128 v[124:127], v100
	ds_read_b128 v[128:131], v99
	ds_read_b128 v[150:153], v101
	s_waitcnt lgkmcnt(1)
	v_mfma_f32_32x32x16_bf16 v[48:63], v[120:123], v[124:127], v[48:63]
	s_nop 0
	v_lshl_add_u64 v[162:163], v[70:71], 0, s[46:47]
	v_mfma_f32_32x32x16_bf16 v[32:47], v[128:131], v[124:127], v[32:47]
	s_and_b32 m0, s32, 7
	s_lshl_b32 m0, m0, 12
	s_add_i32 m0, m0, 0xc400
	s_nop 0
	global_load_lds_dwordx4 v[172:173], off
	s_waitcnt lgkmcnt(0)
	v_mfma_f32_32x32x16_bf16 v[16:31], v[120:123], v[150:153], v[16:31]
	v_mfma_f32_32x32x16_bf16 v[0:15], v[128:131], v[150:153], v[0:15]
	s_and_b32 m0, s32, 7
	s_lshl_b32 m0, m0, 12
	s_add_i32 m0, m0, 0xc800
	s_nop 0
	global_load_lds_dwordx4 v[174:175], off
	ds_read_b128 v[120:123], v102
	ds_read_b128 v[124:127], v104
	ds_read_b128 v[128:131], v103
	ds_read_b128 v[154:157], v105
	s_waitcnt lgkmcnt(1)
	v_mfma_f32_32x32x16_bf16 v[48:63], v[120:123], v[124:127], v[48:63]
	v_mfma_f32_32x32x16_bf16 v[32:47], v[128:131], v[124:127], v[32:47]
	s_and_b32 m0, s32, 7
	s_lshl_b32 m0, m0, 12
	s_add_i32 m0, m0, 0xcc00
	s_nop 0
	global_load_lds_dwordx4 v[176:177], off
	s_waitcnt lgkmcnt(0)
	v_mfma_f32_32x32x16_bf16 v[16:31], v[120:123], v[154:157], v[16:31]
	v_mfma_f32_32x32x16_bf16 v[0:15], v[128:131], v[154:157], v[0:15]
	s_and_b32 m0, s32, 7
	s_lshl_b32 m0, m0, 11
	s_add_i32 m0, m0, 0x14000
	s_nop 0
	global_load_lds_dwordx4 v[178:179], off
	ds_read_b128 v[120:123], v106
	ds_read_b128 v[124:127], v108
	ds_read_b128 v[128:131], v107
	ds_read_b128 v[150:153], v109
	s_waitcnt lgkmcnt(1)
	v_mfma_f32_32x32x16_bf16 v[48:63], v[120:123], v[124:127], v[48:63]
	v_mfma_f32_32x32x16_bf16 v[32:47], v[128:131], v[124:127], v[32:47]
	s_and_b32 m0, s32, 7
	s_lshl_b32 m0, m0, 11
	s_add_i32 m0, m0, 0x14400
	s_nop 0
	global_load_lds_dwordx4 v[180:181], off
	s_waitcnt lgkmcnt(0)
	v_mfma_f32_32x32x16_bf16 v[16:31], v[120:123], v[150:153], v[16:31]
	v_mfma_f32_32x32x16_bf16 v[0:15], v[128:131], v[150:153], v[0:15]
	ds_read_b128 v[120:123], v110
	ds_read_b128 v[124:127], v112
	ds_read_b128 v[128:131], v111
	ds_read_b128 v[154:157], v113
	s_waitcnt lgkmcnt(1)
	v_mfma_f32_32x32x16_bf16 v[48:63], v[120:123], v[124:127], v[48:63]
	v_mfma_f32_32x32x16_bf16 v[32:47], v[128:131], v[124:127], v[32:47]
	s_waitcnt vmcnt(6)
	s_waitcnt lgkmcnt(0)
	s_barrier
	s_waitcnt lgkmcnt(0)
	v_mfma_f32_32x32x16_bf16 v[16:31], v[120:123], v[154:157], v[16:31]
	v_lshl_add_u64 v[158:159], v[66:67], 0, s[46:47]
	s_nop 0
	v_lshl_add_u64 v[160:161], v[68:69], 0, s[46:47]
	s_nop 0
	s_nop 0
	s_nop 0
	s_nop 0
	v_mfma_f32_32x32x16_bf16 v[0:15], v[128:131], v[154:157], v[0:15]
	s_and_b32 m0, s32, 7
	s_lshl_b32 m0, m0, 12
	s_add_i32 m0, m0, 0x18000
	s_nop 0
	global_load_lds_dwordx4 v[158:159], off
	s_nop 0
	v_lshl_add_u64 v[164:165], v[72:73], 0, s[46:47]
	s_nop 0
	s_nop 0
	s_nop 0
	v_lshl_add_u64 v[166:167], v[74:75], 0, s[46:47]
	s_nop 0
	s_nop 0
	s_nop 0
	v_lshl_add_u64 v[168:169], v[76:77], 0, s[46:47]
	s_nop 0
	s_mov_b64 s[46:47], 0x600
	s_nop 0
	ds_read_b128 v[114:117], v83 offset:32768
	ds_read_b128 v[118:121], v82
	ds_read_b128 v[122:125], v83 offset:36864
	ds_read_b128 v[150:153], v82 offset:4096
	s_waitcnt lgkmcnt(1)
	v_mfma_f32_32x32x16_bf16 v[48:63], v[114:117], v[118:121], v[48:63]
	s_nop 0
	v_mfma_f32_32x32x16_bf16 v[32:47], v[122:125], v[118:121], v[32:47]
	s_and_b32 m0, s32, 7
	s_lshl_b32 m0, m0, 12
	s_add_i32 m0, m0, 0x18400
	s_nop 0
	global_load_lds_dwordx4 v[160:161], off
	s_waitcnt lgkmcnt(0)
	v_mfma_f32_32x32x16_bf16 v[16:31], v[114:117], v[150:153], v[16:31]
	v_mfma_f32_32x32x16_bf16 v[0:15], v[122:125], v[150:153], v[0:15]
	s_and_b32 m0, s32, 7
	s_lshl_b32 m0, m0, 12
	s_add_i32 m0, m0, 0x18800
	s_nop 0
	global_load_lds_dwordx4 v[162:163], off
	ds_read_b128 v[114:117], v85 offset:32768
	ds_read_b128 v[118:121], v84
	ds_read_b128 v[122:125], v85 offset:36864
	ds_read_b128 v[154:157], v84 offset:4096
	s_waitcnt lgkmcnt(1)
	v_mfma_f32_32x32x16_bf16 v[48:63], v[114:117], v[118:121], v[48:63]
	v_mfma_f32_32x32x16_bf16 v[32:47], v[122:125], v[118:121], v[32:47]
	s_and_b32 m0, s32, 7
	s_lshl_b32 m0, m0, 12
	s_add_i32 m0, m0, 0x18c00
	s_nop 0
	global_load_lds_dwordx4 v[164:165], off
	s_waitcnt lgkmcnt(0)
	v_mfma_f32_32x32x16_bf16 v[16:31], v[114:117], v[154:157], v[16:31]
	v_mfma_f32_32x32x16_bf16 v[0:15], v[122:125], v[154:157], v[0:15]
	s_and_b32 m0, s32, 7
	s_lshl_b32 m0, m0, 11
	s_add_i32 m0, m0, 0x20000
	s_nop 0
	global_load_lds_dwordx4 v[166:167], off
	ds_read_b128 v[114:117], v87 offset:32768
	ds_read_b128 v[118:121], v86
	ds_read_b128 v[122:125], v87 offset:36864
	ds_read_b128 v[150:153], v86 offset:4096
	s_waitcnt lgkmcnt(1)
	v_mfma_f32_32x32x16_bf16 v[48:63], v[114:117], v[118:121], v[48:63]
	v_mfma_f32_32x32x16_bf16 v[32:47], v[122:125], v[118:121], v[32:47]
	s_and_b32 m0, s32, 7
	s_lshl_b32 m0, m0, 11
	s_add_i32 m0, m0, 0x20400
	s_nop 0
	global_load_lds_dwordx4 v[168:169], off
	s_waitcnt lgkmcnt(0)
	v_mfma_f32_32x32x16_bf16 v[16:31], v[114:117], v[150:153], v[16:31]
	v_mfma_f32_32x32x16_bf16 v[0:15], v[122:125], v[150:153], v[0:15]
	ds_read_b128 v[114:117], v89 offset:32768
	ds_read_b128 v[118:121], v88
	ds_read_b128 v[122:125], v89 offset:36864
	ds_read_b128 v[154:157], v88 offset:4096
	s_waitcnt lgkmcnt(1)
	v_mfma_f32_32x32x16_bf16 v[48:63], v[114:117], v[118:121], v[48:63]
	v_mfma_f32_32x32x16_bf16 v[32:47], v[122:125], v[118:121], v[32:47]
	s_waitcnt vmcnt(6)
	s_waitcnt lgkmcnt(0)
	s_barrier
	s_waitcnt lgkmcnt(0)
	v_mfma_f32_32x32x16_bf16 v[16:31], v[114:117], v[154:157], v[16:31]
	v_lshl_add_u64 v[170:171], v[66:67], 0, s[46:47]
	s_nop 0
	v_lshl_add_u64 v[172:173], v[68:69], 0, s[46:47]
	s_nop 0
	s_nop 0
	s_nop 0
	v_lshl_add_u64 v[174:175], v[70:71], 0, s[46:47]
	s_nop 0
	v_mfma_f32_32x32x16_bf16 v[0:15], v[122:125], v[154:157], v[0:15]
	s_and_b32 m0, s32, 7
	s_lshl_b32 m0, m0, 12
	s_add_i32 m0, m0, 0x0
	s_nop 0
	global_load_lds_dwordx4 v[170:171], off
	s_nop 0
	v_lshl_add_u64 v[176:177], v[72:73], 0, s[46:47]
	s_nop 0
	s_nop 0
	s_nop 0
	v_lshl_add_u64 v[178:179], v[74:75], 0, s[46:47]
	s_nop 0
	s_nop 0
	s_nop 0
	v_lshl_add_u64 v[180:181], v[76:77], 0, s[46:47]
	s_nop 0
	s_mov_b64 s[46:47], 0x680
	s_nop 0
	ds_read_b128 v[114:117], v92
	ds_read_b128 v[118:121], v82 offset:49152
	ds_read_b128 v[122:125], v90
	ds_read_b128 v[150:153], v82 offset:53248
	s_waitcnt lgkmcnt(1)
	v_mfma_f32_32x32x16_bf16 v[48:63], v[114:117], v[118:121], v[48:63]
	s_nop 0
	v_mfma_f32_32x32x16_bf16 v[32:47], v[122:125], v[118:121], v[32:47]
	s_and_b32 m0, s32, 7
	s_lshl_b32 m0, m0, 12
	s_add_i32 m0, m0, 0x400
	s_nop 0
	global_load_lds_dwordx4 v[172:173], off
	s_waitcnt lgkmcnt(0)
	v_mfma_f32_32x32x16_bf16 v[16:31], v[114:117], v[150:153], v[16:31]
	v_mfma_f32_32x32x16_bf16 v[0:15], v[122:125], v[150:153], v[0:15]
	s_and_b32 m0, s32, 7
	s_lshl_b32 m0, m0, 12
	s_add_i32 m0, m0, 0x800
	s_nop 0
	global_load_lds_dwordx4 v[174:175], off
	ds_read_b128 v[114:117], v93
	ds_read_b128 v[118:121], v84 offset:49152
	ds_read_b128 v[122:125], v91
	ds_read_b128 v[154:157], v84 offset:53248
	s_waitcnt lgkmcnt(1)
	v_mfma_f32_32x32x16_bf16 v[48:63], v[114:117], v[118:121], v[48:63]
	v_mfma_f32_32x32x16_bf16 v[32:47], v[122:125], v[118:121], v[32:47]
	s_and_b32 m0, s32, 7
	s_lshl_b32 m0, m0, 12
	s_add_i32 m0, m0, 0xc00
	s_nop 0
	global_load_lds_dwordx4 v[176:177], off
	s_waitcnt lgkmcnt(0)
	v_mfma_f32_32x32x16_bf16 v[16:31], v[114:117], v[154:157], v[16:31]
	v_mfma_f32_32x32x16_bf16 v[0:15], v[122:125], v[154:157], v[0:15]
	s_and_b32 m0, s32, 7
	s_lshl_b32 m0, m0, 11
	s_add_i32 m0, m0, 0x8000
	s_nop 0
	global_load_lds_dwordx4 v[178:179], off
	ds_read_b128 v[114:117], v95
	ds_read_b128 v[118:121], v86 offset:49152
	ds_read_b128 v[122:125], v94
	ds_read_b128 v[150:153], v86 offset:53248
	s_waitcnt lgkmcnt(1)
	v_mfma_f32_32x32x16_bf16 v[48:63], v[114:117], v[118:121], v[48:63]
	v_mfma_f32_32x32x16_bf16 v[32:47], v[122:125], v[118:121], v[32:47]
	s_and_b32 m0, s32, 7
	s_lshl_b32 m0, m0, 11
	s_add_i32 m0, m0, 0x8400
	s_nop 0
	global_load_lds_dwordx4 v[180:181], off
	s_waitcnt lgkmcnt(0)
	v_mfma_f32_32x32x16_bf16 v[16:31], v[114:117], v[150:153], v[16:31]
	v_mfma_f32_32x32x16_bf16 v[0:15], v[122:125], v[150:153], v[0:15]
	ds_read_b128 v[114:117], v97
	ds_read_b128 v[118:121], v88 offset:49152
	ds_read_b128 v[122:125], v96
	ds_read_b128 v[154:157], v88 offset:53248
	s_waitcnt lgkmcnt(1)
	v_mfma_f32_32x32x16_bf16 v[48:63], v[114:117], v[118:121], v[48:63]
	v_mfma_f32_32x32x16_bf16 v[32:47], v[122:125], v[118:121], v[32:47]
	s_waitcnt vmcnt(6)
	s_waitcnt lgkmcnt(0)
	s_barrier
	s_waitcnt lgkmcnt(0)
	v_mfma_f32_32x32x16_bf16 v[16:31], v[114:117], v[154:157], v[16:31]
	v_lshl_add_u64 v[158:159], v[66:67], 0, s[46:47]
	s_nop 0
	v_lshl_add_u64 v[160:161], v[68:69], 0, s[46:47]
	s_nop 0
	s_mov_b64 s[28:29], 0x700
	s_nop 0
	v_lshl_add_u64 v[162:163], v[70:71], 0, s[46:47]
	s_nop 0
	v_mfma_f32_32x32x16_bf16 v[0:15], v[122:125], v[154:157], v[0:15]
	s_and_b32 m0, s32, 7
	s_lshl_b32 m0, m0, 12
	s_add_i32 m0, m0, 0xc000
	s_nop 0
	global_load_lds_dwordx4 v[158:159], off
	s_nop 0
	v_lshl_add_u64 v[164:165], v[72:73], 0, s[46:47]
	s_nop 0
	s_nop 0
	s_nop 0
	v_lshl_add_u64 v[166:167], v[74:75], 0, s[46:47]
	s_nop 0
	s_nop 0
	s_nop 0
	v_lshl_add_u64 v[168:169], v[76:77], 0, s[46:47]
	s_nop 0
	s_nop 0
	s_nop 0
	ds_read_b128 v[114:117], v98
	ds_read_b128 v[118:121], v100
	ds_read_b128 v[122:125], v99
	ds_read_b128 v[150:153], v101
	s_waitcnt lgkmcnt(1)
	v_mfma_f32_32x32x16_bf16 v[48:63], v[114:117], v[118:121], v[48:63]
	s_nop 0
	v_mfma_f32_32x32x16_bf16 v[32:47], v[122:125], v[118:121], v[32:47]
	s_and_b32 m0, s32, 7
	s_lshl_b32 m0, m0, 12
	s_add_i32 m0, m0, 0xc400
	s_nop 0
	global_load_lds_dwordx4 v[160:161], off
	s_waitcnt lgkmcnt(0)
	v_mfma_f32_32x32x16_bf16 v[16:31], v[114:117], v[150:153], v[16:31]
	v_mfma_f32_32x32x16_bf16 v[0:15], v[122:125], v[150:153], v[0:15]
	s_and_b32 m0, s32, 7
	s_lshl_b32 m0, m0, 12
	s_add_i32 m0, m0, 0xc800
	s_nop 0
	global_load_lds_dwordx4 v[162:163], off
	ds_read_b128 v[114:117], v102
	ds_read_b128 v[118:121], v104
	ds_read_b128 v[122:125], v103
	ds_read_b128 v[154:157], v105
	s_waitcnt lgkmcnt(1)
	v_mfma_f32_32x32x16_bf16 v[48:63], v[114:117], v[118:121], v[48:63]
	v_mfma_f32_32x32x16_bf16 v[32:47], v[122:125], v[118:121], v[32:47]
	s_and_b32 m0, s32, 7
	s_lshl_b32 m0, m0, 12
	s_add_i32 m0, m0, 0xcc00
	s_nop 0
	global_load_lds_dwordx4 v[164:165], off
	s_waitcnt lgkmcnt(0)
	v_mfma_f32_32x32x16_bf16 v[16:31], v[114:117], v[154:157], v[16:31]
	v_mfma_f32_32x32x16_bf16 v[0:15], v[122:125], v[154:157], v[0:15]
	s_and_b32 m0, s32, 7
	s_lshl_b32 m0, m0, 11
	s_add_i32 m0, m0, 0x14000
	s_nop 0
	global_load_lds_dwordx4 v[166:167], off
	ds_read_b128 v[114:117], v106
	ds_read_b128 v[118:121], v108
	ds_read_b128 v[122:125], v107
	ds_read_b128 v[150:153], v109
	s_waitcnt lgkmcnt(1)
	v_mfma_f32_32x32x16_bf16 v[48:63], v[114:117], v[118:121], v[48:63]
	v_mfma_f32_32x32x16_bf16 v[32:47], v[122:125], v[118:121], v[32:47]
	s_and_b32 m0, s32, 7
	s_lshl_b32 m0, m0, 11
	s_add_i32 m0, m0, 0x14400
	s_nop 0
	global_load_lds_dwordx4 v[168:169], off
	s_waitcnt lgkmcnt(0)
	v_mfma_f32_32x32x16_bf16 v[16:31], v[114:117], v[150:153], v[16:31]
	v_mfma_f32_32x32x16_bf16 v[0:15], v[122:125], v[150:153], v[0:15]
	ds_read_b128 v[114:117], v110
	ds_read_b128 v[118:121], v112
	ds_read_b128 v[122:125], v111
	ds_read_b128 v[154:157], v113
	s_waitcnt lgkmcnt(1)
	v_mfma_f32_32x32x16_bf16 v[48:63], v[114:117], v[118:121], v[48:63]
	v_mfma_f32_32x32x16_bf16 v[32:47], v[122:125], v[118:121], v[32:47]
	s_waitcnt vmcnt(6)
	s_waitcnt lgkmcnt(0)
	s_barrier
	s_waitcnt lgkmcnt(0)
	v_mfma_f32_32x32x16_bf16 v[16:31], v[114:117], v[154:157], v[16:31]
	v_lshl_add_u64 v[170:171], v[66:67], 0, s[28:29]
	s_nop 0
	v_lshl_add_u64 v[172:173], v[68:69], 0, s[28:29]
	s_nop 0
	s_nop 0
	s_nop 0
	v_lshl_add_u64 v[174:175], v[70:71], 0, s[28:29]
	s_nop 0
	v_mfma_f32_32x32x16_bf16 v[0:15], v[122:125], v[154:157], v[0:15]
	s_and_b32 m0, s32, 7
	s_lshl_b32 m0, m0, 12
	s_add_i32 m0, m0, 0x18000
	s_nop 0
	global_load_lds_dwordx4 v[170:171], off
	s_nop 0
	v_lshl_add_u64 v[176:177], v[72:73], 0, s[28:29]
	s_nop 0
	s_nop 0
	s_nop 0
	v_lshl_add_u64 v[178:179], v[74:75], 0, s[28:29]
	s_nop 0
	s_nop 0
	s_nop 0
	v_lshl_add_u64 v[180:181], v[76:77], 0, s[28:29]
	s_nop 0
	s_mov_b64 s[28:29], 0x780
	s_nop 0
	ds_read_b128 v[114:117], v83 offset:32768
	ds_read_b128 v[118:121], v82
	ds_read_b128 v[122:125], v83 offset:36864
	ds_read_b128 v[150:153], v82 offset:4096
	s_waitcnt lgkmcnt(1)
	v_mfma_f32_32x32x16_bf16 v[48:63], v[114:117], v[118:121], v[48:63]
	v_lshl_add_u64 v[158:159], v[66:67], 0, s[28:29]
	s_nop 0
	v_mfma_f32_32x32x16_bf16 v[32:47], v[122:125], v[118:121], v[32:47]
	s_and_b32 m0, s32, 7
	s_lshl_b32 m0, m0, 12
	s_add_i32 m0, m0, 0x18400
	s_nop 0
	global_load_lds_dwordx4 v[172:173], off
	s_waitcnt lgkmcnt(0)
	v_mfma_f32_32x32x16_bf16 v[16:31], v[114:117], v[150:153], v[16:31]
	v_mfma_f32_32x32x16_bf16 v[0:15], v[122:125], v[150:153], v[0:15]
	s_and_b32 m0, s32, 7
	s_lshl_b32 m0, m0, 12
	s_add_i32 m0, m0, 0x18800
	s_nop 0
	global_load_lds_dwordx4 v[174:175], off
	ds_read_b128 v[114:117], v85 offset:32768
	ds_read_b128 v[118:121], v84
	ds_read_b128 v[122:125], v85 offset:36864
	ds_read_b128 v[154:157], v84 offset:4096
	s_waitcnt lgkmcnt(1)
	v_mfma_f32_32x32x16_bf16 v[48:63], v[114:117], v[118:121], v[48:63]
	v_mfma_f32_32x32x16_bf16 v[32:47], v[122:125], v[118:121], v[32:47]
	s_and_b32 m0, s32, 7
	s_lshl_b32 m0, m0, 12
	s_add_i32 m0, m0, 0x18c00
	s_nop 0
	global_load_lds_dwordx4 v[176:177], off
	s_waitcnt lgkmcnt(0)
	v_mfma_f32_32x32x16_bf16 v[16:31], v[114:117], v[154:157], v[16:31]
	v_mfma_f32_32x32x16_bf16 v[0:15], v[122:125], v[154:157], v[0:15]
	s_and_b32 m0, s32, 7
	s_lshl_b32 m0, m0, 11
	s_add_i32 m0, m0, 0x20000
	s_nop 0
	global_load_lds_dwordx4 v[178:179], off
	ds_read_b128 v[114:117], v87 offset:32768
	ds_read_b128 v[118:121], v86
	ds_read_b128 v[122:125], v87 offset:36864
	ds_read_b128 v[150:153], v86 offset:4096
	s_waitcnt lgkmcnt(1)
	v_mfma_f32_32x32x16_bf16 v[48:63], v[114:117], v[118:121], v[48:63]
	v_mfma_f32_32x32x16_bf16 v[32:47], v[122:125], v[118:121], v[32:47]
	s_and_b32 m0, s32, 7
	s_lshl_b32 m0, m0, 11
	s_add_i32 m0, m0, 0x20400
	s_nop 0
	global_load_lds_dwordx4 v[180:181], off
	s_waitcnt lgkmcnt(0)
	v_mfma_f32_32x32x16_bf16 v[16:31], v[114:117], v[150:153], v[16:31]
	v_mfma_f32_32x32x16_bf16 v[0:15], v[122:125], v[150:153], v[0:15]
	ds_read_b128 v[114:117], v89 offset:32768
	ds_read_b128 v[118:121], v88
	ds_read_b128 v[122:125], v89 offset:36864
	ds_read_b128 v[154:157], v88 offset:4096
	s_waitcnt lgkmcnt(1)
	v_mfma_f32_32x32x16_bf16 v[48:63], v[114:117], v[118:121], v[48:63]
	v_mfma_f32_32x32x16_bf16 v[32:47], v[122:125], v[118:121], v[32:47]
	s_waitcnt vmcnt(6)
	s_waitcnt lgkmcnt(0)
	s_barrier
	s_nop 0
	v_lshl_add_u64 v[160:161], v[68:69], 0, s[28:29]
	s_nop 0
	s_waitcnt lgkmcnt(0)
	v_mfma_f32_32x32x16_bf16 v[16:31], v[114:117], v[154:157], v[16:31]
	s_nop 0
	v_lshl_add_u64 v[162:163], v[70:71], 0, s[28:29]
	s_nop 0
	v_cmp_eq_u32_e64 s[0:1], 0, v79
	s_nop 0
	v_lshl_add_u64 v[164:165], v[72:73], 0, s[28:29]
	s_nop 0
	v_mfma_f32_32x32x16_bf16 v[0:15], v[122:125], v[154:157], v[0:15]
	s_and_b32 m0, s32, 7
	s_lshl_b32 m0, m0, 12
	s_add_i32 m0, m0, 0x0
	s_nop 0
	global_load_lds_dwordx4 v[158:159], off
	s_nop 0
	v_lshl_add_u64 v[166:167], v[74:75], 0, s[28:29]
	s_nop 0
	v_readlane_b32 s20, v215, 52
	s_nop 0
	v_lshl_add_u64 v[168:169], v[76:77], 0, s[28:29]
	s_nop 0
	v_readlane_b32 s21, v215, 53
	s_nop 0
	ds_read_b128 v[66:69], v92
	ds_read_b128 v[70:73], v82 offset:49152
	ds_read_b128 v[74:77], v90
	ds_read_b128 v[150:153], v82 offset:53248
	s_waitcnt lgkmcnt(1)
	v_mfma_f32_32x32x16_bf16 v[48:63], v[66:69], v[70:73], v[48:63]
	s_mov_b32 s23, 0
	v_mfma_f32_32x32x16_bf16 v[32:47], v[74:77], v[70:73], v[32:47]
	s_and_b32 m0, s32, 7
	s_lshl_b32 m0, m0, 12
	s_add_i32 m0, m0, 0x400
	s_nop 0
	global_load_lds_dwordx4 v[160:161], off
	s_waitcnt lgkmcnt(0)
	v_mfma_f32_32x32x16_bf16 v[16:31], v[66:69], v[150:153], v[16:31]
	v_mfma_f32_32x32x16_bf16 v[0:15], v[74:77], v[150:153], v[0:15]
	s_and_b32 m0, s32, 7
	s_lshl_b32 m0, m0, 12
	s_add_i32 m0, m0, 0x800
	s_nop 0
	global_load_lds_dwordx4 v[162:163], off
	ds_read_b128 v[66:69], v93
	ds_read_b128 v[70:73], v84 offset:49152
	ds_read_b128 v[74:77], v91
	ds_read_b128 v[154:157], v84 offset:53248
	s_waitcnt lgkmcnt(1)
	v_mfma_f32_32x32x16_bf16 v[48:63], v[66:69], v[70:73], v[48:63]
	v_mfma_f32_32x32x16_bf16 v[32:47], v[74:77], v[70:73], v[32:47]
	s_and_b32 m0, s32, 7
	s_lshl_b32 m0, m0, 12
	s_add_i32 m0, m0, 0xc00
	s_nop 0
	global_load_lds_dwordx4 v[164:165], off
	s_waitcnt lgkmcnt(0)
	v_mfma_f32_32x32x16_bf16 v[16:31], v[66:69], v[154:157], v[16:31]
	v_mfma_f32_32x32x16_bf16 v[0:15], v[74:77], v[154:157], v[0:15]
	s_and_b32 m0, s32, 7
	s_lshl_b32 m0, m0, 11
	s_add_i32 m0, m0, 0x8000
	s_nop 0
	global_load_lds_dwordx4 v[166:167], off
	ds_read_b128 v[66:69], v95
	ds_read_b128 v[70:73], v86 offset:49152
	ds_read_b128 v[74:77], v94
	ds_read_b128 v[150:153], v86 offset:53248
	s_waitcnt lgkmcnt(1)
	v_mfma_f32_32x32x16_bf16 v[48:63], v[66:69], v[70:73], v[48:63]
	v_mfma_f32_32x32x16_bf16 v[32:47], v[74:77], v[70:73], v[32:47]
	s_and_b32 m0, s32, 7
	s_lshl_b32 m0, m0, 11
	s_add_i32 m0, m0, 0x8400
	s_nop 0
	global_load_lds_dwordx4 v[168:169], off
	s_waitcnt lgkmcnt(0)
	v_mfma_f32_32x32x16_bf16 v[16:31], v[66:69], v[150:153], v[16:31]
	v_mfma_f32_32x32x16_bf16 v[0:15], v[74:77], v[150:153], v[0:15]
	ds_read_b128 v[66:69], v97
	ds_read_b128 v[70:73], v88 offset:49152
	ds_read_b128 v[74:77], v96
	ds_read_b128 v[154:157], v88 offset:53248
	s_waitcnt lgkmcnt(1)
	v_mfma_f32_32x32x16_bf16 v[48:63], v[66:69], v[70:73], v[48:63]
	v_mfma_f32_32x32x16_bf16 v[32:47], v[74:77], v[70:73], v[32:47]
	s_waitcnt vmcnt(6)
	s_waitcnt lgkmcnt(0)
	s_barrier
	s_waitcnt lgkmcnt(0)
	v_mfma_f32_32x32x16_bf16 v[16:31], v[66:69], v[154:157], v[16:31]
	v_mfma_f32_32x32x16_bf16 v[0:15], v[74:77], v[154:157], v[0:15]
	ds_read_b128 v[66:69], v98
	ds_read_b128 v[70:73], v100
	ds_read_b128 v[74:77], v99
	ds_read_b128 v[150:153], v101
	s_waitcnt lgkmcnt(1)
	v_mfma_f32_32x32x16_bf16 v[48:63], v[66:69], v[70:73], v[48:63]
	v_mfma_f32_32x32x16_bf16 v[32:47], v[74:77], v[70:73], v[32:47]
	s_waitcnt lgkmcnt(0)
	v_mfma_f32_32x32x16_bf16 v[16:31], v[66:69], v[150:153], v[16:31]
	v_mfma_f32_32x32x16_bf16 v[0:15], v[74:77], v[150:153], v[0:15]
	ds_read_b128 v[66:69], v102
	ds_read_b128 v[70:73], v104
	ds_read_b128 v[74:77], v103
	ds_read_b128 v[154:157], v105
	s_waitcnt lgkmcnt(1)
	v_mfma_f32_32x32x16_bf16 v[48:63], v[66:69], v[70:73], v[48:63]
	v_mfma_f32_32x32x16_bf16 v[32:47], v[74:77], v[70:73], v[32:47]
	s_waitcnt lgkmcnt(0)
	v_mfma_f32_32x32x16_bf16 v[16:31], v[66:69], v[154:157], v[16:31]
	v_mfma_f32_32x32x16_bf16 v[0:15], v[74:77], v[154:157], v[0:15]
	ds_read_b128 v[66:69], v106
	ds_read_b128 v[70:73], v108
	ds_read_b128 v[74:77], v107
	ds_read_b128 v[150:153], v109
	s_waitcnt lgkmcnt(1)
	v_mfma_f32_32x32x16_bf16 v[48:63], v[66:69], v[70:73], v[48:63]
	v_mfma_f32_32x32x16_bf16 v[32:47], v[74:77], v[70:73], v[32:47]
	s_waitcnt lgkmcnt(0)
	v_mfma_f32_32x32x16_bf16 v[16:31], v[66:69], v[150:153], v[16:31]
	v_mfma_f32_32x32x16_bf16 v[0:15], v[74:77], v[150:153], v[0:15]
	ds_read_b128 v[66:69], v110
	ds_read_b128 v[70:73], v112
	ds_read_b128 v[74:77], v111
	ds_read_b128 v[154:157], v113
	s_waitcnt lgkmcnt(1)
	v_mfma_f32_32x32x16_bf16 v[48:63], v[66:69], v[70:73], v[48:63]
	v_mfma_f32_32x32x16_bf16 v[32:47], v[74:77], v[70:73], v[32:47]
	s_waitcnt vmcnt(0)
	s_waitcnt lgkmcnt(0)
	s_barrier
	s_waitcnt lgkmcnt(0)
	v_mfma_f32_32x32x16_bf16 v[16:31], v[66:69], v[154:157], v[16:31]
	v_mfma_f32_32x32x16_bf16 v[0:15], v[74:77], v[154:157], v[0:15]
	ds_read_b128 v[66:69], v83 offset:32768
	ds_read_b128 v[70:73], v82
	ds_read_b128 v[74:77], v83 offset:36864
	ds_read_b128 v[150:153], v82 offset:4096
	s_waitcnt lgkmcnt(1)
	v_mfma_f32_32x32x16_bf16 v[48:63], v[66:69], v[70:73], v[48:63]
	v_mfma_f32_32x32x16_bf16 v[32:47], v[74:77], v[70:73], v[32:47]
	s_waitcnt lgkmcnt(0)
	v_mfma_f32_32x32x16_bf16 v[16:31], v[66:69], v[150:153], v[16:31]
	v_mfma_f32_32x32x16_bf16 v[0:15], v[74:77], v[150:153], v[0:15]
	ds_read_b128 v[66:69], v85 offset:32768
	ds_read_b128 v[70:73], v84
	ds_read_b128 v[74:77], v85 offset:36864
	ds_read_b128 v[154:157], v84 offset:4096
	s_waitcnt lgkmcnt(1)
	v_mfma_f32_32x32x16_bf16 v[48:63], v[66:69], v[70:73], v[48:63]
	v_mfma_f32_32x32x16_bf16 v[32:47], v[74:77], v[70:73], v[32:47]
	s_waitcnt lgkmcnt(0)
	v_mfma_f32_32x32x16_bf16 v[16:31], v[66:69], v[154:157], v[16:31]
	v_mfma_f32_32x32x16_bf16 v[0:15], v[74:77], v[154:157], v[0:15]
	ds_read_b128 v[66:69], v87 offset:32768
	ds_read_b128 v[70:73], v86
	ds_read_b128 v[74:77], v87 offset:36864
	s_waitcnt lgkmcnt(0)
	v_mfma_f32_32x32x16_bf16 v[48:63], v[66:69], v[70:73], v[48:63]
	v_mfma_f32_32x32x16_bf16 v[32:47], v[74:77], v[70:73], v[32:47]
	ds_read_b128 v[70:73], v86 offset:4096
	s_waitcnt lgkmcnt(0)
	v_mfma_f32_32x32x16_bf16 v[0:15], v[74:77], v[70:73], v[0:15]
	v_mfma_f32_32x32x16_bf16 v[16:31], v[66:69], v[70:73], v[16:31]
	ds_read_b128 v[66:69], v89 offset:32768
	ds_read_b128 v[70:73], v88
	ds_read_b128 v[74:77], v89 offset:36864
	ds_read_b128 v[82:85], v88 offset:4096
	s_waitcnt lgkmcnt(0)
	s_barrier
	s_waitcnt lgkmcnt(0)
	v_mfma_f32_32x32x16_bf16 v[48:63], v[66:69], v[70:73], v[48:63]
	v_mfma_f32_32x32x16_bf16 v[32:47], v[74:77], v[70:73], v[32:47]
	s_nop 10
	ds_write_b128 v64, v[48:51]
	ds_write_b128 v64, v[52:55] offset:32
	ds_write_b128 v64, v[56:59] offset:64
	ds_write_b128 v64, v[60:63] offset:96
	ds_write_b128 v64, v[32:35] offset:128
	v_mfma_f32_32x32x16_bf16 v[0:15], v[74:77], v[82:85], v[0:15]
	v_mfma_f32_32x32x16_bf16 v[16:31], v[66:69], v[82:85], v[16:31]
	ds_write_b128 v64, v[36:39] offset:160
	ds_write_b128 v64, v[40:43] offset:192
	ds_write_b128 v64, v[44:47] offset:224
	s_nop 8
	ds_write_b128 v64, v[16:19] offset:16896
	ds_write_b128 v64, v[20:23] offset:16928
	ds_write_b128 v64, v[24:27] offset:16960
	ds_write_b128 v64, v[28:31] offset:16992
	ds_write_b128 v64, v[0:3] offset:17024
	ds_write_b128 v64, v[4:7] offset:17056
	ds_write_b128 v64, v[8:11] offset:17088
	ds_write_b128 v64, v[12:15] offset:17120
	s_waitcnt lgkmcnt(0)
	s_barrier
	v_lshl_or_b32 v0, v79, 2, s31
	v_ashrrev_i32_e32 v1, 31, v0
	v_lshl_add_u32 v4, v79, 4, 0
	v_lshl_add_u64 v[6:7], v[0:1], 2, s[92:93]
	v_lshl_add_u64 v[8:9], v[0:1], 1, s[20:21]
	s_branch .LBB0_161

.LBB0_161:
	v_lshrrev_b32_e32 v170, 5, v78
	v_mul_u32_u24_e32 v171, 0x210, v170
	v_lshl_add_u32 v171, v79, 4, v171
	v_add_u32_e32 v172, 0x10800, v171
	v_add_u32_e32 v173, s22, v170
	v_lshlrev_b32_e32 v174, 10, v173
	v_add_u32_e32 v174, s31, v174
	v_lshl_add_u32 v174, v79, 2, v174
	v_lshlrev_b32_e32 v174, 2, v174
	v_lshlrev_b32_e32 v175, 2, v173
	v_xor_b32_e32 v176, 16, v192
	v_lshlrev_b32_e32 v176, 2, v176
	s_add_u32 s20, s94, 0x2500000
	s_addc_u32 s21, s95, 0
	s_and_b64 vcc, exec, s[44:45]
	s_cbranch_vccz .Lcepi_last
	ds_read_b128 v[12:15], v171 offset:0
	v_mov_b32_e32 v134, v174
	global_load_dwordx4 v[100:103], v134, s[92:93]
	ds_read_b128 v[16:19], v171 offset:8448
	v_add_u32_e32 v135, 0x10000, v174
	global_load_dwordx4 v[104:107], v135, s[92:93]
	ds_read_b128 v[20:23], v171 offset:16896
	v_add_u32_e32 v136, 0x20000, v174
	global_load_dwordx4 v[108:111], v136, s[92:93]
	ds_read_b128 v[24:27], v171 offset:25344
	v_add_u32_e32 v137, 0x30000, v174
	global_load_dwordx4 v[112:115], v137, s[92:93]
	ds_read_b128 v[28:31], v171 offset:33792
	v_add_u32_e32 v138, 0x40000, v174
	global_load_dwordx4 v[116:119], v138, s[92:93]
	ds_read_b128 v[32:35], v171 offset:42240
	v_add_u32_e32 v139, 0x50000, v174
	global_load_dwordx4 v[120:123], v139, s[92:93]
	ds_read_b128 v[36:39], v171 offset:50688
	v_add_u32_e32 v140, 0x60000, v174
	global_load_dwordx4 v[124:127], v140, s[92:93]
	ds_read_b128 v[40:43], v171 offset:59136
	v_add_u32_e32 v141, 0x70000, v174
	global_load_dwordx4 v[128:131], v141, s[92:93]
	s_waitcnt vmcnt(7) lgkmcnt(7)
	v_pk_add_f32 v[100:101], v[100:101], v[12:13]
	v_pk_add_f32 v[102:103], v[102:103], v[14:15]
	global_store_dwordx4 v134, v[100:103], s[92:93]
	v_cvt_pk_bf16_f32 v12, v100, v101
	v_cvt_pk_bf16_f32 v13, v102, v103
	v_lshrrev_b32_e32 v14, 1, v134
	v_pk_mul_f32 v[100:101], v[100:101], v[100:101]
	v_pk_mul_f32 v[102:103], v[102:103], v[102:103]
	global_store_dwordx2 v14, v[12:13], s[20:21]
	v_add_f32_e32 v100, v100, v101
	v_add_f32_e32 v102, v102, v103
	v_add_f32_e32 v142, v100, v102
	s_waitcnt vmcnt(8) lgkmcnt(6)
	v_pk_add_f32 v[104:105], v[104:105], v[16:17]
	v_pk_add_f32 v[106:107], v[106:107], v[18:19]
	global_store_dwordx4 v135, v[104:107], s[92:93]
	v_cvt_pk_bf16_f32 v16, v104, v105
	v_cvt_pk_bf16_f32 v17, v106, v107
	v_lshrrev_b32_e32 v18, 1, v135
	v_pk_mul_f32 v[104:105], v[104:105], v[104:105]
	v_pk_mul_f32 v[106:107], v[106:107], v[106:107]
	global_store_dwordx2 v18, v[16:17], s[20:21]
	v_add_f32_e32 v104, v104, v105
	v_add_f32_e32 v106, v106, v107
	v_add_f32_e32 v143, v104, v106
	s_waitcnt vmcnt(9) lgkmcnt(5)
	v_pk_add_f32 v[108:109], v[108:109], v[20:21]
	v_pk_add_f32 v[110:111], v[110:111], v[22:23]
	global_store_dwordx4 v136, v[108:111], s[92:93]
	v_cvt_pk_bf16_f32 v20, v108, v109
	v_cvt_pk_bf16_f32 v21, v110, v111
	v_lshrrev_b32_e32 v22, 1, v136
	v_pk_mul_f32 v[108:109], v[108:109], v[108:109]
	v_pk_mul_f32 v[110:111], v[110:111], v[110:111]
	global_store_dwordx2 v22, v[20:21], s[20:21]
	v_add_f32_e32 v108, v108, v109
	v_add_f32_e32 v110, v110, v111
	v_add_f32_e32 v144, v108, v110
	s_waitcnt vmcnt(10) lgkmcnt(4)
	v_pk_add_f32 v[112:113], v[112:113], v[24:25]
	v_pk_add_f32 v[114:115], v[114:115], v[26:27]
	global_store_dwordx4 v137, v[112:115], s[92:93]
	v_cvt_pk_bf16_f32 v24, v112, v113
	v_cvt_pk_bf16_f32 v25, v114, v115
	v_lshrrev_b32_e32 v26, 1, v137
	v_pk_mul_f32 v[112:113], v[112:113], v[112:113]
	v_pk_mul_f32 v[114:115], v[114:115], v[114:115]
	global_store_dwordx2 v26, v[24:25], s[20:21]
	v_add_f32_e32 v112, v112, v113
	v_add_f32_e32 v114, v114, v115
	v_add_f32_e32 v145, v112, v114
	s_waitcnt vmcnt(11) lgkmcnt(3)
	v_pk_add_f32 v[116:117], v[116:117], v[28:29]
	v_pk_add_f32 v[118:119], v[118:119], v[30:31]
	global_store_dwordx4 v138, v[116:119], s[92:93]
	v_cvt_pk_bf16_f32 v28, v116, v117
	v_cvt_pk_bf16_f32 v29, v118, v119
	v_lshrrev_b32_e32 v30, 1, v138
	v_pk_mul_f32 v[116:117], v[116:117], v[116:117]
	v_pk_mul_f32 v[118:119], v[118:119], v[118:119]
	global_store_dwordx2 v30, v[28:29], s[20:21]
	v_add_f32_e32 v116, v116, v117
	v_add_f32_e32 v118, v118, v119
	v_add_f32_e32 v146, v116, v118
	s_waitcnt vmcnt(12) lgkmcnt(2)
	v_pk_add_f32 v[120:121], v[120:121], v[32:33]
	v_pk_add_f32 v[122:123], v[122:123], v[34:35]
	global_store_dwordx4 v139, v[120:123], s[92:93]
	v_cvt_pk_bf16_f32 v32, v120, v121
	v_cvt_pk_bf16_f32 v33, v122, v123
	v_lshrrev_b32_e32 v34, 1, v139
	v_pk_mul_f32 v[120:121], v[120:121], v[120:121]
	v_pk_mul_f32 v[122:123], v[122:123], v[122:123]
	global_store_dwordx2 v34, v[32:33], s[20:21]
	v_add_f32_e32 v120, v120, v121
	v_add_f32_e32 v122, v122, v123
	v_add_f32_e32 v147, v120, v122
	s_waitcnt vmcnt(13) lgkmcnt(1)
	v_pk_add_f32 v[124:125], v[124:125], v[36:37]
	v_pk_add_f32 v[126:127], v[126:127], v[38:39]
	global_store_dwordx4 v140, v[124:127], s[92:93]
	v_cvt_pk_bf16_f32 v36, v124, v125
	v_cvt_pk_bf16_f32 v37, v126, v127
	v_lshrrev_b32_e32 v38, 1, v140
	v_pk_mul_f32 v[124:125], v[124:125], v[124:125]
	v_pk_mul_f32 v[126:127], v[126:127], v[126:127]
	global_store_dwordx2 v38, v[36:37], s[20:21]
	v_add_f32_e32 v124, v124, v125
	v_add_f32_e32 v126, v126, v127
	v_add_f32_e32 v148, v124, v126
	s_waitcnt vmcnt(14) lgkmcnt(0)
	v_pk_add_f32 v[128:129], v[128:129], v[40:41]
	v_pk_add_f32 v[130:131], v[130:131], v[42:43]
	global_store_dwordx4 v141, v[128:131], s[92:93]
	v_cvt_pk_bf16_f32 v40, v128, v129
	v_cvt_pk_bf16_f32 v41, v130, v131
	v_lshrrev_b32_e32 v42, 1, v141
	v_pk_mul_f32 v[128:129], v[128:129], v[128:129]
	v_pk_mul_f32 v[130:131], v[130:131], v[130:131]
	global_store_dwordx2 v42, v[40:41], s[20:21]
	v_add_f32_e32 v128, v128, v129
	v_add_f32_e32 v130, v130, v131
	v_add_f32_e32 v149, v128, v130
	v_add_f32_dpp v142, v142, v142 quad_perm:[1,0,3,2] row_mask:0xf bank_mask:0xf bound_ctrl:1
	v_add_f32_dpp v143, v143, v143 quad_perm:[1,0,3,2] row_mask:0xf bank_mask:0xf bound_ctrl:1
	v_add_f32_dpp v144, v144, v144 quad_perm:[1,0,3,2] row_mask:0xf bank_mask:0xf bound_ctrl:1
	v_add_f32_dpp v145, v145, v145 quad_perm:[1,0,3,2] row_mask:0xf bank_mask:0xf bound_ctrl:1
	v_add_f32_dpp v146, v146, v146 quad_perm:[1,0,3,2] row_mask:0xf bank_mask:0xf bound_ctrl:1
	v_add_f32_dpp v147, v147, v147 quad_perm:[1,0,3,2] row_mask:0xf bank_mask:0xf bound_ctrl:1
	v_add_f32_dpp v148, v148, v148 quad_perm:[1,0,3,2] row_mask:0xf bank_mask:0xf bound_ctrl:1
	v_add_f32_dpp v149, v149, v149 quad_perm:[1,0,3,2] row_mask:0xf bank_mask:0xf bound_ctrl:1
	v_add_f32_dpp v142, v142, v142 quad_perm:[2,3,0,1] row_mask:0xf bank_mask:0xf bound_ctrl:1
	v_add_f32_dpp v143, v143, v143 quad_perm:[2,3,0,1] row_mask:0xf bank_mask:0xf bound_ctrl:1
	v_add_f32_dpp v144, v144, v144 quad_perm:[2,3,0,1] row_mask:0xf bank_mask:0xf bound_ctrl:1
	v_add_f32_dpp v145, v145, v145 quad_perm:[2,3,0,1] row_mask:0xf bank_mask:0xf bound_ctrl:1
	v_add_f32_dpp v146, v146, v146 quad_perm:[2,3,0,1] row_mask:0xf bank_mask:0xf bound_ctrl:1
	v_add_f32_dpp v147, v147, v147 quad_perm:[2,3,0,1] row_mask:0xf bank_mask:0xf bound_ctrl:1
	v_add_f32_dpp v148, v148, v148 quad_perm:[2,3,0,1] row_mask:0xf bank_mask:0xf bound_ctrl:1
	v_add_f32_dpp v149, v149, v149 quad_perm:[2,3,0,1] row_mask:0xf bank_mask:0xf bound_ctrl:1
	v_add_f32_dpp v142, v142, v142 row_half_mirror row_mask:0xf bank_mask:0xf bound_ctrl:1
	v_add_f32_dpp v143, v143, v143 row_half_mirror row_mask:0xf bank_mask:0xf bound_ctrl:1
	v_add_f32_dpp v144, v144, v144 row_half_mirror row_mask:0xf bank_mask:0xf bound_ctrl:1
	v_add_f32_dpp v145, v145, v145 row_half_mirror row_mask:0xf bank_mask:0xf bound_ctrl:1
	v_add_f32_dpp v146, v146, v146 row_half_mirror row_mask:0xf bank_mask:0xf bound_ctrl:1
	v_add_f32_dpp v147, v147, v147 row_half_mirror row_mask:0xf bank_mask:0xf bound_ctrl:1
	v_add_f32_dpp v148, v148, v148 row_half_mirror row_mask:0xf bank_mask:0xf bound_ctrl:1
	v_add_f32_dpp v149, v149, v149 row_half_mirror row_mask:0xf bank_mask:0xf bound_ctrl:1
	v_add_f32_dpp v142, v142, v142 row_mirror row_mask:0xf bank_mask:0xf bound_ctrl:1
	v_add_f32_dpp v143, v143, v143 row_mirror row_mask:0xf bank_mask:0xf bound_ctrl:1
	v_add_f32_dpp v144, v144, v144 row_mirror row_mask:0xf bank_mask:0xf bound_ctrl:1
	v_add_f32_dpp v145, v145, v145 row_mirror row_mask:0xf bank_mask:0xf bound_ctrl:1
	v_add_f32_dpp v146, v146, v146 row_mirror row_mask:0xf bank_mask:0xf bound_ctrl:1
	v_add_f32_dpp v147, v147, v147 row_mirror row_mask:0xf bank_mask:0xf bound_ctrl:1
	v_add_f32_dpp v148, v148, v148 row_mirror row_mask:0xf bank_mask:0xf bound_ctrl:1
	v_add_f32_dpp v149, v149, v149 row_mirror row_mask:0xf bank_mask:0xf bound_ctrl:1
	ds_bpermute_b32 v12, v176, v142
	ds_bpermute_b32 v16, v176, v143
	ds_bpermute_b32 v20, v176, v144
	ds_bpermute_b32 v24, v176, v145
	ds_bpermute_b32 v28, v176, v146
	ds_bpermute_b32 v32, v176, v147
	ds_bpermute_b32 v36, v176, v148
	ds_bpermute_b32 v40, v176, v149
	s_waitcnt lgkmcnt(0)
	v_add_f32_e32 v142, v142, v12
	v_add_f32_e32 v143, v143, v16
	v_add_f32_e32 v144, v144, v20
	v_add_f32_e32 v145, v145, v24
	v_add_f32_e32 v146, v146, v28
	v_add_f32_e32 v147, v147, v32
	v_add_f32_e32 v148, v148, v36
	v_add_f32_e32 v149, v149, v40
	v_add_u32_e32 v13, 0x0, v175
	v_add_u32_e32 v17, 0x40, v175
	v_add_u32_e32 v21, 0x80, v175
	v_add_u32_e32 v25, 0xc0, v175
	v_add_u32_e32 v29, 0x100, v175
	v_add_u32_e32 v33, 0x140, v175
	v_add_u32_e32 v37, 0x180, v175
	v_add_u32_e32 v41, 0x1c0, v175
	s_mov_b64 exec, s[0:1]
	global_atomic_add_f32 v13, v142, s[50:51]
	global_atomic_add_f32 v17, v143, s[50:51]
	global_atomic_add_f32 v21, v144, s[50:51]
	global_atomic_add_f32 v25, v145, s[50:51]
	global_atomic_add_f32 v29, v146, s[50:51]
	global_atomic_add_f32 v33, v147, s[50:51]
	global_atomic_add_f32 v37, v148, s[50:51]
	global_atomic_add_f32 v41, v149, s[50:51]
	s_mov_b64 exec, -1
	ds_read_b128 v[12:15], v172 offset:0
	v_add_u32_e32 v134, 0x80000, v174
	global_load_dwordx4 v[100:103], v134, s[92:93]
	ds_read_b128 v[16:19], v172 offset:8448
	v_add_u32_e32 v135, 0x90000, v174
	global_load_dwordx4 v[104:107], v135, s[92:93]
	ds_read_b128 v[20:23], v172 offset:16896
	v_add_u32_e32 v136, 0xa0000, v174
	global_load_dwordx4 v[108:111], v136, s[92:93]
	ds_read_b128 v[24:27], v172 offset:25344
	v_add_u32_e32 v137, 0xb0000, v174
	global_load_dwordx4 v[112:115], v137, s[92:93]
	ds_read_b128 v[28:31], v172 offset:33792
	v_add_u32_e32 v138, 0xc0000, v174
	global_load_dwordx4 v[116:119], v138, s[92:93]
	ds_read_b128 v[32:35], v172 offset:42240
	v_add_u32_e32 v139, 0xd0000, v174
	global_load_dwordx4 v[120:123], v139, s[92:93]
	ds_read_b128 v[36:39], v172 offset:50688
	v_add_u32_e32 v140, 0xe0000, v174
	global_load_dwordx4 v[124:127], v140, s[92:93]
	ds_read_b128 v[40:43], v172 offset:59136
	v_add_u32_e32 v141, 0xf0000, v174
	global_load_dwordx4 v[128:131], v141, s[92:93]
	s_waitcnt vmcnt(7) lgkmcnt(7)
	v_pk_add_f32 v[100:101], v[100:101], v[12:13]
	v_pk_add_f32 v[102:103], v[102:103], v[14:15]
	global_store_dwordx4 v134, v[100:103], s[92:93]
	v_cvt_pk_bf16_f32 v12, v100, v101
	v_cvt_pk_bf16_f32 v13, v102, v103
	v_lshrrev_b32_e32 v14, 1, v134
	v_pk_mul_f32 v[100:101], v[100:101], v[100:101]
	v_pk_mul_f32 v[102:103], v[102:103], v[102:103]
	global_store_dwordx2 v14, v[12:13], s[20:21]
	v_add_f32_e32 v100, v100, v101
	v_add_f32_e32 v102, v102, v103
	v_add_f32_e32 v142, v100, v102
	s_waitcnt vmcnt(8) lgkmcnt(6)
	v_pk_add_f32 v[104:105], v[104:105], v[16:17]
	v_pk_add_f32 v[106:107], v[106:107], v[18:19]
	global_store_dwordx4 v135, v[104:107], s[92:93]
	v_cvt_pk_bf16_f32 v16, v104, v105
	v_cvt_pk_bf16_f32 v17, v106, v107
	v_lshrrev_b32_e32 v18, 1, v135
	v_pk_mul_f32 v[104:105], v[104:105], v[104:105]
	v_pk_mul_f32 v[106:107], v[106:107], v[106:107]
	global_store_dwordx2 v18, v[16:17], s[20:21]
	v_add_f32_e32 v104, v104, v105
	v_add_f32_e32 v106, v106, v107
	v_add_f32_e32 v143, v104, v106
	s_waitcnt vmcnt(9) lgkmcnt(5)
	v_pk_add_f32 v[108:109], v[108:109], v[20:21]
	v_pk_add_f32 v[110:111], v[110:111], v[22:23]
	global_store_dwordx4 v136, v[108:111], s[92:93]
	v_cvt_pk_bf16_f32 v20, v108, v109
	v_cvt_pk_bf16_f32 v21, v110, v111
	v_lshrrev_b32_e32 v22, 1, v136
	v_pk_mul_f32 v[108:109], v[108:109], v[108:109]
	v_pk_mul_f32 v[110:111], v[110:111], v[110:111]
	global_store_dwordx2 v22, v[20:21], s[20:21]
	v_add_f32_e32 v108, v108, v109
	v_add_f32_e32 v110, v110, v111
	v_add_f32_e32 v144, v108, v110
	s_waitcnt vmcnt(10) lgkmcnt(4)
	v_pk_add_f32 v[112:113], v[112:113], v[24:25]
	v_pk_add_f32 v[114:115], v[114:115], v[26:27]
	global_store_dwordx4 v137, v[112:115], s[92:93]
	v_cvt_pk_bf16_f32 v24, v112, v113
	v_cvt_pk_bf16_f32 v25, v114, v115
	v_lshrrev_b32_e32 v26, 1, v137
	v_pk_mul_f32 v[112:113], v[112:113], v[112:113]
	v_pk_mul_f32 v[114:115], v[114:115], v[114:115]
	global_store_dwordx2 v26, v[24:25], s[20:21]
	v_add_f32_e32 v112, v112, v113
	v_add_f32_e32 v114, v114, v115
	v_add_f32_e32 v145, v112, v114
	s_waitcnt vmcnt(11) lgkmcnt(3)
	v_pk_add_f32 v[116:117], v[116:117], v[28:29]
	v_pk_add_f32 v[118:119], v[118:119], v[30:31]
	global_store_dwordx4 v138, v[116:119], s[92:93]
	v_cvt_pk_bf16_f32 v28, v116, v117
	v_cvt_pk_bf16_f32 v29, v118, v119
	v_lshrrev_b32_e32 v30, 1, v138
	v_pk_mul_f32 v[116:117], v[116:117], v[116:117]
	v_pk_mul_f32 v[118:119], v[118:119], v[118:119]
	global_store_dwordx2 v30, v[28:29], s[20:21]
	v_add_f32_e32 v116, v116, v117
	v_add_f32_e32 v118, v118, v119
	v_add_f32_e32 v146, v116, v118
	s_waitcnt vmcnt(12) lgkmcnt(2)
	v_pk_add_f32 v[120:121], v[120:121], v[32:33]
	v_pk_add_f32 v[122:123], v[122:123], v[34:35]
	global_store_dwordx4 v139, v[120:123], s[92:93]
	v_cvt_pk_bf16_f32 v32, v120, v121
	v_cvt_pk_bf16_f32 v33, v122, v123
	v_lshrrev_b32_e32 v34, 1, v139
	v_pk_mul_f32 v[120:121], v[120:121], v[120:121]
	v_pk_mul_f32 v[122:123], v[122:123], v[122:123]
	global_store_dwordx2 v34, v[32:33], s[20:21]
	v_add_f32_e32 v120, v120, v121
	v_add_f32_e32 v122, v122, v123
	v_add_f32_e32 v147, v120, v122
	s_waitcnt vmcnt(13) lgkmcnt(1)
	v_pk_add_f32 v[124:125], v[124:125], v[36:37]
	v_pk_add_f32 v[126:127], v[126:127], v[38:39]
	global_store_dwordx4 v140, v[124:127], s[92:93]
	v_cvt_pk_bf16_f32 v36, v124, v125
	v_cvt_pk_bf16_f32 v37, v126, v127
	v_lshrrev_b32_e32 v38, 1, v140
	v_pk_mul_f32 v[124:125], v[124:125], v[124:125]
	v_pk_mul_f32 v[126:127], v[126:127], v[126:127]
	global_store_dwordx2 v38, v[36:37], s[20:21]
	v_add_f32_e32 v124, v124, v125
	v_add_f32_e32 v126, v126, v127
	v_add_f32_e32 v148, v124, v126
	s_waitcnt vmcnt(14) lgkmcnt(0)
	v_pk_add_f32 v[128:129], v[128:129], v[40:41]
	v_pk_add_f32 v[130:131], v[130:131], v[42:43]
	global_store_dwordx4 v141, v[128:131], s[92:93]
	v_cvt_pk_bf16_f32 v40, v128, v129
	v_cvt_pk_bf16_f32 v41, v130, v131
	v_lshrrev_b32_e32 v42, 1, v141
	v_pk_mul_f32 v[128:129], v[128:129], v[128:129]
	v_pk_mul_f32 v[130:131], v[130:131], v[130:131]
	global_store_dwordx2 v42, v[40:41], s[20:21]
	v_add_f32_e32 v128, v128, v129
	v_add_f32_e32 v130, v130, v131
	v_add_f32_e32 v149, v128, v130
	v_add_f32_dpp v142, v142, v142 quad_perm:[1,0,3,2] row_mask:0xf bank_mask:0xf bound_ctrl:1
	v_add_f32_dpp v143, v143, v143 quad_perm:[1,0,3,2] row_mask:0xf bank_mask:0xf bound_ctrl:1
	v_add_f32_dpp v144, v144, v144 quad_perm:[1,0,3,2] row_mask:0xf bank_mask:0xf bound_ctrl:1
	v_add_f32_dpp v145, v145, v145 quad_perm:[1,0,3,2] row_mask:0xf bank_mask:0xf bound_ctrl:1
	v_add_f32_dpp v146, v146, v146 quad_perm:[1,0,3,2] row_mask:0xf bank_mask:0xf bound_ctrl:1
	v_add_f32_dpp v147, v147, v147 quad_perm:[1,0,3,2] row_mask:0xf bank_mask:0xf bound_ctrl:1
	v_add_f32_dpp v148, v148, v148 quad_perm:[1,0,3,2] row_mask:0xf bank_mask:0xf bound_ctrl:1
	v_add_f32_dpp v149, v149, v149 quad_perm:[1,0,3,2] row_mask:0xf bank_mask:0xf bound_ctrl:1
	v_add_f32_dpp v142, v142, v142 quad_perm:[2,3,0,1] row_mask:0xf bank_mask:0xf bound_ctrl:1
	v_add_f32_dpp v143, v143, v143 quad_perm:[2,3,0,1] row_mask:0xf bank_mask:0xf bound_ctrl:1
	v_add_f32_dpp v144, v144, v144 quad_perm:[2,3,0,1] row_mask:0xf bank_mask:0xf bound_ctrl:1
	v_add_f32_dpp v145, v145, v145 quad_perm:[2,3,0,1] row_mask:0xf bank_mask:0xf bound_ctrl:1
	v_add_f32_dpp v146, v146, v146 quad_perm:[2,3,0,1] row_mask:0xf bank_mask:0xf bound_ctrl:1
	v_add_f32_dpp v147, v147, v147 quad_perm:[2,3,0,1] row_mask:0xf bank_mask:0xf bound_ctrl:1
	v_add_f32_dpp v148, v148, v148 quad_perm:[2,3,0,1] row_mask:0xf bank_mask:0xf bound_ctrl:1
	v_add_f32_dpp v149, v149, v149 quad_perm:[2,3,0,1] row_mask:0xf bank_mask:0xf bound_ctrl:1
	v_add_f32_dpp v142, v142, v142 row_half_mirror row_mask:0xf bank_mask:0xf bound_ctrl:1
	v_add_f32_dpp v143, v143, v143 row_half_mirror row_mask:0xf bank_mask:0xf bound_ctrl:1
	v_add_f32_dpp v144, v144, v144 row_half_mirror row_mask:0xf bank_mask:0xf bound_ctrl:1
	v_add_f32_dpp v145, v145, v145 row_half_mirror row_mask:0xf bank_mask:0xf bound_ctrl:1
	v_add_f32_dpp v146, v146, v146 row_half_mirror row_mask:0xf bank_mask:0xf bound_ctrl:1
	v_add_f32_dpp v147, v147, v147 row_half_mirror row_mask:0xf bank_mask:0xf bound_ctrl:1
	v_add_f32_dpp v148, v148, v148 row_half_mirror row_mask:0xf bank_mask:0xf bound_ctrl:1
	v_add_f32_dpp v149, v149, v149 row_half_mirror row_mask:0xf bank_mask:0xf bound_ctrl:1
	v_add_f32_dpp v142, v142, v142 row_mirror row_mask:0xf bank_mask:0xf bound_ctrl:1
	v_add_f32_dpp v143, v143, v143 row_mirror row_mask:0xf bank_mask:0xf bound_ctrl:1
	v_add_f32_dpp v144, v144, v144 row_mirror row_mask:0xf bank_mask:0xf bound_ctrl:1
	v_add_f32_dpp v145, v145, v145 row_mirror row_mask:0xf bank_mask:0xf bound_ctrl:1
	v_add_f32_dpp v146, v146, v146 row_mirror row_mask:0xf bank_mask:0xf bound_ctrl:1
	v_add_f32_dpp v147, v147, v147 row_mirror row_mask:0xf bank_mask:0xf bound_ctrl:1
	v_add_f32_dpp v148, v148, v148 row_mirror row_mask:0xf bank_mask:0xf bound_ctrl:1
	v_add_f32_dpp v149, v149, v149 row_mirror row_mask:0xf bank_mask:0xf bound_ctrl:1
	ds_bpermute_b32 v12, v176, v142
	ds_bpermute_b32 v16, v176, v143
	ds_bpermute_b32 v20, v176, v144
	ds_bpermute_b32 v24, v176, v145
	ds_bpermute_b32 v28, v176, v146
	ds_bpermute_b32 v32, v176, v147
	ds_bpermute_b32 v36, v176, v148
	ds_bpermute_b32 v40, v176, v149
	s_waitcnt lgkmcnt(0)
	v_add_f32_e32 v142, v142, v12
	v_add_f32_e32 v143, v143, v16
	v_add_f32_e32 v144, v144, v20
	v_add_f32_e32 v145, v145, v24
	v_add_f32_e32 v146, v146, v28
	v_add_f32_e32 v147, v147, v32
	v_add_f32_e32 v148, v148, v36
	v_add_f32_e32 v149, v149, v40
	v_add_u32_e32 v13, 0x200, v175
	v_add_u32_e32 v17, 0x240, v175
	v_add_u32_e32 v21, 0x280, v175
	v_add_u32_e32 v25, 0x2c0, v175
	v_add_u32_e32 v29, 0x300, v175
	v_add_u32_e32 v33, 0x340, v175
	v_add_u32_e32 v37, 0x380, v175
	v_add_u32_e32 v41, 0x3c0, v175
	s_mov_b64 exec, s[0:1]
	global_atomic_add_f32 v13, v142, s[50:51]
	global_atomic_add_f32 v17, v143, s[50:51]
	global_atomic_add_f32 v21, v144, s[50:51]
	global_atomic_add_f32 v25, v145, s[50:51]
	global_atomic_add_f32 v29, v146, s[50:51]
	global_atomic_add_f32 v33, v147, s[50:51]
	global_atomic_add_f32 v37, v148, s[50:51]
	global_atomic_add_f32 v41, v149, s[50:51]
	s_mov_b64 exec, -1
	s_branch .LBB0_158
.Lcepi_last:
	ds_read_b128 v[12:15], v171 offset:0
	v_mov_b32_e32 v134, v174
	global_load_dwordx4 v[100:103], v134, s[92:93]
	ds_read_b128 v[16:19], v171 offset:8448
	v_add_u32_e32 v135, 0x10000, v174
	global_load_dwordx4 v[104:107], v135, s[92:93]
	ds_read_b128 v[20:23], v171 offset:16896
	v_add_u32_e32 v136, 0x20000, v174
	global_load_dwordx4 v[108:111], v136, s[92:93]
	ds_read_b128 v[24:27], v171 offset:25344
	v_add_u32_e32 v137, 0x30000, v174
	global_load_dwordx4 v[112:115], v137, s[92:93]
	ds_read_b128 v[28:31], v171 offset:33792
	v_add_u32_e32 v138, 0x40000, v174
	global_load_dwordx4 v[116:119], v138, s[92:93]
	ds_read_b128 v[32:35], v171 offset:42240
	v_add_u32_e32 v139, 0x50000, v174
	global_load_dwordx4 v[120:123], v139, s[92:93]
	ds_read_b128 v[36:39], v171 offset:50688
	v_add_u32_e32 v140, 0x60000, v174
	global_load_dwordx4 v[124:127], v140, s[92:93]
	ds_read_b128 v[40:43], v171 offset:59136
	v_add_u32_e32 v141, 0x70000, v174
	global_load_dwordx4 v[128:131], v141, s[92:93]
	s_waitcnt vmcnt(7) lgkmcnt(7)
	v_pk_add_f32 v[100:101], v[100:101], v[12:13]
	v_pk_add_f32 v[102:103], v[102:103], v[14:15]
	global_store_dwordx4 v134, v[100:103], s[92:93]
	s_waitcnt vmcnt(7) lgkmcnt(6)
	v_pk_add_f32 v[104:105], v[104:105], v[16:17]
	v_pk_add_f32 v[106:107], v[106:107], v[18:19]
	global_store_dwordx4 v135, v[104:107], s[92:93]
	s_waitcnt vmcnt(7) lgkmcnt(5)
	v_pk_add_f32 v[108:109], v[108:109], v[20:21]
	v_pk_add_f32 v[110:111], v[110:111], v[22:23]
	global_store_dwordx4 v136, v[108:111], s[92:93]
	s_waitcnt vmcnt(7) lgkmcnt(4)
	v_pk_add_f32 v[112:113], v[112:113], v[24:25]
	v_pk_add_f32 v[114:115], v[114:115], v[26:27]
	global_store_dwordx4 v137, v[112:115], s[92:93]
	s_waitcnt vmcnt(7) lgkmcnt(3)
	v_pk_add_f32 v[116:117], v[116:117], v[28:29]
	v_pk_add_f32 v[118:119], v[118:119], v[30:31]
	global_store_dwordx4 v138, v[116:119], s[92:93]
	s_waitcnt vmcnt(7) lgkmcnt(2)
	v_pk_add_f32 v[120:121], v[120:121], v[32:33]
	v_pk_add_f32 v[122:123], v[122:123], v[34:35]
	global_store_dwordx4 v139, v[120:123], s[92:93]
	s_waitcnt vmcnt(7) lgkmcnt(1)
	v_pk_add_f32 v[124:125], v[124:125], v[36:37]
	v_pk_add_f32 v[126:127], v[126:127], v[38:39]
	global_store_dwordx4 v140, v[124:127], s[92:93]
	s_waitcnt vmcnt(7) lgkmcnt(0)
	v_pk_add_f32 v[128:129], v[128:129], v[40:41]
	v_pk_add_f32 v[130:131], v[130:131], v[42:43]
	global_store_dwordx4 v141, v[128:131], s[92:93]
	ds_read_b128 v[12:15], v172 offset:0
	v_add_u32_e32 v134, 0x80000, v174
	global_load_dwordx4 v[100:103], v134, s[92:93]
	ds_read_b128 v[16:19], v172 offset:8448
	v_add_u32_e32 v135, 0x90000, v174
	global_load_dwordx4 v[104:107], v135, s[92:93]
	ds_read_b128 v[20:23], v172 offset:16896
	v_add_u32_e32 v136, 0xa0000, v174
	global_load_dwordx4 v[108:111], v136, s[92:93]
	ds_read_b128 v[24:27], v172 offset:25344
	v_add_u32_e32 v137, 0xb0000, v174
	global_load_dwordx4 v[112:115], v137, s[92:93]
	ds_read_b128 v[28:31], v172 offset:33792
	v_add_u32_e32 v138, 0xc0000, v174
	global_load_dwordx4 v[116:119], v138, s[92:93]
	ds_read_b128 v[32:35], v172 offset:42240
	v_add_u32_e32 v139, 0xd0000, v174
	global_load_dwordx4 v[120:123], v139, s[92:93]
	ds_read_b128 v[36:39], v172 offset:50688
	v_add_u32_e32 v140, 0xe0000, v174
	global_load_dwordx4 v[124:127], v140, s[92:93]
	ds_read_b128 v[40:43], v172 offset:59136
	v_add_u32_e32 v141, 0xf0000, v174
	global_load_dwordx4 v[128:131], v141, s[92:93]
	s_waitcnt vmcnt(7) lgkmcnt(7)
	v_pk_add_f32 v[100:101], v[100:101], v[12:13]
	v_pk_add_f32 v[102:103], v[102:103], v[14:15]
	global_store_dwordx4 v134, v[100:103], s[92:93]
	s_waitcnt vmcnt(7) lgkmcnt(6)
	v_pk_add_f32 v[104:105], v[104:105], v[16:17]
	v_pk_add_f32 v[106:107], v[106:107], v[18:19]
	global_store_dwordx4 v135, v[104:107], s[92:93]
	s_waitcnt vmcnt(7) lgkmcnt(5)
	v_pk_add_f32 v[108:109], v[108:109], v[20:21]
	v_pk_add_f32 v[110:111], v[110:111], v[22:23]
	global_store_dwordx4 v136, v[108:111], s[92:93]
	s_waitcnt vmcnt(7) lgkmcnt(4)
	v_pk_add_f32 v[112:113], v[112:113], v[24:25]
	v_pk_add_f32 v[114:115], v[114:115], v[26:27]
	global_store_dwordx4 v137, v[112:115], s[92:93]
	s_waitcnt vmcnt(7) lgkmcnt(3)
	v_pk_add_f32 v[116:117], v[116:117], v[28:29]
	v_pk_add_f32 v[118:119], v[118:119], v[30:31]
	global_store_dwordx4 v138, v[116:119], s[92:93]
	s_waitcnt vmcnt(7) lgkmcnt(2)
	v_pk_add_f32 v[120:121], v[120:121], v[32:33]
	v_pk_add_f32 v[122:123], v[122:123], v[34:35]
	global_store_dwordx4 v139, v[120:123], s[92:93]
	s_waitcnt vmcnt(7) lgkmcnt(1)
	v_pk_add_f32 v[124:125], v[124:125], v[36:37]
	v_pk_add_f32 v[126:127], v[126:127], v[38:39]
	global_store_dwordx4 v140, v[124:127], s[92:93]
	s_waitcnt vmcnt(7) lgkmcnt(0)
	v_pk_add_f32 v[128:129], v[128:129], v[40:41]
	v_pk_add_f32 v[130:131], v[130:131], v[42:43]
	global_store_dwordx4 v141, v[128:131], s[92:93]
	s_branch .LBB0_158

.LBB0_242:
	s_or_b64 exec, exec, s[0:1]
	v_mov_b32_e32 v74, v133
	s_barrier
	v_readlane_b32 s53, v214, 24
	v_ashrrev_i32_e32 v12, 6, v74
	v_bfe_u32 v4, v74, 3, 3
	v_lshl_or_b32 v2, v12, 4, v4
	v_add_u32_e32 v0, s53, v2
	v_bfe_u32 v5, v74, 4, 2
	v_ashrrev_i32_e32 v1, 31, v0
	v_xor_b32_e32 v5, v5, v74
	v_lshlrev_b64 v[0:1], 11, v[0:1]
	v_lshlrev_b32_e32 v5, 4, v5
	v_lshl_add_u64 v[0:1], s[40:41], 0, v[0:1]
	v_or_b32_e32 v13, 8, v2
	v_lshl_or_b32 v4, v12, 5, v4
	v_and_b32_e32 v64, 0x70, v5
	v_add_u32_e32 v2, s53, v13
	v_ashrrev_i32_e32 v5, 31, v4
	v_readlane_b32 s0, v214, 4
	v_lshl_add_u64 v[70:71], v[0:1], 0, v[64:65]
	v_lshrrev_b32_e32 v0, 1, v13
	v_ashrrev_i32_e32 v3, 31, v2
	v_lshlrev_b64 v[6:7], 11, v[4:5]
	v_readlane_b32 s1, v214, 5
	v_xor_b32_e32 v0, v0, v74
	v_lshlrev_b64 v[2:3], 11, v[2:3]
	v_lshl_add_u64 v[6:7], s[0:1], 0, v[6:7]
	v_lshlrev_b32_e32 v0, 4, v0
	v_lshl_add_u64 v[2:3], s[40:41], 0, v[2:3]
	v_lshl_add_u64 v[66:67], v[6:7], 0, v[64:65]
	v_lshrrev_b32_e32 v4, 1, v4
	v_and_b32_e32 v64, 0x70, v0
	v_bitop3_b32 v4, v4, v74, 4 bitop3:0x36
	v_lshl_add_u64 v[72:73], v[2:3], 0, v[64:65]
	v_lshlrev_b32_e32 v3, 12, v12
	v_lshlrev_b32_e32 v4, 4, v4
	v_add_u32_e32 v127, 0, v3
	s_mov_b64 s[0:1], 0x2000000
	v_and_b32_e32 v4, 0x70, v4
	v_mov_b32_e32 v5, v65
	s_waitcnt vmcnt(0)
	v_readfirstlane_b32 s38, v127
	v_add_u32_e32 v126, 0x400, v127
	v_lshl_add_u64 v[8:9], v[66:67], 0, s[0:1]
	v_lshl_add_u64 v[68:69], v[6:7], 0, v[4:5]
	s_mov_b64 s[0:1], 0x2004000
	s_waitcnt lgkmcnt(0)
	s_barrier
	s_mov_b32 m0, s38
	v_readfirstlane_b32 s37, v126
	v_lshl_add_u64 v[4:5], v[68:69], 0, s[0:1]
	global_load_lds_dwordx4 v[8:9], off
	s_mov_b32 m0, s37
	v_add_u32_e32 v124, 0x800, v127
	global_load_lds_dwordx4 v[4:5], off
	v_lshlrev_b32_e32 v4, 11, v12
	s_mov_b64 s[0:1], 0x2008000
	v_readfirstlane_b32 s36, v124
	v_add_u32_e32 v122, 0xc00, v127
	v_add_u32_e32 v5, 0, v4
	v_lshl_add_u64 v[6:7], v[66:67], 0, s[0:1]
	s_mov_b64 s[0:1], 0x200c000
	s_mov_b32 m0, s36
	v_readfirstlane_b32 s35, v122
	v_add_u32_e32 v125, 0x8000, v5
	v_lshl_add_u64 v[10:11], v[68:69], 0, s[0:1]
	global_load_lds_dwordx4 v[6:7], off
	s_mov_b32 m0, s35
	v_readfirstlane_b32 s39, v125
	v_add_u32_e32 v123, 0x8400, v5
	global_load_lds_dwordx4 v[10:11], off
	s_mov_b32 m0, s39
	v_readfirstlane_b32 s40, v123
	v_add_u32_e32 v116, 0xc000, v127
	global_load_lds_dwordx4 v[70:71], off
	s_mov_b32 m0, s40
	s_mov_b64 s[0:1], 0x2000080
	v_readfirstlane_b32 s23, v116
	v_add_u32_e32 v117, 0xc400, v127
	global_load_lds_dwordx4 v[72:73], off
	v_lshl_add_u64 v[0:1], v[66:67], 0, s[0:1]
	s_mov_b32 m0, s23
	s_mov_b64 s[0:1], 0x2004080
	v_readfirstlane_b32 s24, v117
	v_add_u32_e32 v118, 0xc800, v127
	global_load_lds_dwordx4 v[0:1], off
	v_lshl_add_u64 v[0:1], v[68:69], 0, s[0:1]
	s_mov_b32 m0, s24
	s_mov_b64 s[0:1], 0x2008080
	v_readfirstlane_b32 s28, v118
	v_add_u32_e32 v119, 0xcc00, v127
	global_load_lds_dwordx4 v[0:1], off
	v_lshl_add_u64 v[0:1], v[66:67], 0, s[0:1]
	s_mov_b32 m0, s28
	s_mov_b64 s[0:1], 0x200c080
	v_readfirstlane_b32 s29, v119
	v_add_u32_e32 v120, s85, v4
	global_load_lds_dwordx4 v[0:1], off
	v_lshl_add_u64 v[0:1], v[68:69], 0, s[0:1]
	s_mov_b32 m0, s29
	s_mov_b64 s[0:1], 0x80
	v_readfirstlane_b32 s33, v120
	v_add_u32_e32 v121, 0x14400, v5
	global_load_lds_dwordx4 v[0:1], off
	v_lshl_add_u64 v[0:1], v[70:71], 0, s[0:1]
	s_mov_b32 m0, s33
	v_readfirstlane_b32 s34, v121
	v_lshrrev_b32_e32 v2, 1, v74
	v_bfe_u32 v64, v74, 5, 1
	global_load_lds_dwordx4 v[0:1], off
	v_lshl_add_u64 v[0:1], v[72:73], 0, s[0:1]
	s_mov_b32 m0, s34
	s_mov_b64 s[0:1], 0x2000100
	global_load_lds_dwordx4 v[0:1], off
	v_bitop3_b32 v0, v2, v64, 7 bitop3:0x6c
	v_add_u32_e32 v110, s3, v3
	v_lshlrev_b32_e32 v128, 4, v0
	s_waitcnt vmcnt(6)
	v_lshl_add_u64 v[0:1], v[66:67], 0, s[0:1]
	v_readfirstlane_b32 s0, v110
	v_add_u32_e32 v111, 0x400, v110
	s_waitcnt lgkmcnt(0)
	s_barrier
	s_mov_b32 m0, s0
	s_mov_b64 s[20:21], 0x2004100
	v_readfirstlane_b32 s1, v111
	v_add_u32_e32 v112, 0x800, v110
	global_load_lds_dwordx4 v[0:1], off
	v_lshl_add_u64 v[0:1], v[68:69], 0, s[20:21]
	s_mov_b32 m0, s1
	s_mov_b64 s[20:21], 0x2008100
	v_readfirstlane_b32 s2, v112
	global_load_lds_dwordx4 v[0:1], off
	v_lshl_add_u64 v[0:1], v[66:67], 0, s[20:21]
	s_mov_b32 m0, s2
	s_mov_b64 s[20:21], 0x200c100
	global_load_lds_dwordx4 v[0:1], off
	v_lshl_add_u64 v[0:1], v[68:69], 0, s[20:21]
	v_add_u32_e32 v113, 0xc00, v110
	v_readlane_b32 s21, v212, 31
	v_and_b32_e32 v75, 31, v74
	v_readfirstlane_b32 s20, v113
	v_add_u32_e32 v114, s21, v4
	v_add_u32_e32 v2, s3, v4
	v_and_b32_e32 v76, 1, v12
	v_lshlrev_b32_e32 v13, 7, v75
	s_mov_b32 m0, s20
	s_mov_b64 s[30:31], 0x100
	v_readfirstlane_b32 s21, v114
	v_add_u32_e32 v115, 0x8400, v2
	v_lshl_or_b32 v98, v76, 13, v13
	global_load_lds_dwordx4 v[0:1], off
	v_lshl_add_u64 v[0:1], v[70:71], 0, s[30:31]
	s_mov_b32 m0, s21
	v_readfirstlane_b32 s22, v115
	global_load_lds_dwordx4 v[0:1], off
	v_lshl_add_u64 v[0:1], v[72:73], 0, s[30:31]
	s_mov_b32 m0, s22
	v_add_u32_e32 v96, 0, v98
	global_load_lds_dwordx4 v[0:1], off
	v_add_u32_e32 v79, v96, v128
	v_ashrrev_i32_e32 v77, 7, v74
	ds_read_b128 v[0:3], v79 offset:32768
	ds_read_b128 v[8:11], v79 offset:36864
	v_lshl_or_b32 v129, v77, 13, v13
	v_add_u32_e32 v97, 0, v129
	v_add_u32_e32 v78, v97, v128
	ds_read_b128 v[4:7], v78
	ds_read_b128 v[150:153], v78 offset:4096
	s_waitcnt lgkmcnt(1)
	v_mfma_f32_32x32x16_bf16 v[48:63], v[0:3], v[4:7], 0
	v_bfe_u32 v99, v74, 1, 3
	s_mov_b64 s[30:31], 0x2000180
	s_mov_b32 m0, s38
	v_or_b32_e32 v139, 0x8000, v98
	v_or_b32_e32 v140, 0x9000, v98
	v_add_u32_e32 v141, s3, v129
	v_or_b32_e32 v142, 0x1000, v129
	v_mfma_f32_32x32x16_bf16 v[32:47], v[8:11], v[4:7], 0
	v_lshl_or_b32 v77, v77, 6, v75
	v_mul_lo_u32 v77, v77, s26
	s_mov_b64 s[80:81], 0x200
	s_waitcnt lgkmcnt(0)
	v_mfma_f32_32x32x16_bf16 v[16:31], v[0:3], v[150:153], 0
	v_bitop3_b32 v0, v64, v99, 2 bitop3:0x36
	v_lshlrev_b32_e32 v132, 4, v0
	v_add_u32_e32 v81, v96, v132
	ds_read_b128 v[82:85], v81 offset:32768
	ds_read_b128 v[90:93], v81 offset:36864
	v_add_u32_e32 v80, v97, v132
	ds_read_b128 v[86:89], v80
	v_mfma_f32_32x32x16_bf16 v[0:15], v[8:11], v[150:153], 0
	ds_read_b128 v[154:157], v80 offset:4096
	s_waitcnt lgkmcnt(1)
	v_mfma_f32_32x32x16_bf16 v[48:63], v[82:85], v[86:89], v[48:63]
	v_mfma_f32_32x32x16_bf16 v[32:47], v[90:93], v[86:89], v[32:47]
	s_waitcnt lgkmcnt(0)
	v_mfma_f32_32x32x16_bf16 v[16:31], v[82:85], v[154:157], v[16:31]
	v_bitop3_b32 v82, v64, v99, 4 bitop3:0x36
	v_lshlrev_b32_e32 v134, 4, v82
	v_add_u32_e32 v83, v96, v134
	v_add_u32_e32 v82, v97, v134
	v_mfma_f32_32x32x16_bf16 v[0:15], v[90:93], v[154:157], v[0:15]
	ds_read_b128 v[84:87], v83 offset:32768
	ds_read_b128 v[88:91], v82
	ds_read_b128 v[92:95], v83 offset:36864
	ds_read_b128 v[150:153], v82 offset:4096
	s_waitcnt lgkmcnt(1)
	v_mfma_f32_32x32x16_bf16 v[48:63], v[84:87], v[88:91], v[48:63]
	v_mfma_f32_32x32x16_bf16 v[32:47], v[92:95], v[88:91], v[32:47]
	s_waitcnt lgkmcnt(0)
	v_mfma_f32_32x32x16_bf16 v[16:31], v[84:87], v[150:153], v[16:31]
	v_bitop3_b32 v84, v64, v99, 6 bitop3:0x36
	v_lshlrev_b32_e32 v138, 4, v84
	v_add_u32_e32 v85, v96, v138
	v_add_u32_e32 v84, v97, v138
	v_lshlrev_b32_e32 v64, 4, v64
	v_lshl_or_b32 v64, v76, 8, v64
	v_add3_u32 v64, 0, v77, v64
	v_mfma_f32_32x32x16_bf16 v[0:15], v[92:95], v[150:153], v[0:15]
	ds_read_b128 v[86:89], v85 offset:32768
	ds_read_b128 v[90:93], v84
	ds_read_b128 v[94:97], v85 offset:36864
	ds_read_b128 v[154:157], v84 offset:4096
	s_waitcnt lgkmcnt(1)
	v_mfma_f32_32x32x16_bf16 v[48:63], v[86:89], v[90:93], v[48:63]
	v_mfma_f32_32x32x16_bf16 v[32:47], v[94:97], v[90:93], v[32:47]
	s_waitcnt vmcnt(6)
	s_waitcnt lgkmcnt(0)
	s_barrier
	s_waitcnt lgkmcnt(0)
	v_mfma_f32_32x32x16_bf16 v[16:31], v[86:89], v[154:157], v[16:31]
	v_lshl_add_u64 v[86:87], v[66:67], 0, s[30:31]
	s_mov_b64 s[30:31], 0x2004180
	global_load_lds_dwordx4 v[86:87], off
	v_lshl_add_u64 v[86:87], v[68:69], 0, s[30:31]
	s_mov_b32 m0, s37
	s_mov_b64 s[30:31], 0x2008180
	global_load_lds_dwordx4 v[86:87], off
	v_lshl_add_u64 v[86:87], v[66:67], 0, s[30:31]
	s_mov_b32 m0, s36
	s_mov_b64 s[30:31], 0x200c180
	global_load_lds_dwordx4 v[86:87], off
	v_lshl_add_u64 v[86:87], v[68:69], 0, s[30:31]
	s_mov_b32 m0, s35
	s_mov_b64 s[30:31], 0x180
	global_load_lds_dwordx4 v[86:87], off
	v_lshl_add_u64 v[86:87], v[70:71], 0, s[30:31]
	s_mov_b32 m0, s39
	v_mfma_f32_32x32x16_bf16 v[0:15], v[94:97], v[154:157], v[0:15]
	global_load_lds_dwordx4 v[86:87], off
	v_lshl_add_u64 v[86:87], v[72:73], 0, s[30:31]
	s_mov_b32 m0, s40
	s_add_i32 s30, 0, 0xc000
	global_load_lds_dwordx4 v[86:87], off
	v_add_u32_e32 v86, s30, v128
	v_add_u32_e32 v88, v86, v139
	v_add_u32_e32 v86, v86, v140
	ds_read_b128 v[90:93], v88
	ds_read_b128 v[94:97], v78 offset:49152
	ds_read_b128 v[98:101], v86
	ds_read_b128 v[150:153], v78 offset:53248
	s_waitcnt lgkmcnt(1)
	v_mfma_f32_32x32x16_bf16 v[48:63], v[90:93], v[94:97], v[48:63]
	v_add_u32_e32 v87, s30, v132
	v_add_u32_e32 v89, v87, v139
	v_add_u32_e32 v87, v87, v140
	s_mov_b32 m0, s23
	v_mfma_f32_32x32x16_bf16 v[32:47], v[98:101], v[94:97], v[32:47]
	s_waitcnt lgkmcnt(0)
	v_mfma_f32_32x32x16_bf16 v[16:31], v[90:93], v[150:153], v[16:31]
	v_mfma_f32_32x32x16_bf16 v[0:15], v[98:101], v[150:153], v[0:15]
	ds_read_b128 v[90:93], v89
	ds_read_b128 v[94:97], v80 offset:49152
	ds_read_b128 v[98:101], v87
	ds_read_b128 v[154:157], v80 offset:53248
	s_waitcnt lgkmcnt(1)
	v_mfma_f32_32x32x16_bf16 v[48:63], v[90:93], v[94:97], v[48:63]
	v_mfma_f32_32x32x16_bf16 v[32:47], v[98:101], v[94:97], v[32:47]
	s_waitcnt lgkmcnt(0)
	v_mfma_f32_32x32x16_bf16 v[16:31], v[90:93], v[154:157], v[16:31]
	v_add_u32_e32 v90, s30, v134
	v_add_u32_e32 v91, v90, v139
	v_add_u32_e32 v90, v90, v140
	v_mfma_f32_32x32x16_bf16 v[0:15], v[98:101], v[154:157], v[0:15]
	ds_read_b128 v[92:95], v91
	ds_read_b128 v[96:99], v82 offset:49152
	ds_read_b128 v[100:103], v90
	ds_read_b128 v[150:153], v82 offset:53248
	s_waitcnt lgkmcnt(1)
	v_mfma_f32_32x32x16_bf16 v[48:63], v[92:95], v[96:99], v[48:63]
	v_mfma_f32_32x32x16_bf16 v[32:47], v[100:103], v[96:99], v[32:47]
	s_waitcnt lgkmcnt(0)
	v_mfma_f32_32x32x16_bf16 v[16:31], v[92:95], v[150:153], v[16:31]
	v_add_u32_e32 v92, s30, v138
	v_add_u32_e32 v93, v92, v139
	v_add_u32_e32 v92, v92, v140
	s_mov_b64 s[30:31], 0x2000200
	v_mfma_f32_32x32x16_bf16 v[0:15], v[100:103], v[150:153], v[0:15]
	ds_read_b128 v[94:97], v93
	ds_read_b128 v[98:101], v84 offset:49152
	ds_read_b128 v[102:105], v92
	ds_read_b128 v[154:157], v84 offset:53248
	s_waitcnt lgkmcnt(1)
	v_mfma_f32_32x32x16_bf16 v[48:63], v[94:97], v[98:101], v[48:63]
	v_mfma_f32_32x32x16_bf16 v[32:47], v[102:105], v[98:101], v[32:47]
	s_waitcnt vmcnt(6)
	s_waitcnt lgkmcnt(0)
	s_barrier
	s_waitcnt lgkmcnt(0)
	v_mfma_f32_32x32x16_bf16 v[16:31], v[94:97], v[154:157], v[16:31]
	v_lshl_add_u64 v[94:95], v[66:67], 0, s[30:31]
	s_mov_b64 s[30:31], 0x2004200
	global_load_lds_dwordx4 v[94:95], off
	v_lshl_add_u64 v[94:95], v[68:69], 0, s[30:31]
	s_mov_b32 m0, s24
	s_mov_b64 s[30:31], 0x2008200
	global_load_lds_dwordx4 v[94:95], off
	v_lshl_add_u64 v[94:95], v[66:67], 0, s[30:31]
	s_mov_b32 m0, s28
	s_mov_b64 s[30:31], 0x200c200
	global_load_lds_dwordx4 v[94:95], off
	v_lshl_add_u64 v[94:95], v[68:69], 0, s[30:31]
	s_mov_b32 m0, s29
	s_mov_b64 s[30:31], 0x200
	global_load_lds_dwordx4 v[94:95], off
	v_lshl_add_u64 v[94:95], v[70:71], 0, s[30:31]
	s_mov_b32 m0, s33
	v_add_u32_e32 v97, s3, v128
	global_load_lds_dwordx4 v[94:95], off
	v_lshl_add_u64 v[94:95], v[72:73], 0, s[30:31]
	s_mov_b32 m0, s34
	v_mfma_f32_32x32x16_bf16 v[0:15], v[102:105], v[154:157], v[0:15]
	global_load_lds_dwordx4 v[94:95], off
	v_add_u32_e32 v94, v97, v139
	v_add_u32_e32 v95, v97, v140
	ds_read_b128 v[106:109], v94
	ds_read_b128 v[102:105], v95
	v_add_u32_e32 v96, v141, v128
	ds_read_b128 v[98:101], v96
	v_add_u32_e32 v97, v97, v142
	ds_read_b128 v[128:131], v97
	s_waitcnt lgkmcnt(0)
	v_mfma_f32_32x32x16_bf16 v[48:63], v[106:109], v[98:101], v[48:63]
	s_mov_b64 s[30:31], 0x2000280
	s_mov_b32 m0, s0
	v_mfma_f32_32x32x16_bf16 v[32:47], v[102:105], v[98:101], v[32:47]
	v_add_u32_e32 v101, s3, v132
	v_add_u32_e32 v98, v101, v139
	v_add_u32_e32 v99, v101, v140
	v_add_u32_e32 v100, v141, v132
	v_add_u32_e32 v101, v101, v142
	v_mfma_f32_32x32x16_bf16 v[16:31], v[106:109], v[128:131], v[16:31]
	ds_read_b128 v[106:109], v100
	v_mfma_f32_32x32x16_bf16 v[0:15], v[102:105], v[128:131], v[0:15]
	ds_read_b128 v[102:105], v98
	ds_read_b128 v[128:131], v99
	ds_read_b128 v[150:153], v101
	s_waitcnt lgkmcnt(1)
	v_mfma_f32_32x32x16_bf16 v[48:63], v[102:105], v[106:109], v[48:63]
	v_mfma_f32_32x32x16_bf16 v[32:47], v[128:131], v[106:109], v[32:47]
	s_waitcnt lgkmcnt(0)
	v_mfma_f32_32x32x16_bf16 v[16:31], v[102:105], v[150:153], v[16:31]
	v_add_u32_e32 v105, s3, v134
	v_add_u32_e32 v102, v105, v139
	v_add_u32_e32 v103, v105, v140
	v_add_u32_e32 v104, v141, v134
	ds_read_b128 v[134:137], v103
	v_add_u32_e32 v105, v105, v142
	v_mfma_f32_32x32x16_bf16 v[0:15], v[128:131], v[150:153], v[0:15]
	ds_read_b128 v[106:109], v102
	ds_read_b128 v[128:131], v104
	ds_read_b128 v[154:157], v105
	s_waitcnt lgkmcnt(1)
	v_mfma_f32_32x32x16_bf16 v[48:63], v[106:109], v[128:131], v[48:63]
	v_mfma_f32_32x32x16_bf16 v[32:47], v[134:137], v[128:131], v[32:47]
	s_waitcnt lgkmcnt(0)
	v_mfma_f32_32x32x16_bf16 v[16:31], v[106:109], v[154:157], v[16:31]
	v_add_u32_e32 v109, s3, v138
	v_add_u32_e32 v106, v109, v139
	v_add_u32_e32 v107, v109, v140
	v_add_u32_e32 v108, v141, v138
	ds_read_b128 v[138:141], v107
	v_add_u32_e32 v109, v109, v142
	v_mfma_f32_32x32x16_bf16 v[0:15], v[134:137], v[154:157], v[0:15]
	ds_read_b128 v[128:131], v106
	ds_read_b128 v[134:137], v108
	ds_read_b128 v[150:153], v109
	s_waitcnt lgkmcnt(1)
	v_mfma_f32_32x32x16_bf16 v[48:63], v[128:131], v[134:137], v[48:63]
	v_mfma_f32_32x32x16_bf16 v[32:47], v[138:141], v[134:137], v[32:47]
	s_waitcnt vmcnt(6)
	s_waitcnt lgkmcnt(0)
	s_barrier
	s_waitcnt lgkmcnt(0)
	v_mfma_f32_32x32x16_bf16 v[16:31], v[128:131], v[150:153], v[16:31]
	v_lshl_add_u64 v[128:129], v[66:67], 0, s[30:31]
	s_mov_b64 s[30:31], 0x2004280
	global_load_lds_dwordx4 v[128:129], off
	v_lshl_add_u64 v[128:129], v[68:69], 0, s[30:31]
	s_mov_b32 m0, s1
	s_mov_b64 s[30:31], 0x2008280
	global_load_lds_dwordx4 v[128:129], off
	v_lshl_add_u64 v[128:129], v[66:67], 0, s[30:31]
	s_mov_b32 m0, s2
	s_mov_b64 s[30:31], 0x200c280
	global_load_lds_dwordx4 v[128:129], off
	v_lshl_add_u64 v[128:129], v[68:69], 0, s[30:31]
	s_mov_b32 m0, s20
	s_mov_b64 s[30:31], 0x280
	global_load_lds_dwordx4 v[128:129], off
	v_lshl_add_u64 v[128:129], v[70:71], 0, s[30:31]
	s_mov_b32 m0, s21
	v_mfma_f32_32x32x16_bf16 v[0:15], v[138:141], v[150:153], v[0:15]
	global_load_lds_dwordx4 v[128:129], off
	v_lshl_add_u64 v[128:129], v[72:73], 0, s[30:31]
	s_mov_b32 m0, s22
	s_mov_b64 s[30:31], 0x2000300
	global_load_lds_dwordx4 v[128:129], off
	ds_read_b128 v[128:131], v79 offset:32768
	ds_read_b128 v[134:137], v78
	ds_read_b128 v[138:141], v79 offset:36864
	ds_read_b128 v[154:157], v78 offset:4096
	s_waitcnt lgkmcnt(1)
	v_mfma_f32_32x32x16_bf16 v[48:63], v[128:131], v[134:137], v[48:63]
	s_mov_b32 m0, s38
	v_readfirstlane_b32 s38, v113
	v_mfma_f32_32x32x16_bf16 v[32:47], v[138:141], v[134:137], v[32:47]
	s_waitcnt lgkmcnt(0)
	v_mfma_f32_32x32x16_bf16 v[16:31], v[128:131], v[154:157], v[16:31]
	v_mfma_f32_32x32x16_bf16 v[0:15], v[138:141], v[154:157], v[0:15]
	ds_read_b128 v[128:131], v81 offset:32768
	ds_read_b128 v[134:137], v80
	ds_read_b128 v[138:141], v81 offset:36864
	ds_read_b128 v[150:153], v80 offset:4096
	s_waitcnt lgkmcnt(1)
	v_mfma_f32_32x32x16_bf16 v[48:63], v[128:131], v[134:137], v[48:63]
	v_mfma_f32_32x32x16_bf16 v[32:47], v[138:141], v[134:137], v[32:47]
	s_waitcnt lgkmcnt(0)
	v_mfma_f32_32x32x16_bf16 v[16:31], v[128:131], v[150:153], v[16:31]
	v_mfma_f32_32x32x16_bf16 v[0:15], v[138:141], v[150:153], v[0:15]
	ds_read_b128 v[128:131], v83 offset:32768
	ds_read_b128 v[134:137], v82
	ds_read_b128 v[138:141], v83 offset:36864
	ds_read_b128 v[154:157], v82 offset:4096
	s_waitcnt lgkmcnt(1)
	v_mfma_f32_32x32x16_bf16 v[48:63], v[128:131], v[134:137], v[48:63]
	v_mfma_f32_32x32x16_bf16 v[32:47], v[138:141], v[134:137], v[32:47]
	s_waitcnt lgkmcnt(0)
	v_mfma_f32_32x32x16_bf16 v[16:31], v[128:131], v[154:157], v[16:31]
	v_mfma_f32_32x32x16_bf16 v[0:15], v[138:141], v[154:157], v[0:15]
	ds_read_b128 v[128:131], v85 offset:32768
	ds_read_b128 v[134:137], v84
	ds_read_b128 v[138:141], v85 offset:36864
	ds_read_b128 v[150:153], v84 offset:4096
	s_waitcnt lgkmcnt(1)
	v_mfma_f32_32x32x16_bf16 v[48:63], v[128:131], v[134:137], v[48:63]
	v_mfma_f32_32x32x16_bf16 v[32:47], v[138:141], v[134:137], v[32:47]
	s_waitcnt vmcnt(6)
	s_waitcnt lgkmcnt(0)
	s_barrier
	s_waitcnt lgkmcnt(0)
	v_mfma_f32_32x32x16_bf16 v[16:31], v[128:131], v[150:153], v[16:31]
	v_lshl_add_u64 v[128:129], v[66:67], 0, s[30:31]
	s_mov_b64 s[30:31], 0x2004300
	global_load_lds_dwordx4 v[128:129], off
	v_lshl_add_u64 v[128:129], v[68:69], 0, s[30:31]
	s_mov_b32 m0, s37
	s_mov_b64 s[30:31], 0x2008300
	global_load_lds_dwordx4 v[128:129], off
	v_lshl_add_u64 v[128:129], v[66:67], 0, s[30:31]
	s_mov_b32 m0, s36
	s_mov_b64 s[30:31], 0x200c300
	global_load_lds_dwordx4 v[128:129], off
	v_lshl_add_u64 v[128:129], v[68:69], 0, s[30:31]
	s_mov_b32 m0, s35
	s_mov_b64 s[30:31], 0x300
	global_load_lds_dwordx4 v[128:129], off
	v_lshl_add_u64 v[128:129], v[70:71], 0, s[30:31]
	s_mov_b32 m0, s39
	v_mfma_f32_32x32x16_bf16 v[0:15], v[138:141], v[150:153], v[0:15]
	global_load_lds_dwordx4 v[128:129], off
	v_lshl_add_u64 v[128:129], v[72:73], 0, s[30:31]
	s_mov_b32 m0, s40
	s_mov_b64 s[30:31], 0x2000380
	global_load_lds_dwordx4 v[128:129], off
	ds_read_b128 v[128:131], v88
	ds_read_b128 v[134:137], v78 offset:49152
	ds_read_b128 v[138:141], v86
	ds_read_b128 v[154:157], v78 offset:53248
	s_waitcnt lgkmcnt(1)
	v_mfma_f32_32x32x16_bf16 v[48:63], v[128:131], v[134:137], v[48:63]
	s_mov_b32 m0, s23
	v_readfirstlane_b32 s35, v110
	v_readfirstlane_b32 s36, v111
	v_readfirstlane_b32 s37, v112
	v_readfirstlane_b32 s39, v114
	v_readfirstlane_b32 s40, v115
	v_mfma_f32_32x32x16_bf16 v[32:47], v[138:141], v[134:137], v[32:47]
	s_waitcnt lgkmcnt(0)
	v_mfma_f32_32x32x16_bf16 v[16:31], v[128:131], v[154:157], v[16:31]
	v_mfma_f32_32x32x16_bf16 v[0:15], v[138:141], v[154:157], v[0:15]
	ds_read_b128 v[128:131], v89
	ds_read_b128 v[134:137], v80 offset:49152
	ds_read_b128 v[138:141], v87
	ds_read_b128 v[150:153], v80 offset:53248
	s_waitcnt lgkmcnt(1)
	v_mfma_f32_32x32x16_bf16 v[48:63], v[128:131], v[134:137], v[48:63]
	v_mfma_f32_32x32x16_bf16 v[32:47], v[138:141], v[134:137], v[32:47]
	s_waitcnt lgkmcnt(0)
	v_mfma_f32_32x32x16_bf16 v[16:31], v[128:131], v[150:153], v[16:31]
	v_mfma_f32_32x32x16_bf16 v[0:15], v[138:141], v[150:153], v[0:15]
	ds_read_b128 v[128:131], v91
	ds_read_b128 v[134:137], v82 offset:49152
	ds_read_b128 v[138:141], v90
	ds_read_b128 v[154:157], v82 offset:53248
	s_waitcnt lgkmcnt(1)
	v_mfma_f32_32x32x16_bf16 v[48:63], v[128:131], v[134:137], v[48:63]
	v_mfma_f32_32x32x16_bf16 v[32:47], v[138:141], v[134:137], v[32:47]
	s_waitcnt lgkmcnt(0)
	v_mfma_f32_32x32x16_bf16 v[16:31], v[128:131], v[154:157], v[16:31]
	v_mfma_f32_32x32x16_bf16 v[0:15], v[138:141], v[154:157], v[0:15]
	ds_read_b128 v[128:131], v93
	ds_read_b128 v[134:137], v84 offset:49152
	ds_read_b128 v[138:141], v92
	ds_read_b128 v[150:153], v84 offset:53248
	s_waitcnt lgkmcnt(1)
	v_mfma_f32_32x32x16_bf16 v[48:63], v[128:131], v[134:137], v[48:63]
	v_mfma_f32_32x32x16_bf16 v[32:47], v[138:141], v[134:137], v[32:47]
	s_waitcnt vmcnt(6)
	s_waitcnt lgkmcnt(0)
	s_barrier
	s_waitcnt lgkmcnt(0)
	v_mfma_f32_32x32x16_bf16 v[16:31], v[128:131], v[150:153], v[16:31]
	v_lshl_add_u64 v[128:129], v[66:67], 0, s[30:31]
	s_mov_b64 s[30:31], 0x2004380
	global_load_lds_dwordx4 v[128:129], off
	v_lshl_add_u64 v[128:129], v[68:69], 0, s[30:31]
	s_mov_b32 m0, s24
	s_mov_b64 s[30:31], 0x2008380
	global_load_lds_dwordx4 v[128:129], off
	v_lshl_add_u64 v[128:129], v[66:67], 0, s[30:31]
	s_mov_b32 m0, s28
	s_mov_b64 s[30:31], 0x200c380
	global_load_lds_dwordx4 v[128:129], off
	v_lshl_add_u64 v[128:129], v[68:69], 0, s[30:31]
	s_mov_b32 m0, s29
	s_mov_b64 s[28:29], 0x380
	global_load_lds_dwordx4 v[128:129], off
	v_lshl_add_u64 v[128:129], v[70:71], 0, s[28:29]
	s_mov_b32 m0, s33
	v_mfma_f32_32x32x16_bf16 v[0:15], v[138:141], v[150:153], v[0:15]
	global_load_lds_dwordx4 v[128:129], off
	v_lshl_add_u64 v[128:129], v[72:73], 0, s[28:29]
	s_mov_b32 m0, s34
	s_mov_b64 s[28:29], 0x2000400
	global_load_lds_dwordx4 v[128:129], off
	ds_read_b128 v[128:131], v94
	ds_read_b128 v[134:137], v96
	ds_read_b128 v[138:141], v95
	ds_read_b128 v[154:157], v97
	s_waitcnt lgkmcnt(1)
	v_mfma_f32_32x32x16_bf16 v[48:63], v[128:131], v[134:137], v[48:63]
	s_mov_b32 m0, s0
	v_readfirstlane_b32 s24, v117
	s_mov_b64 s[30:31], 0x200c500
	v_readfirstlane_b32 s33, v120
	v_readfirstlane_b32 s34, v121
	v_mfma_f32_32x32x16_bf16 v[32:47], v[138:141], v[134:137], v[32:47]
	s_waitcnt lgkmcnt(0)
	v_mfma_f32_32x32x16_bf16 v[16:31], v[128:131], v[154:157], v[16:31]
	v_mfma_f32_32x32x16_bf16 v[0:15], v[138:141], v[154:157], v[0:15]
	ds_read_b128 v[128:131], v98
	ds_read_b128 v[134:137], v100
	ds_read_b128 v[138:141], v99
	ds_read_b128 v[150:153], v101
	s_waitcnt lgkmcnt(1)
	v_mfma_f32_32x32x16_bf16 v[48:63], v[128:131], v[134:137], v[48:63]
	v_mfma_f32_32x32x16_bf16 v[32:47], v[138:141], v[134:137], v[32:47]
	s_waitcnt lgkmcnt(0)
	v_mfma_f32_32x32x16_bf16 v[16:31], v[128:131], v[150:153], v[16:31]
	v_mfma_f32_32x32x16_bf16 v[0:15], v[138:141], v[150:153], v[0:15]
	ds_read_b128 v[128:131], v102
	ds_read_b128 v[134:137], v104
	ds_read_b128 v[138:141], v103
	ds_read_b128 v[154:157], v105
	s_waitcnt lgkmcnt(1)
	v_mfma_f32_32x32x16_bf16 v[48:63], v[128:131], v[134:137], v[48:63]
	v_mfma_f32_32x32x16_bf16 v[32:47], v[138:141], v[134:137], v[32:47]
	s_waitcnt lgkmcnt(0)
	v_mfma_f32_32x32x16_bf16 v[16:31], v[128:131], v[154:157], v[16:31]
	v_mfma_f32_32x32x16_bf16 v[0:15], v[138:141], v[154:157], v[0:15]
	ds_read_b128 v[128:131], v106
	ds_read_b128 v[134:137], v108
	ds_read_b128 v[138:141], v107
	ds_read_b128 v[150:153], v109
	s_waitcnt lgkmcnt(1)
	v_mfma_f32_32x32x16_bf16 v[48:63], v[128:131], v[134:137], v[48:63]
	v_mfma_f32_32x32x16_bf16 v[32:47], v[138:141], v[134:137], v[32:47]
	s_waitcnt vmcnt(6)
	s_waitcnt lgkmcnt(0)
	s_barrier
	s_waitcnt lgkmcnt(0)
	v_mfma_f32_32x32x16_bf16 v[16:31], v[128:131], v[150:153], v[16:31]
	v_lshl_add_u64 v[128:129], v[66:67], 0, s[28:29]
	s_mov_b64 s[28:29], 0x2004400
	global_load_lds_dwordx4 v[128:129], off
	v_lshl_add_u64 v[128:129], v[68:69], 0, s[28:29]
	s_mov_b32 m0, s1
	s_mov_b64 s[0:1], 0x2008400
	global_load_lds_dwordx4 v[128:129], off
	v_lshl_add_u64 v[128:129], v[66:67], 0, s[0:1]
	s_mov_b32 m0, s2
	s_mov_b64 s[0:1], 0x200c400
	global_load_lds_dwordx4 v[128:129], off
	v_lshl_add_u64 v[128:129], v[68:69], 0, s[0:1]
	s_mov_b32 m0, s20
	s_mov_b64 s[0:1], 0x400
	global_load_lds_dwordx4 v[128:129], off
	v_lshl_add_u64 v[128:129], v[70:71], 0, s[0:1]
	s_mov_b32 m0, s21
	v_mfma_f32_32x32x16_bf16 v[0:15], v[138:141], v[150:153], v[0:15]
	global_load_lds_dwordx4 v[128:129], off
	v_lshl_add_u64 v[128:129], v[72:73], 0, s[0:1]
	s_mov_b32 m0, s22
	s_mov_b64 s[0:1], 0x2000480
	global_load_lds_dwordx4 v[128:129], off
	ds_read_b128 v[128:131], v79 offset:32768
	ds_read_b128 v[134:137], v78
	ds_read_b128 v[138:141], v79 offset:36864
	ds_read_b128 v[154:157], v78 offset:4096
	s_waitcnt lgkmcnt(1)
	v_mfma_f32_32x32x16_bf16 v[48:63], v[128:131], v[134:137], v[48:63]
	s_mov_b64 s[20:21], 0x2004480
	v_readfirstlane_b32 s2, v124
	s_mov_b64 s[22:23], 0x480
	s_mov_b64 s[28:29], 0x2000500
	v_mfma_f32_32x32x16_bf16 v[32:47], v[138:141], v[134:137], v[32:47]
	s_waitcnt lgkmcnt(0)
	v_mfma_f32_32x32x16_bf16 v[16:31], v[128:131], v[154:157], v[16:31]
	v_mfma_f32_32x32x16_bf16 v[0:15], v[138:141], v[154:157], v[0:15]
	ds_read_b128 v[128:131], v81 offset:32768
	ds_read_b128 v[134:137], v80
	ds_read_b128 v[138:141], v81 offset:36864
	ds_read_b128 v[150:153], v80 offset:4096
	s_waitcnt lgkmcnt(1)
	v_mfma_f32_32x32x16_bf16 v[48:63], v[128:131], v[134:137], v[48:63]
	v_mfma_f32_32x32x16_bf16 v[32:47], v[138:141], v[134:137], v[32:47]
	s_waitcnt lgkmcnt(0)
	v_mfma_f32_32x32x16_bf16 v[16:31], v[128:131], v[150:153], v[16:31]
	v_mfma_f32_32x32x16_bf16 v[0:15], v[138:141], v[150:153], v[0:15]
	ds_read_b128 v[128:131], v83 offset:32768
	ds_read_b128 v[134:137], v82
	ds_read_b128 v[138:141], v83 offset:36864
	ds_read_b128 v[154:157], v82 offset:4096
	s_waitcnt lgkmcnt(1)
	v_mfma_f32_32x32x16_bf16 v[48:63], v[128:131], v[134:137], v[48:63]
	v_mfma_f32_32x32x16_bf16 v[32:47], v[138:141], v[134:137], v[32:47]
	s_waitcnt lgkmcnt(0)
	v_mfma_f32_32x32x16_bf16 v[16:31], v[128:131], v[154:157], v[16:31]
	v_mfma_f32_32x32x16_bf16 v[0:15], v[138:141], v[154:157], v[0:15]
	ds_read_b128 v[128:131], v85 offset:32768
	ds_read_b128 v[134:137], v84
	ds_read_b128 v[138:141], v85 offset:36864
	ds_read_b128 v[150:153], v84 offset:4096
	s_waitcnt lgkmcnt(1)
	v_mfma_f32_32x32x16_bf16 v[48:63], v[128:131], v[134:137], v[48:63]
	v_mfma_f32_32x32x16_bf16 v[32:47], v[138:141], v[134:137], v[32:47]
	s_waitcnt vmcnt(6)
	s_waitcnt lgkmcnt(0)
	s_barrier
	s_waitcnt lgkmcnt(0)
	v_mfma_f32_32x32x16_bf16 v[16:31], v[128:131], v[150:153], v[16:31]
	v_lshl_add_u64 v[128:129], v[66:67], 0, s[0:1]
	v_readfirstlane_b32 s0, v127
	s_mov_b32 m0, s0
	v_readfirstlane_b32 s1, v126
	global_load_lds_dwordx4 v[128:129], off
	v_lshl_add_u64 v[128:129], v[68:69], 0, s[20:21]
	s_mov_b32 m0, s1
	s_mov_b64 s[20:21], 0x2008480
	global_load_lds_dwordx4 v[128:129], off
	v_lshl_add_u64 v[126:127], v[66:67], 0, s[20:21]
	s_mov_b32 m0, s2
	s_mov_b64 s[20:21], 0x200c480
	global_load_lds_dwordx4 v[126:127], off
	v_lshl_add_u64 v[126:127], v[68:69], 0, s[20:21]
	v_readfirstlane_b32 s20, v122
	s_mov_b32 m0, s20
	v_readfirstlane_b32 s21, v125
	global_load_lds_dwordx4 v[126:127], off
	v_lshl_add_u64 v[126:127], v[70:71], 0, s[22:23]
	s_mov_b32 m0, s21
	v_lshl_add_u64 v[124:125], v[72:73], 0, s[22:23]
	v_readfirstlane_b32 s22, v123
	global_load_lds_dwordx4 v[126:127], off
	s_mov_b32 m0, s22
	v_mfma_f32_32x32x16_bf16 v[0:15], v[138:141], v[150:153], v[0:15]
	global_load_lds_dwordx4 v[124:125], off
	ds_read_b128 v[122:125], v88
	ds_read_b128 v[126:129], v78 offset:49152
	ds_read_b128 v[134:137], v86
	v_readfirstlane_b32 s23, v116
	s_mov_b32 m0, s23
	ds_read_b128 v[154:157], v78 offset:53248
	s_waitcnt lgkmcnt(1)
	v_mfma_f32_32x32x16_bf16 v[48:63], v[122:125], v[126:129], v[48:63]
	v_mfma_f32_32x32x16_bf16 v[32:47], v[134:137], v[126:129], v[32:47]
	s_waitcnt lgkmcnt(0)
	v_mfma_f32_32x32x16_bf16 v[16:31], v[122:125], v[154:157], v[16:31]
	v_mfma_f32_32x32x16_bf16 v[0:15], v[134:137], v[154:157], v[0:15]
	ds_read_b128 v[122:125], v89
	ds_read_b128 v[126:129], v80 offset:49152
	ds_read_b128 v[134:137], v87
	ds_read_b128 v[150:153], v80 offset:53248
	s_waitcnt lgkmcnt(1)
	v_mfma_f32_32x32x16_bf16 v[48:63], v[122:125], v[126:129], v[48:63]
	v_mfma_f32_32x32x16_bf16 v[32:47], v[134:137], v[126:129], v[32:47]
	s_waitcnt lgkmcnt(0)
	v_mfma_f32_32x32x16_bf16 v[16:31], v[122:125], v[150:153], v[16:31]
	v_mfma_f32_32x32x16_bf16 v[0:15], v[134:137], v[150:153], v[0:15]
	ds_read_b128 v[122:125], v91
	ds_read_b128 v[126:129], v82 offset:49152
	ds_read_b128 v[134:137], v90
	ds_read_b128 v[154:157], v82 offset:53248
	s_waitcnt lgkmcnt(1)
	v_mfma_f32_32x32x16_bf16 v[48:63], v[122:125], v[126:129], v[48:63]
	v_mfma_f32_32x32x16_bf16 v[32:47], v[134:137], v[126:129], v[32:47]
	s_waitcnt lgkmcnt(0)
	v_mfma_f32_32x32x16_bf16 v[16:31], v[122:125], v[154:157], v[16:31]
	v_mfma_f32_32x32x16_bf16 v[0:15], v[134:137], v[154:157], v[0:15]
	ds_read_b128 v[122:125], v93
	ds_read_b128 v[126:129], v84 offset:49152
	ds_read_b128 v[134:137], v92
	ds_read_b128 v[150:153], v84 offset:53248
	s_waitcnt lgkmcnt(1)
	v_mfma_f32_32x32x16_bf16 v[48:63], v[122:125], v[126:129], v[48:63]
	v_mfma_f32_32x32x16_bf16 v[32:47], v[134:137], v[126:129], v[32:47]
	s_waitcnt vmcnt(6)
	s_waitcnt lgkmcnt(0)
	s_barrier
	s_waitcnt lgkmcnt(0)
	v_mfma_f32_32x32x16_bf16 v[16:31], v[122:125], v[150:153], v[16:31]
	v_lshl_add_u64 v[122:123], v[66:67], 0, s[28:29]
	s_mov_b64 s[28:29], 0x2004500
	global_load_lds_dwordx4 v[122:123], off
	v_lshl_add_u64 v[122:123], v[68:69], 0, s[28:29]
	s_mov_b64 s[28:29], 0x2008500
	s_mov_b32 m0, s24
	v_lshl_add_u64 v[116:117], v[66:67], 0, s[28:29]
	v_readfirstlane_b32 s28, v118
	global_load_lds_dwordx4 v[122:123], off
	s_mov_b32 m0, s28
	v_readfirstlane_b32 s29, v119
	global_load_lds_dwordx4 v[116:117], off
	v_lshl_add_u64 v[116:117], v[68:69], 0, s[30:31]
	s_mov_b32 m0, s29
	s_mov_b64 s[30:31], 0x500
	global_load_lds_dwordx4 v[116:117], off
	v_lshl_add_u64 v[116:117], v[70:71], 0, s[30:31]
	s_mov_b32 m0, s33
	v_mfma_f32_32x32x16_bf16 v[0:15], v[134:137], v[150:153], v[0:15]
	global_load_lds_dwordx4 v[116:117], off
	v_lshl_add_u64 v[116:117], v[72:73], 0, s[30:31]
	s_mov_b32 m0, s34
	s_mov_b64 s[30:31], 0x2000580
	global_load_lds_dwordx4 v[116:117], off
	ds_read_b128 v[116:119], v94
	ds_read_b128 v[120:123], v96
	ds_read_b128 v[124:127], v95
	ds_read_b128 v[154:157], v97
	s_waitcnt lgkmcnt(1)
	v_mfma_f32_32x32x16_bf16 v[48:63], v[116:119], v[120:123], v[48:63]
	s_mov_b32 m0, s35
	v_mfma_f32_32x32x16_bf16 v[32:47], v[124:127], v[120:123], v[32:47]
	s_waitcnt lgkmcnt(0)
	v_mfma_f32_32x32x16_bf16 v[16:31], v[116:119], v[154:157], v[16:31]
	v_mfma_f32_32x32x16_bf16 v[0:15], v[124:127], v[154:157], v[0:15]
	ds_read_b128 v[116:119], v98
	ds_read_b128 v[120:123], v100
	ds_read_b128 v[124:127], v99
	ds_read_b128 v[150:153], v101
	s_waitcnt lgkmcnt(1)
	v_mfma_f32_32x32x16_bf16 v[48:63], v[116:119], v[120:123], v[48:63]
	v_mfma_f32_32x32x16_bf16 v[32:47], v[124:127], v[120:123], v[32:47]
	s_waitcnt lgkmcnt(0)
	v_mfma_f32_32x32x16_bf16 v[16:31], v[116:119], v[150:153], v[16:31]
	v_mfma_f32_32x32x16_bf16 v[0:15], v[124:127], v[150:153], v[0:15]
	ds_read_b128 v[116:119], v102
	ds_read_b128 v[120:123], v104
	ds_read_b128 v[124:127], v103
	ds_read_b128 v[154:157], v105
	s_waitcnt lgkmcnt(1)
	v_mfma_f32_32x32x16_bf16 v[48:63], v[116:119], v[120:123], v[48:63]
	v_mfma_f32_32x32x16_bf16 v[32:47], v[124:127], v[120:123], v[32:47]
	s_waitcnt lgkmcnt(0)
	v_mfma_f32_32x32x16_bf16 v[16:31], v[116:119], v[154:157], v[16:31]
	v_mfma_f32_32x32x16_bf16 v[0:15], v[124:127], v[154:157], v[0:15]
	ds_read_b128 v[116:119], v106
	ds_read_b128 v[120:123], v108
	ds_read_b128 v[124:127], v107
	ds_read_b128 v[150:153], v109
	s_waitcnt lgkmcnt(1)
	v_mfma_f32_32x32x16_bf16 v[48:63], v[116:119], v[120:123], v[48:63]
	v_mfma_f32_32x32x16_bf16 v[32:47], v[124:127], v[120:123], v[32:47]
	s_waitcnt vmcnt(6)
	s_waitcnt lgkmcnt(0)
	s_barrier
	s_waitcnt lgkmcnt(0)
	v_mfma_f32_32x32x16_bf16 v[16:31], v[116:119], v[150:153], v[16:31]
	v_lshl_add_u64 v[116:117], v[66:67], 0, s[30:31]
	s_mov_b64 s[30:31], 0x2004580
	global_load_lds_dwordx4 v[116:117], off
	v_lshl_add_u64 v[116:117], v[68:69], 0, s[30:31]
	s_mov_b32 m0, s36
	s_mov_b64 s[30:31], 0x2008580
	global_load_lds_dwordx4 v[116:117], off
	v_lshl_add_u64 v[110:111], v[66:67], 0, s[30:31]
	s_mov_b32 m0, s37
	s_mov_b64 s[30:31], 0x200c580
	global_load_lds_dwordx4 v[110:111], off
	v_lshl_add_u64 v[110:111], v[68:69], 0, s[30:31]
	s_mov_b32 m0, s38
	s_mov_b64 s[30:31], 0x580
	global_load_lds_dwordx4 v[110:111], off
	v_lshl_add_u64 v[110:111], v[70:71], 0, s[30:31]
	s_mov_b32 m0, s39
	v_mfma_f32_32x32x16_bf16 v[0:15], v[124:127], v[150:153], v[0:15]
	global_load_lds_dwordx4 v[110:111], off
	v_lshl_add_u64 v[110:111], v[72:73], 0, s[30:31]
	s_mov_b32 m0, s40
	s_mov_b64 s[30:31], 0x2000600
	global_load_lds_dwordx4 v[110:111], off
	ds_read_b128 v[110:113], v79 offset:32768
	ds_read_b128 v[114:117], v78
	ds_read_b128 v[118:121], v79 offset:36864
	ds_read_b128 v[154:157], v78 offset:4096
	s_waitcnt lgkmcnt(1)
	v_mfma_f32_32x32x16_bf16 v[48:63], v[110:113], v[114:117], v[48:63]
	s_mov_b32 m0, s0
	v_mfma_f32_32x32x16_bf16 v[32:47], v[118:121], v[114:117], v[32:47]
	s_waitcnt lgkmcnt(0)
	v_mfma_f32_32x32x16_bf16 v[16:31], v[110:113], v[154:157], v[16:31]
	v_mfma_f32_32x32x16_bf16 v[0:15], v[118:121], v[154:157], v[0:15]
	ds_read_b128 v[110:113], v81 offset:32768
	ds_read_b128 v[114:117], v80
	ds_read_b128 v[118:121], v81 offset:36864
	ds_read_b128 v[150:153], v80 offset:4096
	s_waitcnt lgkmcnt(1)
	v_mfma_f32_32x32x16_bf16 v[48:63], v[110:113], v[114:117], v[48:63]
	v_mfma_f32_32x32x16_bf16 v[32:47], v[118:121], v[114:117], v[32:47]
	s_waitcnt lgkmcnt(0)
	v_mfma_f32_32x32x16_bf16 v[16:31], v[110:113], v[150:153], v[16:31]
	v_mfma_f32_32x32x16_bf16 v[0:15], v[118:121], v[150:153], v[0:15]
	ds_read_b128 v[110:113], v83 offset:32768
	ds_read_b128 v[114:117], v82
	ds_read_b128 v[118:121], v83 offset:36864
	ds_read_b128 v[154:157], v82 offset:4096
	s_waitcnt lgkmcnt(1)
	v_mfma_f32_32x32x16_bf16 v[48:63], v[110:113], v[114:117], v[48:63]
	v_mfma_f32_32x32x16_bf16 v[32:47], v[118:121], v[114:117], v[32:47]
	s_waitcnt lgkmcnt(0)
	v_mfma_f32_32x32x16_bf16 v[16:31], v[110:113], v[154:157], v[16:31]
	v_mfma_f32_32x32x16_bf16 v[0:15], v[118:121], v[154:157], v[0:15]
	ds_read_b128 v[110:113], v85 offset:32768
	ds_read_b128 v[114:117], v84
	ds_read_b128 v[118:121], v85 offset:36864
	ds_read_b128 v[150:153], v84 offset:4096
	s_waitcnt lgkmcnt(1)
	v_mfma_f32_32x32x16_bf16 v[48:63], v[110:113], v[114:117], v[48:63]
	v_mfma_f32_32x32x16_bf16 v[32:47], v[118:121], v[114:117], v[32:47]
	s_waitcnt vmcnt(6)
	s_waitcnt lgkmcnt(0)
	s_barrier
	s_waitcnt lgkmcnt(0)
	v_mfma_f32_32x32x16_bf16 v[16:31], v[110:113], v[150:153], v[16:31]
	v_lshl_add_u64 v[110:111], v[66:67], 0, s[30:31]
	s_mov_b64 s[30:31], 0x2004600
	global_load_lds_dwordx4 v[110:111], off
	v_lshl_add_u64 v[110:111], v[68:69], 0, s[30:31]
	s_mov_b32 m0, s1
	s_mov_b64 s[30:31], 0x2008600
	global_load_lds_dwordx4 v[110:111], off
	v_lshl_add_u64 v[110:111], v[66:67], 0, s[30:31]
	s_mov_b32 m0, s2
	s_mov_b64 s[30:31], 0x200c600
	global_load_lds_dwordx4 v[110:111], off
	v_lshl_add_u64 v[110:111], v[68:69], 0, s[30:31]
	s_mov_b32 m0, s20
	s_mov_b64 s[30:31], 0x600
	global_load_lds_dwordx4 v[110:111], off
	v_lshl_add_u64 v[110:111], v[70:71], 0, s[30:31]
	s_mov_b32 m0, s21
	v_mfma_f32_32x32x16_bf16 v[0:15], v[118:121], v[150:153], v[0:15]
	global_load_lds_dwordx4 v[110:111], off
	v_lshl_add_u64 v[110:111], v[72:73], 0, s[30:31]
	s_mov_b32 m0, s22
	s_mov_b64 s[30:31], 0x2000680
	global_load_lds_dwordx4 v[110:111], off
	ds_read_b128 v[110:113], v88
	ds_read_b128 v[114:117], v78 offset:49152
	ds_read_b128 v[118:121], v86
	ds_read_b128 v[154:157], v78 offset:53248
	s_waitcnt lgkmcnt(1)
	v_mfma_f32_32x32x16_bf16 v[48:63], v[110:113], v[114:117], v[48:63]
	s_mov_b32 m0, s23
	v_mfma_f32_32x32x16_bf16 v[32:47], v[118:121], v[114:117], v[32:47]
	s_waitcnt lgkmcnt(0)
	v_mfma_f32_32x32x16_bf16 v[16:31], v[110:113], v[154:157], v[16:31]
	v_mfma_f32_32x32x16_bf16 v[0:15], v[118:121], v[154:157], v[0:15]
	ds_read_b128 v[110:113], v89
	ds_read_b128 v[114:117], v80 offset:49152
	ds_read_b128 v[118:121], v87
	ds_read_b128 v[150:153], v80 offset:53248
	s_waitcnt lgkmcnt(1)
	v_mfma_f32_32x32x16_bf16 v[48:63], v[110:113], v[114:117], v[48:63]
	v_mfma_f32_32x32x16_bf16 v[32:47], v[118:121], v[114:117], v[32:47]
	s_waitcnt lgkmcnt(0)
	v_mfma_f32_32x32x16_bf16 v[16:31], v[110:113], v[150:153], v[16:31]
	v_mfma_f32_32x32x16_bf16 v[0:15], v[118:121], v[150:153], v[0:15]
	ds_read_b128 v[110:113], v91
	ds_read_b128 v[114:117], v82 offset:49152
	ds_read_b128 v[118:121], v90
	ds_read_b128 v[154:157], v82 offset:53248
	s_waitcnt lgkmcnt(1)
	v_mfma_f32_32x32x16_bf16 v[48:63], v[110:113], v[114:117], v[48:63]
	v_mfma_f32_32x32x16_bf16 v[32:47], v[118:121], v[114:117], v[32:47]
	s_waitcnt lgkmcnt(0)
	v_mfma_f32_32x32x16_bf16 v[16:31], v[110:113], v[154:157], v[16:31]
	v_mfma_f32_32x32x16_bf16 v[0:15], v[118:121], v[154:157], v[0:15]
	ds_read_b128 v[110:113], v93
	ds_read_b128 v[114:117], v84 offset:49152
	ds_read_b128 v[118:121], v92
	ds_read_b128 v[150:153], v84 offset:53248
	s_waitcnt lgkmcnt(1)
	v_mfma_f32_32x32x16_bf16 v[48:63], v[110:113], v[114:117], v[48:63]
	v_mfma_f32_32x32x16_bf16 v[32:47], v[118:121], v[114:117], v[32:47]
	s_waitcnt vmcnt(6)
	s_waitcnt lgkmcnt(0)
	s_barrier
	s_waitcnt lgkmcnt(0)
	v_mfma_f32_32x32x16_bf16 v[16:31], v[110:113], v[150:153], v[16:31]
	v_lshl_add_u64 v[110:111], v[66:67], 0, s[30:31]
	s_mov_b64 s[30:31], 0x2004680
	global_load_lds_dwordx4 v[110:111], off
	v_lshl_add_u64 v[110:111], v[68:69], 0, s[30:31]
	s_mov_b32 m0, s24
	s_mov_b64 s[30:31], 0x2008680
	global_load_lds_dwordx4 v[110:111], off
	v_lshl_add_u64 v[110:111], v[66:67], 0, s[30:31]
	s_mov_b32 m0, s28
	s_mov_b64 s[30:31], 0x200c680
	global_load_lds_dwordx4 v[110:111], off
	v_lshl_add_u64 v[110:111], v[68:69], 0, s[30:31]
	s_mov_b32 m0, s29
	s_mov_b64 s[28:29], 0x680
	global_load_lds_dwordx4 v[110:111], off
	v_lshl_add_u64 v[110:111], v[70:71], 0, s[28:29]
	s_mov_b32 m0, s33
	v_mfma_f32_32x32x16_bf16 v[0:15], v[118:121], v[150:153], v[0:15]
	global_load_lds_dwordx4 v[110:111], off
	v_lshl_add_u64 v[110:111], v[72:73], 0, s[28:29]
	s_mov_b32 m0, s34
	s_mov_b64 s[28:29], 0x2000700
	global_load_lds_dwordx4 v[110:111], off
	ds_read_b128 v[110:113], v94
	ds_read_b128 v[114:117], v96
	ds_read_b128 v[118:121], v95
	ds_read_b128 v[154:157], v97
	s_waitcnt lgkmcnt(1)
	v_mfma_f32_32x32x16_bf16 v[48:63], v[110:113], v[114:117], v[48:63]
	s_mov_b32 m0, s35
	v_mfma_f32_32x32x16_bf16 v[32:47], v[118:121], v[114:117], v[32:47]
	s_waitcnt lgkmcnt(0)
	v_mfma_f32_32x32x16_bf16 v[16:31], v[110:113], v[154:157], v[16:31]
	v_mfma_f32_32x32x16_bf16 v[0:15], v[118:121], v[154:157], v[0:15]
	ds_read_b128 v[110:113], v98
	ds_read_b128 v[114:117], v100
	ds_read_b128 v[118:121], v99
	ds_read_b128 v[150:153], v101
	s_waitcnt lgkmcnt(1)
	v_mfma_f32_32x32x16_bf16 v[48:63], v[110:113], v[114:117], v[48:63]
	v_mfma_f32_32x32x16_bf16 v[32:47], v[118:121], v[114:117], v[32:47]
	s_waitcnt lgkmcnt(0)
	v_mfma_f32_32x32x16_bf16 v[16:31], v[110:113], v[150:153], v[16:31]
	v_mfma_f32_32x32x16_bf16 v[0:15], v[118:121], v[150:153], v[0:15]
	ds_read_b128 v[110:113], v102
	ds_read_b128 v[114:117], v104
	ds_read_b128 v[118:121], v103
	ds_read_b128 v[154:157], v105
	s_waitcnt lgkmcnt(1)
	v_mfma_f32_32x32x16_bf16 v[48:63], v[110:113], v[114:117], v[48:63]
	v_mfma_f32_32x32x16_bf16 v[32:47], v[118:121], v[114:117], v[32:47]
	s_waitcnt lgkmcnt(0)
	v_mfma_f32_32x32x16_bf16 v[16:31], v[110:113], v[154:157], v[16:31]
	v_mfma_f32_32x32x16_bf16 v[0:15], v[118:121], v[154:157], v[0:15]
	ds_read_b128 v[110:113], v106
	ds_read_b128 v[114:117], v108
	ds_read_b128 v[118:121], v107
	ds_read_b128 v[150:153], v109
	s_waitcnt lgkmcnt(1)
	v_mfma_f32_32x32x16_bf16 v[48:63], v[110:113], v[114:117], v[48:63]
	v_mfma_f32_32x32x16_bf16 v[32:47], v[118:121], v[114:117], v[32:47]
	s_waitcnt vmcnt(6)
	s_waitcnt lgkmcnt(0)
	s_barrier
	s_waitcnt lgkmcnt(0)
	v_mfma_f32_32x32x16_bf16 v[16:31], v[110:113], v[150:153], v[16:31]
	v_lshl_add_u64 v[110:111], v[66:67], 0, s[28:29]
	s_mov_b64 s[28:29], 0x2004700
	global_load_lds_dwordx4 v[110:111], off
	v_lshl_add_u64 v[110:111], v[68:69], 0, s[28:29]
	s_mov_b32 m0, s36
	s_mov_b64 s[28:29], 0x2008700
	global_load_lds_dwordx4 v[110:111], off
	v_lshl_add_u64 v[110:111], v[66:67], 0, s[28:29]
	s_mov_b32 m0, s37
	s_mov_b64 s[28:29], 0x200c700
	global_load_lds_dwordx4 v[110:111], off
	v_lshl_add_u64 v[110:111], v[68:69], 0, s[28:29]
	s_mov_b32 m0, s38
	s_mov_b64 s[28:29], 0x700
	global_load_lds_dwordx4 v[110:111], off
	v_lshl_add_u64 v[110:111], v[70:71], 0, s[28:29]
	s_mov_b32 m0, s39
	v_mfma_f32_32x32x16_bf16 v[0:15], v[118:121], v[150:153], v[0:15]
	global_load_lds_dwordx4 v[110:111], off
	v_lshl_add_u64 v[110:111], v[72:73], 0, s[28:29]
	s_mov_b32 m0, s40
	s_mov_b64 s[28:29], 0x2000780
	global_load_lds_dwordx4 v[110:111], off
	ds_read_b128 v[110:113], v79 offset:32768
	ds_read_b128 v[114:117], v78
	ds_read_b128 v[118:121], v79 offset:36864
	ds_read_b128 v[154:157], v78 offset:4096
	s_waitcnt lgkmcnt(1)
	v_mfma_f32_32x32x16_bf16 v[48:63], v[110:113], v[114:117], v[48:63]
	s_mov_b32 m0, s0
	v_mfma_f32_32x32x16_bf16 v[32:47], v[118:121], v[114:117], v[32:47]
	s_waitcnt lgkmcnt(0)
	v_mfma_f32_32x32x16_bf16 v[16:31], v[110:113], v[154:157], v[16:31]
	v_mfma_f32_32x32x16_bf16 v[0:15], v[118:121], v[154:157], v[0:15]
	ds_read_b128 v[110:113], v81 offset:32768
	ds_read_b128 v[114:117], v80
	ds_read_b128 v[118:121], v81 offset:36864
	ds_read_b128 v[150:153], v80 offset:4096
	s_waitcnt lgkmcnt(1)
	v_mfma_f32_32x32x16_bf16 v[48:63], v[110:113], v[114:117], v[48:63]
	v_mfma_f32_32x32x16_bf16 v[32:47], v[118:121], v[114:117], v[32:47]
	s_waitcnt lgkmcnt(0)
	v_mfma_f32_32x32x16_bf16 v[16:31], v[110:113], v[150:153], v[16:31]
	v_mfma_f32_32x32x16_bf16 v[0:15], v[118:121], v[150:153], v[0:15]
	ds_read_b128 v[110:113], v83 offset:32768
	ds_read_b128 v[114:117], v82
	ds_read_b128 v[118:121], v83 offset:36864
	ds_read_b128 v[154:157], v82 offset:4096
	s_waitcnt lgkmcnt(1)
	v_mfma_f32_32x32x16_bf16 v[48:63], v[110:113], v[114:117], v[48:63]
	v_mfma_f32_32x32x16_bf16 v[32:47], v[118:121], v[114:117], v[32:47]
	s_waitcnt lgkmcnt(0)
	v_mfma_f32_32x32x16_bf16 v[16:31], v[110:113], v[154:157], v[16:31]
	v_mfma_f32_32x32x16_bf16 v[0:15], v[118:121], v[154:157], v[0:15]
	ds_read_b128 v[110:113], v85 offset:32768
	ds_read_b128 v[114:117], v84
	ds_read_b128 v[118:121], v85 offset:36864
	ds_read_b128 v[150:153], v84 offset:4096
	s_waitcnt lgkmcnt(1)
	v_mfma_f32_32x32x16_bf16 v[48:63], v[110:113], v[114:117], v[48:63]
	v_mfma_f32_32x32x16_bf16 v[32:47], v[118:121], v[114:117], v[32:47]
	s_waitcnt vmcnt(6)
	s_waitcnt lgkmcnt(0)
	s_barrier
	s_waitcnt lgkmcnt(0)
	v_mfma_f32_32x32x16_bf16 v[16:31], v[110:113], v[150:153], v[16:31]
	v_lshl_add_u64 v[110:111], v[66:67], 0, s[28:29]
	s_mov_b64 s[28:29], 0x2004780
	global_load_lds_dwordx4 v[110:111], off
	v_lshl_add_u64 v[110:111], v[68:69], 0, s[28:29]
	s_mov_b32 m0, s1
	s_mov_b64 s[0:1], 0x2008780
	global_load_lds_dwordx4 v[110:111], off
	v_lshl_add_u64 v[66:67], v[66:67], 0, s[0:1]
	s_mov_b32 m0, s2
	s_mov_b64 s[0:1], 0x200c780
	global_load_lds_dwordx4 v[66:67], off
	v_lshl_add_u64 v[66:67], v[68:69], 0, s[0:1]
	s_mov_b32 m0, s20
	s_mov_b64 s[0:1], 0x780
	global_load_lds_dwordx4 v[66:67], off
	v_lshl_add_u64 v[66:67], v[70:71], 0, s[0:1]
	s_mov_b32 m0, s21
	v_mfma_f32_32x32x16_bf16 v[0:15], v[118:121], v[150:153], v[0:15]
	global_load_lds_dwordx4 v[66:67], off
	v_lshl_add_u64 v[66:67], v[72:73], 0, s[0:1]
	s_mov_b32 m0, s22
	v_readlane_b32 s0, v215, 52
	global_load_lds_dwordx4 v[66:67], off
	ds_read_b128 v[66:69], v88
	ds_read_b128 v[70:73], v78 offset:49152
	ds_read_b128 v[110:113], v86
	ds_read_b128 v[154:157], v78 offset:53248
	s_waitcnt lgkmcnt(1)
	v_mfma_f32_32x32x16_bf16 v[48:63], v[66:69], v[70:73], v[48:63]
	v_readlane_b32 s1, v215, 53
	s_mov_b32 s2, 0
	v_mfma_f32_32x32x16_bf16 v[32:47], v[110:113], v[70:73], v[32:47]
	s_waitcnt lgkmcnt(0)
	v_mfma_f32_32x32x16_bf16 v[16:31], v[66:69], v[154:157], v[16:31]
	v_mfma_f32_32x32x16_bf16 v[0:15], v[110:113], v[154:157], v[0:15]
	ds_read_b128 v[66:69], v89
	ds_read_b128 v[70:73], v80 offset:49152
	ds_read_b128 v[86:89], v87
	ds_read_b128 v[150:153], v80 offset:53248
	s_waitcnt lgkmcnt(1)
	v_mfma_f32_32x32x16_bf16 v[48:63], v[66:69], v[70:73], v[48:63]
	v_mfma_f32_32x32x16_bf16 v[32:47], v[86:89], v[70:73], v[32:47]
	s_waitcnt lgkmcnt(0)
	v_mfma_f32_32x32x16_bf16 v[16:31], v[66:69], v[150:153], v[16:31]
	v_mfma_f32_32x32x16_bf16 v[0:15], v[86:89], v[150:153], v[0:15]
	ds_read_b128 v[66:69], v91
	ds_read_b128 v[70:73], v82 offset:49152
	ds_read_b128 v[86:89], v90
	ds_read_b128 v[154:157], v82 offset:53248
	s_waitcnt lgkmcnt(1)
	v_mfma_f32_32x32x16_bf16 v[48:63], v[66:69], v[70:73], v[48:63]
	v_mfma_f32_32x32x16_bf16 v[32:47], v[86:89], v[70:73], v[32:47]
	s_waitcnt lgkmcnt(0)
	v_mfma_f32_32x32x16_bf16 v[16:31], v[66:69], v[154:157], v[16:31]
	v_mfma_f32_32x32x16_bf16 v[0:15], v[86:89], v[154:157], v[0:15]
	ds_read_b128 v[66:69], v93
	ds_read_b128 v[70:73], v84 offset:49152
	ds_read_b128 v[86:89], v92
	ds_read_b128 v[150:153], v84 offset:53248
	s_waitcnt lgkmcnt(1)
	v_mfma_f32_32x32x16_bf16 v[48:63], v[66:69], v[70:73], v[48:63]
	v_mfma_f32_32x32x16_bf16 v[32:47], v[86:89], v[70:73], v[32:47]
	s_waitcnt vmcnt(6)
	s_waitcnt lgkmcnt(0)
	s_barrier
	s_waitcnt lgkmcnt(0)
	v_mfma_f32_32x32x16_bf16 v[16:31], v[66:69], v[150:153], v[16:31]
	v_mfma_f32_32x32x16_bf16 v[0:15], v[86:89], v[150:153], v[0:15]
	ds_read_b128 v[66:69], v94
	ds_read_b128 v[70:73], v96
	ds_read_b128 v[86:89], v95
	ds_read_b128 v[154:157], v97
	s_waitcnt lgkmcnt(1)
	v_mfma_f32_32x32x16_bf16 v[48:63], v[66:69], v[70:73], v[48:63]
	v_mfma_f32_32x32x16_bf16 v[32:47], v[86:89], v[70:73], v[32:47]
	s_waitcnt lgkmcnt(0)
	v_mfma_f32_32x32x16_bf16 v[16:31], v[66:69], v[154:157], v[16:31]
	v_mfma_f32_32x32x16_bf16 v[0:15], v[86:89], v[154:157], v[0:15]
	ds_read_b128 v[66:69], v98
	ds_read_b128 v[70:73], v100
	ds_read_b128 v[86:89], v99
	ds_read_b128 v[150:153], v101
	s_waitcnt lgkmcnt(1)
	v_mfma_f32_32x32x16_bf16 v[48:63], v[66:69], v[70:73], v[48:63]
	v_mfma_f32_32x32x16_bf16 v[32:47], v[86:89], v[70:73], v[32:47]
	s_waitcnt lgkmcnt(0)
	v_mfma_f32_32x32x16_bf16 v[16:31], v[66:69], v[150:153], v[16:31]
	v_mfma_f32_32x32x16_bf16 v[0:15], v[86:89], v[150:153], v[0:15]
	ds_read_b128 v[66:69], v102
	ds_read_b128 v[70:73], v104
	ds_read_b128 v[86:89], v103
	ds_read_b128 v[154:157], v105
	s_waitcnt lgkmcnt(1)
	v_mfma_f32_32x32x16_bf16 v[48:63], v[66:69], v[70:73], v[48:63]
	v_mfma_f32_32x32x16_bf16 v[32:47], v[86:89], v[70:73], v[32:47]
	s_waitcnt lgkmcnt(0)
	v_mfma_f32_32x32x16_bf16 v[16:31], v[66:69], v[154:157], v[16:31]
	v_mfma_f32_32x32x16_bf16 v[0:15], v[86:89], v[154:157], v[0:15]
	ds_read_b128 v[66:69], v106
	ds_read_b128 v[70:73], v108
	ds_read_b128 v[86:89], v107
	ds_read_b128 v[150:153], v109
	s_waitcnt lgkmcnt(1)
	v_mfma_f32_32x32x16_bf16 v[48:63], v[66:69], v[70:73], v[48:63]
	v_mfma_f32_32x32x16_bf16 v[32:47], v[86:89], v[70:73], v[32:47]
	s_waitcnt vmcnt(0)
	s_waitcnt lgkmcnt(0)
	s_barrier
	s_waitcnt lgkmcnt(0)
	v_mfma_f32_32x32x16_bf16 v[16:31], v[66:69], v[150:153], v[16:31]
	v_mfma_f32_32x32x16_bf16 v[0:15], v[86:89], v[150:153], v[0:15]
	ds_read_b128 v[66:69], v79 offset:32768
	ds_read_b128 v[70:73], v78
	ds_read_b128 v[86:89], v79 offset:36864
	ds_read_b128 v[154:157], v78 offset:4096
	s_waitcnt lgkmcnt(1)
	v_mfma_f32_32x32x16_bf16 v[48:63], v[66:69], v[70:73], v[48:63]
	v_mfma_f32_32x32x16_bf16 v[32:47], v[86:89], v[70:73], v[32:47]
	s_waitcnt lgkmcnt(0)
	v_mfma_f32_32x32x16_bf16 v[16:31], v[66:69], v[154:157], v[16:31]
	v_mfma_f32_32x32x16_bf16 v[0:15], v[86:89], v[154:157], v[0:15]
	ds_read_b128 v[66:69], v81 offset:32768
	ds_read_b128 v[70:73], v80
	ds_read_b128 v[86:89], v81 offset:36864
	ds_read_b128 v[150:153], v80 offset:4096
	s_waitcnt lgkmcnt(1)
	v_mfma_f32_32x32x16_bf16 v[48:63], v[66:69], v[70:73], v[48:63]
	v_mfma_f32_32x32x16_bf16 v[32:47], v[86:89], v[70:73], v[32:47]
	s_waitcnt lgkmcnt(0)
	v_mfma_f32_32x32x16_bf16 v[16:31], v[66:69], v[150:153], v[16:31]
	v_mfma_f32_32x32x16_bf16 v[0:15], v[86:89], v[150:153], v[0:15]
	ds_read_b128 v[66:69], v83 offset:32768
	ds_read_b128 v[70:73], v82
	ds_read_b128 v[78:81], v83 offset:36864
	s_waitcnt lgkmcnt(0)
	v_mfma_f32_32x32x16_bf16 v[48:63], v[66:69], v[70:73], v[48:63]
	v_mfma_f32_32x32x16_bf16 v[32:47], v[78:81], v[70:73], v[32:47]
	ds_read_b128 v[70:73], v82 offset:4096
	s_waitcnt lgkmcnt(0)
	v_mfma_f32_32x32x16_bf16 v[0:15], v[78:81], v[70:73], v[0:15]
	v_mfma_f32_32x32x16_bf16 v[16:31], v[66:69], v[70:73], v[16:31]
	ds_read_b128 v[66:69], v85 offset:32768
	ds_read_b128 v[70:73], v84
	ds_read_b128 v[78:81], v85 offset:36864
	ds_read_b128 v[82:85], v84 offset:4096
	s_waitcnt lgkmcnt(0)
	s_barrier
	s_waitcnt lgkmcnt(0)
	v_mfma_f32_32x32x16_bf16 v[48:63], v[66:69], v[70:73], v[48:63]
	v_mfma_f32_32x32x16_bf16 v[32:47], v[78:81], v[70:73], v[32:47]
	s_nop 10
	ds_write_b128 v64, v[48:51]
	ds_write_b128 v64, v[52:55] offset:32
	ds_write_b128 v64, v[56:59] offset:64
	ds_write_b128 v64, v[60:63] offset:96
	ds_write_b128 v64, v[32:35] offset:128
	v_mfma_f32_32x32x16_bf16 v[0:15], v[78:81], v[82:85], v[0:15]
	v_mfma_f32_32x32x16_bf16 v[16:31], v[66:69], v[82:85], v[16:31]
	ds_write_b128 v64, v[36:39] offset:160
	ds_write_b128 v64, v[40:43] offset:192
	ds_write_b128 v64, v[44:47] offset:224
	s_nop 8
	ds_write_b128 v64, v[16:19] offset:16896
	ds_write_b128 v64, v[20:23] offset:16928
	ds_write_b128 v64, v[24:27] offset:16960
	ds_write_b128 v64, v[28:31] offset:16992
	ds_write_b128 v64, v[0:3] offset:17024
	ds_write_b128 v64, v[4:7] offset:17056
	ds_write_b128 v64, v[8:11] offset:17088
	ds_write_b128 v64, v[12:15] offset:17120
	s_waitcnt lgkmcnt(0)
	s_barrier
	v_lshl_or_b32 v0, v75, 2, s53
	v_ashrrev_i32_e32 v1, 31, v0
	v_lshl_add_u32 v4, v75, 4, 0
	v_lshl_add_u64 v[6:7], v[0:1], 2, s[92:93]
	v_lshl_add_u64 v[8:9], v[0:1], 1, s[0:1]
	v_cmp_eq_u32_e64 s[0:1], 0, v75
	s_branch .LBB0_244

.LBB0_519:
	s_cmpk_gt_i32 s33, 0x658
	s_mov_b64 s[0:1], -1
	s_cbranch_scc0 .LBB0_585
	s_add_i32 s0, s33, 0xfffff9a7
	s_lshr_b32 s24, s0, 5
	s_lshl_b64 s[0:1], s[24:25], 20
	v_readlane_b32 s20, v215, 46
	v_mov_b32_e32 v12, v133
	s_add_u32 s20, s20, s0
	v_readlane_b32 s21, v215, 47
	s_addc_u32 s21, s21, s1
	v_ashrrev_i32_e32 v6, 6, v12
	v_bfe_u32 v7, v12, 3, 3
	s_and_b32 s29, s22, 0x700
	v_lshl_or_b32 v8, v6, 5, v7
	v_add_u32_e32 v0, s29, v8
	s_waitcnt lgkmcnt(0)
	v_ashrrev_i32_e32 v1, 31, v0
	v_lshlrev_b64 v[2:3], 11, v[0:1]
	v_bfe_u32 v1, v12, 4, 2
	v_readlane_b32 s30, v215, 50
	v_xor_b32_e32 v1, v1, v12
	v_readlane_b32 s31, v215, 51
	v_lshlrev_b32_e32 v1, 4, v1
	v_and_b32_e32 v64, 0x70, v1
	v_lshl_add_u64 v[2:3], s[30:31], 0, v[2:3]
	v_or_b32_e32 v1, 8, v8
	v_lshl_add_u64 v[66:67], v[2:3], 0, v[64:65]
	v_add_u32_e32 v2, s29, v1
	v_lshrrev_b32_e32 v1, 1, v1
	v_xor_b32_e32 v1, v1, v12
	v_ashrrev_i32_e32 v3, 31, v2
	v_lshlrev_b32_e32 v1, 4, v1
	v_or_b32_e32 v0, 16, v0
	v_lshlrev_b64 v[2:3], 11, v[2:3]
	v_and_b32_e32 v4, 0x70, v1
	v_ashrrev_i32_e32 v1, 31, v0
	v_lshl_add_u64 v[2:3], s[30:31], 0, v[2:3]
	v_mov_b32_e32 v5, v65
	v_lshlrev_b64 v[0:1], 11, v[0:1]
	v_lshl_add_u64 v[68:69], v[2:3], 0, v[4:5]
	v_lshl_add_u64 v[0:1], s[30:31], 0, v[0:1]
	v_or_b32_e32 v2, 24, v8
	v_lshl_add_u64 v[70:71], v[0:1], 0, v[64:65]
	v_add_u32_e32 v0, s29, v2
	v_lshrrev_b32_e32 v2, 1, v2
	v_ashrrev_i32_e32 v1, 31, v0
	v_xor_b32_e32 v2, v2, v12
	v_lshlrev_b64 v[0:1], 11, v[0:1]
	v_lshlrev_b32_e32 v2, 4, v2
	s_add_i32 s28, s23, 0xfffcd380
	v_lshl_add_u64 v[0:1], s[30:31], 0, v[0:1]
	v_and_b32_e32 v2, 0x70, v2
	v_mov_b32_e32 v3, v65
	s_and_b32 s28, s28, 0x180
	v_lshl_add_u64 v[72:73], v[0:1], 0, v[2:3]
	v_lshl_or_b32 v2, v6, 4, v7
	v_add_u32_e32 v0, s28, v2
	v_lshlrev_b32_e32 v3, 12, v6
	v_ashrrev_i32_e32 v1, 31, v0
	v_add_u32_e32 v125, 0, v3
	v_lshlrev_b64 v[0:1], 11, v[0:1]
	s_waitcnt vmcnt(0)
	v_readfirstlane_b32 s44, v125
	v_add_u32_e32 v126, 0x400, v125
	v_lshl_add_u64 v[0:1], s[20:21], 0, v[0:1]
	v_or_b32_e32 v2, 8, v2
	s_waitcnt lgkmcnt(0)
	s_barrier
	s_mov_b32 m0, s44
	v_readfirstlane_b32 s45, v126
	v_add_u32_e32 v127, 0x800, v125
	v_lshlrev_b32_e32 v5, 11, v6
	v_and_b32_e32 v79, 1, v6
	v_lshl_add_u64 v[74:75], v[0:1], 0, v[64:65]
	v_add_u32_e32 v0, s28, v2
	v_lshrrev_b32_e32 v2, 1, v2
	global_load_lds_dwordx4 v[66:67], off
	s_mov_b32 m0, s45
	v_readfirstlane_b32 s46, v127
	v_add_u32_e32 v128, 0xc00, v125
	v_add_u32_e32 v6, 0, v5
	v_ashrrev_i32_e32 v1, 31, v0
	v_xor_b32_e32 v2, v2, v12
	global_load_lds_dwordx4 v[68:69], off
	s_mov_b32 m0, s46
	v_readfirstlane_b32 s47, v128
	v_add_u32_e32 v130, 0x8000, v6
	v_lshlrev_b64 v[0:1], 11, v[0:1]
	v_lshlrev_b32_e32 v2, 4, v2
	global_load_lds_dwordx4 v[70:71], off
	s_mov_b32 m0, s47
	v_readfirstlane_b32 s48, v130
	v_add_u32_e32 v129, 0x8400, v6
	v_lshl_add_u64 v[0:1], s[20:21], 0, v[0:1]
	v_and_b32_e32 v64, 0x70, v2
	global_load_lds_dwordx4 v[72:73], off
	s_mov_b32 m0, s48
	v_readfirstlane_b32 s49, v129
	v_add_u32_e32 v119, 0xc000, v125
	v_lshl_add_u64 v[76:77], v[0:1], 0, v[64:65]
	global_load_lds_dwordx4 v[74:75], off
	s_mov_b32 m0, s49
	s_mov_b64 s[20:21], 0x80
	v_readfirstlane_b32 s38, v119
	v_add_u32_e32 v120, 0xc400, v125
	global_load_lds_dwordx4 v[76:77], off
	v_lshl_add_u64 v[0:1], v[66:67], 0, s[20:21]
	s_mov_b32 m0, s38
	v_readfirstlane_b32 s39, v120
	v_add_u32_e32 v121, 0xc800, v125
	global_load_lds_dwordx4 v[0:1], off
	v_lshl_add_u64 v[0:1], v[68:69], 0, s[20:21]
	s_mov_b32 m0, s39
	v_readfirstlane_b32 s40, v121
	v_add_u32_e32 v122, 0xcc00, v125
	global_load_lds_dwordx4 v[0:1], off
	v_lshl_add_u64 v[0:1], v[70:71], 0, s[20:21]
	s_mov_b32 m0, s40
	v_readfirstlane_b32 s41, v122
	v_add_u32_e32 v123, s85, v5
	global_load_lds_dwordx4 v[0:1], off
	v_lshl_add_u64 v[0:1], v[72:73], 0, s[20:21]
	s_mov_b32 m0, s41
	v_readfirstlane_b32 s42, v123
	v_add_u32_e32 v124, 0x14400, v6
	global_load_lds_dwordx4 v[0:1], off
	v_lshl_add_u64 v[0:1], v[74:75], 0, s[20:21]
	s_mov_b32 m0, s42
	v_readfirstlane_b32 s43, v124
	global_load_lds_dwordx4 v[0:1], off
	v_lshl_add_u64 v[0:1], v[76:77], 0, s[20:21]
	s_mov_b32 m0, s43
	v_lshrrev_b32_e32 v2, 1, v12
	v_bfe_u32 v81, v12, 5, 1
	global_load_lds_dwordx4 v[0:1], off
	v_add_u32_e32 v113, s3, v3
	v_bitop3_b32 v0, v2, v81, 7 bitop3:0x6c
	s_waitcnt vmcnt(6)
	s_mov_b64 s[50:51], 0x100
	v_readfirstlane_b32 s20, v113
	v_add_u32_e32 v114, 0x400, v113
	v_lshlrev_b32_e32 v110, 4, v0
	s_waitcnt lgkmcnt(0)
	s_barrier
	v_lshl_add_u64 v[0:1], v[66:67], 0, s[50:51]
	s_mov_b32 m0, s20
	v_readfirstlane_b32 s21, v114
	v_add_u32_e32 v115, 0x800, v113
	global_load_lds_dwordx4 v[0:1], off
	v_lshl_add_u64 v[0:1], v[68:69], 0, s[50:51]
	s_mov_b32 m0, s21
	v_readfirstlane_b32 s34, v115
	v_add_u32_e32 v116, 0xc00, v113
	v_readlane_b32 s30, v212, 31
	v_and_b32_e32 v80, 31, v12
	global_load_lds_dwordx4 v[0:1], off
	v_lshl_add_u64 v[0:1], v[70:71], 0, s[50:51]
	s_mov_b32 m0, s34
	v_readfirstlane_b32 s35, v116
	v_add_u32_e32 v117, s30, v5
	v_add_u32_e32 v2, s3, v5
	v_lshlrev_b32_e32 v4, 7, v80
	global_load_lds_dwordx4 v[0:1], off
	v_lshl_add_u64 v[0:1], v[72:73], 0, s[50:51]
	s_mov_b32 m0, s35
	v_readfirstlane_b32 s36, v117
	v_add_u32_e32 v118, 0x8400, v2
	v_lshl_or_b32 v102, v79, 13, v4
	global_load_lds_dwordx4 v[0:1], off
	v_lshl_add_u64 v[0:1], v[74:75], 0, s[50:51]
	s_mov_b32 m0, s36
	v_readfirstlane_b32 s37, v118
	global_load_lds_dwordx4 v[0:1], off
	v_lshl_add_u64 v[0:1], v[76:77], 0, s[50:51]
	s_mov_b32 m0, s37
	v_add_u32_e32 v85, 0, v102
	global_load_lds_dwordx4 v[0:1], off
	v_add_u32_e32 v82, v85, v110
	v_ashrrev_i32_e32 v78, 7, v12
	ds_read_b128 v[0:3], v82 offset:32768
	ds_read_b128 v[8:11], v82 offset:36864
	v_lshl_or_b32 v111, v78, 13, v4
	v_add_u32_e32 v100, 0, v111
	v_add_u32_e32 v64, v100, v110
	ds_read_b128 v[4:7], v64
	ds_read_b128 v[154:157], v64 offset:4096
	s_waitcnt lgkmcnt(1)
	v_mfma_f32_32x32x16_bf16 v[48:63], v[0:3], v[4:7], 0
	v_bfe_u32 v101, v12, 1, 3
	s_mov_b64 s[30:31], 0x180
	s_mov_b32 m0, s44
	v_or_b32_e32 v146, 0x8000, v102
	v_or_b32_e32 v147, 0x9000, v102
	v_add_u32_e32 v138, s3, v110
	v_add_u32_e32 v148, s3, v111
	s_waitcnt vmcnt(12)
	v_mfma_f32_32x32x16_bf16 v[32:47], v[8:11], v[4:7], 0
	v_or_b32_e32 v149, 0x1000, v111
	s_mov_b64 s[74:75], 0x80
	s_mov_b64 s[80:81], 0x200
	s_waitcnt lgkmcnt(0)
	v_mfma_f32_32x32x16_bf16 v[16:31], v[0:3], v[154:157], 0
	v_bitop3_b32 v0, v81, v101, 2 bitop3:0x36
	v_lshlrev_b32_e32 v112, 4, v0
	v_add_u32_e32 v84, v85, v112
	ds_read_b128 v[86:89], v84 offset:32768
	ds_read_b128 v[94:97], v84 offset:36864
	v_add_u32_e32 v83, v100, v112
	ds_read_b128 v[90:93], v83
	v_mfma_f32_32x32x16_bf16 v[0:15], v[8:11], v[154:157], 0
	v_add_u32_e32 v142, s3, v112
	ds_read_b128 v[150:153], v83 offset:4096
	s_waitcnt lgkmcnt(1)
	v_mfma_f32_32x32x16_bf16 v[48:63], v[86:89], v[90:93], v[48:63]
	v_mfma_f32_32x32x16_bf16 v[32:47], v[94:97], v[90:93], v[32:47]
	s_waitcnt lgkmcnt(0)
	v_mfma_f32_32x32x16_bf16 v[16:31], v[86:89], v[150:153], v[16:31]
	v_bitop3_b32 v86, v81, v101, 4 bitop3:0x36
	v_lshlrev_b32_e32 v131, 4, v86
	v_add_u32_e32 v87, v85, v131
	v_add_u32_e32 v86, v100, v131
	v_mfma_f32_32x32x16_bf16 v[0:15], v[94:97], v[150:153], v[0:15]
	ds_read_b128 v[88:91], v87 offset:32768
	ds_read_b128 v[92:95], v86
	ds_read_b128 v[96:99], v87 offset:36864
	s_waitcnt lgkmcnt(1)
	v_mfma_f32_32x32x16_bf16 v[48:63], v[88:91], v[92:95], v[48:63]
	s_waitcnt lgkmcnt(0)
	v_mfma_f32_32x32x16_bf16 v[32:47], v[96:99], v[92:95], v[32:47]
	ds_read_b128 v[92:95], v86 offset:4096
	s_waitcnt lgkmcnt(0)
	v_mfma_f32_32x32x16_bf16 v[16:31], v[88:91], v[92:95], v[16:31]
	v_bitop3_b32 v88, v81, v101, 6 bitop3:0x36
	v_lshlrev_b32_e32 v132, 4, v88
	v_add_u32_e32 v85, v85, v132
	v_add_u32_e32 v88, v100, v132
	v_mfma_f32_32x32x16_bf16 v[0:15], v[96:99], v[92:95], v[0:15]
	ds_read_b128 v[90:93], v85 offset:32768
	ds_read_b128 v[98:101], v85 offset:36864
	ds_read_b128 v[94:97], v88
	ds_read_b128 v[154:157], v88 offset:4096
	s_waitcnt lgkmcnt(1)
	v_mfma_f32_32x32x16_bf16 v[48:63], v[90:93], v[94:97], v[48:63]
	v_mfma_f32_32x32x16_bf16 v[32:47], v[98:101], v[94:97], v[32:47]
	s_waitcnt vmcnt(6)
	s_waitcnt lgkmcnt(0)
	s_barrier
	s_waitcnt lgkmcnt(0)
	v_mfma_f32_32x32x16_bf16 v[16:31], v[90:93], v[154:157], v[16:31]
	v_lshl_add_u64 v[90:91], v[66:67], 0, s[30:31]
	global_load_lds_dwordx4 v[90:91], off
	v_lshl_add_u64 v[90:91], v[68:69], 0, s[30:31]
	s_mov_b32 m0, s45
	s_nop 0
	global_load_lds_dwordx4 v[90:91], off
	v_lshl_add_u64 v[90:91], v[70:71], 0, s[30:31]
	s_mov_b32 m0, s46
	v_mfma_f32_32x32x16_bf16 v[0:15], v[98:101], v[154:157], v[0:15]
	global_load_lds_dwordx4 v[90:91], off
	v_lshl_add_u64 v[90:91], v[72:73], 0, s[30:31]
	s_mov_b32 m0, s47
	s_nop 0
	global_load_lds_dwordx4 v[90:91], off
	v_lshl_add_u64 v[90:91], v[74:75], 0, s[30:31]
	s_mov_b32 m0, s48
	s_nop 0
	global_load_lds_dwordx4 v[90:91], off
	v_lshl_add_u64 v[90:91], v[76:77], 0, s[30:31]
	s_add_i32 s30, 0, 0xc000
	s_mov_b32 m0, s49
	v_add_u32_e32 v89, s30, v110
	global_load_lds_dwordx4 v[90:91], off
	v_add_u32_e32 v91, v89, v146
	v_add_u32_e32 v89, v89, v147
	ds_read_b128 v[92:95], v91
	ds_read_b128 v[96:99], v64 offset:49152
	ds_read_b128 v[100:103], v89
	ds_read_b128 v[150:153], v64 offset:53248
	s_waitcnt lgkmcnt(1)
	v_mfma_f32_32x32x16_bf16 v[48:63], v[92:95], v[96:99], v[48:63]
	v_add_u32_e32 v90, s30, v112
	s_mov_b32 m0, s38
	v_mfma_f32_32x32x16_bf16 v[32:47], v[100:103], v[96:99], v[32:47]
	s_waitcnt lgkmcnt(0)
	v_mfma_f32_32x32x16_bf16 v[16:31], v[92:95], v[150:153], v[16:31]
	v_add_u32_e32 v92, v90, v146
	v_add_u32_e32 v90, v90, v147
	v_add_u32_e32 v93, s30, v131
	v_mfma_f32_32x32x16_bf16 v[0:15], v[100:103], v[150:153], v[0:15]
	ds_read_b128 v[94:97], v92
	ds_read_b128 v[98:101], v83 offset:49152
	ds_read_b128 v[102:105], v90
	ds_read_b128 v[154:157], v83 offset:53248
	s_waitcnt lgkmcnt(1)
	v_mfma_f32_32x32x16_bf16 v[48:63], v[94:97], v[98:101], v[48:63]
	v_mfma_f32_32x32x16_bf16 v[32:47], v[102:105], v[98:101], v[32:47]
	s_waitcnt lgkmcnt(0)
	v_mfma_f32_32x32x16_bf16 v[16:31], v[94:97], v[154:157], v[16:31]
	v_add_u32_e32 v94, v93, v146
	v_add_u32_e32 v93, v93, v147
	v_add_u32_e32 v95, s30, v132
	s_mov_b64 s[30:31], 0x200
	v_mfma_f32_32x32x16_bf16 v[0:15], v[102:105], v[154:157], v[0:15]
	ds_read_b128 v[96:99], v94
	ds_read_b128 v[100:103], v86 offset:49152
	ds_read_b128 v[104:107], v93
	ds_read_b128 v[150:153], v86 offset:53248
	s_waitcnt lgkmcnt(1)
	v_mfma_f32_32x32x16_bf16 v[48:63], v[96:99], v[100:103], v[48:63]
	v_mfma_f32_32x32x16_bf16 v[32:47], v[104:107], v[100:103], v[32:47]
	s_waitcnt lgkmcnt(0)
	v_mfma_f32_32x32x16_bf16 v[16:31], v[96:99], v[150:153], v[16:31]
	v_add_u32_e32 v96, v95, v146
	v_add_u32_e32 v95, v95, v147
	v_add_u32_e32 v97, v138, v146
	v_mfma_f32_32x32x16_bf16 v[0:15], v[104:107], v[150:153], v[0:15]
	ds_read_b128 v[98:101], v96
	ds_read_b128 v[102:105], v88 offset:49152
	ds_read_b128 v[106:109], v95
	ds_read_b128 v[154:157], v88 offset:53248
	s_waitcnt lgkmcnt(1)
	v_mfma_f32_32x32x16_bf16 v[48:63], v[98:101], v[102:105], v[48:63]
	v_mfma_f32_32x32x16_bf16 v[32:47], v[106:109], v[102:105], v[32:47]
	s_waitcnt vmcnt(6)
	s_waitcnt lgkmcnt(0)
	s_barrier
	s_waitcnt lgkmcnt(0)
	v_mfma_f32_32x32x16_bf16 v[16:31], v[98:101], v[154:157], v[16:31]
	v_lshl_add_u64 v[98:99], v[66:67], 0, s[30:31]
	global_load_lds_dwordx4 v[98:99], off
	v_lshl_add_u64 v[98:99], v[68:69], 0, s[30:31]
	s_mov_b32 m0, s39
	s_nop 0
	global_load_lds_dwordx4 v[98:99], off
	v_lshl_add_u64 v[98:99], v[70:71], 0, s[30:31]
	s_mov_b32 m0, s40
	v_mfma_f32_32x32x16_bf16 v[0:15], v[106:109], v[154:157], v[0:15]
	global_load_lds_dwordx4 v[98:99], off
	v_lshl_add_u64 v[98:99], v[72:73], 0, s[30:31]
	s_mov_b32 m0, s41
	s_nop 0
	global_load_lds_dwordx4 v[98:99], off
	v_lshl_add_u64 v[98:99], v[74:75], 0, s[30:31]
	s_mov_b32 m0, s42
	s_nop 0
	global_load_lds_dwordx4 v[98:99], off
	v_lshl_add_u64 v[98:99], v[76:77], 0, s[30:31]
	s_mov_b32 m0, s43
	s_mov_b64 s[30:31], 0x280
	global_load_lds_dwordx4 v[98:99], off
	v_add_u32_e32 v98, v138, v147
	ds_read_b128 v[134:137], v97
	ds_read_b128 v[104:107], v98
	v_add_u32_e32 v99, v148, v110
	ds_read_b128 v[100:103], v99
	s_waitcnt lgkmcnt(0)
	v_mfma_f32_32x32x16_bf16 v[48:63], v[134:137], v[100:103], v[48:63]
	s_mov_b32 m0, s20
	v_mfma_f32_32x32x16_bf16 v[32:47], v[104:107], v[100:103], v[32:47]
	v_add_u32_e32 v100, v138, v149
	ds_read_b128 v[108:111], v100
	v_add_u32_e32 v101, v142, v146
	v_add_u32_e32 v102, v142, v147
	ds_read_b128 v[138:141], v102
	v_add_u32_e32 v103, v148, v112
	v_add_u32_e32 v112, s3, v131
	s_waitcnt lgkmcnt(0)
	v_mfma_f32_32x32x16_bf16 v[16:31], v[134:137], v[108:111], v[16:31]
	ds_read_b128 v[134:137], v103
	v_mfma_f32_32x32x16_bf16 v[0:15], v[104:107], v[108:111], v[0:15]
	ds_read_b128 v[106:109], v101
	v_add_u32_e32 v104, v142, v149
	v_add_u32_e32 v105, v112, v146
	ds_read_b128 v[150:153], v104
	s_waitcnt lgkmcnt(1)
	v_mfma_f32_32x32x16_bf16 v[48:63], v[106:109], v[134:137], v[48:63]
	v_mfma_f32_32x32x16_bf16 v[32:47], v[138:141], v[134:137], v[32:47]
	s_waitcnt lgkmcnt(0)
	v_mfma_f32_32x32x16_bf16 v[16:31], v[106:109], v[150:153], v[16:31]
	v_add_u32_e32 v106, v112, v147
	v_add_u32_e32 v107, v148, v131
	ds_read_b128 v[108:111], v107
	v_mfma_f32_32x32x16_bf16 v[0:15], v[138:141], v[150:153], v[0:15]
	ds_read_b128 v[134:137], v105
	ds_read_b128 v[138:141], v106
	s_waitcnt lgkmcnt(0)
	v_mfma_f32_32x32x16_bf16 v[48:63], v[134:137], v[108:111], v[48:63]
	v_mfma_f32_32x32x16_bf16 v[32:47], v[138:141], v[108:111], v[32:47]
	v_add_u32_e32 v108, v112, v149
	ds_read_b128 v[142:145], v108
	v_add_u32_e32 v112, s3, v132
	v_add_u32_e32 v109, v112, v146
	v_add_u32_e32 v110, v112, v147
	v_add_u32_e32 v111, v148, v132
	v_add_u32_e32 v112, v112, v149
	s_waitcnt lgkmcnt(0)
	v_mfma_f32_32x32x16_bf16 v[16:31], v[134:137], v[142:145], v[16:31]
	ds_read_b128 v[134:137], v109
	v_mfma_f32_32x32x16_bf16 v[0:15], v[138:141], v[142:145], v[0:15]
	ds_read_b128 v[142:145], v110
	ds_read_b128 v[138:141], v111
	ds_read_b128 v[154:157], v112
	s_waitcnt lgkmcnt(1)
	v_mfma_f32_32x32x16_bf16 v[48:63], v[134:137], v[138:141], v[48:63]
	v_mfma_f32_32x32x16_bf16 v[32:47], v[142:145], v[138:141], v[32:47]
	s_waitcnt vmcnt(6)
	s_waitcnt lgkmcnt(0)
	s_barrier
	s_waitcnt lgkmcnt(0)
	v_mfma_f32_32x32x16_bf16 v[16:31], v[134:137], v[154:157], v[16:31]
	v_lshl_add_u64 v[134:135], v[66:67], 0, s[30:31]
	global_load_lds_dwordx4 v[134:135], off
	v_lshl_add_u64 v[134:135], v[68:69], 0, s[30:31]
	s_mov_b32 m0, s21
	s_nop 0
	global_load_lds_dwordx4 v[134:135], off
	v_lshl_add_u64 v[134:135], v[70:71], 0, s[30:31]
	s_mov_b32 m0, s34
	v_mfma_f32_32x32x16_bf16 v[0:15], v[142:145], v[154:157], v[0:15]
	global_load_lds_dwordx4 v[134:135], off
	v_lshl_add_u64 v[134:135], v[72:73], 0, s[30:31]
	s_mov_b32 m0, s35
	s_nop 0
	global_load_lds_dwordx4 v[134:135], off
	v_lshl_add_u64 v[134:135], v[74:75], 0, s[30:31]
	s_mov_b32 m0, s36
	s_nop 0
	global_load_lds_dwordx4 v[134:135], off
	v_lshl_add_u64 v[134:135], v[76:77], 0, s[30:31]
	s_mov_b32 m0, s37
	s_mov_b64 s[30:31], 0x300
	global_load_lds_dwordx4 v[134:135], off
	ds_read_b128 v[134:137], v82 offset:32768
	ds_read_b128 v[138:141], v64
	ds_read_b128 v[142:145], v82 offset:36864
	ds_read_b128 v[150:153], v64 offset:4096
	s_waitcnt lgkmcnt(1)
	v_mfma_f32_32x32x16_bf16 v[48:63], v[134:137], v[138:141], v[48:63]
	s_mov_b32 m0, s44
	v_readfirstlane_b32 s44, v113
	v_mfma_f32_32x32x16_bf16 v[32:47], v[142:145], v[138:141], v[32:47]
	s_waitcnt lgkmcnt(0)
	v_mfma_f32_32x32x16_bf16 v[16:31], v[134:137], v[150:153], v[16:31]
	v_mfma_f32_32x32x16_bf16 v[0:15], v[142:145], v[150:153], v[0:15]
	ds_read_b128 v[134:137], v84 offset:32768
	ds_read_b128 v[138:141], v83
	ds_read_b128 v[142:145], v84 offset:36864
	ds_read_b128 v[154:157], v83 offset:4096
	s_waitcnt lgkmcnt(1)
	v_mfma_f32_32x32x16_bf16 v[48:63], v[134:137], v[138:141], v[48:63]
	v_mfma_f32_32x32x16_bf16 v[32:47], v[142:145], v[138:141], v[32:47]
	s_waitcnt lgkmcnt(0)
	v_mfma_f32_32x32x16_bf16 v[16:31], v[134:137], v[154:157], v[16:31]
	v_mfma_f32_32x32x16_bf16 v[0:15], v[142:145], v[154:157], v[0:15]
	ds_read_b128 v[134:137], v87 offset:32768
	ds_read_b128 v[138:141], v86
	ds_read_b128 v[142:145], v87 offset:36864
	ds_read_b128 v[150:153], v86 offset:4096
	s_waitcnt lgkmcnt(1)
	v_mfma_f32_32x32x16_bf16 v[48:63], v[134:137], v[138:141], v[48:63]
	v_mfma_f32_32x32x16_bf16 v[32:47], v[142:145], v[138:141], v[32:47]
	s_waitcnt lgkmcnt(0)
	v_mfma_f32_32x32x16_bf16 v[16:31], v[134:137], v[150:153], v[16:31]
	v_mfma_f32_32x32x16_bf16 v[0:15], v[142:145], v[150:153], v[0:15]
	ds_read_b128 v[134:137], v85 offset:32768
	ds_read_b128 v[138:141], v88
	ds_read_b128 v[142:145], v85 offset:36864
	ds_read_b128 v[154:157], v88 offset:4096
	s_waitcnt lgkmcnt(1)
	v_mfma_f32_32x32x16_bf16 v[48:63], v[134:137], v[138:141], v[48:63]
	v_mfma_f32_32x32x16_bf16 v[32:47], v[142:145], v[138:141], v[32:47]
	s_waitcnt vmcnt(6)
	s_waitcnt lgkmcnt(0)
	s_barrier
	s_waitcnt lgkmcnt(0)
	v_mfma_f32_32x32x16_bf16 v[16:31], v[134:137], v[154:157], v[16:31]
	v_lshl_add_u64 v[134:135], v[66:67], 0, s[30:31]
	global_load_lds_dwordx4 v[134:135], off
	v_lshl_add_u64 v[134:135], v[68:69], 0, s[30:31]
	s_mov_b32 m0, s45
	v_readfirstlane_b32 s45, v114
	global_load_lds_dwordx4 v[134:135], off
	v_lshl_add_u64 v[134:135], v[70:71], 0, s[30:31]
	s_mov_b32 m0, s46
	v_mfma_f32_32x32x16_bf16 v[0:15], v[142:145], v[154:157], v[0:15]
	global_load_lds_dwordx4 v[134:135], off
	v_lshl_add_u64 v[134:135], v[72:73], 0, s[30:31]
	s_mov_b32 m0, s47
	v_readfirstlane_b32 s46, v115
	global_load_lds_dwordx4 v[134:135], off
	v_lshl_add_u64 v[134:135], v[74:75], 0, s[30:31]
	s_mov_b32 m0, s48
	v_readfirstlane_b32 s47, v116
	global_load_lds_dwordx4 v[134:135], off
	v_lshl_add_u64 v[134:135], v[76:77], 0, s[30:31]
	s_mov_b32 m0, s49
	s_mov_b64 s[30:31], 0x380
	global_load_lds_dwordx4 v[134:135], off
	ds_read_b128 v[134:137], v91
	ds_read_b128 v[138:141], v64 offset:49152
	ds_read_b128 v[142:145], v89
	ds_read_b128 v[150:153], v64 offset:53248
	s_waitcnt lgkmcnt(1)
	v_mfma_f32_32x32x16_bf16 v[48:63], v[134:137], v[138:141], v[48:63]
	s_mov_b32 m0, s38
	v_readfirstlane_b32 s38, v119
	v_readfirstlane_b32 s48, v117
	v_readfirstlane_b32 s49, v118
	v_mfma_f32_32x32x16_bf16 v[32:47], v[142:145], v[138:141], v[32:47]
	s_waitcnt lgkmcnt(0)
	v_mfma_f32_32x32x16_bf16 v[16:31], v[134:137], v[150:153], v[16:31]
	v_mfma_f32_32x32x16_bf16 v[0:15], v[142:145], v[150:153], v[0:15]
	ds_read_b128 v[134:137], v92
	ds_read_b128 v[138:141], v83 offset:49152
	ds_read_b128 v[142:145], v90
	ds_read_b128 v[154:157], v83 offset:53248
	s_waitcnt lgkmcnt(1)
	v_mfma_f32_32x32x16_bf16 v[48:63], v[134:137], v[138:141], v[48:63]
	v_mfma_f32_32x32x16_bf16 v[32:47], v[142:145], v[138:141], v[32:47]
	s_waitcnt lgkmcnt(0)
	v_mfma_f32_32x32x16_bf16 v[16:31], v[134:137], v[154:157], v[16:31]
	v_mfma_f32_32x32x16_bf16 v[0:15], v[142:145], v[154:157], v[0:15]
	ds_read_b128 v[134:137], v94
	ds_read_b128 v[138:141], v86 offset:49152
	ds_read_b128 v[142:145], v93
	ds_read_b128 v[150:153], v86 offset:53248
	s_waitcnt lgkmcnt(1)
	v_mfma_f32_32x32x16_bf16 v[48:63], v[134:137], v[138:141], v[48:63]
	v_mfma_f32_32x32x16_bf16 v[32:47], v[142:145], v[138:141], v[32:47]
	s_waitcnt lgkmcnt(0)
	v_mfma_f32_32x32x16_bf16 v[16:31], v[134:137], v[150:153], v[16:31]
	v_mfma_f32_32x32x16_bf16 v[0:15], v[142:145], v[150:153], v[0:15]
	ds_read_b128 v[134:137], v96
	ds_read_b128 v[138:141], v88 offset:49152
	ds_read_b128 v[142:145], v95
	ds_read_b128 v[154:157], v88 offset:53248
	s_waitcnt lgkmcnt(1)
	v_mfma_f32_32x32x16_bf16 v[48:63], v[134:137], v[138:141], v[48:63]
	v_mfma_f32_32x32x16_bf16 v[32:47], v[142:145], v[138:141], v[32:47]
	s_waitcnt vmcnt(6)
	s_waitcnt lgkmcnt(0)
	s_barrier
	s_waitcnt lgkmcnt(0)
	v_mfma_f32_32x32x16_bf16 v[16:31], v[134:137], v[154:157], v[16:31]
	v_lshl_add_u64 v[134:135], v[66:67], 0, s[30:31]
	global_load_lds_dwordx4 v[134:135], off
	v_lshl_add_u64 v[134:135], v[68:69], 0, s[30:31]
	s_mov_b32 m0, s39
	v_readfirstlane_b32 s39, v120
	global_load_lds_dwordx4 v[134:135], off
	v_lshl_add_u64 v[134:135], v[70:71], 0, s[30:31]
	s_mov_b32 m0, s40
	v_mfma_f32_32x32x16_bf16 v[0:15], v[142:145], v[154:157], v[0:15]
	global_load_lds_dwordx4 v[134:135], off
	v_lshl_add_u64 v[134:135], v[72:73], 0, s[30:31]
	s_mov_b32 m0, s41
	v_readfirstlane_b32 s40, v121
	global_load_lds_dwordx4 v[134:135], off
	v_lshl_add_u64 v[134:135], v[74:75], 0, s[30:31]
	s_mov_b32 m0, s42
	v_readfirstlane_b32 s41, v122
	global_load_lds_dwordx4 v[134:135], off
	v_lshl_add_u64 v[134:135], v[76:77], 0, s[30:31]
	s_mov_b32 m0, s43
	s_mov_b64 s[30:31], 0x400
	global_load_lds_dwordx4 v[134:135], off
	ds_read_b128 v[134:137], v97
	ds_read_b128 v[138:141], v99
	ds_read_b128 v[142:145], v98
	ds_read_b128 v[150:153], v100
	s_waitcnt lgkmcnt(1)
	v_mfma_f32_32x32x16_bf16 v[48:63], v[134:137], v[138:141], v[48:63]
	s_mov_b32 m0, s20
	v_readfirstlane_b32 s20, v125
	v_readfirstlane_b32 s42, v123
	v_readfirstlane_b32 s43, v124
	v_mfma_f32_32x32x16_bf16 v[32:47], v[142:145], v[138:141], v[32:47]
	s_waitcnt lgkmcnt(0)
	v_mfma_f32_32x32x16_bf16 v[16:31], v[134:137], v[150:153], v[16:31]
	v_mfma_f32_32x32x16_bf16 v[0:15], v[142:145], v[150:153], v[0:15]
	ds_read_b128 v[134:137], v101
	ds_read_b128 v[138:141], v103
	ds_read_b128 v[142:145], v102
	ds_read_b128 v[154:157], v104
	s_waitcnt lgkmcnt(1)
	v_mfma_f32_32x32x16_bf16 v[48:63], v[134:137], v[138:141], v[48:63]
	v_mfma_f32_32x32x16_bf16 v[32:47], v[142:145], v[138:141], v[32:47]
	s_waitcnt lgkmcnt(0)
	v_mfma_f32_32x32x16_bf16 v[16:31], v[134:137], v[154:157], v[16:31]
	v_mfma_f32_32x32x16_bf16 v[0:15], v[142:145], v[154:157], v[0:15]
	ds_read_b128 v[134:137], v105
	ds_read_b128 v[138:141], v107
	ds_read_b128 v[142:145], v106
	ds_read_b128 v[150:153], v108
	s_waitcnt lgkmcnt(1)
	v_mfma_f32_32x32x16_bf16 v[48:63], v[134:137], v[138:141], v[48:63]
	v_mfma_f32_32x32x16_bf16 v[32:47], v[142:145], v[138:141], v[32:47]
	s_waitcnt lgkmcnt(0)
	v_mfma_f32_32x32x16_bf16 v[16:31], v[134:137], v[150:153], v[16:31]
	v_mfma_f32_32x32x16_bf16 v[0:15], v[142:145], v[150:153], v[0:15]
	ds_read_b128 v[134:137], v109
	ds_read_b128 v[138:141], v111
	ds_read_b128 v[142:145], v110
	ds_read_b128 v[154:157], v112
	s_waitcnt lgkmcnt(1)
	v_mfma_f32_32x32x16_bf16 v[48:63], v[134:137], v[138:141], v[48:63]
	v_mfma_f32_32x32x16_bf16 v[32:47], v[142:145], v[138:141], v[32:47]
	s_waitcnt vmcnt(6)
	s_waitcnt lgkmcnt(0)
	s_barrier
	s_waitcnt lgkmcnt(0)
	v_mfma_f32_32x32x16_bf16 v[16:31], v[134:137], v[154:157], v[16:31]
	v_lshl_add_u64 v[134:135], v[66:67], 0, s[30:31]
	global_load_lds_dwordx4 v[134:135], off
	v_lshl_add_u64 v[134:135], v[68:69], 0, s[30:31]
	s_mov_b32 m0, s21
	v_readfirstlane_b32 s21, v126
	global_load_lds_dwordx4 v[134:135], off
	v_lshl_add_u64 v[134:135], v[70:71], 0, s[30:31]
	s_mov_b32 m0, s34
	v_mfma_f32_32x32x16_bf16 v[0:15], v[142:145], v[154:157], v[0:15]
	global_load_lds_dwordx4 v[134:135], off
	v_lshl_add_u64 v[134:135], v[72:73], 0, s[30:31]
	s_mov_b32 m0, s35
	v_readfirstlane_b32 s34, v127
	global_load_lds_dwordx4 v[134:135], off
	v_lshl_add_u64 v[134:135], v[74:75], 0, s[30:31]
	s_mov_b32 m0, s36
	v_readfirstlane_b32 s35, v128
	global_load_lds_dwordx4 v[134:135], off
	v_lshl_add_u64 v[134:135], v[76:77], 0, s[30:31]
	s_mov_b32 m0, s37
	s_mov_b64 s[30:31], 0x480
	global_load_lds_dwordx4 v[134:135], off
	ds_read_b128 v[134:137], v82 offset:32768
	ds_read_b128 v[138:141], v64
	ds_read_b128 v[142:145], v82 offset:36864
	ds_read_b128 v[150:153], v64 offset:4096
	s_waitcnt lgkmcnt(1)
	v_mfma_f32_32x32x16_bf16 v[48:63], v[134:137], v[138:141], v[48:63]
	s_mov_b32 m0, s20
	v_lshl_add_u64 v[126:127], v[72:73], 0, s[30:31]
	v_readfirstlane_b32 s36, v130
	v_readfirstlane_b32 s37, v129
	v_mfma_f32_32x32x16_bf16 v[32:47], v[142:145], v[138:141], v[32:47]
	s_waitcnt lgkmcnt(0)
	v_mfma_f32_32x32x16_bf16 v[16:31], v[134:137], v[150:153], v[16:31]
	v_mfma_f32_32x32x16_bf16 v[0:15], v[142:145], v[150:153], v[0:15]
	ds_read_b128 v[134:137], v84 offset:32768
	ds_read_b128 v[138:141], v83
	ds_read_b128 v[142:145], v84 offset:36864
	ds_read_b128 v[154:157], v83 offset:4096
	s_waitcnt lgkmcnt(1)
	v_mfma_f32_32x32x16_bf16 v[48:63], v[134:137], v[138:141], v[48:63]
	v_mfma_f32_32x32x16_bf16 v[32:47], v[142:145], v[138:141], v[32:47]
	s_waitcnt lgkmcnt(0)
	v_mfma_f32_32x32x16_bf16 v[16:31], v[134:137], v[154:157], v[16:31]
	v_mfma_f32_32x32x16_bf16 v[0:15], v[142:145], v[154:157], v[0:15]
	ds_read_b128 v[134:137], v87 offset:32768
	ds_read_b128 v[138:141], v86
	ds_read_b128 v[142:145], v87 offset:36864
	ds_read_b128 v[150:153], v86 offset:4096
	s_waitcnt lgkmcnt(1)
	v_mfma_f32_32x32x16_bf16 v[48:63], v[134:137], v[138:141], v[48:63]
	v_mfma_f32_32x32x16_bf16 v[32:47], v[142:145], v[138:141], v[32:47]
	s_waitcnt lgkmcnt(0)
	v_mfma_f32_32x32x16_bf16 v[16:31], v[134:137], v[150:153], v[16:31]
	v_mfma_f32_32x32x16_bf16 v[0:15], v[142:145], v[150:153], v[0:15]
	ds_read_b128 v[134:137], v85 offset:32768
	ds_read_b128 v[138:141], v88
	ds_read_b128 v[142:145], v85 offset:36864
	ds_read_b128 v[154:157], v88 offset:4096
	s_waitcnt lgkmcnt(1)
	v_mfma_f32_32x32x16_bf16 v[48:63], v[134:137], v[138:141], v[48:63]
	v_mfma_f32_32x32x16_bf16 v[32:47], v[142:145], v[138:141], v[32:47]
	s_waitcnt vmcnt(6)
	s_waitcnt lgkmcnt(0)
	s_barrier
	s_waitcnt lgkmcnt(0)
	v_mfma_f32_32x32x16_bf16 v[16:31], v[134:137], v[154:157], v[16:31]
	v_lshl_add_u64 v[134:135], v[66:67], 0, s[30:31]
	global_load_lds_dwordx4 v[134:135], off
	v_lshl_add_u64 v[134:135], v[68:69], 0, s[30:31]
	s_mov_b32 m0, s21
	s_nop 0
	global_load_lds_dwordx4 v[134:135], off
	v_lshl_add_u64 v[134:135], v[70:71], 0, s[30:31]
	s_mov_b32 m0, s34
	v_mfma_f32_32x32x16_bf16 v[0:15], v[142:145], v[154:157], v[0:15]
	global_load_lds_dwordx4 v[134:135], off
	s_mov_b32 m0, s35
	s_nop 0
	global_load_lds_dwordx4 v[126:127], off
	v_lshl_add_u64 v[126:127], v[74:75], 0, s[30:31]
	s_mov_b32 m0, s36
	s_nop 0
	global_load_lds_dwordx4 v[126:127], off
	v_lshl_add_u64 v[126:127], v[76:77], 0, s[30:31]
	s_mov_b32 m0, s37
	s_mov_b64 s[30:31], 0x500
	global_load_lds_dwordx4 v[126:127], off
	ds_read_b128 v[126:129], v91
	ds_read_b128 v[134:137], v64 offset:49152
	ds_read_b128 v[138:141], v89
	ds_read_b128 v[150:153], v64 offset:53248
	s_waitcnt lgkmcnt(1)
	v_mfma_f32_32x32x16_bf16 v[48:63], v[126:129], v[134:137], v[48:63]
	s_mov_b32 m0, s38
	v_lshl_add_u64 v[120:121], v[72:73], 0, s[30:31]
	v_mfma_f32_32x32x16_bf16 v[32:47], v[138:141], v[134:137], v[32:47]
	s_waitcnt lgkmcnt(0)
	v_mfma_f32_32x32x16_bf16 v[16:31], v[126:129], v[150:153], v[16:31]
	v_mfma_f32_32x32x16_bf16 v[0:15], v[138:141], v[150:153], v[0:15]
	ds_read_b128 v[126:129], v92
	ds_read_b128 v[134:137], v83 offset:49152
	ds_read_b128 v[138:141], v90
	ds_read_b128 v[154:157], v83 offset:53248
	s_waitcnt lgkmcnt(1)
	v_mfma_f32_32x32x16_bf16 v[48:63], v[126:129], v[134:137], v[48:63]
	v_mfma_f32_32x32x16_bf16 v[32:47], v[138:141], v[134:137], v[32:47]
	s_waitcnt lgkmcnt(0)
	v_mfma_f32_32x32x16_bf16 v[16:31], v[126:129], v[154:157], v[16:31]
	v_mfma_f32_32x32x16_bf16 v[0:15], v[138:141], v[154:157], v[0:15]
	ds_read_b128 v[126:129], v94
	ds_read_b128 v[134:137], v86 offset:49152
	ds_read_b128 v[138:141], v93
	ds_read_b128 v[150:153], v86 offset:53248
	s_waitcnt lgkmcnt(1)
	v_mfma_f32_32x32x16_bf16 v[48:63], v[126:129], v[134:137], v[48:63]
	v_mfma_f32_32x32x16_bf16 v[32:47], v[138:141], v[134:137], v[32:47]
	s_waitcnt lgkmcnt(0)
	v_mfma_f32_32x32x16_bf16 v[16:31], v[126:129], v[150:153], v[16:31]
	v_mfma_f32_32x32x16_bf16 v[0:15], v[138:141], v[150:153], v[0:15]
	ds_read_b128 v[126:129], v96
	ds_read_b128 v[134:137], v88 offset:49152
	ds_read_b128 v[138:141], v95
	ds_read_b128 v[154:157], v88 offset:53248
	s_waitcnt lgkmcnt(1)
	v_mfma_f32_32x32x16_bf16 v[48:63], v[126:129], v[134:137], v[48:63]
	v_mfma_f32_32x32x16_bf16 v[32:47], v[138:141], v[134:137], v[32:47]
	s_waitcnt vmcnt(6)
	s_waitcnt lgkmcnt(0)
	s_barrier
	s_waitcnt lgkmcnt(0)
	v_mfma_f32_32x32x16_bf16 v[16:31], v[126:129], v[154:157], v[16:31]
	v_lshl_add_u64 v[126:127], v[66:67], 0, s[30:31]
	global_load_lds_dwordx4 v[126:127], off
	v_lshl_add_u64 v[126:127], v[68:69], 0, s[30:31]
	s_mov_b32 m0, s39
	s_nop 0
	global_load_lds_dwordx4 v[126:127], off
	v_lshl_add_u64 v[126:127], v[70:71], 0, s[30:31]
	s_mov_b32 m0, s40
	v_mfma_f32_32x32x16_bf16 v[0:15], v[138:141], v[154:157], v[0:15]
	global_load_lds_dwordx4 v[126:127], off
	s_mov_b32 m0, s41
	s_nop 0
	global_load_lds_dwordx4 v[120:121], off
	v_lshl_add_u64 v[120:121], v[74:75], 0, s[30:31]
	s_mov_b32 m0, s42
	s_nop 0
	global_load_lds_dwordx4 v[120:121], off
	v_lshl_add_u64 v[120:121], v[76:77], 0, s[30:31]
	s_mov_b32 m0, s43
	s_mov_b64 s[30:31], 0x580
	global_load_lds_dwordx4 v[120:121], off
	ds_read_b128 v[120:123], v97
	ds_read_b128 v[124:127], v99
	ds_read_b128 v[128:131], v98
	ds_read_b128 v[150:153], v100
	s_waitcnt lgkmcnt(1)
	v_mfma_f32_32x32x16_bf16 v[48:63], v[120:123], v[124:127], v[48:63]
	s_mov_b32 m0, s44
	v_lshl_add_u64 v[114:115], v[72:73], 0, s[30:31]
	v_mfma_f32_32x32x16_bf16 v[32:47], v[128:131], v[124:127], v[32:47]
	s_waitcnt lgkmcnt(0)
	v_mfma_f32_32x32x16_bf16 v[16:31], v[120:123], v[150:153], v[16:31]
	v_mfma_f32_32x32x16_bf16 v[0:15], v[128:131], v[150:153], v[0:15]
	ds_read_b128 v[120:123], v101
	ds_read_b128 v[124:127], v103
	ds_read_b128 v[128:131], v102
	ds_read_b128 v[154:157], v104
	s_waitcnt lgkmcnt(1)
	v_mfma_f32_32x32x16_bf16 v[48:63], v[120:123], v[124:127], v[48:63]
	v_mfma_f32_32x32x16_bf16 v[32:47], v[128:131], v[124:127], v[32:47]
	s_waitcnt lgkmcnt(0)
	v_mfma_f32_32x32x16_bf16 v[16:31], v[120:123], v[154:157], v[16:31]
	v_mfma_f32_32x32x16_bf16 v[0:15], v[128:131], v[154:157], v[0:15]
	ds_read_b128 v[120:123], v105
	ds_read_b128 v[124:127], v107
	ds_read_b128 v[128:131], v106
	ds_read_b128 v[150:153], v108
	s_waitcnt lgkmcnt(1)
	v_mfma_f32_32x32x16_bf16 v[48:63], v[120:123], v[124:127], v[48:63]
	v_mfma_f32_32x32x16_bf16 v[32:47], v[128:131], v[124:127], v[32:47]
	s_waitcnt lgkmcnt(0)
	v_mfma_f32_32x32x16_bf16 v[16:31], v[120:123], v[150:153], v[16:31]
	v_mfma_f32_32x32x16_bf16 v[0:15], v[128:131], v[150:153], v[0:15]
	ds_read_b128 v[120:123], v109
	ds_read_b128 v[124:127], v111
	ds_read_b128 v[128:131], v110
	ds_read_b128 v[154:157], v112
	s_waitcnt lgkmcnt(1)
	v_mfma_f32_32x32x16_bf16 v[48:63], v[120:123], v[124:127], v[48:63]
	v_mfma_f32_32x32x16_bf16 v[32:47], v[128:131], v[124:127], v[32:47]
	s_waitcnt vmcnt(6)
	s_waitcnt lgkmcnt(0)
	s_barrier
	s_waitcnt lgkmcnt(0)
	v_mfma_f32_32x32x16_bf16 v[16:31], v[120:123], v[154:157], v[16:31]
	v_lshl_add_u64 v[120:121], v[66:67], 0, s[30:31]
	global_load_lds_dwordx4 v[120:121], off
	v_lshl_add_u64 v[120:121], v[68:69], 0, s[30:31]
	s_mov_b32 m0, s45
	s_nop 0
	global_load_lds_dwordx4 v[120:121], off
	v_lshl_add_u64 v[120:121], v[70:71], 0, s[30:31]
	s_mov_b32 m0, s46
	v_mfma_f32_32x32x16_bf16 v[0:15], v[128:131], v[154:157], v[0:15]
	global_load_lds_dwordx4 v[120:121], off
	s_mov_b32 m0, s47
	s_nop 0
	global_load_lds_dwordx4 v[114:115], off
	v_lshl_add_u64 v[114:115], v[74:75], 0, s[30:31]
	s_mov_b32 m0, s48
	s_nop 0
	global_load_lds_dwordx4 v[114:115], off
	v_lshl_add_u64 v[114:115], v[76:77], 0, s[30:31]
	s_mov_b32 m0, s49
	s_mov_b64 s[30:31], 0x600
	global_load_lds_dwordx4 v[114:115], off
	ds_read_b128 v[114:117], v82 offset:32768
	ds_read_b128 v[118:121], v64
	ds_read_b128 v[122:125], v82 offset:36864
	ds_read_b128 v[150:153], v64 offset:4096
	s_waitcnt lgkmcnt(1)
	v_mfma_f32_32x32x16_bf16 v[48:63], v[114:117], v[118:121], v[48:63]
	s_mov_b32 m0, s20
	v_mfma_f32_32x32x16_bf16 v[32:47], v[122:125], v[118:121], v[32:47]
	s_waitcnt lgkmcnt(0)
	v_mfma_f32_32x32x16_bf16 v[16:31], v[114:117], v[150:153], v[16:31]
	v_mfma_f32_32x32x16_bf16 v[0:15], v[122:125], v[150:153], v[0:15]
	ds_read_b128 v[114:117], v84 offset:32768
	ds_read_b128 v[118:121], v83
	ds_read_b128 v[122:125], v84 offset:36864
	ds_read_b128 v[154:157], v83 offset:4096
	s_waitcnt lgkmcnt(1)
	v_mfma_f32_32x32x16_bf16 v[48:63], v[114:117], v[118:121], v[48:63]
	v_mfma_f32_32x32x16_bf16 v[32:47], v[122:125], v[118:121], v[32:47]
	s_waitcnt lgkmcnt(0)
	v_mfma_f32_32x32x16_bf16 v[16:31], v[114:117], v[154:157], v[16:31]
	v_mfma_f32_32x32x16_bf16 v[0:15], v[122:125], v[154:157], v[0:15]
	ds_read_b128 v[114:117], v87 offset:32768
	ds_read_b128 v[118:121], v86
	ds_read_b128 v[122:125], v87 offset:36864
	ds_read_b128 v[150:153], v86 offset:4096
	s_waitcnt lgkmcnt(1)
	v_mfma_f32_32x32x16_bf16 v[48:63], v[114:117], v[118:121], v[48:63]
	v_mfma_f32_32x32x16_bf16 v[32:47], v[122:125], v[118:121], v[32:47]
	s_waitcnt lgkmcnt(0)
	v_mfma_f32_32x32x16_bf16 v[16:31], v[114:117], v[150:153], v[16:31]
	v_mfma_f32_32x32x16_bf16 v[0:15], v[122:125], v[150:153], v[0:15]
	ds_read_b128 v[114:117], v85 offset:32768
	ds_read_b128 v[118:121], v88
	ds_read_b128 v[122:125], v85 offset:36864
	ds_read_b128 v[154:157], v88 offset:4096
	s_waitcnt lgkmcnt(1)
	v_mfma_f32_32x32x16_bf16 v[48:63], v[114:117], v[118:121], v[48:63]
	v_mfma_f32_32x32x16_bf16 v[32:47], v[122:125], v[118:121], v[32:47]
	s_waitcnt vmcnt(6)
	s_waitcnt lgkmcnt(0)
	s_barrier
	s_waitcnt lgkmcnt(0)
	v_mfma_f32_32x32x16_bf16 v[16:31], v[114:117], v[154:157], v[16:31]
	v_lshl_add_u64 v[114:115], v[66:67], 0, s[30:31]
	global_load_lds_dwordx4 v[114:115], off
	v_lshl_add_u64 v[114:115], v[68:69], 0, s[30:31]
	s_mov_b32 m0, s21
	s_nop 0
	global_load_lds_dwordx4 v[114:115], off
	v_lshl_add_u64 v[114:115], v[70:71], 0, s[30:31]
	s_mov_b32 m0, s34
	v_mfma_f32_32x32x16_bf16 v[0:15], v[122:125], v[154:157], v[0:15]
	global_load_lds_dwordx4 v[114:115], off
	v_lshl_add_u64 v[114:115], v[72:73], 0, s[30:31]
	s_mov_b32 m0, s35
	s_nop 0
	global_load_lds_dwordx4 v[114:115], off
	v_lshl_add_u64 v[114:115], v[74:75], 0, s[30:31]
	s_mov_b32 m0, s36
	s_nop 0
	global_load_lds_dwordx4 v[114:115], off
	v_lshl_add_u64 v[114:115], v[76:77], 0, s[30:31]
	s_mov_b32 m0, s37
	s_mov_b64 s[30:31], 0x680
	global_load_lds_dwordx4 v[114:115], off
	ds_read_b128 v[114:117], v91
	ds_read_b128 v[118:121], v64 offset:49152
	ds_read_b128 v[122:125], v89
	ds_read_b128 v[150:153], v64 offset:53248
	s_waitcnt lgkmcnt(1)
	v_mfma_f32_32x32x16_bf16 v[48:63], v[114:117], v[118:121], v[48:63]
	s_mov_b32 m0, s38
	v_mfma_f32_32x32x16_bf16 v[32:47], v[122:125], v[118:121], v[32:47]
	s_waitcnt lgkmcnt(0)
	v_mfma_f32_32x32x16_bf16 v[16:31], v[114:117], v[150:153], v[16:31]
	v_mfma_f32_32x32x16_bf16 v[0:15], v[122:125], v[150:153], v[0:15]
	ds_read_b128 v[114:117], v92
	ds_read_b128 v[118:121], v83 offset:49152
	ds_read_b128 v[122:125], v90
	ds_read_b128 v[154:157], v83 offset:53248
	s_waitcnt lgkmcnt(1)
	v_mfma_f32_32x32x16_bf16 v[48:63], v[114:117], v[118:121], v[48:63]
	v_mfma_f32_32x32x16_bf16 v[32:47], v[122:125], v[118:121], v[32:47]
	s_waitcnt lgkmcnt(0)
	v_mfma_f32_32x32x16_bf16 v[16:31], v[114:117], v[154:157], v[16:31]
	v_mfma_f32_32x32x16_bf16 v[0:15], v[122:125], v[154:157], v[0:15]
	ds_read_b128 v[114:117], v94
	ds_read_b128 v[118:121], v86 offset:49152
	ds_read_b128 v[122:125], v93
	ds_read_b128 v[150:153], v86 offset:53248
	s_waitcnt lgkmcnt(1)
	v_mfma_f32_32x32x16_bf16 v[48:63], v[114:117], v[118:121], v[48:63]
	v_mfma_f32_32x32x16_bf16 v[32:47], v[122:125], v[118:121], v[32:47]
	s_waitcnt lgkmcnt(0)
	v_mfma_f32_32x32x16_bf16 v[16:31], v[114:117], v[150:153], v[16:31]
	v_mfma_f32_32x32x16_bf16 v[0:15], v[122:125], v[150:153], v[0:15]
	ds_read_b128 v[114:117], v96
	ds_read_b128 v[118:121], v88 offset:49152
	ds_read_b128 v[122:125], v95
	ds_read_b128 v[154:157], v88 offset:53248
	s_waitcnt lgkmcnt(1)
	v_mfma_f32_32x32x16_bf16 v[48:63], v[114:117], v[118:121], v[48:63]
	v_mfma_f32_32x32x16_bf16 v[32:47], v[122:125], v[118:121], v[32:47]
	s_waitcnt vmcnt(6)
	s_waitcnt lgkmcnt(0)
	s_barrier
	s_waitcnt lgkmcnt(0)
	v_mfma_f32_32x32x16_bf16 v[16:31], v[114:117], v[154:157], v[16:31]
	v_lshl_add_u64 v[114:115], v[66:67], 0, s[30:31]
	global_load_lds_dwordx4 v[114:115], off
	v_lshl_add_u64 v[114:115], v[68:69], 0, s[30:31]
	s_mov_b32 m0, s39
	s_nop 0
	global_load_lds_dwordx4 v[114:115], off
	v_lshl_add_u64 v[114:115], v[70:71], 0, s[30:31]
	s_mov_b32 m0, s40
	v_mfma_f32_32x32x16_bf16 v[0:15], v[122:125], v[154:157], v[0:15]
	global_load_lds_dwordx4 v[114:115], off
	v_lshl_add_u64 v[114:115], v[72:73], 0, s[30:31]
	s_mov_b32 m0, s41
	s_nop 0
	global_load_lds_dwordx4 v[114:115], off
	v_lshl_add_u64 v[114:115], v[74:75], 0, s[30:31]
	s_mov_b32 m0, s42
	s_nop 0
	global_load_lds_dwordx4 v[114:115], off
	v_lshl_add_u64 v[114:115], v[76:77], 0, s[30:31]
	s_mov_b32 m0, s43
	s_mov_b64 s[30:31], 0x700
	global_load_lds_dwordx4 v[114:115], off
	ds_read_b128 v[114:117], v97
	ds_read_b128 v[118:121], v99
	ds_read_b128 v[122:125], v98
	ds_read_b128 v[150:153], v100
	s_waitcnt lgkmcnt(1)
	v_mfma_f32_32x32x16_bf16 v[48:63], v[114:117], v[118:121], v[48:63]
	s_mov_b32 m0, s44
	v_mfma_f32_32x32x16_bf16 v[32:47], v[122:125], v[118:121], v[32:47]
	s_waitcnt lgkmcnt(0)
	v_mfma_f32_32x32x16_bf16 v[16:31], v[114:117], v[150:153], v[16:31]
	v_mfma_f32_32x32x16_bf16 v[0:15], v[122:125], v[150:153], v[0:15]
	ds_read_b128 v[114:117], v101
	ds_read_b128 v[118:121], v103
	ds_read_b128 v[122:125], v102
	ds_read_b128 v[154:157], v104
	s_waitcnt lgkmcnt(1)
	v_mfma_f32_32x32x16_bf16 v[48:63], v[114:117], v[118:121], v[48:63]
	v_mfma_f32_32x32x16_bf16 v[32:47], v[122:125], v[118:121], v[32:47]
	s_waitcnt lgkmcnt(0)
	v_mfma_f32_32x32x16_bf16 v[16:31], v[114:117], v[154:157], v[16:31]
	v_mfma_f32_32x32x16_bf16 v[0:15], v[122:125], v[154:157], v[0:15]
	ds_read_b128 v[114:117], v105
	ds_read_b128 v[118:121], v107
	ds_read_b128 v[122:125], v106
	ds_read_b128 v[150:153], v108
	s_waitcnt lgkmcnt(1)
	v_mfma_f32_32x32x16_bf16 v[48:63], v[114:117], v[118:121], v[48:63]
	v_mfma_f32_32x32x16_bf16 v[32:47], v[122:125], v[118:121], v[32:47]
	s_waitcnt lgkmcnt(0)
	v_mfma_f32_32x32x16_bf16 v[16:31], v[114:117], v[150:153], v[16:31]
	v_mfma_f32_32x32x16_bf16 v[0:15], v[122:125], v[150:153], v[0:15]
	ds_read_b128 v[114:117], v109
	ds_read_b128 v[118:121], v111
	ds_read_b128 v[122:125], v110
	ds_read_b128 v[154:157], v112
	s_waitcnt lgkmcnt(1)
	v_mfma_f32_32x32x16_bf16 v[48:63], v[114:117], v[118:121], v[48:63]
	v_mfma_f32_32x32x16_bf16 v[32:47], v[122:125], v[118:121], v[32:47]
	s_waitcnt vmcnt(6)
	s_waitcnt lgkmcnt(0)
	s_barrier
	s_waitcnt lgkmcnt(0)
	v_mfma_f32_32x32x16_bf16 v[16:31], v[114:117], v[154:157], v[16:31]
	v_lshl_add_u64 v[114:115], v[66:67], 0, s[30:31]
	global_load_lds_dwordx4 v[114:115], off
	v_lshl_add_u64 v[114:115], v[68:69], 0, s[30:31]
	s_mov_b32 m0, s45
	s_nop 0
	global_load_lds_dwordx4 v[114:115], off
	v_lshl_add_u64 v[114:115], v[70:71], 0, s[30:31]
	s_mov_b32 m0, s46
	v_mfma_f32_32x32x16_bf16 v[0:15], v[122:125], v[154:157], v[0:15]
	global_load_lds_dwordx4 v[114:115], off
	v_lshl_add_u64 v[114:115], v[72:73], 0, s[30:31]
	s_mov_b32 m0, s47
	s_nop 0
	global_load_lds_dwordx4 v[114:115], off
	v_lshl_add_u64 v[114:115], v[74:75], 0, s[30:31]
	s_mov_b32 m0, s48
	s_nop 0
	global_load_lds_dwordx4 v[114:115], off
	v_lshl_add_u64 v[114:115], v[76:77], 0, s[30:31]
	s_mov_b32 m0, s49
	s_mov_b64 s[30:31], 0x780
	global_load_lds_dwordx4 v[114:115], off
	ds_read_b128 v[114:117], v82 offset:32768
	ds_read_b128 v[118:121], v64
	ds_read_b128 v[122:125], v82 offset:36864
	ds_read_b128 v[150:153], v64 offset:4096
	s_waitcnt lgkmcnt(1)
	v_mfma_f32_32x32x16_bf16 v[48:63], v[114:117], v[118:121], v[48:63]
	v_lshl_add_u64 v[66:67], v[66:67], 0, s[30:31]
	s_mov_b32 m0, s20
	v_mfma_f32_32x32x16_bf16 v[32:47], v[122:125], v[118:121], v[32:47]
	s_waitcnt lgkmcnt(0)
	v_mfma_f32_32x32x16_bf16 v[16:31], v[114:117], v[150:153], v[16:31]
	v_mfma_f32_32x32x16_bf16 v[0:15], v[122:125], v[150:153], v[0:15]
	ds_read_b128 v[114:117], v84 offset:32768
	ds_read_b128 v[118:121], v83
	ds_read_b128 v[122:125], v84 offset:36864
	ds_read_b128 v[154:157], v83 offset:4096
	s_waitcnt lgkmcnt(1)
	v_mfma_f32_32x32x16_bf16 v[48:63], v[114:117], v[118:121], v[48:63]
	v_mfma_f32_32x32x16_bf16 v[32:47], v[122:125], v[118:121], v[32:47]
	s_waitcnt lgkmcnt(0)
	v_mfma_f32_32x32x16_bf16 v[16:31], v[114:117], v[154:157], v[16:31]
	v_mfma_f32_32x32x16_bf16 v[0:15], v[122:125], v[154:157], v[0:15]
	ds_read_b128 v[114:117], v87 offset:32768
	ds_read_b128 v[118:121], v86
	ds_read_b128 v[122:125], v87 offset:36864
	ds_read_b128 v[150:153], v86 offset:4096
	s_waitcnt lgkmcnt(1)
	v_mfma_f32_32x32x16_bf16 v[48:63], v[114:117], v[118:121], v[48:63]
	v_mfma_f32_32x32x16_bf16 v[32:47], v[122:125], v[118:121], v[32:47]
	s_waitcnt lgkmcnt(0)
	v_mfma_f32_32x32x16_bf16 v[16:31], v[114:117], v[150:153], v[16:31]
	v_mfma_f32_32x32x16_bf16 v[0:15], v[122:125], v[150:153], v[0:15]
	ds_read_b128 v[114:117], v85 offset:32768
	ds_read_b128 v[118:121], v88
	ds_read_b128 v[122:125], v85 offset:36864
	ds_read_b128 v[154:157], v88 offset:4096
	s_waitcnt lgkmcnt(1)
	v_mfma_f32_32x32x16_bf16 v[48:63], v[114:117], v[118:121], v[48:63]
	v_mfma_f32_32x32x16_bf16 v[32:47], v[122:125], v[118:121], v[32:47]
	s_waitcnt vmcnt(6)
	s_waitcnt lgkmcnt(0)
	s_barrier
	global_load_lds_dwordx4 v[66:67], off
	v_lshl_add_u64 v[66:67], v[68:69], 0, s[30:31]
	s_mov_b32 m0, s21
	s_waitcnt lgkmcnt(0)
	v_mfma_f32_32x32x16_bf16 v[16:31], v[114:117], v[154:157], v[16:31]
	global_load_lds_dwordx4 v[66:67], off
	v_lshl_add_u64 v[66:67], v[70:71], 0, s[30:31]
	s_mov_b32 m0, s34
	s_lshl_b64 s[20:21], s[24:25], 21
	global_load_lds_dwordx4 v[66:67], off
	v_lshl_add_u64 v[66:67], v[72:73], 0, s[30:31]
	s_mov_b32 m0, s35
	v_mfma_f32_32x32x16_bf16 v[0:15], v[122:125], v[154:157], v[0:15]
	global_load_lds_dwordx4 v[66:67], off
	v_lshl_add_u64 v[66:67], v[74:75], 0, s[30:31]
	s_mov_b32 m0, s36
	v_readlane_b32 s24, v214, 43
	global_load_lds_dwordx4 v[66:67], off
	v_lshl_add_u64 v[66:67], v[76:77], 0, s[30:31]
	s_mov_b32 m0, s37
	s_add_u32 s34, s24, s20
	global_load_lds_dwordx4 v[66:67], off
	ds_read_b128 v[66:69], v91
	ds_read_b128 v[70:73], v64 offset:49152
	ds_read_b128 v[74:77], v89
	ds_read_b128 v[150:153], v64 offset:53248
	s_waitcnt lgkmcnt(1)
	v_mfma_f32_32x32x16_bf16 v[48:63], v[66:69], v[70:73], v[48:63]
	v_readlane_b32 s24, v214, 44
	s_addc_u32 s35, s24, s21
	v_readlane_b32 s24, v214, 41
	s_add_u32 s52, s24, s20
	v_readlane_b32 s20, v214, 42
	s_addc_u32 s53, s20, s21
	v_readlane_b32 s20, v214, 37
	v_mfma_f32_32x32x16_bf16 v[32:47], v[74:77], v[70:73], v[32:47]
	v_readlane_b32 s21, v214, 38
	s_add_u32 s20, s20, s0
	s_addc_u32 s21, s21, s1
	v_readlane_b32 s30, v214, 39
	v_readlane_b32 s31, v214, 40
	s_add_u32 s36, s30, s0
	s_waitcnt lgkmcnt(0)
	v_mfma_f32_32x32x16_bf16 v[16:31], v[66:69], v[150:153], v[16:31]
	s_addc_u32 s37, s31, s1
	s_movk_i32 s0, 0xfc00
	s_cmpk_lt_u32 s28, 0x100
	s_mov_b32 s1, -1
	s_cselect_b64 s[38:39], -1, 0
	s_cmpk_gt_u32 s28, 0xff
	v_mfma_f32_32x32x16_bf16 v[0:15], v[74:77], v[150:153], v[0:15]
	ds_read_b128 v[66:69], v92
	ds_read_b128 v[70:73], v83 offset:49152
	ds_read_b128 v[74:77], v90
	ds_read_b128 v[154:157], v83 offset:53248
	s_waitcnt lgkmcnt(1)
	v_mfma_f32_32x32x16_bf16 v[48:63], v[66:69], v[70:73], v[48:63]
	v_mfma_f32_32x32x16_bf16 v[32:47], v[74:77], v[70:73], v[32:47]
	s_waitcnt lgkmcnt(0)
	v_mfma_f32_32x32x16_bf16 v[16:31], v[66:69], v[154:157], v[16:31]
	v_mfma_f32_32x32x16_bf16 v[0:15], v[74:77], v[154:157], v[0:15]
	ds_read_b128 v[66:69], v94
	ds_read_b128 v[70:73], v86 offset:49152
	ds_read_b128 v[74:77], v93
	ds_read_b128 v[150:153], v86 offset:53248
	s_waitcnt lgkmcnt(1)
	v_mfma_f32_32x32x16_bf16 v[48:63], v[66:69], v[70:73], v[48:63]
	v_mfma_f32_32x32x16_bf16 v[32:47], v[74:77], v[70:73], v[32:47]
	s_waitcnt lgkmcnt(0)
	v_mfma_f32_32x32x16_bf16 v[16:31], v[66:69], v[150:153], v[16:31]
	v_mfma_f32_32x32x16_bf16 v[0:15], v[74:77], v[150:153], v[0:15]
	ds_read_b128 v[66:69], v96
	ds_read_b128 v[70:73], v88 offset:49152
	ds_read_b128 v[74:77], v95
	ds_read_b128 v[154:157], v88 offset:53248
	s_waitcnt lgkmcnt(1)
	v_mfma_f32_32x32x16_bf16 v[48:63], v[66:69], v[70:73], v[48:63]
	v_mfma_f32_32x32x16_bf16 v[32:47], v[74:77], v[70:73], v[32:47]
	s_waitcnt vmcnt(6)
	s_waitcnt lgkmcnt(0)
	s_barrier
	s_waitcnt lgkmcnt(0)
	v_mfma_f32_32x32x16_bf16 v[16:31], v[66:69], v[154:157], v[16:31]
	v_mfma_f32_32x32x16_bf16 v[0:15], v[74:77], v[154:157], v[0:15]
	ds_read_b128 v[66:69], v97
	ds_read_b128 v[70:73], v99
	ds_read_b128 v[74:77], v98
	ds_read_b128 v[150:153], v100
	s_waitcnt lgkmcnt(1)
	v_mfma_f32_32x32x16_bf16 v[48:63], v[66:69], v[70:73], v[48:63]
	v_mfma_f32_32x32x16_bf16 v[32:47], v[74:77], v[70:73], v[32:47]
	s_waitcnt lgkmcnt(0)
	v_mfma_f32_32x32x16_bf16 v[16:31], v[66:69], v[150:153], v[16:31]
	v_mfma_f32_32x32x16_bf16 v[0:15], v[74:77], v[150:153], v[0:15]
	ds_read_b128 v[66:69], v101
	ds_read_b128 v[70:73], v103
	ds_read_b128 v[74:77], v102
	ds_read_b128 v[154:157], v104
	s_waitcnt lgkmcnt(1)
	v_mfma_f32_32x32x16_bf16 v[48:63], v[66:69], v[70:73], v[48:63]
	v_mfma_f32_32x32x16_bf16 v[32:47], v[74:77], v[70:73], v[32:47]
	s_waitcnt lgkmcnt(0)
	v_mfma_f32_32x32x16_bf16 v[16:31], v[66:69], v[154:157], v[16:31]
	v_mfma_f32_32x32x16_bf16 v[0:15], v[74:77], v[154:157], v[0:15]
	ds_read_b128 v[66:69], v105
	ds_read_b128 v[70:73], v107
	ds_read_b128 v[74:77], v106
	ds_read_b128 v[150:153], v108
	s_waitcnt lgkmcnt(1)
	v_mfma_f32_32x32x16_bf16 v[48:63], v[66:69], v[70:73], v[48:63]
	v_mfma_f32_32x32x16_bf16 v[32:47], v[74:77], v[70:73], v[32:47]
	s_waitcnt lgkmcnt(0)
	v_mfma_f32_32x32x16_bf16 v[16:31], v[66:69], v[150:153], v[16:31]
	v_mfma_f32_32x32x16_bf16 v[0:15], v[74:77], v[150:153], v[0:15]
	ds_read_b128 v[66:69], v109
	ds_read_b128 v[70:73], v111
	ds_read_b128 v[74:77], v110
	ds_read_b128 v[154:157], v112
	s_waitcnt lgkmcnt(1)
	v_mfma_f32_32x32x16_bf16 v[48:63], v[66:69], v[70:73], v[48:63]
	v_mfma_f32_32x32x16_bf16 v[32:47], v[74:77], v[70:73], v[32:47]
	s_waitcnt vmcnt(0)
	s_waitcnt lgkmcnt(0)
	s_barrier
	s_waitcnt lgkmcnt(0)
	v_mfma_f32_32x32x16_bf16 v[16:31], v[66:69], v[154:157], v[16:31]
	v_mfma_f32_32x32x16_bf16 v[0:15], v[74:77], v[154:157], v[0:15]
	ds_read_b128 v[66:69], v82 offset:32768
	ds_read_b128 v[70:73], v64
	ds_read_b128 v[74:77], v82 offset:36864
	ds_read_b128 v[150:153], v64 offset:4096
	s_waitcnt lgkmcnt(1)
	v_mfma_f32_32x32x16_bf16 v[48:63], v[66:69], v[70:73], v[48:63]
	v_mfma_f32_32x32x16_bf16 v[32:47], v[74:77], v[70:73], v[32:47]
	v_or_b32_e32 v64, s29, v80
	s_waitcnt lgkmcnt(0)
	v_mfma_f32_32x32x16_bf16 v[16:31], v[66:69], v[150:153], v[16:31]
	v_mfma_f32_32x32x16_bf16 v[0:15], v[74:77], v[150:153], v[0:15]
	ds_read_b128 v[66:69], v84 offset:32768
	ds_read_b128 v[70:73], v83
	ds_read_b128 v[74:77], v84 offset:36864
	ds_read_b128 v[154:157], v83 offset:4096
	s_waitcnt lgkmcnt(1)
	v_mfma_f32_32x32x16_bf16 v[48:63], v[66:69], v[70:73], v[48:63]
	v_mfma_f32_32x32x16_bf16 v[32:47], v[74:77], v[70:73], v[32:47]
	s_waitcnt lgkmcnt(0)
	v_mfma_f32_32x32x16_bf16 v[16:31], v[66:69], v[154:157], v[16:31]
	v_mfma_f32_32x32x16_bf16 v[0:15], v[74:77], v[154:157], v[0:15]
	ds_read_b128 v[66:69], v87 offset:32768
	ds_read_b128 v[70:73], v86
	ds_read_b128 v[74:77], v87 offset:36864
	ds_read_b128 v[150:153], v86 offset:4096
	s_waitcnt lgkmcnt(1)
	v_mfma_f32_32x32x16_bf16 v[48:63], v[66:69], v[70:73], v[48:63]
	v_mfma_f32_32x32x16_bf16 v[32:47], v[74:77], v[70:73], v[32:47]
	ds_read_b128 v[90:93], v88
	ds_read_b128 v[94:97], v88 offset:4096
	ds_read_b128 v[100:103], v85 offset:32768
	ds_read_b128 v[104:107], v85 offset:36864
	s_waitcnt lgkmcnt(0)
	v_mfma_f32_32x32x16_bf16 v[16:31], v[66:69], v[150:153], v[16:31]
	v_lshl_add_u32 v66, v78, 6, v64
	v_lshlrev_b32_e32 v64, 6, v79
	v_lshlrev_b32_e32 v68, 2, v81
	v_ashrrev_i32_e32 v67, 31, v66
	v_or3_b32 v98, v64, v68, s28
	v_ashrrev_i32_e32 v64, 6, v66
	v_and_b32_e32 v69, 0xdf, v66
	v_mfma_f32_32x32x16_bf16 v[0:15], v[74:77], v[150:153], v[0:15]
	v_lshlrev_b64 v[70:71], 10, v[66:67]
	v_and_b32_e32 v67, -4, v64
	v_lshl_add_u64 v[72:73], s[34:35], 0, v[70:71]
	v_lshlrev_b32_e32 v64, 2, v98
	v_lshl_add_u64 v[70:71], s[52:53], 0, v[70:71]
	v_lshl_add_u64 v[86:87], v[70:71], 0, v[64:65]
	v_lshl_add_u64 v[84:85], v[72:73], 0, v[64:65]
	v_mfma_f32_32x32x16_bf16 v[48:63], v[100:103], v[90:93], v[48:63]
	v_lshl_add_u64 v[70:71], v[86:87], 0, s[0:1]
	s_cselect_b64 s[28:29], -1, 0
	v_cndmask_b32_e64 v71, v71, v85, s[38:39]
	v_cndmask_b32_e64 v70, v70, v84, s[38:39]
	s_mov_b64 s[0:1], -1
	s_and_b64 vcc, exec, s[28:29]
	v_lshlrev_b32_e32 v82, 1, v69
	v_mfma_f32_32x32x16_bf16 v[32:47], v[104:107], v[90:93], v[32:47]
	s_nop 3
	global_store_dwordx4 v[70:71], v[48:51], off
	v_lshlrev_b32_e32 v70, 11, v81
	v_add_u32_e32 v91, 0xffffff00, v98
	v_mfma_f32_32x32x16_bf16 v[16:31], v[100:103], v[94:97], v[16:31]
	v_mfma_f32_32x32x16_bf16 v[0:15], v[104:107], v[94:97], v[0:15]
	s_cbranch_vccz .LBB0_522
	v_lshrrev_b32_e32 v71, 6, v91
	v_add_u32_e32 v72, v71, v67
	v_ashrrev_i32_e32 v73, 31, v72
	v_lshlrev_b64 v[72:73], 15, v[72:73]
	v_lshl_add_u64 v[72:73], s[36:37], 0, v[72:73]
	v_mov_b32_e32 v71, v65
	v_lshl_add_u64 v[72:73], v[72:73], 0, v[70:71]
	v_mov_b32_e32 v83, v65
	v_bfe_u32 v71, v48, 16, 1
	v_lshl_add_u64 v[72:73], v[72:73], 0, v[82:83]
	v_add3_u32 v71, v48, v71, s27
	global_store_short_d16_hi v[72:73], v71, off
	v_bfe_u32 v71, v49, 16, 1
	v_add3_u32 v71, v49, v71, s27
	global_store_short_d16_hi v[72:73], v71, off offset:512
	v_bfe_u32 v71, v50, 16, 1
	v_add3_u32 v71, v50, v71, s27
	global_store_short_d16_hi v[72:73], v71, off offset:1024
	v_bfe_u32 v71, v51, 16, 1
	v_add3_u32 v71, v51, v71, s27
	global_store_short_d16_hi v[72:73], v71, off offset:1536
	s_mov_b64 s[0:1], 0

.LBB0_585:
	s_and_b64 vcc, exec, s[0:1]
	s_cbranch_vccz .LBB0_518
	s_mul_hi_i32 s0, s33, 0x51eb851f
	s_lshr_b32 s1, s0, 31
	s_ashr_i32 s0, s0, 3
	v_mov_b32_e32 v78, v133
	s_add_i32 s21, s0, s1
	s_lshl_b32 s20, s21, 8
	v_ashrrev_i32_e32 v6, 6, v78
	v_bfe_u32 v7, v78, 3, 3
	v_lshl_or_b32 v8, v6, 5, v7
	v_add_u32_e32 v0, s20, v8
	s_waitcnt lgkmcnt(0)
	v_ashrrev_i32_e32 v1, 31, v0
	v_lshlrev_b64 v[2:3], 11, v[0:1]
	v_bfe_u32 v1, v78, 4, 2
	v_readlane_b32 s0, v215, 52
	v_xor_b32_e32 v1, v1, v78
	v_readlane_b32 s1, v215, 53
	v_lshlrev_b32_e32 v1, 4, v1
	v_and_b32_e32 v64, 0x70, v1
	v_lshl_add_u64 v[2:3], s[0:1], 0, v[2:3]
	v_or_b32_e32 v1, 8, v8
	v_lshl_add_u64 v[66:67], v[2:3], 0, v[64:65]
	v_add_u32_e32 v2, s20, v1
	v_lshrrev_b32_e32 v1, 1, v1
	v_xor_b32_e32 v1, v1, v78
	v_ashrrev_i32_e32 v3, 31, v2
	v_lshlrev_b32_e32 v1, 4, v1
	v_or_b32_e32 v0, 16, v0
	v_lshlrev_b64 v[2:3], 11, v[2:3]
	v_and_b32_e32 v4, 0x70, v1
	v_ashrrev_i32_e32 v1, 31, v0
	v_lshl_add_u64 v[2:3], s[0:1], 0, v[2:3]
	v_mov_b32_e32 v5, v65
	v_lshlrev_b64 v[0:1], 11, v[0:1]
	v_lshl_add_u64 v[68:69], v[2:3], 0, v[4:5]
	v_lshl_add_u64 v[0:1], s[0:1], 0, v[0:1]
	v_or_b32_e32 v2, 24, v8
	v_lshl_add_u64 v[70:71], v[0:1], 0, v[64:65]
	v_add_u32_e32 v0, s20, v2
	v_lshrrev_b32_e32 v2, 1, v2
	v_ashrrev_i32_e32 v1, 31, v0
	v_xor_b32_e32 v2, v2, v78
	v_lshlrev_b64 v[0:1], 11, v[0:1]
	v_lshlrev_b32_e32 v2, 4, v2
	v_lshl_add_u64 v[0:1], s[0:1], 0, v[0:1]
	v_and_b32_e32 v2, 0x70, v2
	v_mov_b32_e32 v3, v65
	v_lshl_or_b32 v4, v6, 4, v7
	s_mulk_i32 s21, 0xc80
	v_lshl_add_u64 v[72:73], v[0:1], 0, v[2:3]
	v_subrev_u32_e32 v0, s21, v4
	v_add_u32_e32 v0, s23, v0
	v_ashrrev_i32_e32 v1, 31, v0
	v_lshlrev_b64 v[2:3], 11, v[0:1]
	v_lshl_add_u64 v[2:3], s[96:97], 0, v[2:3]
	v_lshl_add_u64 v[74:75], v[2:3], 0, v[64:65]
	v_lshlrev_b32_e32 v3, 12, v6
	v_add_u32_e32 v126, 0, v3
	s_waitcnt vmcnt(0)
	v_add_u32_e32 v127, 0x400, v126
	v_readfirstlane_b32 s41, v126
	v_or_b32_e32 v2, 8, v4
	s_waitcnt lgkmcnt(0)
	s_barrier
	s_mov_b32 m0, s41
	v_readfirstlane_b32 s42, v127
	v_add_u32_e32 v128, 0x800, v126
	v_lshlrev_b32_e32 v5, 11, v6
	v_and_b32_e32 v79, 1, v6
	v_add_u32_e32 v0, 8, v0
	v_lshrrev_b32_e32 v2, 1, v2
	global_load_lds_dwordx4 v[66:67], off
	s_mov_b32 m0, s42
	v_readfirstlane_b32 s43, v128
	v_add_u32_e32 v129, 0xc00, v126
	v_add_u32_e32 v6, 0, v5
	v_ashrrev_i32_e32 v1, 31, v0
	v_xor_b32_e32 v2, v2, v78
	global_load_lds_dwordx4 v[68:69], off
	s_mov_b32 m0, s43
	v_readfirstlane_b32 s44, v129
	v_add_u32_e32 v131, 0x8000, v6
	v_lshlrev_b64 v[0:1], 11, v[0:1]
	v_lshlrev_b32_e32 v2, 4, v2
	global_load_lds_dwordx4 v[70:71], off
	s_mov_b32 m0, s44
	v_readfirstlane_b32 s45, v131
	v_add_u32_e32 v130, 0x8400, v6
	v_lshl_add_u64 v[0:1], s[96:97], 0, v[0:1]
	v_and_b32_e32 v64, 0x70, v2
	global_load_lds_dwordx4 v[72:73], off
	s_mov_b32 m0, s45
	v_readfirstlane_b32 s46, v130
	v_add_u32_e32 v120, 0xc000, v126
	v_lshl_add_u64 v[76:77], v[0:1], 0, v[64:65]
	global_load_lds_dwordx4 v[74:75], off
	s_mov_b32 m0, s46
	s_mov_b64 s[0:1], 0x80
	v_readfirstlane_b32 s35, v120
	v_add_u32_e32 v121, 0xc400, v126
	global_load_lds_dwordx4 v[76:77], off
	v_lshl_add_u64 v[0:1], v[66:67], 0, s[0:1]
	s_mov_b32 m0, s35
	v_readfirstlane_b32 s36, v121
	v_add_u32_e32 v122, 0xc800, v126
	global_load_lds_dwordx4 v[0:1], off
	v_lshl_add_u64 v[0:1], v[68:69], 0, s[0:1]
	s_mov_b32 m0, s36
	v_readfirstlane_b32 s37, v122
	v_add_u32_e32 v123, 0xcc00, v126
	global_load_lds_dwordx4 v[0:1], off
	v_lshl_add_u64 v[0:1], v[70:71], 0, s[0:1]
	s_mov_b32 m0, s37
	v_readfirstlane_b32 s38, v123
	v_add_u32_e32 v124, s85, v5
	global_load_lds_dwordx4 v[0:1], off
	v_lshl_add_u64 v[0:1], v[72:73], 0, s[0:1]
	s_mov_b32 m0, s38
	v_readfirstlane_b32 s39, v124
	v_add_u32_e32 v125, 0x14400, v6
	global_load_lds_dwordx4 v[0:1], off
	v_lshl_add_u64 v[0:1], v[74:75], 0, s[0:1]
	s_mov_b32 m0, s39
	v_readfirstlane_b32 s40, v125
	global_load_lds_dwordx4 v[0:1], off
	v_lshl_add_u64 v[0:1], v[76:77], 0, s[0:1]
	s_mov_b32 m0, s40
	v_lshrrev_b32_e32 v2, 1, v78
	v_bfe_u32 v64, v78, 5, 1
	global_load_lds_dwordx4 v[0:1], off
	v_add_u32_e32 v114, s3, v3
	v_bitop3_b32 v0, v2, v64, 7 bitop3:0x6c
	s_waitcnt vmcnt(6)
	s_mov_b64 s[30:31], 0x100
	v_readfirstlane_b32 s0, v114
	v_add_u32_e32 v115, 0x400, v114
	v_lshlrev_b32_e32 v132, 4, v0
	s_waitcnt lgkmcnt(0)
	s_barrier
	v_lshl_add_u64 v[0:1], v[66:67], 0, s[30:31]
	s_mov_b32 m0, s0
	v_readfirstlane_b32 s1, v115
	v_add_u32_e32 v116, 0x800, v114
	global_load_lds_dwordx4 v[0:1], off
	v_lshl_add_u64 v[0:1], v[68:69], 0, s[30:31]
	s_mov_b32 m0, s1
	v_readfirstlane_b32 s24, v116
	v_add_u32_e32 v117, 0xc00, v114
	v_readlane_b32 s29, v212, 31
	v_and_b32_e32 v81, 31, v78
	global_load_lds_dwordx4 v[0:1], off
	v_lshl_add_u64 v[0:1], v[70:71], 0, s[30:31]
	s_mov_b32 m0, s24
	v_readfirstlane_b32 s28, v117
	v_add_u32_e32 v118, s29, v5
	v_add_u32_e32 v2, s3, v5
	v_lshlrev_b32_e32 v4, 7, v81
	global_load_lds_dwordx4 v[0:1], off
	v_lshl_add_u64 v[0:1], v[72:73], 0, s[30:31]
	s_mov_b32 m0, s28
	v_readfirstlane_b32 s29, v118
	v_add_u32_e32 v119, 0x8400, v2
	v_lshl_or_b32 v102, v79, 13, v4
	global_load_lds_dwordx4 v[0:1], off
	v_lshl_add_u64 v[0:1], v[74:75], 0, s[30:31]
	s_mov_b32 m0, s29
	v_readfirstlane_b32 s34, v119
	global_load_lds_dwordx4 v[0:1], off
	v_lshl_add_u64 v[0:1], v[76:77], 0, s[30:31]
	s_mov_b32 m0, s34
	v_add_u32_e32 v100, 0, v102
	global_load_lds_dwordx4 v[0:1], off
	v_add_u32_e32 v83, v100, v132
	v_ashrrev_i32_e32 v80, 7, v78
	ds_read_b128 v[0:3], v83 offset:32768
	ds_read_b128 v[8:11], v83 offset:36864
	v_lshl_or_b32 v134, v80, 13, v4
	v_add_u32_e32 v101, 0, v134
	v_add_u32_e32 v82, v101, v132
	ds_read_b128 v[4:7], v82
	ds_read_b128 v[154:157], v82 offset:4096
	s_waitcnt lgkmcnt(1)
	v_lshrrev_b32_e32 v182, 6, v133
	s_nop 0
	v_readfirstlane_b32 s32, v182
	v_mfma_f32_32x32x16_bf16 v[48:63], v[0:3], v[4:7], 0
	v_bfe_u32 v103, v78, 1, 3
	s_mov_b64 s[30:31], 0x180
	s_nop 0
	v_or_b32_e32 v143, 0x8000, v102
	v_or_b32_e32 v144, 0x9000, v102
	v_add_u32_e32 v145, s3, v134
	s_mov_b64 s[80:81], 0x200
	s_waitcnt vmcnt(12)
	v_mfma_f32_32x32x16_bf16 v[32:47], v[8:11], v[4:7], 0
	s_waitcnt lgkmcnt(0)
	v_mfma_f32_32x32x16_bf16 v[16:31], v[0:3], v[154:157], 0
	v_bitop3_b32 v0, v64, v103, 2 bitop3:0x36
	v_lshlrev_b32_e32 v138, 4, v0
	v_add_u32_e32 v85, v100, v138
	ds_read_b128 v[86:89], v85 offset:32768
	ds_read_b128 v[94:97], v85 offset:36864
	v_add_u32_e32 v84, v101, v138
	ds_read_b128 v[90:93], v84
	v_mfma_f32_32x32x16_bf16 v[0:15], v[8:11], v[154:157], 0
	ds_read_b128 v[150:153], v84 offset:4096
	s_waitcnt lgkmcnt(1)
	v_mfma_f32_32x32x16_bf16 v[48:63], v[86:89], v[90:93], v[48:63]
	v_mfma_f32_32x32x16_bf16 v[32:47], v[94:97], v[90:93], v[32:47]
	s_waitcnt lgkmcnt(0)
	v_mfma_f32_32x32x16_bf16 v[16:31], v[86:89], v[150:153], v[16:31]
	v_bitop3_b32 v86, v64, v103, 4 bitop3:0x36
	v_lshlrev_b32_e32 v139, 4, v86
	v_add_u32_e32 v87, v100, v139
	v_add_u32_e32 v86, v101, v139
	v_mfma_f32_32x32x16_bf16 v[0:15], v[94:97], v[150:153], v[0:15]
	ds_read_b128 v[88:91], v87 offset:32768
	ds_read_b128 v[92:95], v86
	ds_read_b128 v[96:99], v87 offset:36864
	s_waitcnt lgkmcnt(1)
	v_mfma_f32_32x32x16_bf16 v[48:63], v[88:91], v[92:95], v[48:63]
	s_waitcnt lgkmcnt(0)
	v_mfma_f32_32x32x16_bf16 v[32:47], v[96:99], v[92:95], v[32:47]
	ds_read_b128 v[92:95], v86 offset:4096
	s_waitcnt lgkmcnt(0)
	v_mfma_f32_32x32x16_bf16 v[16:31], v[88:91], v[92:95], v[16:31]
	v_bitop3_b32 v88, v64, v103, 6 bitop3:0x36
	v_lshlrev_b32_e32 v142, 4, v88
	v_add_u32_e32 v89, v100, v142
	v_add_u32_e32 v88, v101, v142
	v_mfma_f32_32x32x16_bf16 v[0:15], v[96:99], v[92:95], v[0:15]
	ds_read_b128 v[90:93], v89 offset:32768
	ds_read_b128 v[94:97], v88
	ds_read_b128 v[98:101], v89 offset:36864
	s_waitcnt lgkmcnt(1)
	v_mfma_f32_32x32x16_bf16 v[48:63], v[90:93], v[94:97], v[48:63]
	s_waitcnt lgkmcnt(0)
	v_mfma_f32_32x32x16_bf16 v[32:47], v[98:101], v[94:97], v[32:47]
	ds_read_b128 v[94:97], v88 offset:4096
	s_waitcnt vmcnt(6)
	s_waitcnt lgkmcnt(0)
	s_barrier
	s_waitcnt lgkmcnt(0)
	v_mfma_f32_32x32x16_bf16 v[16:31], v[90:93], v[94:97], v[16:31]
	v_lshl_add_u64 v[158:159], v[66:67], 0, s[30:31]
	s_nop 0
	v_lshl_add_u64 v[160:161], v[68:69], 0, s[30:31]
	s_nop 0
	s_nop 0
	s_nop 0
	v_lshl_add_u64 v[162:163], v[70:71], 0, s[30:31]
	s_nop 0
	v_mfma_f32_32x32x16_bf16 v[0:15], v[98:101], v[94:97], v[0:15]
	s_and_b32 m0, s32, 7
	s_lshl_b32 m0, m0, 12
	s_add_i32 m0, m0, 0x0
	s_nop 0
	global_load_lds_dwordx4 v[158:159], off
	s_nop 0
	v_lshl_add_u64 v[164:165], v[72:73], 0, s[30:31]
	s_nop 0
	s_nop 0
	s_nop 0
	v_lshl_add_u64 v[166:167], v[74:75], 0, s[30:31]
	s_nop 0
	s_nop 0
	s_nop 0
	v_lshl_add_u64 v[168:169], v[76:77], 0, s[30:31]
	s_nop 0
	s_add_i32 s30, 0, 0xc000
	s_nop 0
	v_add_u32_e32 v90, s30, v132
	v_add_u32_e32 v92, v90, v143
	v_add_u32_e32 v90, v90, v144
	ds_read_b128 v[94:97], v92
	ds_read_b128 v[98:101], v82 offset:49152
	ds_read_b128 v[102:105], v90
	ds_read_b128 v[154:157], v82 offset:53248
	s_waitcnt lgkmcnt(1)
	v_mfma_f32_32x32x16_bf16 v[48:63], v[94:97], v[98:101], v[48:63]
	v_add_u32_e32 v91, s30, v138
	v_add_u32_e32 v93, v91, v143
	v_add_u32_e32 v91, v91, v144
	s_nop 0
	v_mfma_f32_32x32x16_bf16 v[32:47], v[102:105], v[98:101], v[32:47]
	s_and_b32 m0, s32, 7
	s_lshl_b32 m0, m0, 12
	s_add_i32 m0, m0, 0x400
	s_nop 0
	global_load_lds_dwordx4 v[160:161], off
	s_waitcnt lgkmcnt(0)
	v_mfma_f32_32x32x16_bf16 v[16:31], v[94:97], v[154:157], v[16:31]
	v_mfma_f32_32x32x16_bf16 v[0:15], v[102:105], v[154:157], v[0:15]
	s_and_b32 m0, s32, 7
	s_lshl_b32 m0, m0, 12
	s_add_i32 m0, m0, 0x800
	s_nop 0
	global_load_lds_dwordx4 v[162:163], off
	ds_read_b128 v[94:97], v93
	ds_read_b128 v[98:101], v84 offset:49152
	ds_read_b128 v[102:105], v91
	ds_read_b128 v[150:153], v84 offset:53248
	s_waitcnt lgkmcnt(1)
	v_mfma_f32_32x32x16_bf16 v[48:63], v[94:97], v[98:101], v[48:63]
	v_mfma_f32_32x32x16_bf16 v[32:47], v[102:105], v[98:101], v[32:47]
	s_and_b32 m0, s32, 7
	s_lshl_b32 m0, m0, 12
	s_add_i32 m0, m0, 0xc00
	s_nop 0
	global_load_lds_dwordx4 v[164:165], off
	s_waitcnt lgkmcnt(0)
	v_mfma_f32_32x32x16_bf16 v[16:31], v[94:97], v[150:153], v[16:31]
	v_add_u32_e32 v94, s30, v139
	v_add_u32_e32 v95, v94, v143
	v_add_u32_e32 v94, v94, v144
	v_mfma_f32_32x32x16_bf16 v[0:15], v[102:105], v[150:153], v[0:15]
	s_and_b32 m0, s32, 7
	s_lshl_b32 m0, m0, 11
	s_add_i32 m0, m0, 0x8000
	s_nop 0
	global_load_lds_dwordx4 v[166:167], off
	ds_read_b128 v[96:99], v95
	ds_read_b128 v[100:103], v86 offset:49152
	ds_read_b128 v[104:107], v94
	ds_read_b128 v[154:157], v86 offset:53248
	s_waitcnt lgkmcnt(1)
	v_mfma_f32_32x32x16_bf16 v[48:63], v[96:99], v[100:103], v[48:63]
	v_mfma_f32_32x32x16_bf16 v[32:47], v[104:107], v[100:103], v[32:47]
	s_and_b32 m0, s32, 7
	s_lshl_b32 m0, m0, 11
	s_add_i32 m0, m0, 0x8400
	s_nop 0
	global_load_lds_dwordx4 v[168:169], off
	s_waitcnt lgkmcnt(0)
	v_mfma_f32_32x32x16_bf16 v[16:31], v[96:99], v[154:157], v[16:31]
	v_add_u32_e32 v96, s30, v142
	v_add_u32_e32 v97, v96, v143
	v_add_u32_e32 v96, v96, v144
	s_mov_b64 s[30:31], 0x200
	v_mfma_f32_32x32x16_bf16 v[0:15], v[104:107], v[154:157], v[0:15]
	ds_read_b128 v[98:101], v97
	ds_read_b128 v[102:105], v88 offset:49152
	ds_read_b128 v[106:109], v96
	ds_read_b128 v[150:153], v88 offset:53248
	s_waitcnt lgkmcnt(1)
	v_mfma_f32_32x32x16_bf16 v[48:63], v[98:101], v[102:105], v[48:63]
	v_mfma_f32_32x32x16_bf16 v[32:47], v[106:109], v[102:105], v[32:47]
	s_waitcnt vmcnt(6)
	s_waitcnt lgkmcnt(0)
	s_barrier
	s_waitcnt lgkmcnt(0)
	v_mfma_f32_32x32x16_bf16 v[16:31], v[98:101], v[150:153], v[16:31]
	v_lshl_add_u64 v[170:171], v[66:67], 0, s[30:31]
	s_nop 0
	v_lshl_add_u64 v[172:173], v[68:69], 0, s[30:31]
	s_nop 0
	v_add_u32_e32 v101, s3, v132
	s_nop 0
	v_lshl_add_u64 v[174:175], v[70:71], 0, s[30:31]
	s_nop 0
	v_mfma_f32_32x32x16_bf16 v[0:15], v[106:109], v[150:153], v[0:15]
	s_and_b32 m0, s32, 7
	s_lshl_b32 m0, m0, 12
	s_add_i32 m0, m0, 0xc000
	s_nop 0
	global_load_lds_dwordx4 v[170:171], off
	s_nop 0
	v_lshl_add_u64 v[176:177], v[72:73], 0, s[30:31]
	s_nop 0
	v_add_u32_e32 v100, v145, v132
	s_nop 0
	v_lshl_add_u64 v[178:179], v[74:75], 0, s[30:31]
	s_nop 0
	v_or_b32_e32 v132, 0x1000, v134
	s_nop 0
	v_lshl_add_u64 v[180:181], v[76:77], 0, s[30:31]
	s_nop 0
	s_mov_b64 s[30:31], 0x280
	s_nop 0
	v_add_u32_e32 v98, v101, v143
	v_add_u32_e32 v99, v101, v144
	ds_read_b128 v[110:113], v98
	ds_read_b128 v[106:109], v99
	ds_read_b128 v[102:105], v100
	v_add_u32_e32 v101, v101, v132
	ds_read_b128 v[134:137], v101
	s_waitcnt lgkmcnt(0)
	v_mfma_f32_32x32x16_bf16 v[48:63], v[110:113], v[102:105], v[48:63]
	s_nop 0
	v_mfma_f32_32x32x16_bf16 v[32:47], v[106:109], v[102:105], v[32:47]
	s_and_b32 m0, s32, 7
	s_lshl_b32 m0, m0, 12
	s_add_i32 m0, m0, 0xc400
	s_nop 0
	global_load_lds_dwordx4 v[172:173], off
	v_add_u32_e32 v105, s3, v138
	v_add_u32_e32 v102, v105, v143
	v_add_u32_e32 v103, v105, v144
	v_add_u32_e32 v104, v145, v138
	v_add_u32_e32 v105, v105, v132
	v_mfma_f32_32x32x16_bf16 v[16:31], v[110:113], v[134:137], v[16:31]
	ds_read_b128 v[110:113], v104
	v_mfma_f32_32x32x16_bf16 v[0:15], v[106:109], v[134:137], v[0:15]
	s_and_b32 m0, s32, 7
	s_lshl_b32 m0, m0, 12
	s_add_i32 m0, m0, 0xc800
	s_nop 0
	global_load_lds_dwordx4 v[174:175], off
	ds_read_b128 v[106:109], v102
	ds_read_b128 v[134:137], v103
	ds_read_b128 v[154:157], v105
	s_waitcnt lgkmcnt(1)
	v_mfma_f32_32x32x16_bf16 v[48:63], v[106:109], v[110:113], v[48:63]
	v_mfma_f32_32x32x16_bf16 v[32:47], v[134:137], v[110:113], v[32:47]
	s_and_b32 m0, s32, 7
	s_lshl_b32 m0, m0, 12
	s_add_i32 m0, m0, 0xcc00
	s_nop 0
	global_load_lds_dwordx4 v[176:177], off
	s_waitcnt lgkmcnt(0)
	v_mfma_f32_32x32x16_bf16 v[16:31], v[106:109], v[154:157], v[16:31]
	v_add_u32_e32 v109, s3, v139
	v_add_u32_e32 v106, v109, v143
	v_add_u32_e32 v107, v109, v144
	v_add_u32_e32 v108, v145, v139
	ds_read_b128 v[138:141], v107
	v_add_u32_e32 v109, v109, v132
	v_mfma_f32_32x32x16_bf16 v[0:15], v[134:137], v[154:157], v[0:15]
	s_and_b32 m0, s32, 7
	s_lshl_b32 m0, m0, 11
	s_add_i32 m0, m0, 0x14000
	s_nop 0
	global_load_lds_dwordx4 v[178:179], off
	ds_read_b128 v[110:113], v106
	ds_read_b128 v[134:137], v108
	ds_read_b128 v[150:153], v109
	s_waitcnt lgkmcnt(1)
	v_mfma_f32_32x32x16_bf16 v[48:63], v[110:113], v[134:137], v[48:63]
	v_mfma_f32_32x32x16_bf16 v[32:47], v[138:141], v[134:137], v[32:47]
	s_and_b32 m0, s32, 7
	s_lshl_b32 m0, m0, 11
	s_add_i32 m0, m0, 0x14400
	s_nop 0
	global_load_lds_dwordx4 v[180:181], off
	s_waitcnt lgkmcnt(0)
	v_mfma_f32_32x32x16_bf16 v[16:31], v[110:113], v[150:153], v[16:31]
	v_add_u32_e32 v113, s3, v142
	v_add_u32_e32 v110, v113, v143
	v_add_u32_e32 v111, v113, v144
	v_add_u32_e32 v112, v145, v142
	ds_read_b128 v[142:145], v111
	v_add_u32_e32 v113, v113, v132
	v_mfma_f32_32x32x16_bf16 v[0:15], v[138:141], v[150:153], v[0:15]
	ds_read_b128 v[134:137], v110
	ds_read_b128 v[138:141], v112
	ds_read_b128 v[154:157], v113
	s_waitcnt lgkmcnt(1)
	v_mfma_f32_32x32x16_bf16 v[48:63], v[134:137], v[138:141], v[48:63]
	v_mfma_f32_32x32x16_bf16 v[32:47], v[142:145], v[138:141], v[32:47]
	s_waitcnt vmcnt(6)
	s_waitcnt lgkmcnt(0)
	s_barrier
	s_waitcnt lgkmcnt(0)
	v_mfma_f32_32x32x16_bf16 v[16:31], v[134:137], v[154:157], v[16:31]
	v_lshl_add_u64 v[158:159], v[66:67], 0, s[30:31]
	s_nop 0
	v_lshl_add_u64 v[160:161], v[68:69], 0, s[30:31]
	s_nop 0
	s_nop 0
	s_nop 0
	v_lshl_add_u64 v[162:163], v[70:71], 0, s[30:31]
	s_nop 0
	v_mfma_f32_32x32x16_bf16 v[0:15], v[142:145], v[154:157], v[0:15]
	s_and_b32 m0, s32, 7
	s_lshl_b32 m0, m0, 12
	s_add_i32 m0, m0, 0x18000
	s_nop 0
	global_load_lds_dwordx4 v[158:159], off
	s_nop 0
	v_lshl_add_u64 v[164:165], v[72:73], 0, s[30:31]
	s_nop 0
	s_nop 0
	s_nop 0
	v_lshl_add_u64 v[166:167], v[74:75], 0, s[30:31]
	s_nop 0
	s_nop 0
	s_nop 0
	v_lshl_add_u64 v[168:169], v[76:77], 0, s[30:31]
	s_nop 0
	s_mov_b64 s[30:31], 0x300
	s_nop 0
	ds_read_b128 v[134:137], v83 offset:32768
	ds_read_b128 v[138:141], v82
	ds_read_b128 v[142:145], v83 offset:36864
	ds_read_b128 v[150:153], v82 offset:4096
	s_waitcnt lgkmcnt(1)
	v_mfma_f32_32x32x16_bf16 v[48:63], v[134:137], v[138:141], v[48:63]
	s_nop 0
	v_readfirstlane_b32 s41, v114
	v_mfma_f32_32x32x16_bf16 v[32:47], v[142:145], v[138:141], v[32:47]
	s_and_b32 m0, s32, 7
	s_lshl_b32 m0, m0, 12
	s_add_i32 m0, m0, 0x18400
	s_nop 0
	global_load_lds_dwordx4 v[160:161], off
	s_waitcnt lgkmcnt(0)
	v_mfma_f32_32x32x16_bf16 v[16:31], v[134:137], v[150:153], v[16:31]
	v_mfma_f32_32x32x16_bf16 v[0:15], v[142:145], v[150:153], v[0:15]
	s_and_b32 m0, s32, 7
	s_lshl_b32 m0, m0, 12
	s_add_i32 m0, m0, 0x18800
	s_nop 0
	global_load_lds_dwordx4 v[162:163], off
	ds_read_b128 v[134:137], v85 offset:32768
	ds_read_b128 v[138:141], v84
	ds_read_b128 v[142:145], v85 offset:36864
	ds_read_b128 v[154:157], v84 offset:4096
	s_waitcnt lgkmcnt(1)
	v_mfma_f32_32x32x16_bf16 v[48:63], v[134:137], v[138:141], v[48:63]
	v_mfma_f32_32x32x16_bf16 v[32:47], v[142:145], v[138:141], v[32:47]
	s_and_b32 m0, s32, 7
	s_lshl_b32 m0, m0, 12
	s_add_i32 m0, m0, 0x18c00
	s_nop 0
	global_load_lds_dwordx4 v[164:165], off
	s_waitcnt lgkmcnt(0)
	v_mfma_f32_32x32x16_bf16 v[16:31], v[134:137], v[154:157], v[16:31]
	v_mfma_f32_32x32x16_bf16 v[0:15], v[142:145], v[154:157], v[0:15]
	s_and_b32 m0, s32, 7
	s_lshl_b32 m0, m0, 11
	s_add_i32 m0, m0, 0x20000
	s_nop 0
	global_load_lds_dwordx4 v[166:167], off
	ds_read_b128 v[134:137], v87 offset:32768
	ds_read_b128 v[138:141], v86
	ds_read_b128 v[142:145], v87 offset:36864
	ds_read_b128 v[150:153], v86 offset:4096
	s_waitcnt lgkmcnt(1)
	v_mfma_f32_32x32x16_bf16 v[48:63], v[134:137], v[138:141], v[48:63]
	v_mfma_f32_32x32x16_bf16 v[32:47], v[142:145], v[138:141], v[32:47]
	s_and_b32 m0, s32, 7
	s_lshl_b32 m0, m0, 11
	s_add_i32 m0, m0, 0x20400
	s_nop 0
	global_load_lds_dwordx4 v[168:169], off
	s_waitcnt lgkmcnt(0)
	v_mfma_f32_32x32x16_bf16 v[16:31], v[134:137], v[150:153], v[16:31]
	v_mfma_f32_32x32x16_bf16 v[0:15], v[142:145], v[150:153], v[0:15]
	ds_read_b128 v[134:137], v89 offset:32768
	ds_read_b128 v[138:141], v88
	ds_read_b128 v[142:145], v89 offset:36864
	ds_read_b128 v[154:157], v88 offset:4096
	s_waitcnt lgkmcnt(1)
	v_mfma_f32_32x32x16_bf16 v[48:63], v[134:137], v[138:141], v[48:63]
	v_mfma_f32_32x32x16_bf16 v[32:47], v[142:145], v[138:141], v[32:47]
	s_waitcnt vmcnt(6)
	s_waitcnt lgkmcnt(0)
	s_barrier
	s_waitcnt lgkmcnt(0)
	v_mfma_f32_32x32x16_bf16 v[16:31], v[134:137], v[154:157], v[16:31]
	v_lshl_add_u64 v[170:171], v[66:67], 0, s[30:31]
	s_nop 0
	v_lshl_add_u64 v[172:173], v[68:69], 0, s[30:31]
	s_nop 0
	v_readfirstlane_b32 s42, v115
	s_nop 0
	v_lshl_add_u64 v[174:175], v[70:71], 0, s[30:31]
	s_nop 0
	v_mfma_f32_32x32x16_bf16 v[0:15], v[142:145], v[154:157], v[0:15]
	s_and_b32 m0, s32, 7
	s_lshl_b32 m0, m0, 12
	s_add_i32 m0, m0, 0x0
	s_nop 0
	global_load_lds_dwordx4 v[170:171], off
	s_nop 0
	v_lshl_add_u64 v[176:177], v[72:73], 0, s[30:31]
	s_nop 0
	v_readfirstlane_b32 s43, v116
	s_nop 0
	v_lshl_add_u64 v[178:179], v[74:75], 0, s[30:31]
	s_nop 0
	v_readfirstlane_b32 s44, v117
	s_nop 0
	v_lshl_add_u64 v[180:181], v[76:77], 0, s[30:31]
	s_nop 0
	s_mov_b64 s[30:31], 0x380
	s_nop 0
	ds_read_b128 v[134:137], v92
	ds_read_b128 v[138:141], v82 offset:49152
	ds_read_b128 v[142:145], v90
	ds_read_b128 v[150:153], v82 offset:53248
	s_waitcnt lgkmcnt(1)
	v_mfma_f32_32x32x16_bf16 v[48:63], v[134:137], v[138:141], v[48:63]
	s_nop 0
	v_readfirstlane_b32 s35, v120
	v_readfirstlane_b32 s45, v118
	v_readfirstlane_b32 s46, v119
	v_mfma_f32_32x32x16_bf16 v[32:47], v[142:145], v[138:141], v[32:47]
	s_and_b32 m0, s32, 7
	s_lshl_b32 m0, m0, 12
	s_add_i32 m0, m0, 0x400
	s_nop 0
	global_load_lds_dwordx4 v[172:173], off
	s_waitcnt lgkmcnt(0)
	v_mfma_f32_32x32x16_bf16 v[16:31], v[134:137], v[150:153], v[16:31]
	v_mfma_f32_32x32x16_bf16 v[0:15], v[142:145], v[150:153], v[0:15]
	s_and_b32 m0, s32, 7
	s_lshl_b32 m0, m0, 12
	s_add_i32 m0, m0, 0x800
	s_nop 0
	global_load_lds_dwordx4 v[174:175], off
	ds_read_b128 v[134:137], v93
	ds_read_b128 v[138:141], v84 offset:49152
	ds_read_b128 v[142:145], v91
	ds_read_b128 v[154:157], v84 offset:53248
	s_waitcnt lgkmcnt(1)
	v_mfma_f32_32x32x16_bf16 v[48:63], v[134:137], v[138:141], v[48:63]
	v_mfma_f32_32x32x16_bf16 v[32:47], v[142:145], v[138:141], v[32:47]
	s_and_b32 m0, s32, 7
	s_lshl_b32 m0, m0, 12
	s_add_i32 m0, m0, 0xc00
	s_nop 0
	global_load_lds_dwordx4 v[176:177], off
	s_waitcnt lgkmcnt(0)
	v_mfma_f32_32x32x16_bf16 v[16:31], v[134:137], v[154:157], v[16:31]
	v_mfma_f32_32x32x16_bf16 v[0:15], v[142:145], v[154:157], v[0:15]
	s_and_b32 m0, s32, 7
	s_lshl_b32 m0, m0, 11
	s_add_i32 m0, m0, 0x8000
	s_nop 0
	global_load_lds_dwordx4 v[178:179], off
	ds_read_b128 v[134:137], v95
	ds_read_b128 v[138:141], v86 offset:49152
	ds_read_b128 v[142:145], v94
	ds_read_b128 v[150:153], v86 offset:53248
	s_waitcnt lgkmcnt(1)
	v_mfma_f32_32x32x16_bf16 v[48:63], v[134:137], v[138:141], v[48:63]
	v_mfma_f32_32x32x16_bf16 v[32:47], v[142:145], v[138:141], v[32:47]
	s_and_b32 m0, s32, 7
	s_lshl_b32 m0, m0, 11
	s_add_i32 m0, m0, 0x8400
	s_nop 0
	global_load_lds_dwordx4 v[180:181], off
	s_waitcnt lgkmcnt(0)
	v_mfma_f32_32x32x16_bf16 v[16:31], v[134:137], v[150:153], v[16:31]
	v_mfma_f32_32x32x16_bf16 v[0:15], v[142:145], v[150:153], v[0:15]
	ds_read_b128 v[134:137], v97
	ds_read_b128 v[138:141], v88 offset:49152
	ds_read_b128 v[142:145], v96
	ds_read_b128 v[154:157], v88 offset:53248
	s_waitcnt lgkmcnt(1)
	v_mfma_f32_32x32x16_bf16 v[48:63], v[134:137], v[138:141], v[48:63]
	v_mfma_f32_32x32x16_bf16 v[32:47], v[142:145], v[138:141], v[32:47]
	s_waitcnt vmcnt(6)
	s_waitcnt lgkmcnt(0)
	s_barrier
	s_waitcnt lgkmcnt(0)
	v_mfma_f32_32x32x16_bf16 v[16:31], v[134:137], v[154:157], v[16:31]
	v_lshl_add_u64 v[158:159], v[66:67], 0, s[30:31]
	s_nop 0
	v_lshl_add_u64 v[160:161], v[68:69], 0, s[30:31]
	s_nop 0
	v_readfirstlane_b32 s36, v121
	s_nop 0
	v_lshl_add_u64 v[162:163], v[70:71], 0, s[30:31]
	s_nop 0
	v_mfma_f32_32x32x16_bf16 v[0:15], v[142:145], v[154:157], v[0:15]
	s_and_b32 m0, s32, 7
	s_lshl_b32 m0, m0, 12
	s_add_i32 m0, m0, 0xc000
	s_nop 0
	global_load_lds_dwordx4 v[158:159], off
	s_nop 0
	v_lshl_add_u64 v[164:165], v[72:73], 0, s[30:31]
	s_nop 0
	v_readfirstlane_b32 s37, v122
	s_nop 0
	v_lshl_add_u64 v[166:167], v[74:75], 0, s[30:31]
	s_nop 0
	v_readfirstlane_b32 s38, v123
	s_nop 0
	v_lshl_add_u64 v[168:169], v[76:77], 0, s[30:31]
	s_nop 0
	s_mov_b64 s[30:31], 0x400
	s_nop 0
	ds_read_b128 v[134:137], v98
	ds_read_b128 v[138:141], v100
	ds_read_b128 v[142:145], v99
	ds_read_b128 v[150:153], v101
	s_waitcnt lgkmcnt(1)
	v_mfma_f32_32x32x16_bf16 v[48:63], v[134:137], v[138:141], v[48:63]
	s_nop 0
	v_readfirstlane_b32 s0, v126
	v_readfirstlane_b32 s39, v124
	v_readfirstlane_b32 s40, v125
	v_mfma_f32_32x32x16_bf16 v[32:47], v[142:145], v[138:141], v[32:47]
	s_and_b32 m0, s32, 7
	s_lshl_b32 m0, m0, 12
	s_add_i32 m0, m0, 0xc400
	s_nop 0
	global_load_lds_dwordx4 v[160:161], off
	s_waitcnt lgkmcnt(0)
	v_mfma_f32_32x32x16_bf16 v[16:31], v[134:137], v[150:153], v[16:31]
	v_mfma_f32_32x32x16_bf16 v[0:15], v[142:145], v[150:153], v[0:15]
	s_and_b32 m0, s32, 7
	s_lshl_b32 m0, m0, 12
	s_add_i32 m0, m0, 0xc800
	s_nop 0
	global_load_lds_dwordx4 v[162:163], off
	ds_read_b128 v[134:137], v102
	ds_read_b128 v[138:141], v104
	ds_read_b128 v[142:145], v103
	ds_read_b128 v[154:157], v105
	s_waitcnt lgkmcnt(1)
	v_mfma_f32_32x32x16_bf16 v[48:63], v[134:137], v[138:141], v[48:63]
	v_mfma_f32_32x32x16_bf16 v[32:47], v[142:145], v[138:141], v[32:47]
	s_and_b32 m0, s32, 7
	s_lshl_b32 m0, m0, 12
	s_add_i32 m0, m0, 0xcc00
	s_nop 0
	global_load_lds_dwordx4 v[164:165], off
	s_waitcnt lgkmcnt(0)
	v_mfma_f32_32x32x16_bf16 v[16:31], v[134:137], v[154:157], v[16:31]
	v_mfma_f32_32x32x16_bf16 v[0:15], v[142:145], v[154:157], v[0:15]
	s_and_b32 m0, s32, 7
	s_lshl_b32 m0, m0, 11
	s_add_i32 m0, m0, 0x14000
	s_nop 0
	global_load_lds_dwordx4 v[166:167], off
	ds_read_b128 v[134:137], v106
	ds_read_b128 v[138:141], v108
	ds_read_b128 v[142:145], v107
	ds_read_b128 v[150:153], v109
	s_waitcnt lgkmcnt(1)
	v_mfma_f32_32x32x16_bf16 v[48:63], v[134:137], v[138:141], v[48:63]
	v_mfma_f32_32x32x16_bf16 v[32:47], v[142:145], v[138:141], v[32:47]
	s_and_b32 m0, s32, 7
	s_lshl_b32 m0, m0, 11
	s_add_i32 m0, m0, 0x14400
	s_nop 0
	global_load_lds_dwordx4 v[168:169], off
	s_waitcnt lgkmcnt(0)
	v_mfma_f32_32x32x16_bf16 v[16:31], v[134:137], v[150:153], v[16:31]
	v_mfma_f32_32x32x16_bf16 v[0:15], v[142:145], v[150:153], v[0:15]
	ds_read_b128 v[134:137], v110
	ds_read_b128 v[138:141], v112
	ds_read_b128 v[142:145], v111
	ds_read_b128 v[154:157], v113
	s_waitcnt lgkmcnt(1)
	v_mfma_f32_32x32x16_bf16 v[48:63], v[134:137], v[138:141], v[48:63]
	v_mfma_f32_32x32x16_bf16 v[32:47], v[142:145], v[138:141], v[32:47]
	s_waitcnt vmcnt(6)
	s_waitcnt lgkmcnt(0)
	s_barrier
	s_waitcnt lgkmcnt(0)
	v_mfma_f32_32x32x16_bf16 v[16:31], v[134:137], v[154:157], v[16:31]
	v_lshl_add_u64 v[170:171], v[66:67], 0, s[30:31]
	s_nop 0
	v_lshl_add_u64 v[172:173], v[68:69], 0, s[30:31]
	s_nop 0
	v_readfirstlane_b32 s1, v127
	s_nop 0
	v_lshl_add_u64 v[174:175], v[70:71], 0, s[30:31]
	s_nop 0
	v_mfma_f32_32x32x16_bf16 v[0:15], v[142:145], v[154:157], v[0:15]
	s_and_b32 m0, s32, 7
	s_lshl_b32 m0, m0, 12
	s_add_i32 m0, m0, 0x18000
	s_nop 0
	global_load_lds_dwordx4 v[170:171], off
	s_nop 0
	v_lshl_add_u64 v[176:177], v[72:73], 0, s[30:31]
	s_nop 0
	v_readfirstlane_b32 s24, v128
	s_nop 0
	v_lshl_add_u64 v[178:179], v[74:75], 0, s[30:31]
	s_nop 0
	v_readfirstlane_b32 s28, v129
	s_nop 0
	v_lshl_add_u64 v[180:181], v[76:77], 0, s[30:31]
	s_nop 0
	s_mov_b64 s[30:31], 0x480
	s_nop 0
	ds_read_b128 v[134:137], v83 offset:32768
	ds_read_b128 v[138:141], v82
	ds_read_b128 v[142:145], v83 offset:36864
	ds_read_b128 v[150:153], v82 offset:4096
	s_waitcnt lgkmcnt(1)
	v_mfma_f32_32x32x16_bf16 v[48:63], v[134:137], v[138:141], v[48:63]
	s_nop 0
	v_lshl_add_u64 v[162:163], v[70:71], 0, s[30:31]
	v_readfirstlane_b32 s29, v131
	v_readfirstlane_b32 s34, v130
	v_mfma_f32_32x32x16_bf16 v[32:47], v[142:145], v[138:141], v[32:47]
	s_and_b32 m0, s32, 7
	s_lshl_b32 m0, m0, 12
	s_add_i32 m0, m0, 0x18400
	s_nop 0
	global_load_lds_dwordx4 v[172:173], off
	s_waitcnt lgkmcnt(0)
	v_mfma_f32_32x32x16_bf16 v[16:31], v[134:137], v[150:153], v[16:31]
	v_mfma_f32_32x32x16_bf16 v[0:15], v[142:145], v[150:153], v[0:15]
	s_and_b32 m0, s32, 7
	s_lshl_b32 m0, m0, 12
	s_add_i32 m0, m0, 0x18800
	s_nop 0
	global_load_lds_dwordx4 v[174:175], off
	ds_read_b128 v[134:137], v85 offset:32768
	ds_read_b128 v[138:141], v84
	ds_read_b128 v[142:145], v85 offset:36864
	ds_read_b128 v[154:157], v84 offset:4096
	s_waitcnt lgkmcnt(1)
	v_mfma_f32_32x32x16_bf16 v[48:63], v[134:137], v[138:141], v[48:63]
	v_mfma_f32_32x32x16_bf16 v[32:47], v[142:145], v[138:141], v[32:47]
	s_and_b32 m0, s32, 7
	s_lshl_b32 m0, m0, 12
	s_add_i32 m0, m0, 0x18c00
	s_nop 0
	global_load_lds_dwordx4 v[176:177], off
	s_waitcnt lgkmcnt(0)
	v_mfma_f32_32x32x16_bf16 v[16:31], v[134:137], v[154:157], v[16:31]
	v_mfma_f32_32x32x16_bf16 v[0:15], v[142:145], v[154:157], v[0:15]
	s_and_b32 m0, s32, 7
	s_lshl_b32 m0, m0, 11
	s_add_i32 m0, m0, 0x20000
	s_nop 0
	global_load_lds_dwordx4 v[178:179], off
	ds_read_b128 v[134:137], v87 offset:32768
	ds_read_b128 v[138:141], v86
	ds_read_b128 v[142:145], v87 offset:36864
	ds_read_b128 v[150:153], v86 offset:4096
	s_waitcnt lgkmcnt(1)
	v_mfma_f32_32x32x16_bf16 v[48:63], v[134:137], v[138:141], v[48:63]
	v_mfma_f32_32x32x16_bf16 v[32:47], v[142:145], v[138:141], v[32:47]
	s_and_b32 m0, s32, 7
	s_lshl_b32 m0, m0, 11
	s_add_i32 m0, m0, 0x20400
	s_nop 0
	global_load_lds_dwordx4 v[180:181], off
	s_waitcnt lgkmcnt(0)
	v_mfma_f32_32x32x16_bf16 v[16:31], v[134:137], v[150:153], v[16:31]
	v_mfma_f32_32x32x16_bf16 v[0:15], v[142:145], v[150:153], v[0:15]
	ds_read_b128 v[134:137], v89 offset:32768
	ds_read_b128 v[138:141], v88
	ds_read_b128 v[142:145], v89 offset:36864
	ds_read_b128 v[154:157], v88 offset:4096
	s_waitcnt lgkmcnt(1)
	v_mfma_f32_32x32x16_bf16 v[48:63], v[134:137], v[138:141], v[48:63]
	v_mfma_f32_32x32x16_bf16 v[32:47], v[142:145], v[138:141], v[32:47]
	s_waitcnt vmcnt(6)
	s_waitcnt lgkmcnt(0)
	s_barrier
	s_waitcnt lgkmcnt(0)
	v_mfma_f32_32x32x16_bf16 v[16:31], v[134:137], v[154:157], v[16:31]
	v_lshl_add_u64 v[158:159], v[66:67], 0, s[30:31]
	s_nop 0
	v_lshl_add_u64 v[160:161], v[68:69], 0, s[30:31]
	s_nop 0
	s_nop 0
	s_nop 0
	s_nop 0
	v_mfma_f32_32x32x16_bf16 v[0:15], v[142:145], v[154:157], v[0:15]
	s_and_b32 m0, s32, 7
	s_lshl_b32 m0, m0, 12
	s_add_i32 m0, m0, 0x0
	s_nop 0
	global_load_lds_dwordx4 v[158:159], off
	s_nop 0
	v_lshl_add_u64 v[164:165], v[72:73], 0, s[30:31]
	s_nop 0
	s_nop 0
	s_nop 0
	v_lshl_add_u64 v[166:167], v[74:75], 0, s[30:31]
	s_nop 0
	s_nop 0
	s_nop 0
	v_lshl_add_u64 v[168:169], v[76:77], 0, s[30:31]
	s_nop 0
	s_mov_b64 s[30:31], 0x500
	s_nop 0
	ds_read_b128 v[126:129], v92
	ds_read_b128 v[134:137], v82 offset:49152
	ds_read_b128 v[138:141], v90
	ds_read_b128 v[150:153], v82 offset:53248
	s_waitcnt lgkmcnt(1)
	v_mfma_f32_32x32x16_bf16 v[48:63], v[126:129], v[134:137], v[48:63]
	s_nop 0
	v_lshl_add_u64 v[174:175], v[70:71], 0, s[30:31]
	v_mfma_f32_32x32x16_bf16 v[32:47], v[138:141], v[134:137], v[32:47]
	s_and_b32 m0, s32, 7
	s_lshl_b32 m0, m0, 12
	s_add_i32 m0, m0, 0x400
	s_nop 0
	global_load_lds_dwordx4 v[160:161], off
	s_waitcnt lgkmcnt(0)
	v_mfma_f32_32x32x16_bf16 v[16:31], v[126:129], v[150:153], v[16:31]
	v_mfma_f32_32x32x16_bf16 v[0:15], v[138:141], v[150:153], v[0:15]
	s_and_b32 m0, s32, 7
	s_lshl_b32 m0, m0, 12
	s_add_i32 m0, m0, 0x800
	s_nop 0
	global_load_lds_dwordx4 v[162:163], off
	ds_read_b128 v[126:129], v93
	ds_read_b128 v[134:137], v84 offset:49152
	ds_read_b128 v[138:141], v91
	ds_read_b128 v[154:157], v84 offset:53248
	s_waitcnt lgkmcnt(1)
	v_mfma_f32_32x32x16_bf16 v[48:63], v[126:129], v[134:137], v[48:63]
	v_mfma_f32_32x32x16_bf16 v[32:47], v[138:141], v[134:137], v[32:47]
	s_and_b32 m0, s32, 7
	s_lshl_b32 m0, m0, 12
	s_add_i32 m0, m0, 0xc00
	s_nop 0
	global_load_lds_dwordx4 v[164:165], off
	s_waitcnt lgkmcnt(0)
	v_mfma_f32_32x32x16_bf16 v[16:31], v[126:129], v[154:157], v[16:31]
	v_mfma_f32_32x32x16_bf16 v[0:15], v[138:141], v[154:157], v[0:15]
	s_and_b32 m0, s32, 7
	s_lshl_b32 m0, m0, 11
	s_add_i32 m0, m0, 0x8000
	s_nop 0
	global_load_lds_dwordx4 v[166:167], off
	ds_read_b128 v[126:129], v95
	ds_read_b128 v[134:137], v86 offset:49152
	ds_read_b128 v[138:141], v94
	ds_read_b128 v[150:153], v86 offset:53248
	s_waitcnt lgkmcnt(1)
	v_mfma_f32_32x32x16_bf16 v[48:63], v[126:129], v[134:137], v[48:63]
	v_mfma_f32_32x32x16_bf16 v[32:47], v[138:141], v[134:137], v[32:47]
	s_and_b32 m0, s32, 7
	s_lshl_b32 m0, m0, 11
	s_add_i32 m0, m0, 0x8400
	s_nop 0
	global_load_lds_dwordx4 v[168:169], off
	s_waitcnt lgkmcnt(0)
	v_mfma_f32_32x32x16_bf16 v[16:31], v[126:129], v[150:153], v[16:31]
	v_mfma_f32_32x32x16_bf16 v[0:15], v[138:141], v[150:153], v[0:15]
	ds_read_b128 v[126:129], v97
	ds_read_b128 v[134:137], v88 offset:49152
	ds_read_b128 v[138:141], v96
	ds_read_b128 v[154:157], v88 offset:53248
	s_waitcnt lgkmcnt(1)
	v_mfma_f32_32x32x16_bf16 v[48:63], v[126:129], v[134:137], v[48:63]
	v_mfma_f32_32x32x16_bf16 v[32:47], v[138:141], v[134:137], v[32:47]
	s_waitcnt vmcnt(6)
	s_waitcnt lgkmcnt(0)
	s_barrier
	s_waitcnt lgkmcnt(0)
	v_mfma_f32_32x32x16_bf16 v[16:31], v[126:129], v[154:157], v[16:31]
	v_lshl_add_u64 v[170:171], v[66:67], 0, s[30:31]
	s_nop 0
	v_lshl_add_u64 v[172:173], v[68:69], 0, s[30:31]
	s_nop 0
	s_nop 0
	s_nop 0
	s_nop 0
	v_mfma_f32_32x32x16_bf16 v[0:15], v[138:141], v[154:157], v[0:15]
	s_and_b32 m0, s32, 7
	s_lshl_b32 m0, m0, 12
	s_add_i32 m0, m0, 0xc000
	s_nop 0
	global_load_lds_dwordx4 v[170:171], off
	s_nop 0
	v_lshl_add_u64 v[176:177], v[72:73], 0, s[30:31]
	s_nop 0
	s_nop 0
	s_nop 0
	v_lshl_add_u64 v[178:179], v[74:75], 0, s[30:31]
	s_nop 0
	s_nop 0
	s_nop 0
	v_lshl_add_u64 v[180:181], v[76:77], 0, s[30:31]
	s_nop 0
	s_mov_b64 s[30:31], 0x580
	s_nop 0
	ds_read_b128 v[120:123], v98
	ds_read_b128 v[124:127], v100
	ds_read_b128 v[128:131], v99
	ds_read_b128 v[150:153], v101
	s_waitcnt lgkmcnt(1)
	v_mfma_f32_32x32x16_bf16 v[48:63], v[120:123], v[124:127], v[48:63]
	s_nop 0
	v_lshl_add_u64 v[162:163], v[70:71], 0, s[30:31]
	v_mfma_f32_32x32x16_bf16 v[32:47], v[128:131], v[124:127], v[32:47]
	s_and_b32 m0, s32, 7
	s_lshl_b32 m0, m0, 12
	s_add_i32 m0, m0, 0xc400
	s_nop 0
	global_load_lds_dwordx4 v[172:173], off
	s_waitcnt lgkmcnt(0)
	v_mfma_f32_32x32x16_bf16 v[16:31], v[120:123], v[150:153], v[16:31]
	v_mfma_f32_32x32x16_bf16 v[0:15], v[128:131], v[150:153], v[0:15]
	s_and_b32 m0, s32, 7
	s_lshl_b32 m0, m0, 12
	s_add_i32 m0, m0, 0xc800
	s_nop 0
	global_load_lds_dwordx4 v[174:175], off
	ds_read_b128 v[120:123], v102
	ds_read_b128 v[124:127], v104
	ds_read_b128 v[128:131], v103
	ds_read_b128 v[154:157], v105
	s_waitcnt lgkmcnt(1)
	v_mfma_f32_32x32x16_bf16 v[48:63], v[120:123], v[124:127], v[48:63]
	v_mfma_f32_32x32x16_bf16 v[32:47], v[128:131], v[124:127], v[32:47]
	s_and_b32 m0, s32, 7
	s_lshl_b32 m0, m0, 12
	s_add_i32 m0, m0, 0xcc00
	s_nop 0
	global_load_lds_dwordx4 v[176:177], off
	s_waitcnt lgkmcnt(0)
	v_mfma_f32_32x32x16_bf16 v[16:31], v[120:123], v[154:157], v[16:31]
	v_mfma_f32_32x32x16_bf16 v[0:15], v[128:131], v[154:157], v[0:15]
	s_and_b32 m0, s32, 7
	s_lshl_b32 m0, m0, 11
	s_add_i32 m0, m0, 0x14000
	s_nop 0
	global_load_lds_dwordx4 v[178:179], off
	ds_read_b128 v[120:123], v106
	ds_read_b128 v[124:127], v108
	ds_read_b128 v[128:131], v107
	ds_read_b128 v[150:153], v109
	s_waitcnt lgkmcnt(1)
	v_mfma_f32_32x32x16_bf16 v[48:63], v[120:123], v[124:127], v[48:63]
	v_mfma_f32_32x32x16_bf16 v[32:47], v[128:131], v[124:127], v[32:47]
	s_and_b32 m0, s32, 7
	s_lshl_b32 m0, m0, 11
	s_add_i32 m0, m0, 0x14400
	s_nop 0
	global_load_lds_dwordx4 v[180:181], off
	s_waitcnt lgkmcnt(0)
	v_mfma_f32_32x32x16_bf16 v[16:31], v[120:123], v[150:153], v[16:31]
	v_mfma_f32_32x32x16_bf16 v[0:15], v[128:131], v[150:153], v[0:15]
	ds_read_b128 v[120:123], v110
	ds_read_b128 v[124:127], v112
	ds_read_b128 v[128:131], v111
	ds_read_b128 v[154:157], v113
	s_waitcnt lgkmcnt(1)
	v_mfma_f32_32x32x16_bf16 v[48:63], v[120:123], v[124:127], v[48:63]
	v_mfma_f32_32x32x16_bf16 v[32:47], v[128:131], v[124:127], v[32:47]
	s_waitcnt vmcnt(6)
	s_waitcnt lgkmcnt(0)
	s_barrier
	s_waitcnt lgkmcnt(0)
	v_mfma_f32_32x32x16_bf16 v[16:31], v[120:123], v[154:157], v[16:31]
	v_lshl_add_u64 v[158:159], v[66:67], 0, s[30:31]
	s_nop 0
	v_lshl_add_u64 v[160:161], v[68:69], 0, s[30:31]
	s_nop 0
	s_nop 0
	s_nop 0
	s_nop 0
	v_mfma_f32_32x32x16_bf16 v[0:15], v[128:131], v[154:157], v[0:15]
	s_and_b32 m0, s32, 7
	s_lshl_b32 m0, m0, 12
	s_add_i32 m0, m0, 0x18000
	s_nop 0
	global_load_lds_dwordx4 v[158:159], off
	s_nop 0
	v_lshl_add_u64 v[164:165], v[72:73], 0, s[30:31]
	s_nop 0
	s_nop 0
	s_nop 0
	v_lshl_add_u64 v[166:167], v[74:75], 0, s[30:31]
	s_nop 0
	s_nop 0
	s_nop 0
	v_lshl_add_u64 v[168:169], v[76:77], 0, s[30:31]
	s_nop 0
	s_mov_b64 s[30:31], 0x600
	s_nop 0
	ds_read_b128 v[114:117], v83 offset:32768
	ds_read_b128 v[118:121], v82
	ds_read_b128 v[122:125], v83 offset:36864
	ds_read_b128 v[150:153], v82 offset:4096
	s_waitcnt lgkmcnt(1)
	v_mfma_f32_32x32x16_bf16 v[48:63], v[114:117], v[118:121], v[48:63]
	s_nop 0
	v_mfma_f32_32x32x16_bf16 v[32:47], v[122:125], v[118:121], v[32:47]
	s_and_b32 m0, s32, 7
	s_lshl_b32 m0, m0, 12
	s_add_i32 m0, m0, 0x18400
	s_nop 0
	global_load_lds_dwordx4 v[160:161], off
	s_waitcnt lgkmcnt(0)
	v_mfma_f32_32x32x16_bf16 v[16:31], v[114:117], v[150:153], v[16:31]
	v_mfma_f32_32x32x16_bf16 v[0:15], v[122:125], v[150:153], v[0:15]
	s_and_b32 m0, s32, 7
	s_lshl_b32 m0, m0, 12
	s_add_i32 m0, m0, 0x18800
	s_nop 0
	global_load_lds_dwordx4 v[162:163], off
	ds_read_b128 v[114:117], v85 offset:32768
	ds_read_b128 v[118:121], v84
	ds_read_b128 v[122:125], v85 offset:36864
	ds_read_b128 v[154:157], v84 offset:4096
	s_waitcnt lgkmcnt(1)
	v_mfma_f32_32x32x16_bf16 v[48:63], v[114:117], v[118:121], v[48:63]
	v_mfma_f32_32x32x16_bf16 v[32:47], v[122:125], v[118:121], v[32:47]
	s_and_b32 m0, s32, 7
	s_lshl_b32 m0, m0, 12
	s_add_i32 m0, m0, 0x18c00
	s_nop 0
	global_load_lds_dwordx4 v[164:165], off
	s_waitcnt lgkmcnt(0)
	v_mfma_f32_32x32x16_bf16 v[16:31], v[114:117], v[154:157], v[16:31]
	v_mfma_f32_32x32x16_bf16 v[0:15], v[122:125], v[154:157], v[0:15]
	s_and_b32 m0, s32, 7
	s_lshl_b32 m0, m0, 11
	s_add_i32 m0, m0, 0x20000
	s_nop 0
	global_load_lds_dwordx4 v[166:167], off
	ds_read_b128 v[114:117], v87 offset:32768
	ds_read_b128 v[118:121], v86
	ds_read_b128 v[122:125], v87 offset:36864
	ds_read_b128 v[150:153], v86 offset:4096
	s_waitcnt lgkmcnt(1)
	v_mfma_f32_32x32x16_bf16 v[48:63], v[114:117], v[118:121], v[48:63]
	v_mfma_f32_32x32x16_bf16 v[32:47], v[122:125], v[118:121], v[32:47]
	s_and_b32 m0, s32, 7
	s_lshl_b32 m0, m0, 11
	s_add_i32 m0, m0, 0x20400
	s_nop 0
	global_load_lds_dwordx4 v[168:169], off
	s_waitcnt lgkmcnt(0)
	v_mfma_f32_32x32x16_bf16 v[16:31], v[114:117], v[150:153], v[16:31]
	v_mfma_f32_32x32x16_bf16 v[0:15], v[122:125], v[150:153], v[0:15]
	ds_read_b128 v[114:117], v89 offset:32768
	ds_read_b128 v[118:121], v88
	ds_read_b128 v[122:125], v89 offset:36864
	ds_read_b128 v[154:157], v88 offset:4096
	s_waitcnt lgkmcnt(1)
	v_mfma_f32_32x32x16_bf16 v[48:63], v[114:117], v[118:121], v[48:63]
	v_mfma_f32_32x32x16_bf16 v[32:47], v[122:125], v[118:121], v[32:47]
	s_waitcnt vmcnt(6)
	s_waitcnt lgkmcnt(0)
	s_barrier
	s_waitcnt lgkmcnt(0)
	v_mfma_f32_32x32x16_bf16 v[16:31], v[114:117], v[154:157], v[16:31]
	v_lshl_add_u64 v[170:171], v[66:67], 0, s[30:31]
	s_nop 0
	v_lshl_add_u64 v[172:173], v[68:69], 0, s[30:31]
	s_nop 0
	s_nop 0
	s_nop 0
	v_lshl_add_u64 v[174:175], v[70:71], 0, s[30:31]
	s_nop 0
	v_mfma_f32_32x32x16_bf16 v[0:15], v[122:125], v[154:157], v[0:15]
	s_and_b32 m0, s32, 7
	s_lshl_b32 m0, m0, 12
	s_add_i32 m0, m0, 0x0
	s_nop 0
	global_load_lds_dwordx4 v[170:171], off
	s_nop 0
	v_lshl_add_u64 v[176:177], v[72:73], 0, s[30:31]
	s_nop 0
	s_nop 0
	s_nop 0
	v_lshl_add_u64 v[178:179], v[74:75], 0, s[30:31]
	s_nop 0
	s_nop 0
	s_nop 0
	v_lshl_add_u64 v[180:181], v[76:77], 0, s[30:31]
	s_nop 0
	s_mov_b64 s[30:31], 0x680
	s_nop 0
	ds_read_b128 v[114:117], v92
	ds_read_b128 v[118:121], v82 offset:49152
	ds_read_b128 v[122:125], v90
	ds_read_b128 v[150:153], v82 offset:53248
	s_waitcnt lgkmcnt(1)
	v_mfma_f32_32x32x16_bf16 v[48:63], v[114:117], v[118:121], v[48:63]
	s_nop 0
	v_mfma_f32_32x32x16_bf16 v[32:47], v[122:125], v[118:121], v[32:47]
	s_and_b32 m0, s32, 7
	s_lshl_b32 m0, m0, 12
	s_add_i32 m0, m0, 0x400
	s_nop 0
	global_load_lds_dwordx4 v[172:173], off
	s_waitcnt lgkmcnt(0)
	v_mfma_f32_32x32x16_bf16 v[16:31], v[114:117], v[150:153], v[16:31]
	v_mfma_f32_32x32x16_bf16 v[0:15], v[122:125], v[150:153], v[0:15]
	s_and_b32 m0, s32, 7
	s_lshl_b32 m0, m0, 12
	s_add_i32 m0, m0, 0x800
	s_nop 0
	global_load_lds_dwordx4 v[174:175], off
	ds_read_b128 v[114:117], v93
	ds_read_b128 v[118:121], v84 offset:49152
	ds_read_b128 v[122:125], v91
	ds_read_b128 v[154:157], v84 offset:53248
	s_waitcnt lgkmcnt(1)
	v_mfma_f32_32x32x16_bf16 v[48:63], v[114:117], v[118:121], v[48:63]
	v_mfma_f32_32x32x16_bf16 v[32:47], v[122:125], v[118:121], v[32:47]
	s_and_b32 m0, s32, 7
	s_lshl_b32 m0, m0, 12
	s_add_i32 m0, m0, 0xc00
	s_nop 0
	global_load_lds_dwordx4 v[176:177], off
	s_waitcnt lgkmcnt(0)
	v_mfma_f32_32x32x16_bf16 v[16:31], v[114:117], v[154:157], v[16:31]
	v_mfma_f32_32x32x16_bf16 v[0:15], v[122:125], v[154:157], v[0:15]
	s_and_b32 m0, s32, 7
	s_lshl_b32 m0, m0, 11
	s_add_i32 m0, m0, 0x8000
	s_nop 0
	global_load_lds_dwordx4 v[178:179], off
	ds_read_b128 v[114:117], v95
	ds_read_b128 v[118:121], v86 offset:49152
	ds_read_b128 v[122:125], v94
	ds_read_b128 v[150:153], v86 offset:53248
	s_waitcnt lgkmcnt(1)
	v_mfma_f32_32x32x16_bf16 v[48:63], v[114:117], v[118:121], v[48:63]
	v_mfma_f32_32x32x16_bf16 v[32:47], v[122:125], v[118:121], v[32:47]
	s_and_b32 m0, s32, 7
	s_lshl_b32 m0, m0, 11
	s_add_i32 m0, m0, 0x8400
	s_nop 0
	global_load_lds_dwordx4 v[180:181], off
	s_waitcnt lgkmcnt(0)
	v_mfma_f32_32x32x16_bf16 v[16:31], v[114:117], v[150:153], v[16:31]
	v_mfma_f32_32x32x16_bf16 v[0:15], v[122:125], v[150:153], v[0:15]
	ds_read_b128 v[114:117], v97
	ds_read_b128 v[118:121], v88 offset:49152
	ds_read_b128 v[122:125], v96
	ds_read_b128 v[154:157], v88 offset:53248
	s_waitcnt lgkmcnt(1)
	v_mfma_f32_32x32x16_bf16 v[48:63], v[114:117], v[118:121], v[48:63]
	v_mfma_f32_32x32x16_bf16 v[32:47], v[122:125], v[118:121], v[32:47]
	s_waitcnt vmcnt(6)
	s_waitcnt lgkmcnt(0)
	s_barrier
	s_waitcnt lgkmcnt(0)
	v_mfma_f32_32x32x16_bf16 v[16:31], v[114:117], v[154:157], v[16:31]
	v_lshl_add_u64 v[158:159], v[66:67], 0, s[30:31]
	s_nop 0
	v_lshl_add_u64 v[160:161], v[68:69], 0, s[30:31]
	s_nop 0
	s_nop 0
	s_nop 0
	v_lshl_add_u64 v[162:163], v[70:71], 0, s[30:31]
	s_nop 0
	v_mfma_f32_32x32x16_bf16 v[0:15], v[122:125], v[154:157], v[0:15]
	s_and_b32 m0, s32, 7
	s_lshl_b32 m0, m0, 12
	s_add_i32 m0, m0, 0xc000
	s_nop 0
	global_load_lds_dwordx4 v[158:159], off
	s_nop 0
	v_lshl_add_u64 v[164:165], v[72:73], 0, s[30:31]
	s_nop 0
	s_nop 0
	s_nop 0
	v_lshl_add_u64 v[166:167], v[74:75], 0, s[30:31]
	s_nop 0
	s_nop 0
	s_nop 0
	v_lshl_add_u64 v[168:169], v[76:77], 0, s[30:31]
	s_nop 0
	s_mov_b64 s[30:31], 0x700
	s_nop 0
	ds_read_b128 v[114:117], v98
	ds_read_b128 v[118:121], v100
	ds_read_b128 v[122:125], v99
	ds_read_b128 v[150:153], v101
	s_waitcnt lgkmcnt(1)
	v_mfma_f32_32x32x16_bf16 v[48:63], v[114:117], v[118:121], v[48:63]
	s_nop 0
	v_mfma_f32_32x32x16_bf16 v[32:47], v[122:125], v[118:121], v[32:47]
	s_and_b32 m0, s32, 7
	s_lshl_b32 m0, m0, 12
	s_add_i32 m0, m0, 0xc400
	s_nop 0
	global_load_lds_dwordx4 v[160:161], off
	s_waitcnt lgkmcnt(0)
	v_mfma_f32_32x32x16_bf16 v[16:31], v[114:117], v[150:153], v[16:31]
	v_mfma_f32_32x32x16_bf16 v[0:15], v[122:125], v[150:153], v[0:15]
	s_and_b32 m0, s32, 7
	s_lshl_b32 m0, m0, 12
	s_add_i32 m0, m0, 0xc800
	s_nop 0
	global_load_lds_dwordx4 v[162:163], off
	ds_read_b128 v[114:117], v102
	ds_read_b128 v[118:121], v104
	ds_read_b128 v[122:125], v103
	ds_read_b128 v[154:157], v105
	s_waitcnt lgkmcnt(1)
	v_mfma_f32_32x32x16_bf16 v[48:63], v[114:117], v[118:121], v[48:63]
	v_mfma_f32_32x32x16_bf16 v[32:47], v[122:125], v[118:121], v[32:47]
	s_and_b32 m0, s32, 7
	s_lshl_b32 m0, m0, 12
	s_add_i32 m0, m0, 0xcc00
	s_nop 0
	global_load_lds_dwordx4 v[164:165], off
	s_waitcnt lgkmcnt(0)
	v_mfma_f32_32x32x16_bf16 v[16:31], v[114:117], v[154:157], v[16:31]
	v_mfma_f32_32x32x16_bf16 v[0:15], v[122:125], v[154:157], v[0:15]
	s_and_b32 m0, s32, 7
	s_lshl_b32 m0, m0, 11
	s_add_i32 m0, m0, 0x14000
	s_nop 0
	global_load_lds_dwordx4 v[166:167], off
	ds_read_b128 v[114:117], v106
	ds_read_b128 v[118:121], v108
	ds_read_b128 v[122:125], v107
	ds_read_b128 v[150:153], v109
	s_waitcnt lgkmcnt(1)
	v_mfma_f32_32x32x16_bf16 v[48:63], v[114:117], v[118:121], v[48:63]
	v_mfma_f32_32x32x16_bf16 v[32:47], v[122:125], v[118:121], v[32:47]
	s_and_b32 m0, s32, 7
	s_lshl_b32 m0, m0, 11
	s_add_i32 m0, m0, 0x14400
	s_nop 0
	global_load_lds_dwordx4 v[168:169], off
	s_waitcnt lgkmcnt(0)
	v_mfma_f32_32x32x16_bf16 v[16:31], v[114:117], v[150:153], v[16:31]
	v_mfma_f32_32x32x16_bf16 v[0:15], v[122:125], v[150:153], v[0:15]
	ds_read_b128 v[114:117], v110
	ds_read_b128 v[118:121], v112
	ds_read_b128 v[122:125], v111
	ds_read_b128 v[154:157], v113
	s_waitcnt lgkmcnt(1)
	v_mfma_f32_32x32x16_bf16 v[48:63], v[114:117], v[118:121], v[48:63]
	v_mfma_f32_32x32x16_bf16 v[32:47], v[122:125], v[118:121], v[32:47]
	s_waitcnt vmcnt(6)
	s_waitcnt lgkmcnt(0)
	s_barrier
	s_waitcnt lgkmcnt(0)
	v_mfma_f32_32x32x16_bf16 v[16:31], v[114:117], v[154:157], v[16:31]
	v_lshl_add_u64 v[170:171], v[66:67], 0, s[30:31]
	s_nop 0
	v_lshl_add_u64 v[172:173], v[68:69], 0, s[30:31]
	s_nop 0
	s_nop 0
	s_nop 0
	v_lshl_add_u64 v[174:175], v[70:71], 0, s[30:31]
	s_nop 0
	v_mfma_f32_32x32x16_bf16 v[0:15], v[122:125], v[154:157], v[0:15]
	s_and_b32 m0, s32, 7
	s_lshl_b32 m0, m0, 12
	s_add_i32 m0, m0, 0x18000
	s_nop 0
	global_load_lds_dwordx4 v[170:171], off
	s_nop 0
	v_lshl_add_u64 v[176:177], v[72:73], 0, s[30:31]
	s_nop 0
	s_nop 0
	s_nop 0
	v_lshl_add_u64 v[178:179], v[74:75], 0, s[30:31]
	s_nop 0
	s_nop 0
	s_nop 0
	v_lshl_add_u64 v[180:181], v[76:77], 0, s[30:31]
	s_nop 0
	s_mov_b64 s[30:31], 0x780
	s_nop 0
	ds_read_b128 v[114:117], v83 offset:32768
	ds_read_b128 v[118:121], v82
	ds_read_b128 v[122:125], v83 offset:36864
	ds_read_b128 v[150:153], v82 offset:4096
	s_waitcnt lgkmcnt(1)
	v_mfma_f32_32x32x16_bf16 v[48:63], v[114:117], v[118:121], v[48:63]
	v_lshl_add_u64 v[158:159], v[66:67], 0, s[30:31]
	s_nop 0
	v_mfma_f32_32x32x16_bf16 v[32:47], v[122:125], v[118:121], v[32:47]
	s_and_b32 m0, s32, 7
	s_lshl_b32 m0, m0, 12
	s_add_i32 m0, m0, 0x18400
	s_nop 0
	global_load_lds_dwordx4 v[172:173], off
	s_waitcnt lgkmcnt(0)
	v_mfma_f32_32x32x16_bf16 v[16:31], v[114:117], v[150:153], v[16:31]
	v_mfma_f32_32x32x16_bf16 v[0:15], v[122:125], v[150:153], v[0:15]
	s_and_b32 m0, s32, 7
	s_lshl_b32 m0, m0, 12
	s_add_i32 m0, m0, 0x18800
	s_nop 0
	global_load_lds_dwordx4 v[174:175], off
	ds_read_b128 v[114:117], v85 offset:32768
	ds_read_b128 v[118:121], v84
	ds_read_b128 v[122:125], v85 offset:36864
	ds_read_b128 v[154:157], v84 offset:4096
	s_waitcnt lgkmcnt(1)
	v_mfma_f32_32x32x16_bf16 v[48:63], v[114:117], v[118:121], v[48:63]
	v_mfma_f32_32x32x16_bf16 v[32:47], v[122:125], v[118:121], v[32:47]
	s_and_b32 m0, s32, 7
	s_lshl_b32 m0, m0, 12
	s_add_i32 m0, m0, 0x18c00
	s_nop 0
	global_load_lds_dwordx4 v[176:177], off
	s_waitcnt lgkmcnt(0)
	v_mfma_f32_32x32x16_bf16 v[16:31], v[114:117], v[154:157], v[16:31]
	v_mfma_f32_32x32x16_bf16 v[0:15], v[122:125], v[154:157], v[0:15]
	s_and_b32 m0, s32, 7
	s_lshl_b32 m0, m0, 11
	s_add_i32 m0, m0, 0x20000
	s_nop 0
	global_load_lds_dwordx4 v[178:179], off
	ds_read_b128 v[114:117], v87 offset:32768
	ds_read_b128 v[118:121], v86
	ds_read_b128 v[122:125], v87 offset:36864
	ds_read_b128 v[150:153], v86 offset:4096
	s_waitcnt lgkmcnt(1)
	v_mfma_f32_32x32x16_bf16 v[48:63], v[114:117], v[118:121], v[48:63]
	v_mfma_f32_32x32x16_bf16 v[32:47], v[122:125], v[118:121], v[32:47]
	s_and_b32 m0, s32, 7
	s_lshl_b32 m0, m0, 11
	s_add_i32 m0, m0, 0x20400
	s_nop 0
	global_load_lds_dwordx4 v[180:181], off
	s_waitcnt lgkmcnt(0)
	v_mfma_f32_32x32x16_bf16 v[16:31], v[114:117], v[150:153], v[16:31]
	v_mfma_f32_32x32x16_bf16 v[0:15], v[122:125], v[150:153], v[0:15]
	ds_read_b128 v[114:117], v89 offset:32768
	ds_read_b128 v[118:121], v88
	ds_read_b128 v[122:125], v89 offset:36864
	ds_read_b128 v[154:157], v88 offset:4096
	s_waitcnt lgkmcnt(1)
	v_mfma_f32_32x32x16_bf16 v[48:63], v[114:117], v[118:121], v[48:63]
	v_mfma_f32_32x32x16_bf16 v[32:47], v[122:125], v[118:121], v[32:47]
	s_waitcnt vmcnt(6)
	s_waitcnt lgkmcnt(0)
	s_barrier
	s_nop 0
	v_lshl_add_u64 v[160:161], v[68:69], 0, s[30:31]
	s_nop 0
	s_waitcnt lgkmcnt(0)
	v_mfma_f32_32x32x16_bf16 v[16:31], v[114:117], v[154:157], v[16:31]
	s_nop 0
	v_lshl_add_u64 v[162:163], v[70:71], 0, s[30:31]
	s_nop 0
	s_nop 0
	s_nop 0
	v_lshl_add_u64 v[164:165], v[72:73], 0, s[30:31]
	s_nop 0
	v_mfma_f32_32x32x16_bf16 v[0:15], v[122:125], v[154:157], v[0:15]
	s_and_b32 m0, s32, 7
	s_lshl_b32 m0, m0, 12
	s_add_i32 m0, m0, 0x0
	s_nop 0
	global_load_lds_dwordx4 v[158:159], off
	s_nop 0
	v_lshl_add_u64 v[166:167], v[74:75], 0, s[30:31]
	s_nop 0
	s_nop 0
	s_nop 0
	v_lshl_add_u64 v[168:169], v[76:77], 0, s[30:31]
	s_nop 0
	s_nop 0
	s_nop 0
	ds_read_b128 v[66:69], v92
	ds_read_b128 v[70:73], v82 offset:49152
	ds_read_b128 v[74:77], v90
	ds_read_b128 v[150:153], v82 offset:53248
	s_waitcnt lgkmcnt(1)
	v_mfma_f32_32x32x16_bf16 v[48:63], v[66:69], v[70:73], v[48:63]
	v_mfma_f32_32x32x16_bf16 v[32:47], v[74:77], v[70:73], v[32:47]
	s_and_b32 m0, s32, 7
	s_lshl_b32 m0, m0, 12
	s_add_i32 m0, m0, 0x400
	s_nop 0
	global_load_lds_dwordx4 v[160:161], off
	s_waitcnt lgkmcnt(0)
	v_mfma_f32_32x32x16_bf16 v[16:31], v[66:69], v[150:153], v[16:31]
	v_mfma_f32_32x32x16_bf16 v[0:15], v[74:77], v[150:153], v[0:15]
	s_and_b32 m0, s32, 7
	s_lshl_b32 m0, m0, 12
	s_add_i32 m0, m0, 0x800
	s_nop 0
	global_load_lds_dwordx4 v[162:163], off
	ds_read_b128 v[66:69], v93
	ds_read_b128 v[70:73], v84 offset:49152
	ds_read_b128 v[74:77], v91
	ds_read_b128 v[154:157], v84 offset:53248
	s_waitcnt lgkmcnt(1)
	v_mfma_f32_32x32x16_bf16 v[48:63], v[66:69], v[70:73], v[48:63]
	v_mfma_f32_32x32x16_bf16 v[32:47], v[74:77], v[70:73], v[32:47]
	s_and_b32 m0, s32, 7
	s_lshl_b32 m0, m0, 12
	s_add_i32 m0, m0, 0xc00
	s_nop 0
	global_load_lds_dwordx4 v[164:165], off
	s_waitcnt lgkmcnt(0)
	v_mfma_f32_32x32x16_bf16 v[16:31], v[66:69], v[154:157], v[16:31]
	v_mfma_f32_32x32x16_bf16 v[0:15], v[74:77], v[154:157], v[0:15]
	s_and_b32 m0, s32, 7
	s_lshl_b32 m0, m0, 11
	s_add_i32 m0, m0, 0x8000
	s_nop 0
	global_load_lds_dwordx4 v[166:167], off
	ds_read_b128 v[66:69], v95
	ds_read_b128 v[70:73], v86 offset:49152
	ds_read_b128 v[74:77], v94
	ds_read_b128 v[150:153], v86 offset:53248
	s_waitcnt lgkmcnt(1)
	v_mfma_f32_32x32x16_bf16 v[48:63], v[66:69], v[70:73], v[48:63]
	v_mfma_f32_32x32x16_bf16 v[32:47], v[74:77], v[70:73], v[32:47]
	s_and_b32 m0, s32, 7
	s_lshl_b32 m0, m0, 11
	s_add_i32 m0, m0, 0x8400
	s_nop 0
	global_load_lds_dwordx4 v[168:169], off
	s_waitcnt lgkmcnt(0)
	v_mfma_f32_32x32x16_bf16 v[16:31], v[66:69], v[150:153], v[16:31]
	v_mfma_f32_32x32x16_bf16 v[0:15], v[74:77], v[150:153], v[0:15]
	ds_read_b128 v[66:69], v97
	ds_read_b128 v[70:73], v88 offset:49152
	ds_read_b128 v[74:77], v96
	ds_read_b128 v[154:157], v88 offset:53248
	s_waitcnt lgkmcnt(1)
	v_mfma_f32_32x32x16_bf16 v[48:63], v[66:69], v[70:73], v[48:63]
	v_mfma_f32_32x32x16_bf16 v[32:47], v[74:77], v[70:73], v[32:47]
	s_waitcnt vmcnt(6)
	s_waitcnt lgkmcnt(0)
	s_barrier
	s_waitcnt lgkmcnt(0)
	v_mfma_f32_32x32x16_bf16 v[16:31], v[66:69], v[154:157], v[16:31]
	v_mfma_f32_32x32x16_bf16 v[0:15], v[74:77], v[154:157], v[0:15]
	ds_read_b128 v[66:69], v98
	ds_read_b128 v[70:73], v100
	ds_read_b128 v[74:77], v99
	ds_read_b128 v[150:153], v101
	s_waitcnt lgkmcnt(1)
	v_mfma_f32_32x32x16_bf16 v[48:63], v[66:69], v[70:73], v[48:63]
	v_mfma_f32_32x32x16_bf16 v[32:47], v[74:77], v[70:73], v[32:47]
	s_waitcnt lgkmcnt(0)
	v_mfma_f32_32x32x16_bf16 v[16:31], v[66:69], v[150:153], v[16:31]
	v_mfma_f32_32x32x16_bf16 v[0:15], v[74:77], v[150:153], v[0:15]
	ds_read_b128 v[66:69], v102
	ds_read_b128 v[70:73], v104
	ds_read_b128 v[74:77], v103
	ds_read_b128 v[154:157], v105
	s_waitcnt lgkmcnt(1)
	v_mfma_f32_32x32x16_bf16 v[48:63], v[66:69], v[70:73], v[48:63]
	v_mfma_f32_32x32x16_bf16 v[32:47], v[74:77], v[70:73], v[32:47]
	s_waitcnt lgkmcnt(0)
	v_mfma_f32_32x32x16_bf16 v[16:31], v[66:69], v[154:157], v[16:31]
	v_mfma_f32_32x32x16_bf16 v[0:15], v[74:77], v[154:157], v[0:15]
	ds_read_b128 v[66:69], v106
	ds_read_b128 v[70:73], v108
	ds_read_b128 v[74:77], v107
	ds_read_b128 v[150:153], v109
	s_waitcnt lgkmcnt(1)
	v_mfma_f32_32x32x16_bf16 v[48:63], v[66:69], v[70:73], v[48:63]
	v_mfma_f32_32x32x16_bf16 v[32:47], v[74:77], v[70:73], v[32:47]
	s_waitcnt lgkmcnt(0)
	v_mfma_f32_32x32x16_bf16 v[16:31], v[66:69], v[150:153], v[16:31]
	v_mfma_f32_32x32x16_bf16 v[0:15], v[74:77], v[150:153], v[0:15]
	ds_read_b128 v[66:69], v110
	ds_read_b128 v[70:73], v112
	ds_read_b128 v[74:77], v111
	ds_read_b128 v[154:157], v113
	s_waitcnt lgkmcnt(1)
	v_mfma_f32_32x32x16_bf16 v[48:63], v[66:69], v[70:73], v[48:63]
	v_mfma_f32_32x32x16_bf16 v[32:47], v[74:77], v[70:73], v[32:47]
	s_waitcnt vmcnt(0)
	s_waitcnt lgkmcnt(0)
	s_barrier
	s_waitcnt lgkmcnt(0)
	v_mfma_f32_32x32x16_bf16 v[16:31], v[66:69], v[154:157], v[16:31]
	v_mfma_f32_32x32x16_bf16 v[0:15], v[74:77], v[154:157], v[0:15]
	ds_read_b128 v[66:69], v83 offset:32768
	ds_read_b128 v[70:73], v82
	ds_read_b128 v[74:77], v83 offset:36864
	ds_read_b128 v[150:153], v82 offset:4096
	s_waitcnt lgkmcnt(1)
	v_mfma_f32_32x32x16_bf16 v[48:63], v[66:69], v[70:73], v[48:63]
	v_mfma_f32_32x32x16_bf16 v[32:47], v[74:77], v[70:73], v[32:47]
	s_waitcnt lgkmcnt(0)
	v_mfma_f32_32x32x16_bf16 v[16:31], v[66:69], v[150:153], v[16:31]
	v_mfma_f32_32x32x16_bf16 v[0:15], v[74:77], v[150:153], v[0:15]
	ds_read_b128 v[66:69], v85 offset:32768
	ds_read_b128 v[70:73], v84
	ds_read_b128 v[74:77], v85 offset:36864
	ds_read_b128 v[154:157], v84 offset:4096
	s_waitcnt lgkmcnt(1)
	v_mfma_f32_32x32x16_bf16 v[48:63], v[66:69], v[70:73], v[48:63]
	v_mfma_f32_32x32x16_bf16 v[32:47], v[74:77], v[70:73], v[32:47]
	s_waitcnt lgkmcnt(0)
	v_mfma_f32_32x32x16_bf16 v[16:31], v[66:69], v[154:157], v[16:31]
	v_mfma_f32_32x32x16_bf16 v[0:15], v[74:77], v[154:157], v[0:15]
	ds_read_b128 v[66:69], v87 offset:32768
	ds_read_b128 v[70:73], v86
	ds_read_b128 v[74:77], v87 offset:36864
	ds_read_b128 v[150:153], v86 offset:4096
	s_waitcnt lgkmcnt(1)
	v_mfma_f32_32x32x16_bf16 v[48:63], v[66:69], v[70:73], v[48:63]
	v_mfma_f32_32x32x16_bf16 v[32:47], v[74:77], v[70:73], v[32:47]
	s_waitcnt lgkmcnt(0)
	v_mfma_f32_32x32x16_bf16 v[16:31], v[66:69], v[150:153], v[16:31]
	v_mfma_f32_32x32x16_bf16 v[0:15], v[74:77], v[150:153], v[0:15]
	ds_read_b128 v[66:69], v89 offset:32768
	ds_read_b128 v[70:73], v88
	ds_read_b128 v[74:77], v89 offset:36864
	ds_read_b128 v[82:85], v88 offset:4096
	s_waitcnt lgkmcnt(0)
	s_barrier
	s_waitcnt lgkmcnt(0)
	v_mfma_f32_32x32x16_bf16 v[48:63], v[66:69], v[70:73], v[48:63]
	v_mfma_f32_32x32x16_bf16 v[32:47], v[74:77], v[70:73], v[32:47]
	v_mov_b32_e32 v70, 0
	v_mfma_f32_32x32x16_bf16 v[16:31], v[66:69], v[82:85], v[16:31]
	v_lshl_or_b32 v69, v80, 6, v81
	v_add_u32_e32 v66, s20, v69
	v_cmp_gt_i32_e32 vcc, s69, v66
	v_mov_b32_e32 v68, 0
	v_ashrrev_i32_e32 v67, 31, v66
	v_mfma_f32_32x32x16_bf16 v[0:15], v[74:77], v[82:85], v[0:15]
	s_and_saveexec_b64 s[0:1], vcc
	s_cbranch_execz .LBB0_588
	v_lshl_add_u64 v[70:71], v[66:67], 2, s[76:77]
	global_load_dword v70, v[70:71], off
	s_waitcnt vmcnt(0)
	v_fmamk_f32 v70, v70, 0x3a800000, v188
	v_mul_f32_e32 v71, 0x4b800000, v70
	v_cmp_gt_f32_e32 vcc, s82, v70
	s_nop 1
	v_cndmask_b32_e32 v70, v70, v71, vcc
	v_rsq_f32_e32 v70, v70
	s_nop 0
	v_mul_f32_e32 v71, 0x45800000, v70
	v_cndmask_b32_e32 v70, v70, v71, vcc

.LBB0_612:
	v_readlane_b32 s0, v212, 1
	s_cmp_ge_i32 s56, s0
	s_mov_b64 s[0:1], -1
	s_cbranch_scc0 .LBB0_742
	s_ashr_i32 s1, s52, 31
	s_lshr_b32 s0, s1, 27
	s_add_i32 s2, s52, s0
	s_ashr_i32 s0, s2, 5
	s_and_b32 s2, s2, 0xffe0
	s_sub_i32 s2, s52, s2
	s_lshr_b32 s1, s1, 30
	s_bfe_i32 s20, s2, 0x80000
	s_add_i32 s1, s52, s1
	s_bfe_u32 s20, s20, 0x2000d
	s_and_b32 s1, s1, 0x1fffffc
	s_add_i32 s2, s2, s20
	s_sub_i32 s23, s52, s1
	s_ashr_i32 s1, s0, 31
	s_bfe_i32 s2, s2, 0x80000
	s_lshl_b64 s[20:21], s[0:1], 20
	v_readlane_b32 s22, v215, 46
	s_sext_i32_i16 s2, s2
	s_add_u32 s20, s22, s20
	v_readlane_b32 s22, v215, 47
	v_mov_b32_e32 v12, v133
	s_addc_u32 s21, s22, s21
	s_lshl_b32 s2, s2, 6
	s_and_b32 s22, s2, 0xffffff00
	v_ashrrev_i32_e32 v6, 6, v12
	v_bfe_u32 v7, v12, 3, 3
	v_lshl_or_b32 v8, v6, 5, v7
	v_add_u32_e32 v0, s22, v8
	s_waitcnt lgkmcnt(0)
	v_ashrrev_i32_e32 v1, 31, v0
	v_lshlrev_b64 v[2:3], 11, v[0:1]
	v_bfe_u32 v1, v12, 4, 2
	v_readlane_b32 s28, v215, 50
	v_xor_b32_e32 v1, v1, v12
	v_readlane_b32 s29, v215, 51
	v_lshlrev_b32_e32 v1, 4, v1
	v_and_b32_e32 v64, 0x70, v1
	v_lshl_add_u64 v[2:3], s[28:29], 0, v[2:3]
	v_or_b32_e32 v1, 8, v8
	v_lshl_add_u64 v[66:67], v[2:3], 0, v[64:65]
	v_add_u32_e32 v2, s22, v1
	v_lshrrev_b32_e32 v1, 1, v1
	v_xor_b32_e32 v1, v1, v12
	v_ashrrev_i32_e32 v3, 31, v2
	v_lshlrev_b32_e32 v1, 4, v1
	v_or_b32_e32 v0, 16, v0
	v_lshlrev_b64 v[2:3], 11, v[2:3]
	v_and_b32_e32 v4, 0x70, v1
	v_ashrrev_i32_e32 v1, 31, v0
	v_lshl_add_u64 v[2:3], s[28:29], 0, v[2:3]
	v_mov_b32_e32 v5, v65
	v_lshlrev_b64 v[0:1], 11, v[0:1]
	v_lshl_add_u64 v[68:69], v[2:3], 0, v[4:5]
	v_lshl_add_u64 v[0:1], s[28:29], 0, v[0:1]
	v_or_b32_e32 v2, 24, v8
	v_lshl_add_u64 v[70:71], v[0:1], 0, v[64:65]
	v_add_u32_e32 v0, s22, v2
	v_lshrrev_b32_e32 v2, 1, v2
	v_ashrrev_i32_e32 v1, 31, v0
	v_xor_b32_e32 v2, v2, v12
	v_lshlrev_b64 v[0:1], 11, v[0:1]
	v_lshlrev_b32_e32 v2, 4, v2
	v_lshl_add_u64 v[0:1], s[28:29], 0, v[0:1]
	v_and_b32_e32 v2, 0x70, v2
	v_mov_b32_e32 v3, v65
	s_lshl_b32 s2, s23, 7
	v_lshl_add_u64 v[72:73], v[0:1], 0, v[2:3]
	v_lshl_or_b32 v2, v6, 4, v7
	v_add_u32_e32 v0, s2, v2
	v_lshlrev_b32_e32 v3, 12, v6
	v_ashrrev_i32_e32 v1, 31, v0
	v_add_u32_e32 v125, 0, v3
	v_lshlrev_b64 v[0:1], 11, v[0:1]
	s_waitcnt vmcnt(0)
	v_readfirstlane_b32 s42, v125
	v_add_u32_e32 v126, 0x400, v125
	v_lshl_add_u64 v[0:1], s[20:21], 0, v[0:1]
	v_or_b32_e32 v2, 8, v2
	s_waitcnt lgkmcnt(0)
	s_barrier
	s_mov_b32 m0, s42
	v_readfirstlane_b32 s43, v126
	v_add_u32_e32 v127, 0x800, v125
	v_lshlrev_b32_e32 v5, 11, v6
	v_and_b32_e32 v79, 1, v6
	v_lshl_add_u64 v[74:75], v[0:1], 0, v[64:65]
	v_add_u32_e32 v0, s2, v2
	v_lshrrev_b32_e32 v2, 1, v2
	global_load_lds_dwordx4 v[66:67], off
	s_mov_b32 m0, s43
	v_readfirstlane_b32 s44, v127
	v_add_u32_e32 v128, 0xc00, v125
	v_add_u32_e32 v6, 0, v5
	v_ashrrev_i32_e32 v1, 31, v0
	v_xor_b32_e32 v2, v2, v12
	global_load_lds_dwordx4 v[68:69], off
	s_mov_b32 m0, s44
	v_readfirstlane_b32 s45, v128
	v_add_u32_e32 v130, 0x8000, v6
	v_lshlrev_b64 v[0:1], 11, v[0:1]
	v_lshlrev_b32_e32 v2, 4, v2
	global_load_lds_dwordx4 v[70:71], off
	s_mov_b32 m0, s45
	v_readfirstlane_b32 s46, v130
	v_add_u32_e32 v129, 0x8400, v6
	v_lshl_add_u64 v[0:1], s[20:21], 0, v[0:1]
	v_and_b32_e32 v64, 0x70, v2
	global_load_lds_dwordx4 v[72:73], off
	s_mov_b32 m0, s46
	v_readfirstlane_b32 s47, v129
	v_add_u32_e32 v119, 0xc000, v125
	v_lshl_add_u64 v[76:77], v[0:1], 0, v[64:65]
	global_load_lds_dwordx4 v[74:75], off
	s_mov_b32 m0, s47
	s_mov_b64 s[20:21], 0x80
	v_readfirstlane_b32 s36, v119
	v_add_u32_e32 v120, 0xc400, v125
	global_load_lds_dwordx4 v[76:77], off
	v_lshl_add_u64 v[0:1], v[66:67], 0, s[20:21]
	s_mov_b32 m0, s36
	v_readfirstlane_b32 s37, v120
	v_add_u32_e32 v121, 0xc800, v125
	global_load_lds_dwordx4 v[0:1], off
	v_lshl_add_u64 v[0:1], v[68:69], 0, s[20:21]
	s_mov_b32 m0, s37
	v_readfirstlane_b32 s38, v121
	v_add_u32_e32 v122, 0xcc00, v125
	global_load_lds_dwordx4 v[0:1], off
	v_lshl_add_u64 v[0:1], v[70:71], 0, s[20:21]
	s_mov_b32 m0, s38
	v_readfirstlane_b32 s39, v122
	v_add_u32_e32 v123, s85, v5
	global_load_lds_dwordx4 v[0:1], off
	v_lshl_add_u64 v[0:1], v[72:73], 0, s[20:21]
	s_mov_b32 m0, s39
	v_readfirstlane_b32 s40, v123
	v_add_u32_e32 v124, 0x14400, v6
	global_load_lds_dwordx4 v[0:1], off
	v_lshl_add_u64 v[0:1], v[74:75], 0, s[20:21]
	s_mov_b32 m0, s40
	v_readfirstlane_b32 s41, v124
	global_load_lds_dwordx4 v[0:1], off
	v_lshl_add_u64 v[0:1], v[76:77], 0, s[20:21]
	s_mov_b32 m0, s41
	v_lshrrev_b32_e32 v2, 1, v12
	v_bfe_u32 v64, v12, 5, 1
	global_load_lds_dwordx4 v[0:1], off
	v_add_u32_e32 v113, s3, v3
	v_bitop3_b32 v0, v2, v64, 7 bitop3:0x6c
	s_waitcnt vmcnt(6)
	s_mov_b64 s[30:31], 0x100
	v_readfirstlane_b32 s20, v113
	v_add_u32_e32 v114, 0x400, v113
	v_lshlrev_b32_e32 v110, 4, v0
	s_waitcnt lgkmcnt(0)
	s_barrier
	v_lshl_add_u64 v[0:1], v[66:67], 0, s[30:31]
	s_mov_b32 m0, s20
	v_readfirstlane_b32 s21, v114
	v_add_u32_e32 v115, 0x800, v113
	global_load_lds_dwordx4 v[0:1], off
	v_lshl_add_u64 v[0:1], v[68:69], 0, s[30:31]
	s_mov_b32 m0, s21
	v_readfirstlane_b32 s23, v115
	v_add_u32_e32 v116, 0xc00, v113
	v_readlane_b32 s29, v212, 31
	v_and_b32_e32 v80, 31, v12
	global_load_lds_dwordx4 v[0:1], off
	v_lshl_add_u64 v[0:1], v[70:71], 0, s[30:31]
	s_mov_b32 m0, s23
	v_readfirstlane_b32 s28, v116
	v_add_u32_e32 v117, s29, v5
	v_add_u32_e32 v2, s3, v5
	v_lshlrev_b32_e32 v4, 7, v80
	global_load_lds_dwordx4 v[0:1], off
	v_lshl_add_u64 v[0:1], v[72:73], 0, s[30:31]
	s_mov_b32 m0, s28
	v_readfirstlane_b32 s29, v117
	v_add_u32_e32 v118, 0x8400, v2
	v_lshl_or_b32 v102, v79, 13, v4
	global_load_lds_dwordx4 v[0:1], off
	v_lshl_add_u64 v[0:1], v[74:75], 0, s[30:31]
	s_mov_b32 m0, s29
	v_readfirstlane_b32 s33, v118
	global_load_lds_dwordx4 v[0:1], off
	v_lshl_add_u64 v[0:1], v[76:77], 0, s[30:31]
	s_mov_b32 m0, s33
	v_add_u32_e32 v100, 0, v102
	global_load_lds_dwordx4 v[0:1], off
	v_add_u32_e32 v82, v100, v110
	v_ashrrev_i32_e32 v78, 7, v12
	ds_read_b128 v[0:3], v82 offset:32768
	ds_read_b128 v[8:11], v82 offset:36864
	v_lshl_or_b32 v111, v78, 13, v4
	v_add_u32_e32 v101, 0, v111
	v_add_u32_e32 v81, v101, v110
	ds_read_b128 v[4:7], v81
	ds_read_b128 v[154:157], v81 offset:4096
	s_waitcnt lgkmcnt(1)
	v_lshrrev_b32_e32 v182, 6, v133
	s_nop 0
	v_readfirstlane_b32 s32, v182
	v_mfma_f32_32x32x16_bf16 v[48:63], v[0:3], v[4:7], 0
	v_bfe_u32 v103, v12, 1, 3
	v_bitop3_b32 v85, v64, v103, 4 bitop3:0x36
	v_lshlrev_b32_e32 v131, 4, v85
	v_add_u32_e32 v85, v101, v131
	s_mov_b64 s[30:31], 0x180
	s_nop 0
	v_or_b32_e32 v146, 0x8000, v102
	s_waitcnt vmcnt(12)
	v_mfma_f32_32x32x16_bf16 v[32:47], v[8:11], v[4:7], 0
	v_or_b32_e32 v147, 0x9000, v102
	v_add_u32_e32 v138, s3, v110
	v_add_u32_e32 v148, s3, v111
	v_or_b32_e32 v149, 0x1000, v111
	s_mov_b64 s[60:61], 0x80
	s_mov_b64 s[80:81], 0x200
	s_waitcnt lgkmcnt(0)
	v_mfma_f32_32x32x16_bf16 v[16:31], v[0:3], v[154:157], 0
	v_bitop3_b32 v0, v64, v103, 2 bitop3:0x36
	v_lshlrev_b32_e32 v112, 4, v0
	v_add_u32_e32 v84, v100, v112
	ds_read_b128 v[86:89], v84 offset:32768
	ds_read_b128 v[94:97], v84 offset:36864
	v_add_u32_e32 v83, v101, v112
	ds_read_b128 v[90:93], v83
	v_mfma_f32_32x32x16_bf16 v[0:15], v[8:11], v[154:157], 0
	v_add_u32_e32 v142, s3, v112
	ds_read_b128 v[150:153], v83 offset:4096
	s_waitcnt lgkmcnt(1)
	v_mfma_f32_32x32x16_bf16 v[48:63], v[86:89], v[90:93], v[48:63]
	v_mfma_f32_32x32x16_bf16 v[32:47], v[94:97], v[90:93], v[32:47]
	s_waitcnt lgkmcnt(0)
	v_mfma_f32_32x32x16_bf16 v[16:31], v[86:89], v[150:153], v[16:31]
	v_add_u32_e32 v86, v100, v131
	v_bitop3_b32 v87, v64, v103, 6 bitop3:0x36
	v_lshlrev_b32_e32 v132, 4, v87
	v_add_u32_e32 v87, v101, v132
	v_lshlrev_b32_e32 v64, 2, v64
	v_mfma_f32_32x32x16_bf16 v[0:15], v[94:97], v[150:153], v[0:15]
	ds_read_b128 v[88:91], v86 offset:32768
	ds_read_b128 v[92:95], v85
	ds_read_b128 v[96:99], v86 offset:36864
	s_waitcnt lgkmcnt(1)
	v_mfma_f32_32x32x16_bf16 v[48:63], v[88:91], v[92:95], v[48:63]
	s_waitcnt lgkmcnt(0)
	v_mfma_f32_32x32x16_bf16 v[32:47], v[96:99], v[92:95], v[32:47]
	ds_read_b128 v[92:95], v85 offset:4096
	s_waitcnt lgkmcnt(0)
	v_mfma_f32_32x32x16_bf16 v[16:31], v[88:91], v[92:95], v[16:31]
	v_add_u32_e32 v88, v100, v132
	v_mfma_f32_32x32x16_bf16 v[0:15], v[96:99], v[92:95], v[0:15]
	ds_read_b128 v[90:93], v88 offset:32768
	ds_read_b128 v[94:97], v87
	ds_read_b128 v[98:101], v88 offset:36864
	s_waitcnt lgkmcnt(1)
	v_mfma_f32_32x32x16_bf16 v[48:63], v[90:93], v[94:97], v[48:63]
	s_waitcnt lgkmcnt(0)
	v_mfma_f32_32x32x16_bf16 v[32:47], v[98:101], v[94:97], v[32:47]
	ds_read_b128 v[94:97], v87 offset:4096
	s_waitcnt vmcnt(6)
	s_waitcnt lgkmcnt(0)
	s_barrier
	s_waitcnt lgkmcnt(0)
	v_mfma_f32_32x32x16_bf16 v[16:31], v[90:93], v[94:97], v[16:31]
	v_lshl_add_u64 v[158:159], v[66:67], 0, s[30:31]
	s_nop 0
	v_lshl_add_u64 v[160:161], v[68:69], 0, s[30:31]
	s_nop 0
	s_nop 0
	s_nop 0
	v_lshl_add_u64 v[162:163], v[70:71], 0, s[30:31]
	s_nop 0
	v_mfma_f32_32x32x16_bf16 v[0:15], v[98:101], v[94:97], v[0:15]
	s_and_b32 m0, s32, 7
	s_lshl_b32 m0, m0, 12
	s_add_i32 m0, m0, 0x0
	s_nop 0
	global_load_lds_dwordx4 v[158:159], off
	s_nop 0
	v_lshl_add_u64 v[164:165], v[72:73], 0, s[30:31]
	s_nop 0
	s_nop 0
	s_nop 0
	v_lshl_add_u64 v[166:167], v[74:75], 0, s[30:31]
	s_nop 0
	s_nop 0
	s_nop 0
	v_lshl_add_u64 v[168:169], v[76:77], 0, s[30:31]
	s_add_i32 s30, 0, 0xc000
	s_nop 0
	v_add_u32_e32 v89, s30, v110
	s_nop 0
	v_add_u32_e32 v91, v89, v146
	v_add_u32_e32 v89, v89, v147
	ds_read_b128 v[92:95], v91
	ds_read_b128 v[96:99], v81 offset:49152
	ds_read_b128 v[100:103], v89
	ds_read_b128 v[154:157], v81 offset:53248
	s_waitcnt lgkmcnt(1)
	v_mfma_f32_32x32x16_bf16 v[48:63], v[92:95], v[96:99], v[48:63]
	v_add_u32_e32 v90, s30, v112
	s_nop 0
	v_mfma_f32_32x32x16_bf16 v[32:47], v[100:103], v[96:99], v[32:47]
	s_and_b32 m0, s32, 7
	s_lshl_b32 m0, m0, 12
	s_add_i32 m0, m0, 0x400
	s_nop 0
	global_load_lds_dwordx4 v[160:161], off
	s_waitcnt lgkmcnt(0)
	v_mfma_f32_32x32x16_bf16 v[16:31], v[92:95], v[154:157], v[16:31]
	v_add_u32_e32 v92, v90, v146
	v_add_u32_e32 v90, v90, v147
	v_add_u32_e32 v93, s30, v131
	v_mfma_f32_32x32x16_bf16 v[0:15], v[100:103], v[154:157], v[0:15]
	s_and_b32 m0, s32, 7
	s_lshl_b32 m0, m0, 12
	s_add_i32 m0, m0, 0x800
	s_nop 0
	global_load_lds_dwordx4 v[162:163], off
	ds_read_b128 v[94:97], v92
	ds_read_b128 v[98:101], v83 offset:49152
	ds_read_b128 v[102:105], v90
	ds_read_b128 v[150:153], v83 offset:53248
	s_waitcnt lgkmcnt(1)
	v_mfma_f32_32x32x16_bf16 v[48:63], v[94:97], v[98:101], v[48:63]
	v_mfma_f32_32x32x16_bf16 v[32:47], v[102:105], v[98:101], v[32:47]
	s_and_b32 m0, s32, 7
	s_lshl_b32 m0, m0, 12
	s_add_i32 m0, m0, 0xc00
	s_nop 0
	global_load_lds_dwordx4 v[164:165], off
	s_waitcnt lgkmcnt(0)
	v_mfma_f32_32x32x16_bf16 v[16:31], v[94:97], v[150:153], v[16:31]
	v_add_u32_e32 v94, v93, v146
	v_add_u32_e32 v93, v93, v147
	v_add_u32_e32 v95, s30, v132
	s_mov_b64 s[30:31], 0x200
	v_mfma_f32_32x32x16_bf16 v[0:15], v[102:105], v[150:153], v[0:15]
	s_and_b32 m0, s32, 7
	s_lshl_b32 m0, m0, 11
	s_add_i32 m0, m0, 0x8000
	s_nop 0
	global_load_lds_dwordx4 v[166:167], off
	ds_read_b128 v[96:99], v94
	ds_read_b128 v[100:103], v85 offset:49152
	ds_read_b128 v[104:107], v93
	ds_read_b128 v[154:157], v85 offset:53248
	s_waitcnt lgkmcnt(1)
	v_mfma_f32_32x32x16_bf16 v[48:63], v[96:99], v[100:103], v[48:63]
	v_mfma_f32_32x32x16_bf16 v[32:47], v[104:107], v[100:103], v[32:47]
	s_and_b32 m0, s32, 7
	s_lshl_b32 m0, m0, 11
	s_add_i32 m0, m0, 0x8400
	s_nop 0
	global_load_lds_dwordx4 v[168:169], off
	s_waitcnt lgkmcnt(0)
	v_mfma_f32_32x32x16_bf16 v[16:31], v[96:99], v[154:157], v[16:31]
	v_add_u32_e32 v96, v95, v146
	v_add_u32_e32 v95, v95, v147
	v_add_u32_e32 v97, v138, v146
	v_mfma_f32_32x32x16_bf16 v[0:15], v[104:107], v[154:157], v[0:15]
	ds_read_b128 v[98:101], v96
	ds_read_b128 v[102:105], v87 offset:49152
	ds_read_b128 v[106:109], v95
	ds_read_b128 v[150:153], v87 offset:53248
	s_waitcnt lgkmcnt(1)
	v_mfma_f32_32x32x16_bf16 v[48:63], v[98:101], v[102:105], v[48:63]
	v_mfma_f32_32x32x16_bf16 v[32:47], v[106:109], v[102:105], v[32:47]
	s_waitcnt vmcnt(6)
	s_waitcnt lgkmcnt(0)
	s_barrier
	s_waitcnt lgkmcnt(0)
	v_mfma_f32_32x32x16_bf16 v[16:31], v[98:101], v[150:153], v[16:31]
	v_lshl_add_u64 v[170:171], v[66:67], 0, s[30:31]
	s_nop 0
	v_lshl_add_u64 v[172:173], v[68:69], 0, s[30:31]
	s_nop 0
	s_nop 0
	s_nop 0
	v_lshl_add_u64 v[174:175], v[70:71], 0, s[30:31]
	s_nop 0
	v_mfma_f32_32x32x16_bf16 v[0:15], v[106:109], v[150:153], v[0:15]
	s_and_b32 m0, s32, 7
	s_lshl_b32 m0, m0, 12
	s_add_i32 m0, m0, 0xc000
	s_nop 0
	global_load_lds_dwordx4 v[170:171], off
	s_nop 0
	v_lshl_add_u64 v[176:177], v[72:73], 0, s[30:31]
	s_nop 0
	s_nop 0
	s_nop 0
	v_lshl_add_u64 v[178:179], v[74:75], 0, s[30:31]
	s_nop 0
	s_nop 0
	s_nop 0
	v_lshl_add_u64 v[180:181], v[76:77], 0, s[30:31]
	s_nop 0
	s_mov_b64 s[30:31], 0x280
	s_nop 0
	v_add_u32_e32 v98, v138, v147
	ds_read_b128 v[134:137], v97
	ds_read_b128 v[104:107], v98
	v_add_u32_e32 v99, v148, v110
	ds_read_b128 v[100:103], v99
	s_waitcnt lgkmcnt(0)
	v_mfma_f32_32x32x16_bf16 v[48:63], v[134:137], v[100:103], v[48:63]
	s_nop 0
	v_mfma_f32_32x32x16_bf16 v[32:47], v[104:107], v[100:103], v[32:47]
	s_and_b32 m0, s32, 7
	s_lshl_b32 m0, m0, 12
	s_add_i32 m0, m0, 0xc400
	s_nop 0
	global_load_lds_dwordx4 v[172:173], off
	v_add_u32_e32 v100, v138, v149
	ds_read_b128 v[108:111], v100
	v_add_u32_e32 v101, v142, v146
	v_add_u32_e32 v102, v142, v147
	ds_read_b128 v[138:141], v102
	v_add_u32_e32 v103, v148, v112
	v_add_u32_e32 v112, s3, v131
	s_waitcnt lgkmcnt(0)
	v_mfma_f32_32x32x16_bf16 v[16:31], v[134:137], v[108:111], v[16:31]
	ds_read_b128 v[134:137], v103
	v_mfma_f32_32x32x16_bf16 v[0:15], v[104:107], v[108:111], v[0:15]
	s_and_b32 m0, s32, 7
	s_lshl_b32 m0, m0, 12
	s_add_i32 m0, m0, 0xc800
	s_nop 0
	global_load_lds_dwordx4 v[174:175], off
	ds_read_b128 v[106:109], v101
	v_add_u32_e32 v104, v142, v149
	v_add_u32_e32 v105, v112, v146
	ds_read_b128 v[154:157], v104
	s_waitcnt lgkmcnt(1)
	v_mfma_f32_32x32x16_bf16 v[48:63], v[106:109], v[134:137], v[48:63]
	v_mfma_f32_32x32x16_bf16 v[32:47], v[138:141], v[134:137], v[32:47]
	s_and_b32 m0, s32, 7
	s_lshl_b32 m0, m0, 12
	s_add_i32 m0, m0, 0xcc00
	s_nop 0
	global_load_lds_dwordx4 v[176:177], off
	s_waitcnt lgkmcnt(0)
	v_mfma_f32_32x32x16_bf16 v[16:31], v[106:109], v[154:157], v[16:31]
	v_add_u32_e32 v106, v112, v147
	v_add_u32_e32 v107, v148, v131
	ds_read_b128 v[108:111], v107
	v_mfma_f32_32x32x16_bf16 v[0:15], v[138:141], v[154:157], v[0:15]
	s_and_b32 m0, s32, 7
	s_lshl_b32 m0, m0, 11
	s_add_i32 m0, m0, 0x14000
	s_nop 0
	global_load_lds_dwordx4 v[178:179], off
	ds_read_b128 v[134:137], v105
	ds_read_b128 v[138:141], v106
	s_waitcnt lgkmcnt(0)
	v_mfma_f32_32x32x16_bf16 v[48:63], v[134:137], v[108:111], v[48:63]
	v_mfma_f32_32x32x16_bf16 v[32:47], v[138:141], v[108:111], v[32:47]
	s_and_b32 m0, s32, 7
	s_lshl_b32 m0, m0, 11
	s_add_i32 m0, m0, 0x14400
	s_nop 0
	global_load_lds_dwordx4 v[180:181], off
	v_add_u32_e32 v108, v112, v149
	ds_read_b128 v[142:145], v108
	v_add_u32_e32 v112, s3, v132
	v_add_u32_e32 v109, v112, v146
	v_add_u32_e32 v110, v112, v147
	v_add_u32_e32 v111, v148, v132
	v_add_u32_e32 v112, v112, v149
	s_waitcnt lgkmcnt(0)
	v_mfma_f32_32x32x16_bf16 v[16:31], v[134:137], v[142:145], v[16:31]
	ds_read_b128 v[134:137], v109
	v_mfma_f32_32x32x16_bf16 v[0:15], v[138:141], v[142:145], v[0:15]
	ds_read_b128 v[142:145], v110
	ds_read_b128 v[138:141], v111
	ds_read_b128 v[150:153], v112
	s_waitcnt lgkmcnt(1)
	v_mfma_f32_32x32x16_bf16 v[48:63], v[134:137], v[138:141], v[48:63]
	v_mfma_f32_32x32x16_bf16 v[32:47], v[142:145], v[138:141], v[32:47]
	s_waitcnt vmcnt(6)
	s_waitcnt lgkmcnt(0)
	s_barrier
	s_waitcnt lgkmcnt(0)
	v_mfma_f32_32x32x16_bf16 v[16:31], v[134:137], v[150:153], v[16:31]
	v_lshl_add_u64 v[158:159], v[66:67], 0, s[30:31]
	s_nop 0
	v_lshl_add_u64 v[160:161], v[68:69], 0, s[30:31]
	s_nop 0
	s_nop 0
	s_nop 0
	v_lshl_add_u64 v[162:163], v[70:71], 0, s[30:31]
	s_nop 0
	v_mfma_f32_32x32x16_bf16 v[0:15], v[142:145], v[150:153], v[0:15]
	s_and_b32 m0, s32, 7
	s_lshl_b32 m0, m0, 12
	s_add_i32 m0, m0, 0x18000
	s_nop 0
	global_load_lds_dwordx4 v[158:159], off
	s_nop 0
	v_lshl_add_u64 v[164:165], v[72:73], 0, s[30:31]
	s_nop 0
	s_nop 0
	s_nop 0
	v_lshl_add_u64 v[166:167], v[74:75], 0, s[30:31]
	s_nop 0
	s_nop 0
	s_nop 0
	v_lshl_add_u64 v[168:169], v[76:77], 0, s[30:31]
	s_nop 0
	s_mov_b64 s[30:31], 0x300
	s_nop 0
	ds_read_b128 v[134:137], v82 offset:32768
	ds_read_b128 v[138:141], v81
	ds_read_b128 v[142:145], v82 offset:36864
	ds_read_b128 v[154:157], v81 offset:4096
	s_waitcnt lgkmcnt(1)
	v_mfma_f32_32x32x16_bf16 v[48:63], v[134:137], v[138:141], v[48:63]
	s_nop 0
	v_readfirstlane_b32 s42, v113
	v_mfma_f32_32x32x16_bf16 v[32:47], v[142:145], v[138:141], v[32:47]
	s_and_b32 m0, s32, 7
	s_lshl_b32 m0, m0, 12
	s_add_i32 m0, m0, 0x18400
	s_nop 0
	global_load_lds_dwordx4 v[160:161], off
	s_waitcnt lgkmcnt(0)
	v_mfma_f32_32x32x16_bf16 v[16:31], v[134:137], v[154:157], v[16:31]
	v_mfma_f32_32x32x16_bf16 v[0:15], v[142:145], v[154:157], v[0:15]
	s_and_b32 m0, s32, 7
	s_lshl_b32 m0, m0, 12
	s_add_i32 m0, m0, 0x18800
	s_nop 0
	global_load_lds_dwordx4 v[162:163], off
	ds_read_b128 v[134:137], v84 offset:32768
	ds_read_b128 v[138:141], v83
	ds_read_b128 v[142:145], v84 offset:36864
	ds_read_b128 v[150:153], v83 offset:4096
	s_waitcnt lgkmcnt(1)
	v_mfma_f32_32x32x16_bf16 v[48:63], v[134:137], v[138:141], v[48:63]
	v_mfma_f32_32x32x16_bf16 v[32:47], v[142:145], v[138:141], v[32:47]
	s_and_b32 m0, s32, 7
	s_lshl_b32 m0, m0, 12
	s_add_i32 m0, m0, 0x18c00
	s_nop 0
	global_load_lds_dwordx4 v[164:165], off
	s_waitcnt lgkmcnt(0)
	v_mfma_f32_32x32x16_bf16 v[16:31], v[134:137], v[150:153], v[16:31]
	v_mfma_f32_32x32x16_bf16 v[0:15], v[142:145], v[150:153], v[0:15]
	s_and_b32 m0, s32, 7
	s_lshl_b32 m0, m0, 11
	s_add_i32 m0, m0, 0x20000
	s_nop 0
	global_load_lds_dwordx4 v[166:167], off
	ds_read_b128 v[134:137], v86 offset:32768
	ds_read_b128 v[138:141], v85
	ds_read_b128 v[142:145], v86 offset:36864
	ds_read_b128 v[154:157], v85 offset:4096
	s_waitcnt lgkmcnt(1)
	v_mfma_f32_32x32x16_bf16 v[48:63], v[134:137], v[138:141], v[48:63]
	v_mfma_f32_32x32x16_bf16 v[32:47], v[142:145], v[138:141], v[32:47]
	s_and_b32 m0, s32, 7
	s_lshl_b32 m0, m0, 11
	s_add_i32 m0, m0, 0x20400
	s_nop 0
	global_load_lds_dwordx4 v[168:169], off
	s_waitcnt lgkmcnt(0)
	v_mfma_f32_32x32x16_bf16 v[16:31], v[134:137], v[154:157], v[16:31]
	v_mfma_f32_32x32x16_bf16 v[0:15], v[142:145], v[154:157], v[0:15]
	ds_read_b128 v[134:137], v88 offset:32768
	ds_read_b128 v[138:141], v87
	ds_read_b128 v[142:145], v88 offset:36864
	ds_read_b128 v[150:153], v87 offset:4096
	s_waitcnt lgkmcnt(1)
	v_mfma_f32_32x32x16_bf16 v[48:63], v[134:137], v[138:141], v[48:63]
	v_mfma_f32_32x32x16_bf16 v[32:47], v[142:145], v[138:141], v[32:47]
	s_waitcnt vmcnt(6)
	s_waitcnt lgkmcnt(0)
	s_barrier
	s_waitcnt lgkmcnt(0)
	v_mfma_f32_32x32x16_bf16 v[16:31], v[134:137], v[150:153], v[16:31]
	v_lshl_add_u64 v[170:171], v[66:67], 0, s[30:31]
	s_nop 0
	v_lshl_add_u64 v[172:173], v[68:69], 0, s[30:31]
	s_nop 0
	v_readfirstlane_b32 s43, v114
	s_nop 0
	v_lshl_add_u64 v[174:175], v[70:71], 0, s[30:31]
	s_nop 0
	v_mfma_f32_32x32x16_bf16 v[0:15], v[142:145], v[150:153], v[0:15]
	s_and_b32 m0, s32, 7
	s_lshl_b32 m0, m0, 12
	s_add_i32 m0, m0, 0x0
	s_nop 0
	global_load_lds_dwordx4 v[170:171], off
	s_nop 0
	v_lshl_add_u64 v[176:177], v[72:73], 0, s[30:31]
	s_nop 0
	v_readfirstlane_b32 s44, v115
	s_nop 0
	v_lshl_add_u64 v[178:179], v[74:75], 0, s[30:31]
	s_nop 0
	v_readfirstlane_b32 s45, v116
	s_nop 0
	v_lshl_add_u64 v[180:181], v[76:77], 0, s[30:31]
	s_nop 0
	s_mov_b64 s[30:31], 0x380
	s_nop 0
	ds_read_b128 v[134:137], v91
	ds_read_b128 v[138:141], v81 offset:49152
	ds_read_b128 v[142:145], v89
	ds_read_b128 v[154:157], v81 offset:53248
	s_waitcnt lgkmcnt(1)
	v_mfma_f32_32x32x16_bf16 v[48:63], v[134:137], v[138:141], v[48:63]
	s_nop 0
	v_readfirstlane_b32 s36, v119
	v_readfirstlane_b32 s46, v117
	v_readfirstlane_b32 s47, v118
	v_mfma_f32_32x32x16_bf16 v[32:47], v[142:145], v[138:141], v[32:47]
	s_and_b32 m0, s32, 7
	s_lshl_b32 m0, m0, 12
	s_add_i32 m0, m0, 0x400
	s_nop 0
	global_load_lds_dwordx4 v[172:173], off
	s_waitcnt lgkmcnt(0)
	v_mfma_f32_32x32x16_bf16 v[16:31], v[134:137], v[154:157], v[16:31]
	v_mfma_f32_32x32x16_bf16 v[0:15], v[142:145], v[154:157], v[0:15]
	s_and_b32 m0, s32, 7
	s_lshl_b32 m0, m0, 12
	s_add_i32 m0, m0, 0x800
	s_nop 0
	global_load_lds_dwordx4 v[174:175], off
	ds_read_b128 v[134:137], v92
	ds_read_b128 v[138:141], v83 offset:49152
	ds_read_b128 v[142:145], v90
	ds_read_b128 v[150:153], v83 offset:53248
	s_waitcnt lgkmcnt(1)
	v_mfma_f32_32x32x16_bf16 v[48:63], v[134:137], v[138:141], v[48:63]
	v_mfma_f32_32x32x16_bf16 v[32:47], v[142:145], v[138:141], v[32:47]
	s_and_b32 m0, s32, 7
	s_lshl_b32 m0, m0, 12
	s_add_i32 m0, m0, 0xc00
	s_nop 0
	global_load_lds_dwordx4 v[176:177], off
	s_waitcnt lgkmcnt(0)
	v_mfma_f32_32x32x16_bf16 v[16:31], v[134:137], v[150:153], v[16:31]
	v_mfma_f32_32x32x16_bf16 v[0:15], v[142:145], v[150:153], v[0:15]
	s_and_b32 m0, s32, 7
	s_lshl_b32 m0, m0, 11
	s_add_i32 m0, m0, 0x8000
	s_nop 0
	global_load_lds_dwordx4 v[178:179], off
	ds_read_b128 v[134:137], v94
	ds_read_b128 v[138:141], v85 offset:49152
	ds_read_b128 v[142:145], v93
	ds_read_b128 v[154:157], v85 offset:53248
	s_waitcnt lgkmcnt(1)
	v_mfma_f32_32x32x16_bf16 v[48:63], v[134:137], v[138:141], v[48:63]
	v_mfma_f32_32x32x16_bf16 v[32:47], v[142:145], v[138:141], v[32:47]
	s_and_b32 m0, s32, 7
	s_lshl_b32 m0, m0, 11
	s_add_i32 m0, m0, 0x8400
	s_nop 0
	global_load_lds_dwordx4 v[180:181], off
	s_waitcnt lgkmcnt(0)
	v_mfma_f32_32x32x16_bf16 v[16:31], v[134:137], v[154:157], v[16:31]
	v_mfma_f32_32x32x16_bf16 v[0:15], v[142:145], v[154:157], v[0:15]
	ds_read_b128 v[134:137], v96
	ds_read_b128 v[138:141], v87 offset:49152
	ds_read_b128 v[142:145], v95
	ds_read_b128 v[150:153], v87 offset:53248
	s_waitcnt lgkmcnt(1)
	v_mfma_f32_32x32x16_bf16 v[48:63], v[134:137], v[138:141], v[48:63]
	v_mfma_f32_32x32x16_bf16 v[32:47], v[142:145], v[138:141], v[32:47]
	s_waitcnt vmcnt(6)
	s_waitcnt lgkmcnt(0)
	s_barrier
	s_waitcnt lgkmcnt(0)
	v_mfma_f32_32x32x16_bf16 v[16:31], v[134:137], v[150:153], v[16:31]
	v_lshl_add_u64 v[158:159], v[66:67], 0, s[30:31]
	s_nop 0
	v_lshl_add_u64 v[160:161], v[68:69], 0, s[30:31]
	s_nop 0
	v_readfirstlane_b32 s37, v120
	s_nop 0
	v_lshl_add_u64 v[162:163], v[70:71], 0, s[30:31]
	s_nop 0
	v_mfma_f32_32x32x16_bf16 v[0:15], v[142:145], v[150:153], v[0:15]
	s_and_b32 m0, s32, 7
	s_lshl_b32 m0, m0, 12
	s_add_i32 m0, m0, 0xc000
	s_nop 0
	global_load_lds_dwordx4 v[158:159], off
	s_nop 0
	v_lshl_add_u64 v[164:165], v[72:73], 0, s[30:31]
	s_nop 0
	v_readfirstlane_b32 s38, v121
	s_nop 0
	v_lshl_add_u64 v[166:167], v[74:75], 0, s[30:31]
	s_nop 0
	v_readfirstlane_b32 s39, v122
	s_nop 0
	v_lshl_add_u64 v[168:169], v[76:77], 0, s[30:31]
	s_nop 0
	s_mov_b64 s[30:31], 0x400
	s_nop 0
	ds_read_b128 v[134:137], v97
	ds_read_b128 v[138:141], v99
	ds_read_b128 v[142:145], v98
	ds_read_b128 v[154:157], v100
	s_waitcnt lgkmcnt(1)
	v_mfma_f32_32x32x16_bf16 v[48:63], v[134:137], v[138:141], v[48:63]
	s_nop 0
	v_readfirstlane_b32 s20, v125
	v_readfirstlane_b32 s40, v123
	v_readfirstlane_b32 s41, v124
	v_mfma_f32_32x32x16_bf16 v[32:47], v[142:145], v[138:141], v[32:47]
	s_and_b32 m0, s32, 7
	s_lshl_b32 m0, m0, 12
	s_add_i32 m0, m0, 0xc400
	s_nop 0
	global_load_lds_dwordx4 v[160:161], off
	s_waitcnt lgkmcnt(0)
	v_mfma_f32_32x32x16_bf16 v[16:31], v[134:137], v[154:157], v[16:31]
	v_mfma_f32_32x32x16_bf16 v[0:15], v[142:145], v[154:157], v[0:15]
	s_and_b32 m0, s32, 7
	s_lshl_b32 m0, m0, 12
	s_add_i32 m0, m0, 0xc800
	s_nop 0
	global_load_lds_dwordx4 v[162:163], off
	ds_read_b128 v[134:137], v101
	ds_read_b128 v[138:141], v103
	ds_read_b128 v[142:145], v102
	ds_read_b128 v[150:153], v104
	s_waitcnt lgkmcnt(1)
	v_mfma_f32_32x32x16_bf16 v[48:63], v[134:137], v[138:141], v[48:63]
	v_mfma_f32_32x32x16_bf16 v[32:47], v[142:145], v[138:141], v[32:47]
	s_and_b32 m0, s32, 7
	s_lshl_b32 m0, m0, 12
	s_add_i32 m0, m0, 0xcc00
	s_nop 0
	global_load_lds_dwordx4 v[164:165], off
	s_waitcnt lgkmcnt(0)
	v_mfma_f32_32x32x16_bf16 v[16:31], v[134:137], v[150:153], v[16:31]
	v_mfma_f32_32x32x16_bf16 v[0:15], v[142:145], v[150:153], v[0:15]
	s_and_b32 m0, s32, 7
	s_lshl_b32 m0, m0, 11
	s_add_i32 m0, m0, 0x14000
	s_nop 0
	global_load_lds_dwordx4 v[166:167], off
	ds_read_b128 v[134:137], v105
	ds_read_b128 v[138:141], v107
	ds_read_b128 v[142:145], v106
	ds_read_b128 v[154:157], v108
	s_waitcnt lgkmcnt(1)
	v_mfma_f32_32x32x16_bf16 v[48:63], v[134:137], v[138:141], v[48:63]
	v_mfma_f32_32x32x16_bf16 v[32:47], v[142:145], v[138:141], v[32:47]
	s_and_b32 m0, s32, 7
	s_lshl_b32 m0, m0, 11
	s_add_i32 m0, m0, 0x14400
	s_nop 0
	global_load_lds_dwordx4 v[168:169], off
	s_waitcnt lgkmcnt(0)
	v_mfma_f32_32x32x16_bf16 v[16:31], v[134:137], v[154:157], v[16:31]
	v_mfma_f32_32x32x16_bf16 v[0:15], v[142:145], v[154:157], v[0:15]
	ds_read_b128 v[134:137], v109
	ds_read_b128 v[138:141], v111
	ds_read_b128 v[142:145], v110
	ds_read_b128 v[150:153], v112
	s_waitcnt lgkmcnt(1)
	v_mfma_f32_32x32x16_bf16 v[48:63], v[134:137], v[138:141], v[48:63]
	v_mfma_f32_32x32x16_bf16 v[32:47], v[142:145], v[138:141], v[32:47]
	s_waitcnt vmcnt(6)
	s_waitcnt lgkmcnt(0)
	s_barrier
	s_waitcnt lgkmcnt(0)
	v_mfma_f32_32x32x16_bf16 v[16:31], v[134:137], v[150:153], v[16:31]
	v_lshl_add_u64 v[170:171], v[66:67], 0, s[30:31]
	s_nop 0
	v_lshl_add_u64 v[172:173], v[68:69], 0, s[30:31]
	s_nop 0
	v_readfirstlane_b32 s21, v126
	s_nop 0
	v_lshl_add_u64 v[174:175], v[70:71], 0, s[30:31]
	s_nop 0
	v_mfma_f32_32x32x16_bf16 v[0:15], v[142:145], v[150:153], v[0:15]
	s_and_b32 m0, s32, 7
	s_lshl_b32 m0, m0, 12
	s_add_i32 m0, m0, 0x18000
	s_nop 0
	global_load_lds_dwordx4 v[170:171], off
	s_nop 0
	v_lshl_add_u64 v[176:177], v[72:73], 0, s[30:31]
	s_nop 0
	v_readfirstlane_b32 s23, v127
	s_nop 0
	v_lshl_add_u64 v[178:179], v[74:75], 0, s[30:31]
	s_nop 0
	v_readfirstlane_b32 s28, v128
	s_nop 0
	v_lshl_add_u64 v[180:181], v[76:77], 0, s[30:31]
	s_nop 0
	s_mov_b64 s[30:31], 0x480
	s_nop 0
	ds_read_b128 v[134:137], v82 offset:32768
	ds_read_b128 v[138:141], v81
	ds_read_b128 v[142:145], v82 offset:36864
	ds_read_b128 v[154:157], v81 offset:4096
	s_waitcnt lgkmcnt(1)
	v_mfma_f32_32x32x16_bf16 v[48:63], v[134:137], v[138:141], v[48:63]
	s_nop 0
	v_lshl_add_u64 v[164:165], v[72:73], 0, s[30:31]
	v_readfirstlane_b32 s29, v130
	v_readfirstlane_b32 s33, v129
	v_mfma_f32_32x32x16_bf16 v[32:47], v[142:145], v[138:141], v[32:47]
	s_and_b32 m0, s32, 7
	s_lshl_b32 m0, m0, 12
	s_add_i32 m0, m0, 0x18400
	s_nop 0
	global_load_lds_dwordx4 v[172:173], off
	s_waitcnt lgkmcnt(0)
	v_mfma_f32_32x32x16_bf16 v[16:31], v[134:137], v[154:157], v[16:31]
	v_mfma_f32_32x32x16_bf16 v[0:15], v[142:145], v[154:157], v[0:15]
	s_and_b32 m0, s32, 7
	s_lshl_b32 m0, m0, 12
	s_add_i32 m0, m0, 0x18800
	s_nop 0
	global_load_lds_dwordx4 v[174:175], off
	ds_read_b128 v[134:137], v84 offset:32768
	ds_read_b128 v[138:141], v83
	ds_read_b128 v[142:145], v84 offset:36864
	ds_read_b128 v[150:153], v83 offset:4096
	s_waitcnt lgkmcnt(1)
	v_mfma_f32_32x32x16_bf16 v[48:63], v[134:137], v[138:141], v[48:63]
	v_mfma_f32_32x32x16_bf16 v[32:47], v[142:145], v[138:141], v[32:47]
	s_and_b32 m0, s32, 7
	s_lshl_b32 m0, m0, 12
	s_add_i32 m0, m0, 0x18c00
	s_nop 0
	global_load_lds_dwordx4 v[176:177], off
	s_waitcnt lgkmcnt(0)
	v_mfma_f32_32x32x16_bf16 v[16:31], v[134:137], v[150:153], v[16:31]
	v_mfma_f32_32x32x16_bf16 v[0:15], v[142:145], v[150:153], v[0:15]
	s_and_b32 m0, s32, 7
	s_lshl_b32 m0, m0, 11
	s_add_i32 m0, m0, 0x20000
	s_nop 0
	global_load_lds_dwordx4 v[178:179], off
	ds_read_b128 v[134:137], v86 offset:32768
	ds_read_b128 v[138:141], v85
	ds_read_b128 v[142:145], v86 offset:36864
	ds_read_b128 v[154:157], v85 offset:4096
	s_waitcnt lgkmcnt(1)
	v_mfma_f32_32x32x16_bf16 v[48:63], v[134:137], v[138:141], v[48:63]
	v_mfma_f32_32x32x16_bf16 v[32:47], v[142:145], v[138:141], v[32:47]
	s_and_b32 m0, s32, 7
	s_lshl_b32 m0, m0, 11
	s_add_i32 m0, m0, 0x20400
	s_nop 0
	global_load_lds_dwordx4 v[180:181], off
	s_waitcnt lgkmcnt(0)
	v_mfma_f32_32x32x16_bf16 v[16:31], v[134:137], v[154:157], v[16:31]
	v_mfma_f32_32x32x16_bf16 v[0:15], v[142:145], v[154:157], v[0:15]
	ds_read_b128 v[134:137], v88 offset:32768
	ds_read_b128 v[138:141], v87
	ds_read_b128 v[142:145], v88 offset:36864
	ds_read_b128 v[150:153], v87 offset:4096
	s_waitcnt lgkmcnt(1)
	v_mfma_f32_32x32x16_bf16 v[48:63], v[134:137], v[138:141], v[48:63]
	v_mfma_f32_32x32x16_bf16 v[32:47], v[142:145], v[138:141], v[32:47]
	s_waitcnt vmcnt(6)
	s_waitcnt lgkmcnt(0)
	s_barrier
	s_waitcnt lgkmcnt(0)
	v_mfma_f32_32x32x16_bf16 v[16:31], v[134:137], v[150:153], v[16:31]
	v_lshl_add_u64 v[158:159], v[66:67], 0, s[30:31]
	s_nop 0
	v_lshl_add_u64 v[160:161], v[68:69], 0, s[30:31]
	s_nop 0
	s_nop 0
	s_nop 0
	v_lshl_add_u64 v[162:163], v[70:71], 0, s[30:31]
	s_nop 0
	v_mfma_f32_32x32x16_bf16 v[0:15], v[142:145], v[150:153], v[0:15]
	s_and_b32 m0, s32, 7
	s_lshl_b32 m0, m0, 12
	s_add_i32 m0, m0, 0x0
	s_nop 0
	global_load_lds_dwordx4 v[158:159], off
	s_nop 0
	s_nop 0
	s_nop 0
	s_nop 0
	v_lshl_add_u64 v[166:167], v[74:75], 0, s[30:31]
	s_nop 0
	s_nop 0
	s_nop 0
	v_lshl_add_u64 v[168:169], v[76:77], 0, s[30:31]
	s_nop 0
	s_mov_b64 s[30:31], 0x500
	s_nop 0
	ds_read_b128 v[126:129], v91
	ds_read_b128 v[134:137], v81 offset:49152
	ds_read_b128 v[138:141], v89
	ds_read_b128 v[154:157], v81 offset:53248
	s_waitcnt lgkmcnt(1)
	v_mfma_f32_32x32x16_bf16 v[48:63], v[126:129], v[134:137], v[48:63]
	s_nop 0
	v_lshl_add_u64 v[176:177], v[72:73], 0, s[30:31]
	v_mfma_f32_32x32x16_bf16 v[32:47], v[138:141], v[134:137], v[32:47]
	s_and_b32 m0, s32, 7
	s_lshl_b32 m0, m0, 12
	s_add_i32 m0, m0, 0x400
	s_nop 0
	global_load_lds_dwordx4 v[160:161], off
	s_waitcnt lgkmcnt(0)
	v_mfma_f32_32x32x16_bf16 v[16:31], v[126:129], v[154:157], v[16:31]
	v_mfma_f32_32x32x16_bf16 v[0:15], v[138:141], v[154:157], v[0:15]
	s_and_b32 m0, s32, 7
	s_lshl_b32 m0, m0, 12
	s_add_i32 m0, m0, 0x800
	s_nop 0
	global_load_lds_dwordx4 v[162:163], off
	ds_read_b128 v[126:129], v92
	ds_read_b128 v[134:137], v83 offset:49152
	ds_read_b128 v[138:141], v90
	ds_read_b128 v[150:153], v83 offset:53248
	s_waitcnt lgkmcnt(1)
	v_mfma_f32_32x32x16_bf16 v[48:63], v[126:129], v[134:137], v[48:63]
	v_mfma_f32_32x32x16_bf16 v[32:47], v[138:141], v[134:137], v[32:47]
	s_and_b32 m0, s32, 7
	s_lshl_b32 m0, m0, 12
	s_add_i32 m0, m0, 0xc00
	s_nop 0
	global_load_lds_dwordx4 v[164:165], off
	s_waitcnt lgkmcnt(0)
	v_mfma_f32_32x32x16_bf16 v[16:31], v[126:129], v[150:153], v[16:31]
	v_mfma_f32_32x32x16_bf16 v[0:15], v[138:141], v[150:153], v[0:15]
	s_and_b32 m0, s32, 7
	s_lshl_b32 m0, m0, 11
	s_add_i32 m0, m0, 0x8000
	s_nop 0
	global_load_lds_dwordx4 v[166:167], off
	ds_read_b128 v[126:129], v94
	ds_read_b128 v[134:137], v85 offset:49152
	ds_read_b128 v[138:141], v93
	ds_read_b128 v[154:157], v85 offset:53248
	s_waitcnt lgkmcnt(1)
	v_mfma_f32_32x32x16_bf16 v[48:63], v[126:129], v[134:137], v[48:63]
	v_mfma_f32_32x32x16_bf16 v[32:47], v[138:141], v[134:137], v[32:47]
	s_and_b32 m0, s32, 7
	s_lshl_b32 m0, m0, 11
	s_add_i32 m0, m0, 0x8400
	s_nop 0
	global_load_lds_dwordx4 v[168:169], off
	s_waitcnt lgkmcnt(0)
	v_mfma_f32_32x32x16_bf16 v[16:31], v[126:129], v[154:157], v[16:31]
	v_mfma_f32_32x32x16_bf16 v[0:15], v[138:141], v[154:157], v[0:15]
	ds_read_b128 v[126:129], v96
	ds_read_b128 v[134:137], v87 offset:49152
	ds_read_b128 v[138:141], v95
	ds_read_b128 v[150:153], v87 offset:53248
	s_waitcnt lgkmcnt(1)
	v_mfma_f32_32x32x16_bf16 v[48:63], v[126:129], v[134:137], v[48:63]
	v_mfma_f32_32x32x16_bf16 v[32:47], v[138:141], v[134:137], v[32:47]
	s_waitcnt vmcnt(6)
	s_waitcnt lgkmcnt(0)
	s_barrier
	s_waitcnt lgkmcnt(0)
	v_mfma_f32_32x32x16_bf16 v[16:31], v[126:129], v[150:153], v[16:31]
	v_lshl_add_u64 v[170:171], v[66:67], 0, s[30:31]
	s_nop 0
	v_lshl_add_u64 v[172:173], v[68:69], 0, s[30:31]
	s_nop 0
	s_nop 0
	s_nop 0
	v_lshl_add_u64 v[174:175], v[70:71], 0, s[30:31]
	s_nop 0
	v_mfma_f32_32x32x16_bf16 v[0:15], v[138:141], v[150:153], v[0:15]
	s_and_b32 m0, s32, 7
	s_lshl_b32 m0, m0, 12
	s_add_i32 m0, m0, 0xc000
	s_nop 0
	global_load_lds_dwordx4 v[170:171], off
	s_nop 0
	s_nop 0
	s_nop 0
	s_nop 0
	v_lshl_add_u64 v[178:179], v[74:75], 0, s[30:31]
	s_nop 0
	s_nop 0
	s_nop 0
	v_lshl_add_u64 v[180:181], v[76:77], 0, s[30:31]
	s_nop 0
	s_mov_b64 s[30:31], 0x580
	s_nop 0
	ds_read_b128 v[120:123], v97
	ds_read_b128 v[124:127], v99
	ds_read_b128 v[128:131], v98
	ds_read_b128 v[154:157], v100
	s_waitcnt lgkmcnt(1)
	v_mfma_f32_32x32x16_bf16 v[48:63], v[120:123], v[124:127], v[48:63]
	s_nop 0
	v_lshl_add_u64 v[164:165], v[72:73], 0, s[30:31]
	v_mfma_f32_32x32x16_bf16 v[32:47], v[128:131], v[124:127], v[32:47]
	s_and_b32 m0, s32, 7
	s_lshl_b32 m0, m0, 12
	s_add_i32 m0, m0, 0xc400
	s_nop 0
	global_load_lds_dwordx4 v[172:173], off
	s_waitcnt lgkmcnt(0)
	v_mfma_f32_32x32x16_bf16 v[16:31], v[120:123], v[154:157], v[16:31]
	v_mfma_f32_32x32x16_bf16 v[0:15], v[128:131], v[154:157], v[0:15]
	s_and_b32 m0, s32, 7
	s_lshl_b32 m0, m0, 12
	s_add_i32 m0, m0, 0xc800
	s_nop 0
	global_load_lds_dwordx4 v[174:175], off
	ds_read_b128 v[120:123], v101
	ds_read_b128 v[124:127], v103
	ds_read_b128 v[128:131], v102
	ds_read_b128 v[150:153], v104
	s_waitcnt lgkmcnt(1)
	v_mfma_f32_32x32x16_bf16 v[48:63], v[120:123], v[124:127], v[48:63]
	v_mfma_f32_32x32x16_bf16 v[32:47], v[128:131], v[124:127], v[32:47]
	s_and_b32 m0, s32, 7
	s_lshl_b32 m0, m0, 12
	s_add_i32 m0, m0, 0xcc00
	s_nop 0
	global_load_lds_dwordx4 v[176:177], off
	s_waitcnt lgkmcnt(0)
	v_mfma_f32_32x32x16_bf16 v[16:31], v[120:123], v[150:153], v[16:31]
	v_mfma_f32_32x32x16_bf16 v[0:15], v[128:131], v[150:153], v[0:15]
	s_and_b32 m0, s32, 7
	s_lshl_b32 m0, m0, 11
	s_add_i32 m0, m0, 0x14000
	s_nop 0
	global_load_lds_dwordx4 v[178:179], off
	ds_read_b128 v[120:123], v105
	ds_read_b128 v[124:127], v107
	ds_read_b128 v[128:131], v106
	ds_read_b128 v[154:157], v108
	s_waitcnt lgkmcnt(1)
	v_mfma_f32_32x32x16_bf16 v[48:63], v[120:123], v[124:127], v[48:63]
	v_mfma_f32_32x32x16_bf16 v[32:47], v[128:131], v[124:127], v[32:47]
	s_and_b32 m0, s32, 7
	s_lshl_b32 m0, m0, 11
	s_add_i32 m0, m0, 0x14400
	s_nop 0
	global_load_lds_dwordx4 v[180:181], off
	s_waitcnt lgkmcnt(0)
	v_mfma_f32_32x32x16_bf16 v[16:31], v[120:123], v[154:157], v[16:31]
	v_mfma_f32_32x32x16_bf16 v[0:15], v[128:131], v[154:157], v[0:15]
	ds_read_b128 v[120:123], v109
	ds_read_b128 v[124:127], v111
	ds_read_b128 v[128:131], v110
	ds_read_b128 v[150:153], v112
	s_waitcnt lgkmcnt(1)
	v_mfma_f32_32x32x16_bf16 v[48:63], v[120:123], v[124:127], v[48:63]
	v_mfma_f32_32x32x16_bf16 v[32:47], v[128:131], v[124:127], v[32:47]
	s_waitcnt vmcnt(6)
	s_waitcnt lgkmcnt(0)
	s_barrier
	s_waitcnt lgkmcnt(0)
	v_mfma_f32_32x32x16_bf16 v[16:31], v[120:123], v[150:153], v[16:31]
	v_lshl_add_u64 v[158:159], v[66:67], 0, s[30:31]
	s_nop 0
	v_lshl_add_u64 v[160:161], v[68:69], 0, s[30:31]
	s_nop 0
	s_nop 0
	s_nop 0
	v_lshl_add_u64 v[162:163], v[70:71], 0, s[30:31]
	s_nop 0
	v_mfma_f32_32x32x16_bf16 v[0:15], v[128:131], v[150:153], v[0:15]
	s_and_b32 m0, s32, 7
	s_lshl_b32 m0, m0, 12
	s_add_i32 m0, m0, 0x18000
	s_nop 0
	global_load_lds_dwordx4 v[158:159], off
	s_nop 0
	s_nop 0
	s_nop 0
	s_nop 0
	v_lshl_add_u64 v[166:167], v[74:75], 0, s[30:31]
	s_nop 0
	s_nop 0
	s_nop 0
	v_lshl_add_u64 v[168:169], v[76:77], 0, s[30:31]
	s_nop 0
	s_mov_b64 s[30:31], 0x600
	s_nop 0
	ds_read_b128 v[114:117], v82 offset:32768
	ds_read_b128 v[118:121], v81
	ds_read_b128 v[122:125], v82 offset:36864
	ds_read_b128 v[154:157], v81 offset:4096
	s_waitcnt lgkmcnt(1)
	v_mfma_f32_32x32x16_bf16 v[48:63], v[114:117], v[118:121], v[48:63]
	s_nop 0
	v_mfma_f32_32x32x16_bf16 v[32:47], v[122:125], v[118:121], v[32:47]
	s_and_b32 m0, s32, 7
	s_lshl_b32 m0, m0, 12
	s_add_i32 m0, m0, 0x18400
	s_nop 0
	global_load_lds_dwordx4 v[160:161], off
	s_waitcnt lgkmcnt(0)
	v_mfma_f32_32x32x16_bf16 v[16:31], v[114:117], v[154:157], v[16:31]
	v_mfma_f32_32x32x16_bf16 v[0:15], v[122:125], v[154:157], v[0:15]
	s_and_b32 m0, s32, 7
	s_lshl_b32 m0, m0, 12
	s_add_i32 m0, m0, 0x18800
	s_nop 0
	global_load_lds_dwordx4 v[162:163], off
	ds_read_b128 v[114:117], v84 offset:32768
	ds_read_b128 v[118:121], v83
	ds_read_b128 v[122:125], v84 offset:36864
	ds_read_b128 v[150:153], v83 offset:4096
	s_waitcnt lgkmcnt(1)
	v_mfma_f32_32x32x16_bf16 v[48:63], v[114:117], v[118:121], v[48:63]
	v_mfma_f32_32x32x16_bf16 v[32:47], v[122:125], v[118:121], v[32:47]
	s_and_b32 m0, s32, 7
	s_lshl_b32 m0, m0, 12
	s_add_i32 m0, m0, 0x18c00
	s_nop 0
	global_load_lds_dwordx4 v[164:165], off
	s_waitcnt lgkmcnt(0)
	v_mfma_f32_32x32x16_bf16 v[16:31], v[114:117], v[150:153], v[16:31]
	v_mfma_f32_32x32x16_bf16 v[0:15], v[122:125], v[150:153], v[0:15]
	s_and_b32 m0, s32, 7
	s_lshl_b32 m0, m0, 11
	s_add_i32 m0, m0, 0x20000
	s_nop 0
	global_load_lds_dwordx4 v[166:167], off
	ds_read_b128 v[114:117], v86 offset:32768
	ds_read_b128 v[118:121], v85
	ds_read_b128 v[122:125], v86 offset:36864
	ds_read_b128 v[154:157], v85 offset:4096
	s_waitcnt lgkmcnt(1)
	v_mfma_f32_32x32x16_bf16 v[48:63], v[114:117], v[118:121], v[48:63]
	v_mfma_f32_32x32x16_bf16 v[32:47], v[122:125], v[118:121], v[32:47]
	s_and_b32 m0, s32, 7
	s_lshl_b32 m0, m0, 11
	s_add_i32 m0, m0, 0x20400
	s_nop 0
	global_load_lds_dwordx4 v[168:169], off
	s_waitcnt lgkmcnt(0)
	v_mfma_f32_32x32x16_bf16 v[16:31], v[114:117], v[154:157], v[16:31]
	v_mfma_f32_32x32x16_bf16 v[0:15], v[122:125], v[154:157], v[0:15]
	ds_read_b128 v[114:117], v88 offset:32768
	ds_read_b128 v[118:121], v87
	ds_read_b128 v[122:125], v88 offset:36864
	ds_read_b128 v[150:153], v87 offset:4096
	s_waitcnt lgkmcnt(1)
	v_mfma_f32_32x32x16_bf16 v[48:63], v[114:117], v[118:121], v[48:63]
	v_mfma_f32_32x32x16_bf16 v[32:47], v[122:125], v[118:121], v[32:47]
	s_waitcnt vmcnt(6)
	s_waitcnt lgkmcnt(0)
	s_barrier
	s_waitcnt lgkmcnt(0)
	v_mfma_f32_32x32x16_bf16 v[16:31], v[114:117], v[150:153], v[16:31]
	v_lshl_add_u64 v[170:171], v[66:67], 0, s[30:31]
	s_nop 0
	v_lshl_add_u64 v[172:173], v[68:69], 0, s[30:31]
	s_nop 0
	s_nop 0
	s_nop 0
	v_lshl_add_u64 v[174:175], v[70:71], 0, s[30:31]
	s_nop 0
	v_mfma_f32_32x32x16_bf16 v[0:15], v[122:125], v[150:153], v[0:15]
	s_and_b32 m0, s32, 7
	s_lshl_b32 m0, m0, 12
	s_add_i32 m0, m0, 0x0
	s_nop 0
	global_load_lds_dwordx4 v[170:171], off
	s_nop 0
	v_lshl_add_u64 v[176:177], v[72:73], 0, s[30:31]
	s_nop 0
	s_nop 0
	s_nop 0
	v_lshl_add_u64 v[178:179], v[74:75], 0, s[30:31]
	s_nop 0
	s_nop 0
	s_nop 0
	v_lshl_add_u64 v[180:181], v[76:77], 0, s[30:31]
	s_nop 0
	s_mov_b64 s[30:31], 0x680
	s_nop 0
	ds_read_b128 v[114:117], v91
	ds_read_b128 v[118:121], v81 offset:49152
	ds_read_b128 v[122:125], v89
	ds_read_b128 v[154:157], v81 offset:53248
	s_waitcnt lgkmcnt(1)
	v_mfma_f32_32x32x16_bf16 v[48:63], v[114:117], v[118:121], v[48:63]
	s_nop 0
	v_mfma_f32_32x32x16_bf16 v[32:47], v[122:125], v[118:121], v[32:47]
	s_and_b32 m0, s32, 7
	s_lshl_b32 m0, m0, 12
	s_add_i32 m0, m0, 0x400
	s_nop 0
	global_load_lds_dwordx4 v[172:173], off
	s_waitcnt lgkmcnt(0)
	v_mfma_f32_32x32x16_bf16 v[16:31], v[114:117], v[154:157], v[16:31]
	v_mfma_f32_32x32x16_bf16 v[0:15], v[122:125], v[154:157], v[0:15]
	s_and_b32 m0, s32, 7
	s_lshl_b32 m0, m0, 12
	s_add_i32 m0, m0, 0x800
	s_nop 0
	global_load_lds_dwordx4 v[174:175], off
	ds_read_b128 v[114:117], v92
	ds_read_b128 v[118:121], v83 offset:49152
	ds_read_b128 v[122:125], v90
	ds_read_b128 v[150:153], v83 offset:53248
	s_waitcnt lgkmcnt(1)
	v_mfma_f32_32x32x16_bf16 v[48:63], v[114:117], v[118:121], v[48:63]
	v_mfma_f32_32x32x16_bf16 v[32:47], v[122:125], v[118:121], v[32:47]
	s_and_b32 m0, s32, 7
	s_lshl_b32 m0, m0, 12
	s_add_i32 m0, m0, 0xc00
	s_nop 0
	global_load_lds_dwordx4 v[176:177], off
	s_waitcnt lgkmcnt(0)
	v_mfma_f32_32x32x16_bf16 v[16:31], v[114:117], v[150:153], v[16:31]
	v_mfma_f32_32x32x16_bf16 v[0:15], v[122:125], v[150:153], v[0:15]
	s_and_b32 m0, s32, 7
	s_lshl_b32 m0, m0, 11
	s_add_i32 m0, m0, 0x8000
	s_nop 0
	global_load_lds_dwordx4 v[178:179], off
	ds_read_b128 v[114:117], v94
	ds_read_b128 v[118:121], v85 offset:49152
	ds_read_b128 v[122:125], v93
	ds_read_b128 v[154:157], v85 offset:53248
	s_waitcnt lgkmcnt(1)
	v_mfma_f32_32x32x16_bf16 v[48:63], v[114:117], v[118:121], v[48:63]
	v_mfma_f32_32x32x16_bf16 v[32:47], v[122:125], v[118:121], v[32:47]
	s_and_b32 m0, s32, 7
	s_lshl_b32 m0, m0, 11
	s_add_i32 m0, m0, 0x8400
	s_nop 0
	global_load_lds_dwordx4 v[180:181], off
	s_waitcnt lgkmcnt(0)
	v_mfma_f32_32x32x16_bf16 v[16:31], v[114:117], v[154:157], v[16:31]
	v_mfma_f32_32x32x16_bf16 v[0:15], v[122:125], v[154:157], v[0:15]
	ds_read_b128 v[114:117], v96
	ds_read_b128 v[118:121], v87 offset:49152
	ds_read_b128 v[122:125], v95
	ds_read_b128 v[150:153], v87 offset:53248
	s_waitcnt lgkmcnt(1)
	v_mfma_f32_32x32x16_bf16 v[48:63], v[114:117], v[118:121], v[48:63]
	v_mfma_f32_32x32x16_bf16 v[32:47], v[122:125], v[118:121], v[32:47]
	s_waitcnt vmcnt(6)
	s_waitcnt lgkmcnt(0)
	s_barrier
	s_waitcnt lgkmcnt(0)
	v_mfma_f32_32x32x16_bf16 v[16:31], v[114:117], v[150:153], v[16:31]
	v_lshl_add_u64 v[158:159], v[66:67], 0, s[30:31]
	s_nop 0
	v_lshl_add_u64 v[160:161], v[68:69], 0, s[30:31]
	s_nop 0
	s_nop 0
	s_nop 0
	v_lshl_add_u64 v[162:163], v[70:71], 0, s[30:31]
	s_nop 0
	v_mfma_f32_32x32x16_bf16 v[0:15], v[122:125], v[150:153], v[0:15]
	s_and_b32 m0, s32, 7
	s_lshl_b32 m0, m0, 12
	s_add_i32 m0, m0, 0xc000
	s_nop 0
	global_load_lds_dwordx4 v[158:159], off
	s_nop 0
	v_lshl_add_u64 v[164:165], v[72:73], 0, s[30:31]
	s_nop 0
	s_nop 0
	s_nop 0
	v_lshl_add_u64 v[166:167], v[74:75], 0, s[30:31]
	s_nop 0
	s_nop 0
	s_nop 0
	v_lshl_add_u64 v[168:169], v[76:77], 0, s[30:31]
	s_nop 0
	s_mov_b64 s[30:31], 0x700
	s_nop 0
	ds_read_b128 v[114:117], v97
	ds_read_b128 v[118:121], v99
	ds_read_b128 v[122:125], v98
	ds_read_b128 v[154:157], v100
	s_waitcnt lgkmcnt(1)
	v_mfma_f32_32x32x16_bf16 v[48:63], v[114:117], v[118:121], v[48:63]
	s_nop 0
	v_mfma_f32_32x32x16_bf16 v[32:47], v[122:125], v[118:121], v[32:47]
	s_and_b32 m0, s32, 7
	s_lshl_b32 m0, m0, 12
	s_add_i32 m0, m0, 0xc400
	s_nop 0
	global_load_lds_dwordx4 v[160:161], off
	s_waitcnt lgkmcnt(0)
	v_mfma_f32_32x32x16_bf16 v[16:31], v[114:117], v[154:157], v[16:31]
	v_mfma_f32_32x32x16_bf16 v[0:15], v[122:125], v[154:157], v[0:15]
	s_and_b32 m0, s32, 7
	s_lshl_b32 m0, m0, 12
	s_add_i32 m0, m0, 0xc800
	s_nop 0
	global_load_lds_dwordx4 v[162:163], off
	ds_read_b128 v[114:117], v101
	ds_read_b128 v[118:121], v103
	ds_read_b128 v[122:125], v102
	ds_read_b128 v[150:153], v104
	s_waitcnt lgkmcnt(1)
	v_mfma_f32_32x32x16_bf16 v[48:63], v[114:117], v[118:121], v[48:63]
	v_mfma_f32_32x32x16_bf16 v[32:47], v[122:125], v[118:121], v[32:47]
	s_and_b32 m0, s32, 7
	s_lshl_b32 m0, m0, 12
	s_add_i32 m0, m0, 0xcc00
	s_nop 0
	global_load_lds_dwordx4 v[164:165], off
	s_waitcnt lgkmcnt(0)
	v_mfma_f32_32x32x16_bf16 v[16:31], v[114:117], v[150:153], v[16:31]
	v_mfma_f32_32x32x16_bf16 v[0:15], v[122:125], v[150:153], v[0:15]
	s_and_b32 m0, s32, 7
	s_lshl_b32 m0, m0, 11
	s_add_i32 m0, m0, 0x14000
	s_nop 0
	global_load_lds_dwordx4 v[166:167], off
	ds_read_b128 v[114:117], v105
	ds_read_b128 v[118:121], v107
	ds_read_b128 v[122:125], v106
	ds_read_b128 v[154:157], v108
	s_waitcnt lgkmcnt(1)
	v_mfma_f32_32x32x16_bf16 v[48:63], v[114:117], v[118:121], v[48:63]
	v_mfma_f32_32x32x16_bf16 v[32:47], v[122:125], v[118:121], v[32:47]
	s_and_b32 m0, s32, 7
	s_lshl_b32 m0, m0, 11
	s_add_i32 m0, m0, 0x14400
	s_nop 0
	global_load_lds_dwordx4 v[168:169], off
	s_waitcnt lgkmcnt(0)
	v_mfma_f32_32x32x16_bf16 v[16:31], v[114:117], v[154:157], v[16:31]
	v_mfma_f32_32x32x16_bf16 v[0:15], v[122:125], v[154:157], v[0:15]
	ds_read_b128 v[114:117], v109
	ds_read_b128 v[118:121], v111
	ds_read_b128 v[122:125], v110
	ds_read_b128 v[150:153], v112
	s_waitcnt lgkmcnt(1)
	v_mfma_f32_32x32x16_bf16 v[48:63], v[114:117], v[118:121], v[48:63]
	v_mfma_f32_32x32x16_bf16 v[32:47], v[122:125], v[118:121], v[32:47]
	s_waitcnt vmcnt(6)
	s_waitcnt lgkmcnt(0)
	s_barrier
	s_waitcnt lgkmcnt(0)
	v_mfma_f32_32x32x16_bf16 v[16:31], v[114:117], v[150:153], v[16:31]
	v_lshl_add_u64 v[170:171], v[66:67], 0, s[30:31]
	s_nop 0
	v_lshl_add_u64 v[172:173], v[68:69], 0, s[30:31]
	s_nop 0
	s_nop 0
	s_nop 0
	v_lshl_add_u64 v[174:175], v[70:71], 0, s[30:31]
	s_nop 0
	v_mfma_f32_32x32x16_bf16 v[0:15], v[122:125], v[150:153], v[0:15]
	s_and_b32 m0, s32, 7
	s_lshl_b32 m0, m0, 12
	s_add_i32 m0, m0, 0x18000
	s_nop 0
	global_load_lds_dwordx4 v[170:171], off
	s_nop 0
	v_lshl_add_u64 v[176:177], v[72:73], 0, s[30:31]
	s_nop 0
	s_nop 0
	s_nop 0
	v_lshl_add_u64 v[178:179], v[74:75], 0, s[30:31]
	s_nop 0
	s_nop 0
	s_nop 0
	v_lshl_add_u64 v[180:181], v[76:77], 0, s[30:31]
	s_nop 0
	s_mov_b64 s[30:31], 0x780
	s_nop 0
	ds_read_b128 v[114:117], v82 offset:32768
	ds_read_b128 v[118:121], v81
	ds_read_b128 v[122:125], v82 offset:36864
	ds_read_b128 v[154:157], v81 offset:4096
	s_waitcnt lgkmcnt(1)
	v_mfma_f32_32x32x16_bf16 v[48:63], v[114:117], v[118:121], v[48:63]
	v_lshl_add_u64 v[158:159], v[66:67], 0, s[30:31]
	s_nop 0
	v_readlane_b32 s20, v214, 43
	v_mfma_f32_32x32x16_bf16 v[32:47], v[122:125], v[118:121], v[32:47]
	s_and_b32 m0, s32, 7
	s_lshl_b32 m0, m0, 12
	s_add_i32 m0, m0, 0x18400
	s_nop 0
	global_load_lds_dwordx4 v[172:173], off
	s_waitcnt lgkmcnt(0)
	v_mfma_f32_32x32x16_bf16 v[16:31], v[114:117], v[154:157], v[16:31]
	v_mfma_f32_32x32x16_bf16 v[0:15], v[122:125], v[154:157], v[0:15]
	s_and_b32 m0, s32, 7
	s_lshl_b32 m0, m0, 12
	s_add_i32 m0, m0, 0x18800
	s_nop 0
	global_load_lds_dwordx4 v[174:175], off
	ds_read_b128 v[114:117], v84 offset:32768
	ds_read_b128 v[118:121], v83
	ds_read_b128 v[122:125], v84 offset:36864
	ds_read_b128 v[150:153], v83 offset:4096
	s_waitcnt lgkmcnt(1)
	v_mfma_f32_32x32x16_bf16 v[48:63], v[114:117], v[118:121], v[48:63]
	v_mfma_f32_32x32x16_bf16 v[32:47], v[122:125], v[118:121], v[32:47]
	s_and_b32 m0, s32, 7
	s_lshl_b32 m0, m0, 12
	s_add_i32 m0, m0, 0x18c00
	s_nop 0
	global_load_lds_dwordx4 v[176:177], off
	s_waitcnt lgkmcnt(0)
	v_mfma_f32_32x32x16_bf16 v[16:31], v[114:117], v[150:153], v[16:31]
	v_mfma_f32_32x32x16_bf16 v[0:15], v[122:125], v[150:153], v[0:15]
	s_and_b32 m0, s32, 7
	s_lshl_b32 m0, m0, 11
	s_add_i32 m0, m0, 0x20000
	s_nop 0
	global_load_lds_dwordx4 v[178:179], off
	ds_read_b128 v[114:117], v86 offset:32768
	ds_read_b128 v[118:121], v85
	ds_read_b128 v[122:125], v86 offset:36864
	ds_read_b128 v[154:157], v85 offset:4096
	s_waitcnt lgkmcnt(1)
	v_mfma_f32_32x32x16_bf16 v[48:63], v[114:117], v[118:121], v[48:63]
	v_mfma_f32_32x32x16_bf16 v[32:47], v[122:125], v[118:121], v[32:47]
	s_and_b32 m0, s32, 7
	s_lshl_b32 m0, m0, 11
	s_add_i32 m0, m0, 0x20400
	s_nop 0
	global_load_lds_dwordx4 v[180:181], off
	s_waitcnt lgkmcnt(0)
	v_mfma_f32_32x32x16_bf16 v[16:31], v[114:117], v[154:157], v[16:31]
	v_mfma_f32_32x32x16_bf16 v[0:15], v[122:125], v[154:157], v[0:15]
	ds_read_b128 v[114:117], v88 offset:32768
	ds_read_b128 v[118:121], v87
	ds_read_b128 v[122:125], v88 offset:36864
	ds_read_b128 v[150:153], v87 offset:4096
	s_waitcnt lgkmcnt(1)
	v_mfma_f32_32x32x16_bf16 v[48:63], v[114:117], v[118:121], v[48:63]
	v_mfma_f32_32x32x16_bf16 v[32:47], v[122:125], v[118:121], v[32:47]
	s_waitcnt vmcnt(6)
	s_waitcnt lgkmcnt(0)
	s_barrier
	s_nop 0
	v_lshl_add_u64 v[160:161], v[68:69], 0, s[30:31]
	s_nop 0
	s_waitcnt lgkmcnt(0)
	v_mfma_f32_32x32x16_bf16 v[16:31], v[114:117], v[150:153], v[16:31]
	s_nop 0
	v_lshl_add_u64 v[162:163], v[70:71], 0, s[30:31]
	s_nop 0
	v_readlane_b32 s21, v214, 44
	s_nop 0
	v_lshl_add_u64 v[164:165], v[72:73], 0, s[30:31]
	s_nop 0
	v_mfma_f32_32x32x16_bf16 v[0:15], v[122:125], v[150:153], v[0:15]
	s_and_b32 m0, s32, 7
	s_lshl_b32 m0, m0, 12
	s_add_i32 m0, m0, 0x0
	s_nop 0
	global_load_lds_dwordx4 v[158:159], off
	s_nop 0
	v_lshl_add_u64 v[166:167], v[74:75], 0, s[30:31]
	s_nop 0
	s_lshl_b64 s[28:29], s[0:1], 21
	s_nop 0
	v_lshl_add_u64 v[168:169], v[76:77], 0, s[30:31]
	s_nop 0
	s_add_u32 s20, s20, s28
	s_nop 0
	ds_read_b128 v[66:69], v91
	ds_read_b128 v[70:73], v81 offset:49152
	ds_read_b128 v[74:77], v89
	ds_read_b128 v[154:157], v81 offset:53248
	s_waitcnt lgkmcnt(1)
	v_mfma_f32_32x32x16_bf16 v[48:63], v[66:69], v[70:73], v[48:63]
	s_addc_u32 s21, s21, s29
	v_readlane_b32 s23, v214, 41
	s_add_u32 s36, s23, s28
	v_readlane_b32 s23, v214, 42
	s_addc_u32 s37, s23, s29
	v_mfma_f32_32x32x16_bf16 v[32:47], v[74:77], v[70:73], v[32:47]
	s_and_b32 m0, s32, 7
	s_lshl_b32 m0, m0, 12
	s_add_i32 m0, m0, 0x400
	s_nop 0
	global_load_lds_dwordx4 v[160:161], off
	s_waitcnt lgkmcnt(0)
	v_mfma_f32_32x32x16_bf16 v[16:31], v[66:69], v[154:157], v[16:31]
	v_mfma_f32_32x32x16_bf16 v[0:15], v[74:77], v[154:157], v[0:15]
	s_and_b32 m0, s32, 7
	s_lshl_b32 m0, m0, 12
	s_add_i32 m0, m0, 0x800
	s_nop 0
	global_load_lds_dwordx4 v[162:163], off
	ds_read_b128 v[66:69], v92
	ds_read_b128 v[70:73], v83 offset:49152
	ds_read_b128 v[74:77], v90
	ds_read_b128 v[150:153], v83 offset:53248
	s_waitcnt lgkmcnt(1)
	v_mfma_f32_32x32x16_bf16 v[48:63], v[66:69], v[70:73], v[48:63]
	v_mfma_f32_32x32x16_bf16 v[32:47], v[74:77], v[70:73], v[32:47]
	s_and_b32 m0, s32, 7
	s_lshl_b32 m0, m0, 12
	s_add_i32 m0, m0, 0xc00
	s_nop 0
	global_load_lds_dwordx4 v[164:165], off
	s_waitcnt lgkmcnt(0)
	v_mfma_f32_32x32x16_bf16 v[16:31], v[66:69], v[150:153], v[16:31]
	v_mfma_f32_32x32x16_bf16 v[0:15], v[74:77], v[150:153], v[0:15]
	s_and_b32 m0, s32, 7
	s_lshl_b32 m0, m0, 11
	s_add_i32 m0, m0, 0x8000
	s_nop 0
	global_load_lds_dwordx4 v[166:167], off
	ds_read_b128 v[66:69], v94
	ds_read_b128 v[70:73], v85 offset:49152
	ds_read_b128 v[74:77], v93
	ds_read_b128 v[154:157], v85 offset:53248
	s_waitcnt lgkmcnt(1)
	v_mfma_f32_32x32x16_bf16 v[48:63], v[66:69], v[70:73], v[48:63]
	v_mfma_f32_32x32x16_bf16 v[32:47], v[74:77], v[70:73], v[32:47]
	s_and_b32 m0, s32, 7
	s_lshl_b32 m0, m0, 11
	s_add_i32 m0, m0, 0x8400
	s_nop 0
	global_load_lds_dwordx4 v[168:169], off
	s_waitcnt lgkmcnt(0)
	v_mfma_f32_32x32x16_bf16 v[16:31], v[66:69], v[154:157], v[16:31]
	v_mfma_f32_32x32x16_bf16 v[0:15], v[74:77], v[154:157], v[0:15]
	ds_read_b128 v[66:69], v96
	ds_read_b128 v[70:73], v87 offset:49152
	ds_read_b128 v[74:77], v95
	ds_read_b128 v[150:153], v87 offset:53248
	s_waitcnt lgkmcnt(1)
	v_mfma_f32_32x32x16_bf16 v[48:63], v[66:69], v[70:73], v[48:63]
	v_mfma_f32_32x32x16_bf16 v[32:47], v[74:77], v[70:73], v[32:47]
	s_waitcnt vmcnt(6)
	s_waitcnt lgkmcnt(0)
	s_barrier
	s_waitcnt lgkmcnt(0)
	v_mfma_f32_32x32x16_bf16 v[16:31], v[66:69], v[150:153], v[16:31]
	v_mfma_f32_32x32x16_bf16 v[0:15], v[74:77], v[150:153], v[0:15]
	ds_read_b128 v[66:69], v97
	ds_read_b128 v[70:73], v99
	ds_read_b128 v[74:77], v98
	ds_read_b128 v[154:157], v100
	s_waitcnt lgkmcnt(1)
	v_mfma_f32_32x32x16_bf16 v[48:63], v[66:69], v[70:73], v[48:63]
	v_mfma_f32_32x32x16_bf16 v[32:47], v[74:77], v[70:73], v[32:47]
	s_waitcnt lgkmcnt(0)
	v_mfma_f32_32x32x16_bf16 v[16:31], v[66:69], v[154:157], v[16:31]
	v_mfma_f32_32x32x16_bf16 v[0:15], v[74:77], v[154:157], v[0:15]
	ds_read_b128 v[66:69], v101
	ds_read_b128 v[70:73], v103
	ds_read_b128 v[74:77], v102
	ds_read_b128 v[150:153], v104
	s_waitcnt lgkmcnt(1)
	v_mfma_f32_32x32x16_bf16 v[48:63], v[66:69], v[70:73], v[48:63]
	v_mfma_f32_32x32x16_bf16 v[32:47], v[74:77], v[70:73], v[32:47]
	s_waitcnt lgkmcnt(0)
	v_mfma_f32_32x32x16_bf16 v[16:31], v[66:69], v[150:153], v[16:31]
	v_mfma_f32_32x32x16_bf16 v[0:15], v[74:77], v[150:153], v[0:15]
	ds_read_b128 v[66:69], v105
	ds_read_b128 v[70:73], v107
	ds_read_b128 v[74:77], v106
	ds_read_b128 v[154:157], v108
	s_waitcnt lgkmcnt(1)
	v_mfma_f32_32x32x16_bf16 v[48:63], v[66:69], v[70:73], v[48:63]
	v_mfma_f32_32x32x16_bf16 v[32:47], v[74:77], v[70:73], v[32:47]
	s_waitcnt lgkmcnt(0)
	v_mfma_f32_32x32x16_bf16 v[16:31], v[66:69], v[154:157], v[16:31]
	v_mfma_f32_32x32x16_bf16 v[0:15], v[74:77], v[154:157], v[0:15]
	ds_read_b128 v[66:69], v109
	ds_read_b128 v[70:73], v111
	ds_read_b128 v[74:77], v110
	ds_read_b128 v[150:153], v112
	s_waitcnt lgkmcnt(1)
	v_mfma_f32_32x32x16_bf16 v[48:63], v[66:69], v[70:73], v[48:63]
	v_mfma_f32_32x32x16_bf16 v[32:47], v[74:77], v[70:73], v[32:47]
	s_waitcnt vmcnt(0)
	s_waitcnt lgkmcnt(0)
	s_barrier
	s_waitcnt lgkmcnt(0)
	v_mfma_f32_32x32x16_bf16 v[16:31], v[66:69], v[150:153], v[16:31]
	v_mfma_f32_32x32x16_bf16 v[0:15], v[74:77], v[150:153], v[0:15]
	ds_read_b128 v[66:69], v82 offset:32768
	ds_read_b128 v[70:73], v81
	ds_read_b128 v[74:77], v82 offset:36864
	ds_read_b128 v[154:157], v81 offset:4096
	s_waitcnt lgkmcnt(1)
	v_mfma_f32_32x32x16_bf16 v[48:63], v[66:69], v[70:73], v[48:63]
	v_mfma_f32_32x32x16_bf16 v[32:47], v[74:77], v[70:73], v[32:47]
	s_waitcnt lgkmcnt(0)
	v_mfma_f32_32x32x16_bf16 v[16:31], v[66:69], v[154:157], v[16:31]
	v_mfma_f32_32x32x16_bf16 v[0:15], v[74:77], v[154:157], v[0:15]
	ds_read_b128 v[66:69], v84 offset:32768
	ds_read_b128 v[70:73], v83
	ds_read_b128 v[74:77], v84 offset:36864
	ds_read_b128 v[150:153], v83 offset:4096
	s_waitcnt lgkmcnt(1)
	v_mfma_f32_32x32x16_bf16 v[48:63], v[66:69], v[70:73], v[48:63]
	v_mfma_f32_32x32x16_bf16 v[32:47], v[74:77], v[70:73], v[32:47]
	s_waitcnt lgkmcnt(0)
	v_mfma_f32_32x32x16_bf16 v[16:31], v[66:69], v[150:153], v[16:31]
	v_mfma_f32_32x32x16_bf16 v[0:15], v[74:77], v[150:153], v[0:15]
	ds_read_b128 v[66:69], v86 offset:32768
	ds_read_b128 v[70:73], v85
	ds_read_b128 v[74:77], v86 offset:36864
	ds_read_b128 v[154:157], v85 offset:4096
	s_waitcnt lgkmcnt(1)
	v_mfma_f32_32x32x16_bf16 v[48:63], v[66:69], v[70:73], v[48:63]
	v_mfma_f32_32x32x16_bf16 v[32:47], v[74:77], v[70:73], v[32:47]
	s_waitcnt lgkmcnt(0)
	v_mfma_f32_32x32x16_bf16 v[16:31], v[66:69], v[154:157], v[16:31]
	v_mfma_f32_32x32x16_bf16 v[0:15], v[74:77], v[154:157], v[0:15]
	ds_read_b128 v[66:69], v88 offset:32768
	ds_read_b128 v[70:73], v87
	ds_read_b128 v[74:77], v88 offset:36864
	ds_read_b128 v[82:85], v87 offset:4096
	s_waitcnt lgkmcnt(0)
	v_mfma_f32_32x32x16_bf16 v[48:63], v[66:69], v[70:73], v[48:63]
	v_mfma_f32_32x32x16_bf16 v[32:47], v[74:77], v[70:73], v[32:47]
	v_or_b32_e32 v70, s22, v80
	v_lshl_add_u32 v70, v78, 6, v70
	v_ashrrev_i32_e32 v71, 31, v70
	v_lshlrev_b64 v[72:73], 10, v[70:71]
	v_lshl_add_u64 v[86:87], s[36:37], 0, v[72:73]
	v_mfma_f32_32x32x16_bf16 v[16:31], v[66:69], v[82:85], v[16:31]
	v_lshlrev_b32_e32 v66, 6, v79
	v_or3_b32 v66, v66, v64, s2
	s_movk_i32 s2, 0xff
	v_cmp_lt_i32_e32 vcc, s2, v66
	v_mfma_f32_32x32x16_bf16 v[0:15], v[74:77], v[82:85], v[0:15]
	s_and_saveexec_b64 s[22:23], vcc
	s_xor_b64 s[28:29], exec, s[22:23]
	v_mov_b32_e32 v67, v65
	s_movk_i32 s22, 0xfc00
	v_lshl_add_u64 v[68:69], v[66:67], 2, v[86:87]
	s_mov_b32 s23, -1
	v_lshl_add_u64 v[68:69], v[68:69], 0, s[22:23]
	s_or_saveexec_b64 s[28:29], s[28:29]
	v_lshl_add_u64 v[90:91], s[20:21], 0, v[72:73]
	v_ashrrev_i32_e32 v67, 31, v66
	s_xor_b64 exec, exec, s[28:29]
	v_lshl_add_u64 v[68:69], v[66:67], 2, v[90:91]
	s_or_b64 exec, exec, s[28:29]
	s_lshl_b64 s[0:1], s[0:1], 19
	s_lshl_b64 s[22:23], s[0:1], 1
	v_readlane_b32 s0, v214, 37
	v_readlane_b32 s1, v214, 38
	s_add_u32 s0, s0, s22
	s_addc_u32 s1, s1, s23
	v_readlane_b32 s28, v214, 39
	v_readlane_b32 s29, v214, 40
	s_add_u32 s54, s28, s22
	v_and_b32_e32 v74, 0xdf, v70
	v_ashrrev_i32_e32 v71, 6, v70
	global_store_dwordx4 v[68:69], v[48:51], off
	v_add_u32_e32 v68, 0xffffff00, v66
	v_lshlrev_b32_e32 v69, 9, v66
	s_addc_u32 s55, s29, s23
	v_and_b32_e32 v71, -4, v71
	v_lshrrev_b32_e32 v92, 6, v68
	v_and_b32_e32 v72, 0x7800, v69
	v_lshlrev_b32_e32 v88, 1, v74
	s_and_saveexec_b64 s[22:23], vcc
	s_xor_b64 s[28:29], exec, s[22:23]
	s_cbranch_execz .LBB0_619
	v_add_u32_e32 v68, v92, v71
	v_ashrrev_i32_e32 v69, 31, v68
	v_lshlrev_b64 v[68:69], 15, v[68:69]
	v_lshl_add_u64 v[68:69], s[54:55], 0, v[68:69]
	v_mov_b32_e32 v73, v65
	v_lshl_add_u64 v[68:69], v[68:69], 0, v[72:73]
	v_mov_b32_e32 v89, v65
	v_bfe_u32 v73, v48, 16, 1
	v_lshl_add_u64 v[68:69], v[68:69], 0, v[88:89]
	v_add3_u32 v73, v48, v73, s27
	global_store_short_d16_hi v[68:69], v73, off
	v_bfe_u32 v73, v49, 16, 1
	v_add3_u32 v73, v49, v73, s27
	global_store_short_d16_hi v[68:69], v73, off offset:512
	v_bfe_u32 v73, v50, 16, 1
	v_add3_u32 v73, v50, v73, s27
	global_store_short_d16_hi v[68:69], v73, off offset:1024
	v_bfe_u32 v73, v51, 16, 1
	v_add3_u32 v73, v51, v73, s27
	global_store_short_d16_hi v[68:69], v73, off offset:1536

.LBB0_747:
	v_mov_b32_e32 v78, v133
	s_lshl_b32 s2, s2, 8
	v_ashrrev_i32_e32 v6, 6, v78
	v_bfe_u32 v7, v78, 3, 3
	v_lshl_or_b32 v8, v6, 5, v7
	v_add_u32_e32 v0, s2, v8
	s_waitcnt lgkmcnt(0)
	v_ashrrev_i32_e32 v1, 31, v0
	v_lshlrev_b64 v[2:3], 11, v[0:1]
	v_bfe_u32 v1, v78, 4, 2
	v_readlane_b32 s0, v215, 52
	v_xor_b32_e32 v1, v1, v78
	v_readlane_b32 s1, v215, 53
	v_lshlrev_b32_e32 v1, 4, v1
	v_and_b32_e32 v64, 0x70, v1
	v_lshl_add_u64 v[2:3], s[0:1], 0, v[2:3]
	v_or_b32_e32 v1, 8, v8
	v_lshl_add_u64 v[66:67], v[2:3], 0, v[64:65]
	v_add_u32_e32 v2, s2, v1
	v_lshrrev_b32_e32 v1, 1, v1
	v_xor_b32_e32 v1, v1, v78
	v_ashrrev_i32_e32 v3, 31, v2
	v_lshlrev_b32_e32 v1, 4, v1
	v_or_b32_e32 v0, 16, v0
	v_lshlrev_b64 v[2:3], 11, v[2:3]
	v_and_b32_e32 v4, 0x70, v1
	v_ashrrev_i32_e32 v1, 31, v0
	v_lshl_add_u64 v[2:3], s[0:1], 0, v[2:3]
	v_mov_b32_e32 v5, v65
	v_lshlrev_b64 v[0:1], 11, v[0:1]
	v_lshl_add_u64 v[68:69], v[2:3], 0, v[4:5]
	v_lshl_add_u64 v[0:1], s[0:1], 0, v[0:1]
	v_or_b32_e32 v2, 24, v8
	v_lshl_add_u64 v[70:71], v[0:1], 0, v[64:65]
	v_add_u32_e32 v0, s2, v2
	v_lshrrev_b32_e32 v2, 1, v2
	v_ashrrev_i32_e32 v1, 31, v0
	v_xor_b32_e32 v2, v2, v78
	v_lshlrev_b64 v[0:1], 11, v[0:1]
	v_lshlrev_b32_e32 v2, 4, v2
	v_lshl_add_u64 v[0:1], s[0:1], 0, v[0:1]
	v_and_b32_e32 v2, 0x70, v2
	v_mov_b32_e32 v3, v65
	v_lshl_add_u64 v[72:73], v[0:1], 0, v[2:3]
	v_lshl_or_b32 v2, v6, 4, v7
	v_add_u32_e32 v0, s20, v2
	v_lshlrev_b32_e32 v3, 12, v6
	v_ashrrev_i32_e32 v1, 31, v0
	v_add_u32_e32 v131, 0, v3
	v_lshlrev_b64 v[0:1], 11, v[0:1]
	s_waitcnt vmcnt(0)
	v_readfirstlane_b32 s40, v131
	v_add_u32_e32 v130, 0x400, v131
	v_lshl_add_u64 v[0:1], s[96:97], 0, v[0:1]
	v_or_b32_e32 v2, 8, v2
	s_waitcnt lgkmcnt(0)
	s_barrier
	s_mov_b32 m0, s40
	v_readfirstlane_b32 s41, v130
	v_add_u32_e32 v128, 0x800, v131
	v_lshlrev_b32_e32 v5, 11, v6
	v_and_b32_e32 v79, 1, v6
	v_lshl_add_u64 v[74:75], v[0:1], 0, v[64:65]
	v_add_u32_e32 v0, s20, v2
	v_lshrrev_b32_e32 v2, 1, v2
	global_load_lds_dwordx4 v[66:67], off
	s_mov_b32 m0, s41
	v_readfirstlane_b32 s42, v128
	v_add_u32_e32 v126, 0xc00, v131
	v_add_u32_e32 v6, 0, v5
	v_ashrrev_i32_e32 v1, 31, v0
	v_xor_b32_e32 v2, v2, v78
	global_load_lds_dwordx4 v[68:69], off
	s_mov_b32 m0, s42
	v_readfirstlane_b32 s43, v126
	v_add_u32_e32 v129, 0x8000, v6
	v_lshlrev_b64 v[0:1], 11, v[0:1]
	v_lshlrev_b32_e32 v2, 4, v2
	global_load_lds_dwordx4 v[70:71], off
	s_mov_b32 m0, s43
	v_readfirstlane_b32 s44, v129
	v_add_u32_e32 v127, 0x8400, v6
	v_lshl_add_u64 v[0:1], s[96:97], 0, v[0:1]
	v_and_b32_e32 v64, 0x70, v2
	global_load_lds_dwordx4 v[72:73], off
	s_mov_b32 m0, s44
	v_readfirstlane_b32 s45, v127
	v_add_u32_e32 v125, 0xc000, v131
	v_lshl_add_u64 v[76:77], v[0:1], 0, v[64:65]
	global_load_lds_dwordx4 v[74:75], off
	s_mov_b32 m0, s45
	s_mov_b64 s[0:1], 0x80
	v_readfirstlane_b32 s29, v125
	v_add_u32_e32 v120, 0xc400, v131
	global_load_lds_dwordx4 v[76:77], off
	v_lshl_add_u64 v[0:1], v[66:67], 0, s[0:1]
	s_mov_b32 m0, s29
	v_readfirstlane_b32 s33, v120
	v_add_u32_e32 v121, 0xc800, v131
	global_load_lds_dwordx4 v[0:1], off
	v_lshl_add_u64 v[0:1], v[68:69], 0, s[0:1]
	s_mov_b32 m0, s33
	v_readfirstlane_b32 s36, v121
	v_add_u32_e32 v122, 0xcc00, v131
	global_load_lds_dwordx4 v[0:1], off
	v_lshl_add_u64 v[0:1], v[70:71], 0, s[0:1]
	s_mov_b32 m0, s36
	v_readfirstlane_b32 s37, v122
	v_add_u32_e32 v123, s85, v5
	global_load_lds_dwordx4 v[0:1], off
	v_lshl_add_u64 v[0:1], v[72:73], 0, s[0:1]
	s_mov_b32 m0, s37
	v_readfirstlane_b32 s38, v123
	v_add_u32_e32 v124, 0x14400, v6
	global_load_lds_dwordx4 v[0:1], off
	v_lshl_add_u64 v[0:1], v[74:75], 0, s[0:1]
	s_mov_b32 m0, s38
	v_readfirstlane_b32 s39, v124
	global_load_lds_dwordx4 v[0:1], off
	v_lshl_add_u64 v[0:1], v[76:77], 0, s[0:1]
	s_mov_b32 m0, s39
	v_lshrrev_b32_e32 v2, 1, v78
	v_bfe_u32 v64, v78, 5, 1
	global_load_lds_dwordx4 v[0:1], off
	v_add_u32_e32 v119, s3, v3
	v_bitop3_b32 v0, v2, v64, 7 bitop3:0x6c
	s_waitcnt vmcnt(6)
	s_mov_b64 s[30:31], 0x100
	v_readfirstlane_b32 s0, v119
	v_add_u32_e32 v114, 0x400, v119
	v_lshlrev_b32_e32 v132, 4, v0
	s_waitcnt lgkmcnt(0)
	s_barrier
	v_lshl_add_u64 v[0:1], v[66:67], 0, s[30:31]
	s_mov_b32 m0, s0
	v_readfirstlane_b32 s1, v114
	v_add_u32_e32 v115, 0x800, v119
	global_load_lds_dwordx4 v[0:1], off
	v_lshl_add_u64 v[0:1], v[68:69], 0, s[30:31]
	s_mov_b32 m0, s1
	v_readfirstlane_b32 s21, v115
	v_add_u32_e32 v116, 0xc00, v119
	v_readlane_b32 s23, v212, 31
	v_and_b32_e32 v81, 31, v78
	global_load_lds_dwordx4 v[0:1], off
	v_lshl_add_u64 v[0:1], v[70:71], 0, s[30:31]
	s_mov_b32 m0, s21
	v_readfirstlane_b32 s22, v116
	v_add_u32_e32 v117, s23, v5
	v_add_u32_e32 v2, s3, v5
	v_lshlrev_b32_e32 v4, 7, v81
	global_load_lds_dwordx4 v[0:1], off
	v_lshl_add_u64 v[0:1], v[72:73], 0, s[30:31]
	s_mov_b32 m0, s22
	v_readfirstlane_b32 s23, v117
	v_add_u32_e32 v118, 0x8400, v2
	v_lshl_or_b32 v102, v79, 13, v4
	global_load_lds_dwordx4 v[0:1], off
	v_lshl_add_u64 v[0:1], v[74:75], 0, s[30:31]
	s_mov_b32 m0, s23
	v_readfirstlane_b32 s28, v118
	global_load_lds_dwordx4 v[0:1], off
	v_lshl_add_u64 v[0:1], v[76:77], 0, s[30:31]
	s_mov_b32 m0, s28
	v_add_u32_e32 v100, 0, v102
	global_load_lds_dwordx4 v[0:1], off
	v_add_u32_e32 v85, v100, v132
	v_ashrrev_i32_e32 v80, 7, v78
	ds_read_b128 v[0:3], v85 offset:32768
	ds_read_b128 v[86:89], v85 offset:36864
	v_lshl_or_b32 v134, v80, 13, v4
	v_add_u32_e32 v101, 0, v134
	v_add_u32_e32 v84, v101, v132
	ds_read_b128 v[4:7], v84
	v_bfe_u32 v103, v78, 1, 3
	s_waitcnt lgkmcnt(0)
	v_lshrrev_b32_e32 v182, 6, v133
	s_nop 0
	v_readfirstlane_b32 s32, v182
	v_mfma_f32_32x32x16_bf16 v[48:63], v[0:3], v[4:7], 0
	v_bitop3_b32 v8, v64, v103, 2 bitop3:0x36
	v_lshlrev_b32_e32 v135, 4, v8
	v_add_u32_e32 v83, v100, v135
	ds_read_b128 v[8:11], v83 offset:32768
	ds_read_b128 v[90:93], v83 offset:36864
	v_add_u32_e32 v82, v101, v135
	ds_read_b128 v[12:15], v82
	ds_read_b128 v[94:97], v82 offset:4096
	s_waitcnt vmcnt(12)
	v_mfma_f32_32x32x16_bf16 v[32:47], v[86:89], v[4:7], 0
	ds_read_b128 v[4:7], v84 offset:4096
	s_mov_b64 s[30:31], 0x180
	s_nop 0
	v_or_b32_e32 v143, 0x8000, v102
	v_or_b32_e32 v144, 0x9000, v102
	v_add_u32_e32 v145, s3, v134
	s_mov_b64 s[80:81], 0x200
	s_waitcnt lgkmcnt(0)
	v_mfma_f32_32x32x16_bf16 v[16:31], v[0:3], v[4:7], 0
	v_mfma_f32_32x32x16_bf16 v[48:63], v[8:11], v[12:15], v[48:63]
	v_mfma_f32_32x32x16_bf16 v[32:47], v[90:93], v[12:15], v[32:47]
	v_mfma_f32_32x32x16_bf16 v[16:31], v[8:11], v[94:97], v[16:31]
	v_mfma_f32_32x32x16_bf16 v[0:15], v[86:89], v[4:7], 0
	v_bitop3_b32 v86, v64, v103, 4 bitop3:0x36
	v_lshlrev_b32_e32 v138, 4, v86
	v_add_u32_e32 v87, v100, v138
	v_add_u32_e32 v86, v101, v138
	v_mfma_f32_32x32x16_bf16 v[0:15], v[90:93], v[94:97], v[0:15]
	ds_read_b128 v[88:91], v87 offset:32768
	ds_read_b128 v[92:95], v86
	ds_read_b128 v[96:99], v87 offset:36864
	s_waitcnt lgkmcnt(1)
	v_mfma_f32_32x32x16_bf16 v[48:63], v[88:91], v[92:95], v[48:63]
	s_waitcnt lgkmcnt(0)
	v_mfma_f32_32x32x16_bf16 v[32:47], v[96:99], v[92:95], v[32:47]
	ds_read_b128 v[92:95], v86 offset:4096
	s_waitcnt lgkmcnt(0)
	v_mfma_f32_32x32x16_bf16 v[16:31], v[88:91], v[92:95], v[16:31]
	v_bitop3_b32 v88, v64, v103, 6 bitop3:0x36
	v_lshlrev_b32_e32 v142, 4, v88
	v_add_u32_e32 v89, v100, v142
	v_add_u32_e32 v88, v101, v142
	v_mfma_f32_32x32x16_bf16 v[0:15], v[96:99], v[92:95], v[0:15]
	ds_read_b128 v[90:93], v89 offset:32768
	ds_read_b128 v[94:97], v88
	ds_read_b128 v[98:101], v89 offset:36864
	s_waitcnt lgkmcnt(1)
	v_mfma_f32_32x32x16_bf16 v[48:63], v[90:93], v[94:97], v[48:63]
	s_waitcnt lgkmcnt(0)
	v_mfma_f32_32x32x16_bf16 v[32:47], v[98:101], v[94:97], v[32:47]
	ds_read_b128 v[94:97], v88 offset:4096
	s_waitcnt vmcnt(6)
	s_waitcnt lgkmcnt(0)
	s_barrier
	s_waitcnt lgkmcnt(0)
	v_mfma_f32_32x32x16_bf16 v[16:31], v[90:93], v[94:97], v[16:31]
	v_lshl_add_u64 v[158:159], v[66:67], 0, s[30:31]
	s_nop 0
	v_lshl_add_u64 v[160:161], v[68:69], 0, s[30:31]
	s_nop 0
	s_nop 0
	s_nop 0
	v_lshl_add_u64 v[162:163], v[70:71], 0, s[30:31]
	s_nop 0
	v_mfma_f32_32x32x16_bf16 v[0:15], v[98:101], v[94:97], v[0:15]
	s_and_b32 m0, s32, 7
	s_lshl_b32 m0, m0, 12
	s_add_i32 m0, m0, 0x0
	s_nop 0
	global_load_lds_dwordx4 v[158:159], off
	s_nop 0
	v_lshl_add_u64 v[164:165], v[72:73], 0, s[30:31]
	s_nop 0
	s_nop 0
	s_nop 0
	v_lshl_add_u64 v[166:167], v[74:75], 0, s[30:31]
	s_nop 0
	s_nop 0
	s_nop 0
	v_lshl_add_u64 v[168:169], v[76:77], 0, s[30:31]
	s_nop 0
	s_add_i32 s30, 0, 0xc000
	s_nop 0
	v_add_u32_e32 v90, s30, v132
	v_add_u32_e32 v91, v90, v143
	v_add_u32_e32 v90, v90, v144
	ds_read_b128 v[92:95], v91
	ds_read_b128 v[96:99], v84 offset:49152
	ds_read_b128 v[100:103], v90
	ds_read_b128 v[150:153], v84 offset:53248
	s_waitcnt lgkmcnt(1)
	v_mfma_f32_32x32x16_bf16 v[48:63], v[92:95], v[96:99], v[48:63]
	s_nop 0
	v_mfma_f32_32x32x16_bf16 v[32:47], v[100:103], v[96:99], v[32:47]
	s_and_b32 m0, s32, 7
	s_lshl_b32 m0, m0, 12
	s_add_i32 m0, m0, 0x400
	s_nop 0
	global_load_lds_dwordx4 v[160:161], off
	s_waitcnt lgkmcnt(0)
	v_mfma_f32_32x32x16_bf16 v[16:31], v[92:95], v[150:153], v[16:31]
	v_add_u32_e32 v92, s30, v135
	v_add_u32_e32 v94, v92, v143
	v_add_u32_e32 v92, v92, v144
	v_add_u32_e32 v93, s30, v138
	v_add_u32_e32 v95, v93, v143
	v_add_u32_e32 v93, v93, v144
	v_mfma_f32_32x32x16_bf16 v[0:15], v[100:103], v[150:153], v[0:15]
	s_and_b32 m0, s32, 7
	s_lshl_b32 m0, m0, 12
	s_add_i32 m0, m0, 0x800
	s_nop 0
	global_load_lds_dwordx4 v[162:163], off
	ds_read_b128 v[96:99], v94
	ds_read_b128 v[100:103], v82 offset:49152
	ds_read_b128 v[104:107], v92
	ds_read_b128 v[154:157], v82 offset:53248
	s_waitcnt lgkmcnt(1)
	v_mfma_f32_32x32x16_bf16 v[48:63], v[96:99], v[100:103], v[48:63]
	v_mfma_f32_32x32x16_bf16 v[32:47], v[104:107], v[100:103], v[32:47]
	s_and_b32 m0, s32, 7
	s_lshl_b32 m0, m0, 12
	s_add_i32 m0, m0, 0xc00
	s_nop 0
	global_load_lds_dwordx4 v[164:165], off
	s_waitcnt lgkmcnt(0)
	v_mfma_f32_32x32x16_bf16 v[16:31], v[96:99], v[154:157], v[16:31]
	v_mfma_f32_32x32x16_bf16 v[0:15], v[104:107], v[154:157], v[0:15]
	s_and_b32 m0, s32, 7
	s_lshl_b32 m0, m0, 11
	s_add_i32 m0, m0, 0x8000
	s_nop 0
	global_load_lds_dwordx4 v[166:167], off
	ds_read_b128 v[96:99], v95
	ds_read_b128 v[100:103], v86 offset:49152
	ds_read_b128 v[104:107], v93
	ds_read_b128 v[150:153], v86 offset:53248
	s_waitcnt lgkmcnt(1)
	v_mfma_f32_32x32x16_bf16 v[48:63], v[96:99], v[100:103], v[48:63]
	v_mfma_f32_32x32x16_bf16 v[32:47], v[104:107], v[100:103], v[32:47]
	s_and_b32 m0, s32, 7
	s_lshl_b32 m0, m0, 11
	s_add_i32 m0, m0, 0x8400
	s_nop 0
	global_load_lds_dwordx4 v[168:169], off
	s_waitcnt lgkmcnt(0)
	v_mfma_f32_32x32x16_bf16 v[16:31], v[96:99], v[150:153], v[16:31]
	v_add_u32_e32 v96, s30, v142
	v_add_u32_e32 v97, v96, v143
	v_add_u32_e32 v96, v96, v144
	s_mov_b64 s[30:31], 0x200
	v_mfma_f32_32x32x16_bf16 v[0:15], v[104:107], v[150:153], v[0:15]
	ds_read_b128 v[98:101], v97
	ds_read_b128 v[102:105], v88 offset:49152
	ds_read_b128 v[106:109], v96
	ds_read_b128 v[154:157], v88 offset:53248
	s_waitcnt lgkmcnt(1)
	v_mfma_f32_32x32x16_bf16 v[48:63], v[98:101], v[102:105], v[48:63]
	v_mfma_f32_32x32x16_bf16 v[32:47], v[106:109], v[102:105], v[32:47]
	s_waitcnt vmcnt(6)
	s_waitcnt lgkmcnt(0)
	s_barrier
	s_waitcnt lgkmcnt(0)
	v_mfma_f32_32x32x16_bf16 v[16:31], v[98:101], v[154:157], v[16:31]
	v_lshl_add_u64 v[170:171], v[66:67], 0, s[30:31]
	s_nop 0
	v_lshl_add_u64 v[172:173], v[68:69], 0, s[30:31]
	s_nop 0
	v_add_u32_e32 v101, s3, v132
	s_nop 0
	v_lshl_add_u64 v[174:175], v[70:71], 0, s[30:31]
	s_nop 0
	v_mfma_f32_32x32x16_bf16 v[0:15], v[106:109], v[154:157], v[0:15]
	s_and_b32 m0, s32, 7
	s_lshl_b32 m0, m0, 12
	s_add_i32 m0, m0, 0xc000
	s_nop 0
	global_load_lds_dwordx4 v[170:171], off
	s_nop 0
	v_lshl_add_u64 v[176:177], v[72:73], 0, s[30:31]
	s_nop 0
	v_add_u32_e32 v100, v145, v132
	s_nop 0
	v_lshl_add_u64 v[178:179], v[74:75], 0, s[30:31]
	s_nop 0
	v_or_b32_e32 v132, 0x1000, v134
	s_nop 0
	v_lshl_add_u64 v[180:181], v[76:77], 0, s[30:31]
	s_nop 0
	s_mov_b64 s[30:31], 0x280
	s_nop 0
	v_add_u32_e32 v98, v101, v143
	v_add_u32_e32 v99, v101, v144
	ds_read_b128 v[110:113], v98
	ds_read_b128 v[106:109], v99
	ds_read_b128 v[102:105], v100
	v_add_u32_e32 v101, v101, v132
	ds_read_b128 v[150:153], v101
	s_waitcnt lgkmcnt(1)
	v_mfma_f32_32x32x16_bf16 v[48:63], v[110:113], v[102:105], v[48:63]
	s_nop 0
	v_mfma_f32_32x32x16_bf16 v[32:47], v[106:109], v[102:105], v[32:47]
	s_and_b32 m0, s32, 7
	s_lshl_b32 m0, m0, 12
	s_add_i32 m0, m0, 0xc400
	s_nop 0
	global_load_lds_dwordx4 v[172:173], off
	s_waitcnt lgkmcnt(0)
	v_mfma_f32_32x32x16_bf16 v[16:31], v[110:113], v[150:153], v[16:31]
	v_mfma_f32_32x32x16_bf16 v[0:15], v[106:109], v[150:153], v[0:15]
	s_and_b32 m0, s32, 7
	s_lshl_b32 m0, m0, 12
	s_add_i32 m0, m0, 0xc800
	s_nop 0
	global_load_lds_dwordx4 v[174:175], off
	v_add_u32_e32 v105, s3, v135
	v_add_u32_e32 v103, v105, v143
	v_add_u32_e32 v102, v105, v144
	ds_read_b128 v[106:109], v103
	v_add_u32_e32 v104, v145, v135
	ds_read_b128 v[134:137], v102
	ds_read_b128 v[110:113], v104
	v_add_u32_e32 v105, v105, v132
	ds_read_b128 v[154:157], v105
	s_waitcnt lgkmcnt(1)
	v_mfma_f32_32x32x16_bf16 v[48:63], v[106:109], v[110:113], v[48:63]
	v_mfma_f32_32x32x16_bf16 v[32:47], v[134:137], v[110:113], v[32:47]
	s_and_b32 m0, s32, 7
	s_lshl_b32 m0, m0, 12
	s_add_i32 m0, m0, 0xcc00
	s_nop 0
	global_load_lds_dwordx4 v[176:177], off
	s_waitcnt lgkmcnt(0)
	v_mfma_f32_32x32x16_bf16 v[16:31], v[106:109], v[154:157], v[16:31]
	v_add_u32_e32 v109, s3, v138
	v_add_u32_e32 v107, v109, v143
	v_add_u32_e32 v106, v109, v144
	v_add_u32_e32 v108, v145, v138
	ds_read_b128 v[138:141], v106
	v_add_u32_e32 v109, v109, v132
	v_mfma_f32_32x32x16_bf16 v[0:15], v[134:137], v[154:157], v[0:15]
	s_and_b32 m0, s32, 7
	s_lshl_b32 m0, m0, 11
	s_add_i32 m0, m0, 0x14000
	s_nop 0
	global_load_lds_dwordx4 v[178:179], off
	ds_read_b128 v[110:113], v107
	ds_read_b128 v[134:137], v108
	ds_read_b128 v[150:153], v109
	s_waitcnt lgkmcnt(1)
	v_mfma_f32_32x32x16_bf16 v[48:63], v[110:113], v[134:137], v[48:63]
	v_mfma_f32_32x32x16_bf16 v[32:47], v[138:141], v[134:137], v[32:47]
	s_and_b32 m0, s32, 7
	s_lshl_b32 m0, m0, 11
	s_add_i32 m0, m0, 0x14400
	s_nop 0
	global_load_lds_dwordx4 v[180:181], off
	s_waitcnt lgkmcnt(0)
	v_mfma_f32_32x32x16_bf16 v[16:31], v[110:113], v[150:153], v[16:31]
	v_add_u32_e32 v113, s3, v142
	v_add_u32_e32 v111, v113, v143
	v_add_u32_e32 v110, v113, v144
	v_add_u32_e32 v112, v145, v142
	ds_read_b128 v[142:145], v110
	v_add_u32_e32 v113, v113, v132
	v_mfma_f32_32x32x16_bf16 v[0:15], v[138:141], v[150:153], v[0:15]
	ds_read_b128 v[134:137], v111
	ds_read_b128 v[138:141], v112
	ds_read_b128 v[154:157], v113
	s_waitcnt lgkmcnt(1)
	v_mfma_f32_32x32x16_bf16 v[48:63], v[134:137], v[138:141], v[48:63]
	v_mfma_f32_32x32x16_bf16 v[32:47], v[142:145], v[138:141], v[32:47]
	s_waitcnt vmcnt(6)
	s_waitcnt lgkmcnt(0)
	s_barrier
	s_waitcnt lgkmcnt(0)
	v_mfma_f32_32x32x16_bf16 v[16:31], v[134:137], v[154:157], v[16:31]
	v_lshl_add_u64 v[158:159], v[66:67], 0, s[30:31]
	s_nop 0
	v_lshl_add_u64 v[160:161], v[68:69], 0, s[30:31]
	s_nop 0
	s_nop 0
	s_nop 0
	v_lshl_add_u64 v[162:163], v[70:71], 0, s[30:31]
	s_nop 0
	v_mfma_f32_32x32x16_bf16 v[0:15], v[142:145], v[154:157], v[0:15]
	s_and_b32 m0, s32, 7
	s_lshl_b32 m0, m0, 12
	s_add_i32 m0, m0, 0x18000
	s_nop 0
	global_load_lds_dwordx4 v[158:159], off
	s_nop 0
	v_lshl_add_u64 v[164:165], v[72:73], 0, s[30:31]
	s_nop 0
	s_nop 0
	s_nop 0
	v_lshl_add_u64 v[166:167], v[74:75], 0, s[30:31]
	s_nop 0
	s_nop 0
	s_nop 0
	v_lshl_add_u64 v[168:169], v[76:77], 0, s[30:31]
	s_nop 0
	s_mov_b64 s[30:31], 0x300
	s_nop 0
	ds_read_b128 v[134:137], v85 offset:32768
	ds_read_b128 v[138:141], v84
	ds_read_b128 v[142:145], v85 offset:36864
	ds_read_b128 v[150:153], v84 offset:4096
	s_waitcnt lgkmcnt(1)
	v_mfma_f32_32x32x16_bf16 v[48:63], v[134:137], v[138:141], v[48:63]
	s_nop 0
	v_readfirstlane_b32 s40, v119
	v_mfma_f32_32x32x16_bf16 v[32:47], v[142:145], v[138:141], v[32:47]
	s_and_b32 m0, s32, 7
	s_lshl_b32 m0, m0, 12
	s_add_i32 m0, m0, 0x18400
	s_nop 0
	global_load_lds_dwordx4 v[160:161], off
	s_waitcnt lgkmcnt(0)
	v_mfma_f32_32x32x16_bf16 v[16:31], v[134:137], v[150:153], v[16:31]
	v_mfma_f32_32x32x16_bf16 v[0:15], v[142:145], v[150:153], v[0:15]
	s_and_b32 m0, s32, 7
	s_lshl_b32 m0, m0, 12
	s_add_i32 m0, m0, 0x18800
	s_nop 0
	global_load_lds_dwordx4 v[162:163], off
	ds_read_b128 v[134:137], v83 offset:32768
	ds_read_b128 v[138:141], v82
	ds_read_b128 v[142:145], v83 offset:36864
	ds_read_b128 v[154:157], v82 offset:4096
	s_waitcnt lgkmcnt(1)
	v_mfma_f32_32x32x16_bf16 v[48:63], v[134:137], v[138:141], v[48:63]
	v_mfma_f32_32x32x16_bf16 v[32:47], v[142:145], v[138:141], v[32:47]
	s_and_b32 m0, s32, 7
	s_lshl_b32 m0, m0, 12
	s_add_i32 m0, m0, 0x18c00
	s_nop 0
	global_load_lds_dwordx4 v[164:165], off
	s_waitcnt lgkmcnt(0)
	v_mfma_f32_32x32x16_bf16 v[16:31], v[134:137], v[154:157], v[16:31]
	v_mfma_f32_32x32x16_bf16 v[0:15], v[142:145], v[154:157], v[0:15]
	s_and_b32 m0, s32, 7
	s_lshl_b32 m0, m0, 11
	s_add_i32 m0, m0, 0x20000
	s_nop 0
	global_load_lds_dwordx4 v[166:167], off
	ds_read_b128 v[134:137], v87 offset:32768
	ds_read_b128 v[138:141], v86
	ds_read_b128 v[142:145], v87 offset:36864
	ds_read_b128 v[150:153], v86 offset:4096
	s_waitcnt lgkmcnt(1)
	v_mfma_f32_32x32x16_bf16 v[48:63], v[134:137], v[138:141], v[48:63]
	v_mfma_f32_32x32x16_bf16 v[32:47], v[142:145], v[138:141], v[32:47]
	s_and_b32 m0, s32, 7
	s_lshl_b32 m0, m0, 11
	s_add_i32 m0, m0, 0x20400
	s_nop 0
	global_load_lds_dwordx4 v[168:169], off
	s_waitcnt lgkmcnt(0)
	v_mfma_f32_32x32x16_bf16 v[16:31], v[134:137], v[150:153], v[16:31]
	v_mfma_f32_32x32x16_bf16 v[0:15], v[142:145], v[150:153], v[0:15]
	ds_read_b128 v[134:137], v89 offset:32768
	ds_read_b128 v[138:141], v88
	ds_read_b128 v[142:145], v89 offset:36864
	ds_read_b128 v[154:157], v88 offset:4096
	s_waitcnt lgkmcnt(1)
	v_mfma_f32_32x32x16_bf16 v[48:63], v[134:137], v[138:141], v[48:63]
	v_mfma_f32_32x32x16_bf16 v[32:47], v[142:145], v[138:141], v[32:47]
	s_waitcnt vmcnt(6)
	s_waitcnt lgkmcnt(0)
	s_barrier
	s_waitcnt lgkmcnt(0)
	v_mfma_f32_32x32x16_bf16 v[16:31], v[134:137], v[154:157], v[16:31]
	v_lshl_add_u64 v[170:171], v[66:67], 0, s[30:31]
	s_nop 0
	v_lshl_add_u64 v[172:173], v[68:69], 0, s[30:31]
	s_nop 0
	v_readfirstlane_b32 s41, v114
	s_nop 0
	v_lshl_add_u64 v[174:175], v[70:71], 0, s[30:31]
	s_nop 0
	v_mfma_f32_32x32x16_bf16 v[0:15], v[142:145], v[154:157], v[0:15]
	s_and_b32 m0, s32, 7
	s_lshl_b32 m0, m0, 12
	s_add_i32 m0, m0, 0x0
	s_nop 0
	global_load_lds_dwordx4 v[170:171], off
	s_nop 0
	v_lshl_add_u64 v[176:177], v[72:73], 0, s[30:31]
	s_nop 0
	v_readfirstlane_b32 s42, v115
	s_nop 0
	v_lshl_add_u64 v[178:179], v[74:75], 0, s[30:31]
	s_nop 0
	v_readfirstlane_b32 s43, v116
	s_nop 0
	v_lshl_add_u64 v[180:181], v[76:77], 0, s[30:31]
	s_nop 0
	s_mov_b64 s[30:31], 0x380
	s_nop 0
	ds_read_b128 v[134:137], v91
	ds_read_b128 v[138:141], v84 offset:49152
	ds_read_b128 v[142:145], v90
	ds_read_b128 v[150:153], v84 offset:53248
	s_waitcnt lgkmcnt(1)
	v_mfma_f32_32x32x16_bf16 v[48:63], v[134:137], v[138:141], v[48:63]
	s_nop 0
	v_readfirstlane_b32 s29, v125
	v_readfirstlane_b32 s44, v117
	v_readfirstlane_b32 s45, v118
	v_mfma_f32_32x32x16_bf16 v[32:47], v[142:145], v[138:141], v[32:47]
	s_and_b32 m0, s32, 7
	s_lshl_b32 m0, m0, 12
	s_add_i32 m0, m0, 0x400
	s_nop 0
	global_load_lds_dwordx4 v[172:173], off
	s_waitcnt lgkmcnt(0)
	v_mfma_f32_32x32x16_bf16 v[16:31], v[134:137], v[150:153], v[16:31]
	v_mfma_f32_32x32x16_bf16 v[0:15], v[142:145], v[150:153], v[0:15]
	s_and_b32 m0, s32, 7
	s_lshl_b32 m0, m0, 12
	s_add_i32 m0, m0, 0x800
	s_nop 0
	global_load_lds_dwordx4 v[174:175], off
	ds_read_b128 v[134:137], v94
	ds_read_b128 v[138:141], v82 offset:49152
	ds_read_b128 v[142:145], v92
	ds_read_b128 v[154:157], v82 offset:53248
	s_waitcnt lgkmcnt(1)
	v_mfma_f32_32x32x16_bf16 v[48:63], v[134:137], v[138:141], v[48:63]
	v_mfma_f32_32x32x16_bf16 v[32:47], v[142:145], v[138:141], v[32:47]
	s_and_b32 m0, s32, 7
	s_lshl_b32 m0, m0, 12
	s_add_i32 m0, m0, 0xc00
	s_nop 0
	global_load_lds_dwordx4 v[176:177], off
	s_waitcnt lgkmcnt(0)
	v_mfma_f32_32x32x16_bf16 v[16:31], v[134:137], v[154:157], v[16:31]
	v_mfma_f32_32x32x16_bf16 v[0:15], v[142:145], v[154:157], v[0:15]
	s_and_b32 m0, s32, 7
	s_lshl_b32 m0, m0, 11
	s_add_i32 m0, m0, 0x8000
	s_nop 0
	global_load_lds_dwordx4 v[178:179], off
	ds_read_b128 v[134:137], v95
	ds_read_b128 v[138:141], v86 offset:49152
	ds_read_b128 v[142:145], v93
	ds_read_b128 v[150:153], v86 offset:53248
	s_waitcnt lgkmcnt(1)
	v_mfma_f32_32x32x16_bf16 v[48:63], v[134:137], v[138:141], v[48:63]
	v_mfma_f32_32x32x16_bf16 v[32:47], v[142:145], v[138:141], v[32:47]
	s_and_b32 m0, s32, 7
	s_lshl_b32 m0, m0, 11
	s_add_i32 m0, m0, 0x8400
	s_nop 0
	global_load_lds_dwordx4 v[180:181], off
	s_waitcnt lgkmcnt(0)
	v_mfma_f32_32x32x16_bf16 v[16:31], v[134:137], v[150:153], v[16:31]
	v_mfma_f32_32x32x16_bf16 v[0:15], v[142:145], v[150:153], v[0:15]
	ds_read_b128 v[134:137], v97
	ds_read_b128 v[138:141], v88 offset:49152
	ds_read_b128 v[142:145], v96
	ds_read_b128 v[154:157], v88 offset:53248
	s_waitcnt lgkmcnt(1)
	v_mfma_f32_32x32x16_bf16 v[48:63], v[134:137], v[138:141], v[48:63]
	v_mfma_f32_32x32x16_bf16 v[32:47], v[142:145], v[138:141], v[32:47]
	s_waitcnt vmcnt(6)
	s_waitcnt lgkmcnt(0)
	s_barrier
	s_waitcnt lgkmcnt(0)
	v_mfma_f32_32x32x16_bf16 v[16:31], v[134:137], v[154:157], v[16:31]
	v_lshl_add_u64 v[158:159], v[66:67], 0, s[30:31]
	s_nop 0
	v_lshl_add_u64 v[160:161], v[68:69], 0, s[30:31]
	s_nop 0
	v_readfirstlane_b32 s33, v120
	s_nop 0
	v_lshl_add_u64 v[162:163], v[70:71], 0, s[30:31]
	s_nop 0
	v_mfma_f32_32x32x16_bf16 v[0:15], v[142:145], v[154:157], v[0:15]
	s_and_b32 m0, s32, 7
	s_lshl_b32 m0, m0, 12
	s_add_i32 m0, m0, 0xc000
	s_nop 0
	global_load_lds_dwordx4 v[158:159], off
	s_nop 0
	v_lshl_add_u64 v[164:165], v[72:73], 0, s[30:31]
	s_nop 0
	v_readfirstlane_b32 s36, v121
	s_nop 0
	v_lshl_add_u64 v[166:167], v[74:75], 0, s[30:31]
	s_nop 0
	v_readfirstlane_b32 s37, v122
	s_nop 0
	v_lshl_add_u64 v[168:169], v[76:77], 0, s[30:31]
	s_nop 0
	s_mov_b64 s[30:31], 0x400
	s_nop 0
	ds_read_b128 v[134:137], v98
	ds_read_b128 v[138:141], v100
	ds_read_b128 v[142:145], v99
	ds_read_b128 v[150:153], v101
	s_waitcnt lgkmcnt(1)
	v_mfma_f32_32x32x16_bf16 v[48:63], v[134:137], v[138:141], v[48:63]
	s_nop 0
	v_readfirstlane_b32 s0, v131
	v_readfirstlane_b32 s38, v123
	v_readfirstlane_b32 s39, v124
	v_mfma_f32_32x32x16_bf16 v[32:47], v[142:145], v[138:141], v[32:47]
	s_and_b32 m0, s32, 7
	s_lshl_b32 m0, m0, 12
	s_add_i32 m0, m0, 0xc400
	s_nop 0
	global_load_lds_dwordx4 v[160:161], off
	s_waitcnt lgkmcnt(0)
	v_mfma_f32_32x32x16_bf16 v[16:31], v[134:137], v[150:153], v[16:31]
	v_mfma_f32_32x32x16_bf16 v[0:15], v[142:145], v[150:153], v[0:15]
	s_and_b32 m0, s32, 7
	s_lshl_b32 m0, m0, 12
	s_add_i32 m0, m0, 0xc800
	s_nop 0
	global_load_lds_dwordx4 v[162:163], off
	ds_read_b128 v[134:137], v103
	ds_read_b128 v[138:141], v104
	ds_read_b128 v[142:145], v102
	ds_read_b128 v[154:157], v105
	s_waitcnt lgkmcnt(1)
	v_mfma_f32_32x32x16_bf16 v[48:63], v[134:137], v[138:141], v[48:63]
	v_mfma_f32_32x32x16_bf16 v[32:47], v[142:145], v[138:141], v[32:47]
	s_and_b32 m0, s32, 7
	s_lshl_b32 m0, m0, 12
	s_add_i32 m0, m0, 0xcc00
	s_nop 0
	global_load_lds_dwordx4 v[164:165], off
	s_waitcnt lgkmcnt(0)
	v_mfma_f32_32x32x16_bf16 v[16:31], v[134:137], v[154:157], v[16:31]
	v_mfma_f32_32x32x16_bf16 v[0:15], v[142:145], v[154:157], v[0:15]
	s_and_b32 m0, s32, 7
	s_lshl_b32 m0, m0, 11
	s_add_i32 m0, m0, 0x14000
	s_nop 0
	global_load_lds_dwordx4 v[166:167], off
	ds_read_b128 v[134:137], v107
	ds_read_b128 v[138:141], v108
	ds_read_b128 v[142:145], v106
	ds_read_b128 v[150:153], v109
	s_waitcnt lgkmcnt(1)
	v_mfma_f32_32x32x16_bf16 v[48:63], v[134:137], v[138:141], v[48:63]
	v_mfma_f32_32x32x16_bf16 v[32:47], v[142:145], v[138:141], v[32:47]
	s_and_b32 m0, s32, 7
	s_lshl_b32 m0, m0, 11
	s_add_i32 m0, m0, 0x14400
	s_nop 0
	global_load_lds_dwordx4 v[168:169], off
	s_waitcnt lgkmcnt(0)
	v_mfma_f32_32x32x16_bf16 v[16:31], v[134:137], v[150:153], v[16:31]
	v_mfma_f32_32x32x16_bf16 v[0:15], v[142:145], v[150:153], v[0:15]
	ds_read_b128 v[134:137], v111
	ds_read_b128 v[138:141], v112
	ds_read_b128 v[142:145], v110
	ds_read_b128 v[154:157], v113
	s_waitcnt lgkmcnt(1)
	v_mfma_f32_32x32x16_bf16 v[48:63], v[134:137], v[138:141], v[48:63]
	v_mfma_f32_32x32x16_bf16 v[32:47], v[142:145], v[138:141], v[32:47]
	s_waitcnt vmcnt(6)
	s_waitcnt lgkmcnt(0)
	s_barrier
	s_waitcnt lgkmcnt(0)
	v_mfma_f32_32x32x16_bf16 v[16:31], v[134:137], v[154:157], v[16:31]
	v_lshl_add_u64 v[170:171], v[66:67], 0, s[30:31]
	s_nop 0
	v_lshl_add_u64 v[172:173], v[68:69], 0, s[30:31]
	s_nop 0
	v_readfirstlane_b32 s1, v130
	s_nop 0
	v_lshl_add_u64 v[174:175], v[70:71], 0, s[30:31]
	s_nop 0
	v_mfma_f32_32x32x16_bf16 v[0:15], v[142:145], v[154:157], v[0:15]
	s_and_b32 m0, s32, 7
	s_lshl_b32 m0, m0, 12
	s_add_i32 m0, m0, 0x18000
	s_nop 0
	global_load_lds_dwordx4 v[170:171], off
	s_nop 0
	v_lshl_add_u64 v[176:177], v[72:73], 0, s[30:31]
	s_nop 0
	v_readfirstlane_b32 s21, v128
	s_nop 0
	v_lshl_add_u64 v[178:179], v[74:75], 0, s[30:31]
	s_nop 0
	v_readfirstlane_b32 s22, v126
	s_nop 0
	v_lshl_add_u64 v[180:181], v[76:77], 0, s[30:31]
	s_nop 0
	s_mov_b64 s[30:31], 0x480
	s_nop 0
	ds_read_b128 v[134:137], v85 offset:32768
	ds_read_b128 v[138:141], v84
	ds_read_b128 v[142:145], v85 offset:36864
	ds_read_b128 v[150:153], v84 offset:4096
	s_waitcnt lgkmcnt(1)
	v_mfma_f32_32x32x16_bf16 v[48:63], v[134:137], v[138:141], v[48:63]
	s_nop 0
	v_lshl_add_u64 v[160:161], v[68:69], 0, s[30:31]
	v_readfirstlane_b32 s23, v129
	v_lshl_add_u64 v[166:167], v[74:75], 0, s[30:31]
	v_readfirstlane_b32 s28, v127
	v_lshl_add_u64 v[168:169], v[76:77], 0, s[30:31]
	v_mfma_f32_32x32x16_bf16 v[32:47], v[142:145], v[138:141], v[32:47]
	s_and_b32 m0, s32, 7
	s_lshl_b32 m0, m0, 12
	s_add_i32 m0, m0, 0x18400
	s_nop 0
	global_load_lds_dwordx4 v[172:173], off
	s_waitcnt lgkmcnt(0)
	v_mfma_f32_32x32x16_bf16 v[16:31], v[134:137], v[150:153], v[16:31]
	v_mfma_f32_32x32x16_bf16 v[0:15], v[142:145], v[150:153], v[0:15]
	s_and_b32 m0, s32, 7
	s_lshl_b32 m0, m0, 12
	s_add_i32 m0, m0, 0x18800
	s_nop 0
	global_load_lds_dwordx4 v[174:175], off
	ds_read_b128 v[134:137], v83 offset:32768
	ds_read_b128 v[138:141], v82
	ds_read_b128 v[142:145], v83 offset:36864
	ds_read_b128 v[154:157], v82 offset:4096
	s_waitcnt lgkmcnt(1)
	v_mfma_f32_32x32x16_bf16 v[48:63], v[134:137], v[138:141], v[48:63]
	v_mfma_f32_32x32x16_bf16 v[32:47], v[142:145], v[138:141], v[32:47]
	s_and_b32 m0, s32, 7
	s_lshl_b32 m0, m0, 12
	s_add_i32 m0, m0, 0x18c00
	s_nop 0
	global_load_lds_dwordx4 v[176:177], off
	s_waitcnt lgkmcnt(0)
	v_mfma_f32_32x32x16_bf16 v[16:31], v[134:137], v[154:157], v[16:31]
	v_mfma_f32_32x32x16_bf16 v[0:15], v[142:145], v[154:157], v[0:15]
	s_and_b32 m0, s32, 7
	s_lshl_b32 m0, m0, 11
	s_add_i32 m0, m0, 0x20000
	s_nop 0
	global_load_lds_dwordx4 v[178:179], off
	ds_read_b128 v[134:137], v87 offset:32768
	ds_read_b128 v[138:141], v86
	ds_read_b128 v[142:145], v87 offset:36864
	ds_read_b128 v[150:153], v86 offset:4096
	s_waitcnt lgkmcnt(1)
	v_mfma_f32_32x32x16_bf16 v[48:63], v[134:137], v[138:141], v[48:63]
	v_mfma_f32_32x32x16_bf16 v[32:47], v[142:145], v[138:141], v[32:47]
	s_and_b32 m0, s32, 7
	s_lshl_b32 m0, m0, 11
	s_add_i32 m0, m0, 0x20400
	s_nop 0
	global_load_lds_dwordx4 v[180:181], off
	s_waitcnt lgkmcnt(0)
	v_mfma_f32_32x32x16_bf16 v[16:31], v[134:137], v[150:153], v[16:31]
	v_mfma_f32_32x32x16_bf16 v[0:15], v[142:145], v[150:153], v[0:15]
	ds_read_b128 v[134:137], v89 offset:32768
	ds_read_b128 v[138:141], v88
	ds_read_b128 v[142:145], v89 offset:36864
	ds_read_b128 v[154:157], v88 offset:4096
	s_waitcnt lgkmcnt(1)
	v_mfma_f32_32x32x16_bf16 v[48:63], v[134:137], v[138:141], v[48:63]
	v_mfma_f32_32x32x16_bf16 v[32:47], v[142:145], v[138:141], v[32:47]
	s_waitcnt vmcnt(6)
	s_waitcnt lgkmcnt(0)
	s_barrier
	s_waitcnt lgkmcnt(0)
	v_mfma_f32_32x32x16_bf16 v[16:31], v[134:137], v[154:157], v[16:31]
	v_lshl_add_u64 v[158:159], v[66:67], 0, s[30:31]
	s_nop 0
	s_nop 0
	s_nop 0
	s_nop 0
	v_lshl_add_u64 v[162:163], v[70:71], 0, s[30:31]
	s_nop 0
	v_mfma_f32_32x32x16_bf16 v[0:15], v[142:145], v[154:157], v[0:15]
	s_and_b32 m0, s32, 7
	s_lshl_b32 m0, m0, 12
	s_add_i32 m0, m0, 0x0
	s_nop 0
	global_load_lds_dwordx4 v[158:159], off
	s_nop 0
	v_lshl_add_u64 v[164:165], v[72:73], 0, s[30:31]
	s_nop 0
	s_mov_b64 s[30:31], 0x500
	s_nop 0
	s_nop 0
	v_lshl_add_u64 v[174:175], v[70:71], 0, s[30:31]
	s_nop 0
	s_nop 0
	s_nop 0
	s_nop 0
	ds_read_b128 v[126:129], v91
	ds_read_b128 v[134:137], v84 offset:49152
	ds_read_b128 v[138:141], v90
	ds_read_b128 v[150:153], v84 offset:53248
	s_waitcnt lgkmcnt(1)
	v_mfma_f32_32x32x16_bf16 v[48:63], v[126:129], v[134:137], v[48:63]
	s_nop 0
	v_mfma_f32_32x32x16_bf16 v[32:47], v[138:141], v[134:137], v[32:47]
	s_and_b32 m0, s32, 7
	s_lshl_b32 m0, m0, 12
	s_add_i32 m0, m0, 0x400
	s_nop 0
	global_load_lds_dwordx4 v[160:161], off
	s_waitcnt lgkmcnt(0)
	v_mfma_f32_32x32x16_bf16 v[16:31], v[126:129], v[150:153], v[16:31]
	v_mfma_f32_32x32x16_bf16 v[0:15], v[138:141], v[150:153], v[0:15]
	s_and_b32 m0, s32, 7
	s_lshl_b32 m0, m0, 12
	s_add_i32 m0, m0, 0x800
	s_nop 0
	global_load_lds_dwordx4 v[162:163], off
	ds_read_b128 v[126:129], v94
	ds_read_b128 v[134:137], v82 offset:49152
	ds_read_b128 v[138:141], v92
	ds_read_b128 v[154:157], v82 offset:53248
	s_waitcnt lgkmcnt(1)
	v_mfma_f32_32x32x16_bf16 v[48:63], v[126:129], v[134:137], v[48:63]
	v_mfma_f32_32x32x16_bf16 v[32:47], v[138:141], v[134:137], v[32:47]
	s_and_b32 m0, s32, 7
	s_lshl_b32 m0, m0, 12
	s_add_i32 m0, m0, 0xc00
	s_nop 0
	global_load_lds_dwordx4 v[164:165], off
	s_waitcnt lgkmcnt(0)
	v_mfma_f32_32x32x16_bf16 v[16:31], v[126:129], v[154:157], v[16:31]
	v_mfma_f32_32x32x16_bf16 v[0:15], v[138:141], v[154:157], v[0:15]
	s_and_b32 m0, s32, 7
	s_lshl_b32 m0, m0, 11
	s_add_i32 m0, m0, 0x8000
	s_nop 0
	global_load_lds_dwordx4 v[166:167], off
	ds_read_b128 v[126:129], v95
	ds_read_b128 v[134:137], v86 offset:49152
	ds_read_b128 v[138:141], v93
	ds_read_b128 v[150:153], v86 offset:53248
	s_waitcnt lgkmcnt(1)
	v_mfma_f32_32x32x16_bf16 v[48:63], v[126:129], v[134:137], v[48:63]
	v_mfma_f32_32x32x16_bf16 v[32:47], v[138:141], v[134:137], v[32:47]
	s_and_b32 m0, s32, 7
	s_lshl_b32 m0, m0, 11
	s_add_i32 m0, m0, 0x8400
	s_nop 0
	global_load_lds_dwordx4 v[168:169], off
	s_waitcnt lgkmcnt(0)
	v_mfma_f32_32x32x16_bf16 v[16:31], v[126:129], v[150:153], v[16:31]
	v_mfma_f32_32x32x16_bf16 v[0:15], v[138:141], v[150:153], v[0:15]
	ds_read_b128 v[126:129], v97
	ds_read_b128 v[134:137], v88 offset:49152
	ds_read_b128 v[138:141], v96
	ds_read_b128 v[154:157], v88 offset:53248
	s_waitcnt lgkmcnt(1)
	v_mfma_f32_32x32x16_bf16 v[48:63], v[126:129], v[134:137], v[48:63]
	v_mfma_f32_32x32x16_bf16 v[32:47], v[138:141], v[134:137], v[32:47]
	s_waitcnt vmcnt(6)
	s_waitcnt lgkmcnt(0)
	s_barrier
	s_waitcnt lgkmcnt(0)
	v_mfma_f32_32x32x16_bf16 v[16:31], v[126:129], v[154:157], v[16:31]
	v_lshl_add_u64 v[170:171], v[66:67], 0, s[30:31]
	s_nop 0
	v_lshl_add_u64 v[172:173], v[68:69], 0, s[30:31]
	s_nop 0
	s_nop 0
	s_nop 0
	s_nop 0
	v_mfma_f32_32x32x16_bf16 v[0:15], v[138:141], v[154:157], v[0:15]
	s_and_b32 m0, s32, 7
	s_lshl_b32 m0, m0, 12
	s_add_i32 m0, m0, 0xc000
	s_nop 0
	global_load_lds_dwordx4 v[170:171], off
	s_nop 0
	v_lshl_add_u64 v[176:177], v[72:73], 0, s[30:31]
	s_nop 0
	s_nop 0
	s_nop 0
	v_lshl_add_u64 v[178:179], v[74:75], 0, s[30:31]
	s_nop 0
	s_nop 0
	s_nop 0
	v_lshl_add_u64 v[180:181], v[76:77], 0, s[30:31]
	s_nop 0
	s_mov_b64 s[30:31], 0x580
	s_nop 0
	ds_read_b128 v[120:123], v98
	ds_read_b128 v[124:127], v100
	ds_read_b128 v[128:131], v99
	ds_read_b128 v[150:153], v101
	s_waitcnt lgkmcnt(1)
	v_mfma_f32_32x32x16_bf16 v[48:63], v[120:123], v[124:127], v[48:63]
	s_nop 0
	v_lshl_add_u64 v[162:163], v[70:71], 0, s[30:31]
	v_mfma_f32_32x32x16_bf16 v[32:47], v[128:131], v[124:127], v[32:47]
	s_and_b32 m0, s32, 7
	s_lshl_b32 m0, m0, 12
	s_add_i32 m0, m0, 0xc400
	s_nop 0
	global_load_lds_dwordx4 v[172:173], off
	s_waitcnt lgkmcnt(0)
	v_mfma_f32_32x32x16_bf16 v[16:31], v[120:123], v[150:153], v[16:31]
	v_mfma_f32_32x32x16_bf16 v[0:15], v[128:131], v[150:153], v[0:15]
	s_and_b32 m0, s32, 7
	s_lshl_b32 m0, m0, 12
	s_add_i32 m0, m0, 0xc800
	s_nop 0
	global_load_lds_dwordx4 v[174:175], off
	ds_read_b128 v[120:123], v103
	ds_read_b128 v[124:127], v104
	ds_read_b128 v[128:131], v102
	ds_read_b128 v[154:157], v105
	s_waitcnt lgkmcnt(1)
	v_mfma_f32_32x32x16_bf16 v[48:63], v[120:123], v[124:127], v[48:63]
	v_mfma_f32_32x32x16_bf16 v[32:47], v[128:131], v[124:127], v[32:47]
	s_and_b32 m0, s32, 7
	s_lshl_b32 m0, m0, 12
	s_add_i32 m0, m0, 0xcc00
	s_nop 0
	global_load_lds_dwordx4 v[176:177], off
	s_waitcnt lgkmcnt(0)
	v_mfma_f32_32x32x16_bf16 v[16:31], v[120:123], v[154:157], v[16:31]
	v_mfma_f32_32x32x16_bf16 v[0:15], v[128:131], v[154:157], v[0:15]
	s_and_b32 m0, s32, 7
	s_lshl_b32 m0, m0, 11
	s_add_i32 m0, m0, 0x14000
	s_nop 0
	global_load_lds_dwordx4 v[178:179], off
	ds_read_b128 v[120:123], v107
	ds_read_b128 v[124:127], v108
	ds_read_b128 v[128:131], v106
	ds_read_b128 v[150:153], v109
	s_waitcnt lgkmcnt(1)
	v_mfma_f32_32x32x16_bf16 v[48:63], v[120:123], v[124:127], v[48:63]
	v_mfma_f32_32x32x16_bf16 v[32:47], v[128:131], v[124:127], v[32:47]
	s_and_b32 m0, s32, 7
	s_lshl_b32 m0, m0, 11
	s_add_i32 m0, m0, 0x14400
	s_nop 0
	global_load_lds_dwordx4 v[180:181], off
	s_waitcnt lgkmcnt(0)
	v_mfma_f32_32x32x16_bf16 v[16:31], v[120:123], v[150:153], v[16:31]
	v_mfma_f32_32x32x16_bf16 v[0:15], v[128:131], v[150:153], v[0:15]
	ds_read_b128 v[120:123], v111
	ds_read_b128 v[124:127], v112
	ds_read_b128 v[128:131], v110
	ds_read_b128 v[154:157], v113
	s_waitcnt lgkmcnt(1)
	v_mfma_f32_32x32x16_bf16 v[48:63], v[120:123], v[124:127], v[48:63]
	v_mfma_f32_32x32x16_bf16 v[32:47], v[128:131], v[124:127], v[32:47]
	s_waitcnt vmcnt(6)
	s_waitcnt lgkmcnt(0)
	s_barrier
	s_waitcnt lgkmcnt(0)
	v_mfma_f32_32x32x16_bf16 v[16:31], v[120:123], v[154:157], v[16:31]
	v_lshl_add_u64 v[158:159], v[66:67], 0, s[30:31]
	s_nop 0
	v_lshl_add_u64 v[160:161], v[68:69], 0, s[30:31]
	s_nop 0
	s_nop 0
	s_nop 0
	s_nop 0
	v_mfma_f32_32x32x16_bf16 v[0:15], v[128:131], v[154:157], v[0:15]
	s_and_b32 m0, s32, 7
	s_lshl_b32 m0, m0, 12
	s_add_i32 m0, m0, 0x18000
	s_nop 0
	global_load_lds_dwordx4 v[158:159], off
	s_nop 0
	v_lshl_add_u64 v[164:165], v[72:73], 0, s[30:31]
	s_nop 0
	s_nop 0
	s_nop 0
	v_lshl_add_u64 v[166:167], v[74:75], 0, s[30:31]
	s_nop 0
	s_nop 0
	s_nop 0
	v_lshl_add_u64 v[168:169], v[76:77], 0, s[30:31]
	s_nop 0
	s_mov_b64 s[30:31], 0x600
	s_nop 0
	ds_read_b128 v[114:117], v85 offset:32768
	ds_read_b128 v[118:121], v84
	ds_read_b128 v[122:125], v85 offset:36864
	ds_read_b128 v[150:153], v84 offset:4096
	s_waitcnt lgkmcnt(1)
	v_mfma_f32_32x32x16_bf16 v[48:63], v[114:117], v[118:121], v[48:63]
	s_nop 0
	v_mfma_f32_32x32x16_bf16 v[32:47], v[122:125], v[118:121], v[32:47]
	s_and_b32 m0, s32, 7
	s_lshl_b32 m0, m0, 12
	s_add_i32 m0, m0, 0x18400
	s_nop 0
	global_load_lds_dwordx4 v[160:161], off
	s_waitcnt lgkmcnt(0)
	v_mfma_f32_32x32x16_bf16 v[16:31], v[114:117], v[150:153], v[16:31]
	v_mfma_f32_32x32x16_bf16 v[0:15], v[122:125], v[150:153], v[0:15]
	s_and_b32 m0, s32, 7
	s_lshl_b32 m0, m0, 12
	s_add_i32 m0, m0, 0x18800
	s_nop 0
	global_load_lds_dwordx4 v[162:163], off
	ds_read_b128 v[114:117], v83 offset:32768
	ds_read_b128 v[118:121], v82
	ds_read_b128 v[122:125], v83 offset:36864
	ds_read_b128 v[154:157], v82 offset:4096
	s_waitcnt lgkmcnt(1)
	v_mfma_f32_32x32x16_bf16 v[48:63], v[114:117], v[118:121], v[48:63]
	v_mfma_f32_32x32x16_bf16 v[32:47], v[122:125], v[118:121], v[32:47]
	s_and_b32 m0, s32, 7
	s_lshl_b32 m0, m0, 12
	s_add_i32 m0, m0, 0x18c00
	s_nop 0
	global_load_lds_dwordx4 v[164:165], off
	s_waitcnt lgkmcnt(0)
	v_mfma_f32_32x32x16_bf16 v[16:31], v[114:117], v[154:157], v[16:31]
	v_mfma_f32_32x32x16_bf16 v[0:15], v[122:125], v[154:157], v[0:15]
	s_and_b32 m0, s32, 7
	s_lshl_b32 m0, m0, 11
	s_add_i32 m0, m0, 0x20000
	s_nop 0
	global_load_lds_dwordx4 v[166:167], off
	ds_read_b128 v[114:117], v87 offset:32768
	ds_read_b128 v[118:121], v86
	ds_read_b128 v[122:125], v87 offset:36864
	ds_read_b128 v[150:153], v86 offset:4096
	s_waitcnt lgkmcnt(1)
	v_mfma_f32_32x32x16_bf16 v[48:63], v[114:117], v[118:121], v[48:63]
	v_mfma_f32_32x32x16_bf16 v[32:47], v[122:125], v[118:121], v[32:47]
	s_and_b32 m0, s32, 7
	s_lshl_b32 m0, m0, 11
	s_add_i32 m0, m0, 0x20400
	s_nop 0
	global_load_lds_dwordx4 v[168:169], off
	s_waitcnt lgkmcnt(0)
	v_mfma_f32_32x32x16_bf16 v[16:31], v[114:117], v[150:153], v[16:31]
	v_mfma_f32_32x32x16_bf16 v[0:15], v[122:125], v[150:153], v[0:15]
	ds_read_b128 v[114:117], v89 offset:32768
	ds_read_b128 v[118:121], v88
	ds_read_b128 v[122:125], v89 offset:36864
	ds_read_b128 v[154:157], v88 offset:4096
	s_waitcnt lgkmcnt(1)
	v_mfma_f32_32x32x16_bf16 v[48:63], v[114:117], v[118:121], v[48:63]
	v_mfma_f32_32x32x16_bf16 v[32:47], v[122:125], v[118:121], v[32:47]
	s_waitcnt vmcnt(6)
	s_waitcnt lgkmcnt(0)
	s_barrier
	s_waitcnt lgkmcnt(0)
	v_mfma_f32_32x32x16_bf16 v[16:31], v[114:117], v[154:157], v[16:31]
	v_lshl_add_u64 v[170:171], v[66:67], 0, s[30:31]
	s_nop 0
	v_lshl_add_u64 v[172:173], v[68:69], 0, s[30:31]
	s_nop 0
	s_nop 0
	s_nop 0
	v_lshl_add_u64 v[174:175], v[70:71], 0, s[30:31]
	s_nop 0
	v_mfma_f32_32x32x16_bf16 v[0:15], v[122:125], v[154:157], v[0:15]
	s_and_b32 m0, s32, 7
	s_lshl_b32 m0, m0, 12
	s_add_i32 m0, m0, 0x0
	s_nop 0
	global_load_lds_dwordx4 v[170:171], off
	s_nop 0
	v_lshl_add_u64 v[176:177], v[72:73], 0, s[30:31]
	s_nop 0
	s_nop 0
	s_nop 0
	v_lshl_add_u64 v[178:179], v[74:75], 0, s[30:31]
	s_nop 0
	s_nop 0
	s_nop 0
	v_lshl_add_u64 v[180:181], v[76:77], 0, s[30:31]
	s_nop 0
	s_mov_b64 s[30:31], 0x680
	s_nop 0
	ds_read_b128 v[114:117], v91
	ds_read_b128 v[118:121], v84 offset:49152
	ds_read_b128 v[122:125], v90
	ds_read_b128 v[150:153], v84 offset:53248
	s_waitcnt lgkmcnt(1)
	v_mfma_f32_32x32x16_bf16 v[48:63], v[114:117], v[118:121], v[48:63]
	s_nop 0
	v_mfma_f32_32x32x16_bf16 v[32:47], v[122:125], v[118:121], v[32:47]
	s_and_b32 m0, s32, 7
	s_lshl_b32 m0, m0, 12
	s_add_i32 m0, m0, 0x400
	s_nop 0
	global_load_lds_dwordx4 v[172:173], off
	s_waitcnt lgkmcnt(0)
	v_mfma_f32_32x32x16_bf16 v[16:31], v[114:117], v[150:153], v[16:31]
	v_mfma_f32_32x32x16_bf16 v[0:15], v[122:125], v[150:153], v[0:15]
	s_and_b32 m0, s32, 7
	s_lshl_b32 m0, m0, 12
	s_add_i32 m0, m0, 0x800
	s_nop 0
	global_load_lds_dwordx4 v[174:175], off
	ds_read_b128 v[114:117], v94
	ds_read_b128 v[118:121], v82 offset:49152
	ds_read_b128 v[122:125], v92
	ds_read_b128 v[154:157], v82 offset:53248
	s_waitcnt lgkmcnt(1)
	v_mfma_f32_32x32x16_bf16 v[48:63], v[114:117], v[118:121], v[48:63]
	v_mfma_f32_32x32x16_bf16 v[32:47], v[122:125], v[118:121], v[32:47]
	s_and_b32 m0, s32, 7
	s_lshl_b32 m0, m0, 12
	s_add_i32 m0, m0, 0xc00
	s_nop 0
	global_load_lds_dwordx4 v[176:177], off
	s_waitcnt lgkmcnt(0)
	v_mfma_f32_32x32x16_bf16 v[16:31], v[114:117], v[154:157], v[16:31]
	v_mfma_f32_32x32x16_bf16 v[0:15], v[122:125], v[154:157], v[0:15]
	s_and_b32 m0, s32, 7
	s_lshl_b32 m0, m0, 11
	s_add_i32 m0, m0, 0x8000
	s_nop 0
	global_load_lds_dwordx4 v[178:179], off
	ds_read_b128 v[114:117], v95
	ds_read_b128 v[118:121], v86 offset:49152
	ds_read_b128 v[122:125], v93
	ds_read_b128 v[150:153], v86 offset:53248
	s_waitcnt lgkmcnt(1)
	v_mfma_f32_32x32x16_bf16 v[48:63], v[114:117], v[118:121], v[48:63]
	v_mfma_f32_32x32x16_bf16 v[32:47], v[122:125], v[118:121], v[32:47]
	s_and_b32 m0, s32, 7
	s_lshl_b32 m0, m0, 11
	s_add_i32 m0, m0, 0x8400
	s_nop 0
	global_load_lds_dwordx4 v[180:181], off
	s_waitcnt lgkmcnt(0)
	v_mfma_f32_32x32x16_bf16 v[16:31], v[114:117], v[150:153], v[16:31]
	v_mfma_f32_32x32x16_bf16 v[0:15], v[122:125], v[150:153], v[0:15]
	ds_read_b128 v[114:117], v97
	ds_read_b128 v[118:121], v88 offset:49152
	ds_read_b128 v[122:125], v96
	ds_read_b128 v[154:157], v88 offset:53248
	s_waitcnt lgkmcnt(1)
	v_mfma_f32_32x32x16_bf16 v[48:63], v[114:117], v[118:121], v[48:63]
	v_mfma_f32_32x32x16_bf16 v[32:47], v[122:125], v[118:121], v[32:47]
	s_waitcnt vmcnt(6)
	s_waitcnt lgkmcnt(0)
	s_barrier
	s_waitcnt lgkmcnt(0)
	v_mfma_f32_32x32x16_bf16 v[16:31], v[114:117], v[154:157], v[16:31]
	v_lshl_add_u64 v[158:159], v[66:67], 0, s[30:31]
	s_nop 0
	v_lshl_add_u64 v[160:161], v[68:69], 0, s[30:31]
	s_nop 0
	s_nop 0
	s_nop 0
	v_lshl_add_u64 v[162:163], v[70:71], 0, s[30:31]
	s_nop 0
	v_mfma_f32_32x32x16_bf16 v[0:15], v[122:125], v[154:157], v[0:15]
	s_and_b32 m0, s32, 7
	s_lshl_b32 m0, m0, 12
	s_add_i32 m0, m0, 0xc000
	s_nop 0
	global_load_lds_dwordx4 v[158:159], off
	s_nop 0
	v_lshl_add_u64 v[164:165], v[72:73], 0, s[30:31]
	s_nop 0
	s_nop 0
	s_nop 0
	v_lshl_add_u64 v[166:167], v[74:75], 0, s[30:31]
	s_nop 0
	s_nop 0
	s_nop 0
	v_lshl_add_u64 v[168:169], v[76:77], 0, s[30:31]
	s_nop 0
	s_mov_b64 s[30:31], 0x700
	s_nop 0
	ds_read_b128 v[114:117], v98
	ds_read_b128 v[118:121], v100
	ds_read_b128 v[122:125], v99
	ds_read_b128 v[150:153], v101
	s_waitcnt lgkmcnt(1)
	v_mfma_f32_32x32x16_bf16 v[48:63], v[114:117], v[118:121], v[48:63]
	s_nop 0
	v_mfma_f32_32x32x16_bf16 v[32:47], v[122:125], v[118:121], v[32:47]
	s_and_b32 m0, s32, 7
	s_lshl_b32 m0, m0, 12
	s_add_i32 m0, m0, 0xc400
	s_nop 0
	global_load_lds_dwordx4 v[160:161], off
	s_waitcnt lgkmcnt(0)
	v_mfma_f32_32x32x16_bf16 v[16:31], v[114:117], v[150:153], v[16:31]
	v_mfma_f32_32x32x16_bf16 v[0:15], v[122:125], v[150:153], v[0:15]
	s_and_b32 m0, s32, 7
	s_lshl_b32 m0, m0, 12
	s_add_i32 m0, m0, 0xc800
	s_nop 0
	global_load_lds_dwordx4 v[162:163], off
	ds_read_b128 v[114:117], v103
	ds_read_b128 v[118:121], v104
	ds_read_b128 v[122:125], v102
	ds_read_b128 v[154:157], v105
	s_waitcnt lgkmcnt(1)
	v_mfma_f32_32x32x16_bf16 v[48:63], v[114:117], v[118:121], v[48:63]
	v_mfma_f32_32x32x16_bf16 v[32:47], v[122:125], v[118:121], v[32:47]
	s_and_b32 m0, s32, 7
	s_lshl_b32 m0, m0, 12
	s_add_i32 m0, m0, 0xcc00
	s_nop 0
	global_load_lds_dwordx4 v[164:165], off
	s_waitcnt lgkmcnt(0)
	v_mfma_f32_32x32x16_bf16 v[16:31], v[114:117], v[154:157], v[16:31]
	v_mfma_f32_32x32x16_bf16 v[0:15], v[122:125], v[154:157], v[0:15]
	s_and_b32 m0, s32, 7
	s_lshl_b32 m0, m0, 11
	s_add_i32 m0, m0, 0x14000
	s_nop 0
	global_load_lds_dwordx4 v[166:167], off
	ds_read_b128 v[114:117], v107
	ds_read_b128 v[118:121], v108
	ds_read_b128 v[122:125], v106
	ds_read_b128 v[150:153], v109
	s_waitcnt lgkmcnt(1)
	v_mfma_f32_32x32x16_bf16 v[48:63], v[114:117], v[118:121], v[48:63]
	v_mfma_f32_32x32x16_bf16 v[32:47], v[122:125], v[118:121], v[32:47]
	s_and_b32 m0, s32, 7
	s_lshl_b32 m0, m0, 11
	s_add_i32 m0, m0, 0x14400
	s_nop 0
	global_load_lds_dwordx4 v[168:169], off
	s_waitcnt lgkmcnt(0)
	v_mfma_f32_32x32x16_bf16 v[16:31], v[114:117], v[150:153], v[16:31]
	v_mfma_f32_32x32x16_bf16 v[0:15], v[122:125], v[150:153], v[0:15]
	ds_read_b128 v[114:117], v111
	ds_read_b128 v[118:121], v112
	ds_read_b128 v[122:125], v110
	ds_read_b128 v[154:157], v113
	s_waitcnt lgkmcnt(1)
	v_mfma_f32_32x32x16_bf16 v[48:63], v[114:117], v[118:121], v[48:63]
	v_mfma_f32_32x32x16_bf16 v[32:47], v[122:125], v[118:121], v[32:47]
	s_waitcnt vmcnt(6)
	s_waitcnt lgkmcnt(0)
	s_barrier
	s_waitcnt lgkmcnt(0)
	v_mfma_f32_32x32x16_bf16 v[16:31], v[114:117], v[154:157], v[16:31]
	v_lshl_add_u64 v[170:171], v[66:67], 0, s[30:31]
	s_nop 0
	v_lshl_add_u64 v[172:173], v[68:69], 0, s[30:31]
	s_nop 0
	s_nop 0
	s_nop 0
	v_lshl_add_u64 v[174:175], v[70:71], 0, s[30:31]
	s_nop 0
	v_mfma_f32_32x32x16_bf16 v[0:15], v[122:125], v[154:157], v[0:15]
	s_and_b32 m0, s32, 7
	s_lshl_b32 m0, m0, 12
	s_add_i32 m0, m0, 0x18000
	s_nop 0
	global_load_lds_dwordx4 v[170:171], off
	s_nop 0
	v_lshl_add_u64 v[176:177], v[72:73], 0, s[30:31]
	s_nop 0
	s_nop 0
	s_nop 0
	v_lshl_add_u64 v[178:179], v[74:75], 0, s[30:31]
	s_nop 0
	s_nop 0
	s_nop 0
	v_lshl_add_u64 v[180:181], v[76:77], 0, s[30:31]
	s_nop 0
	s_mov_b64 s[30:31], 0x780
	s_nop 0
	ds_read_b128 v[114:117], v85 offset:32768
	ds_read_b128 v[118:121], v84
	ds_read_b128 v[122:125], v85 offset:36864
	ds_read_b128 v[150:153], v84 offset:4096
	s_waitcnt lgkmcnt(1)
	v_mfma_f32_32x32x16_bf16 v[48:63], v[114:117], v[118:121], v[48:63]
	v_lshl_add_u64 v[158:159], v[66:67], 0, s[30:31]
	s_nop 0
	v_mfma_f32_32x32x16_bf16 v[32:47], v[122:125], v[118:121], v[32:47]
	s_and_b32 m0, s32, 7
	s_lshl_b32 m0, m0, 12
	s_add_i32 m0, m0, 0x18400
	s_nop 0
	global_load_lds_dwordx4 v[172:173], off
	s_waitcnt lgkmcnt(0)
	v_mfma_f32_32x32x16_bf16 v[16:31], v[114:117], v[150:153], v[16:31]
	v_mfma_f32_32x32x16_bf16 v[0:15], v[122:125], v[150:153], v[0:15]
	s_and_b32 m0, s32, 7
	s_lshl_b32 m0, m0, 12
	s_add_i32 m0, m0, 0x18800
	s_nop 0
	global_load_lds_dwordx4 v[174:175], off
	ds_read_b128 v[114:117], v83 offset:32768
	ds_read_b128 v[118:121], v82
	ds_read_b128 v[122:125], v83 offset:36864
	ds_read_b128 v[154:157], v82 offset:4096
	s_waitcnt lgkmcnt(1)
	v_mfma_f32_32x32x16_bf16 v[48:63], v[114:117], v[118:121], v[48:63]
	v_mfma_f32_32x32x16_bf16 v[32:47], v[122:125], v[118:121], v[32:47]
	s_and_b32 m0, s32, 7
	s_lshl_b32 m0, m0, 12
	s_add_i32 m0, m0, 0x18c00
	s_nop 0
	global_load_lds_dwordx4 v[176:177], off
	s_waitcnt lgkmcnt(0)
	v_mfma_f32_32x32x16_bf16 v[16:31], v[114:117], v[154:157], v[16:31]
	v_mfma_f32_32x32x16_bf16 v[0:15], v[122:125], v[154:157], v[0:15]
	s_and_b32 m0, s32, 7
	s_lshl_b32 m0, m0, 11
	s_add_i32 m0, m0, 0x20000
	s_nop 0
	global_load_lds_dwordx4 v[178:179], off
	ds_read_b128 v[114:117], v87 offset:32768
	ds_read_b128 v[118:121], v86
	ds_read_b128 v[122:125], v87 offset:36864
	ds_read_b128 v[150:153], v86 offset:4096
	s_waitcnt lgkmcnt(1)
	v_mfma_f32_32x32x16_bf16 v[48:63], v[114:117], v[118:121], v[48:63]
	v_mfma_f32_32x32x16_bf16 v[32:47], v[122:125], v[118:121], v[32:47]
	s_and_b32 m0, s32, 7
	s_lshl_b32 m0, m0, 11
	s_add_i32 m0, m0, 0x20400
	s_nop 0
	global_load_lds_dwordx4 v[180:181], off
	s_waitcnt lgkmcnt(0)
	v_mfma_f32_32x32x16_bf16 v[16:31], v[114:117], v[150:153], v[16:31]
	v_mfma_f32_32x32x16_bf16 v[0:15], v[122:125], v[150:153], v[0:15]
	ds_read_b128 v[114:117], v89 offset:32768
	ds_read_b128 v[118:121], v88
	ds_read_b128 v[122:125], v89 offset:36864
	ds_read_b128 v[154:157], v88 offset:4096
	s_waitcnt lgkmcnt(1)
	v_mfma_f32_32x32x16_bf16 v[48:63], v[114:117], v[118:121], v[48:63]
	v_mfma_f32_32x32x16_bf16 v[32:47], v[122:125], v[118:121], v[32:47]
	s_waitcnt vmcnt(6)
	s_waitcnt lgkmcnt(0)
	s_barrier
	s_nop 0
	v_lshl_add_u64 v[160:161], v[68:69], 0, s[30:31]
	s_nop 0
	s_waitcnt lgkmcnt(0)
	v_mfma_f32_32x32x16_bf16 v[16:31], v[114:117], v[154:157], v[16:31]
	s_nop 0
	v_lshl_add_u64 v[162:163], v[70:71], 0, s[30:31]
	s_nop 0
	s_nop 0
	s_nop 0
	v_lshl_add_u64 v[164:165], v[72:73], 0, s[30:31]
	s_nop 0
	v_mfma_f32_32x32x16_bf16 v[0:15], v[122:125], v[154:157], v[0:15]
	s_and_b32 m0, s32, 7
	s_lshl_b32 m0, m0, 12
	s_add_i32 m0, m0, 0x0
	s_nop 0
	global_load_lds_dwordx4 v[158:159], off
	s_nop 0
	v_lshl_add_u64 v[166:167], v[74:75], 0, s[30:31]
	s_nop 0
	s_nop 0
	s_nop 0
	v_lshl_add_u64 v[168:169], v[76:77], 0, s[30:31]
	s_nop 0
	s_nop 0
	s_nop 0
	ds_read_b128 v[66:69], v91
	ds_read_b128 v[70:73], v84 offset:49152
	ds_read_b128 v[74:77], v90
	ds_read_b128 v[150:153], v84 offset:53248
	s_waitcnt lgkmcnt(1)
	v_mfma_f32_32x32x16_bf16 v[48:63], v[66:69], v[70:73], v[48:63]
	v_mfma_f32_32x32x16_bf16 v[32:47], v[74:77], v[70:73], v[32:47]
	s_and_b32 m0, s32, 7
	s_lshl_b32 m0, m0, 12
	s_add_i32 m0, m0, 0x400
	s_nop 0
	global_load_lds_dwordx4 v[160:161], off
	s_waitcnt lgkmcnt(0)
	v_mfma_f32_32x32x16_bf16 v[16:31], v[66:69], v[150:153], v[16:31]
	v_mfma_f32_32x32x16_bf16 v[0:15], v[74:77], v[150:153], v[0:15]
	s_and_b32 m0, s32, 7
	s_lshl_b32 m0, m0, 12
	s_add_i32 m0, m0, 0x800
	s_nop 0
	global_load_lds_dwordx4 v[162:163], off
	ds_read_b128 v[66:69], v94
	ds_read_b128 v[70:73], v82 offset:49152
	ds_read_b128 v[74:77], v92
	ds_read_b128 v[154:157], v82 offset:53248
	s_waitcnt lgkmcnt(1)
	v_mfma_f32_32x32x16_bf16 v[48:63], v[66:69], v[70:73], v[48:63]
	v_mfma_f32_32x32x16_bf16 v[32:47], v[74:77], v[70:73], v[32:47]
	s_and_b32 m0, s32, 7
	s_lshl_b32 m0, m0, 12
	s_add_i32 m0, m0, 0xc00
	s_nop 0
	global_load_lds_dwordx4 v[164:165], off
	s_waitcnt lgkmcnt(0)
	v_mfma_f32_32x32x16_bf16 v[16:31], v[66:69], v[154:157], v[16:31]
	v_mfma_f32_32x32x16_bf16 v[0:15], v[74:77], v[154:157], v[0:15]
	s_and_b32 m0, s32, 7
	s_lshl_b32 m0, m0, 11
	s_add_i32 m0, m0, 0x8000
	s_nop 0
	global_load_lds_dwordx4 v[166:167], off
	ds_read_b128 v[66:69], v95
	ds_read_b128 v[70:73], v86 offset:49152
	ds_read_b128 v[74:77], v93
	ds_read_b128 v[150:153], v86 offset:53248
	s_waitcnt lgkmcnt(1)
	v_mfma_f32_32x32x16_bf16 v[48:63], v[66:69], v[70:73], v[48:63]
	v_mfma_f32_32x32x16_bf16 v[32:47], v[74:77], v[70:73], v[32:47]
	s_and_b32 m0, s32, 7
	s_lshl_b32 m0, m0, 11
	s_add_i32 m0, m0, 0x8400
	s_nop 0
	global_load_lds_dwordx4 v[168:169], off
	s_waitcnt lgkmcnt(0)
	v_mfma_f32_32x32x16_bf16 v[16:31], v[66:69], v[150:153], v[16:31]
	v_mfma_f32_32x32x16_bf16 v[0:15], v[74:77], v[150:153], v[0:15]
	ds_read_b128 v[66:69], v97
	ds_read_b128 v[70:73], v88 offset:49152
	ds_read_b128 v[74:77], v96
	ds_read_b128 v[154:157], v88 offset:53248
	s_waitcnt lgkmcnt(1)
	v_mfma_f32_32x32x16_bf16 v[48:63], v[66:69], v[70:73], v[48:63]
	v_mfma_f32_32x32x16_bf16 v[32:47], v[74:77], v[70:73], v[32:47]
	s_waitcnt vmcnt(6)
	s_waitcnt lgkmcnt(0)
	s_barrier
	s_waitcnt lgkmcnt(0)
	v_mfma_f32_32x32x16_bf16 v[16:31], v[66:69], v[154:157], v[16:31]
	v_mfma_f32_32x32x16_bf16 v[0:15], v[74:77], v[154:157], v[0:15]
	ds_read_b128 v[66:69], v98
	ds_read_b128 v[70:73], v100
	ds_read_b128 v[74:77], v99
	ds_read_b128 v[150:153], v101
	s_waitcnt lgkmcnt(1)
	v_mfma_f32_32x32x16_bf16 v[48:63], v[66:69], v[70:73], v[48:63]
	v_mfma_f32_32x32x16_bf16 v[32:47], v[74:77], v[70:73], v[32:47]
	s_waitcnt lgkmcnt(0)
	v_mfma_f32_32x32x16_bf16 v[16:31], v[66:69], v[150:153], v[16:31]
	v_mfma_f32_32x32x16_bf16 v[0:15], v[74:77], v[150:153], v[0:15]
	ds_read_b128 v[66:69], v103
	ds_read_b128 v[70:73], v104
	ds_read_b128 v[74:77], v102
	ds_read_b128 v[154:157], v105
	s_waitcnt lgkmcnt(1)
	v_mfma_f32_32x32x16_bf16 v[48:63], v[66:69], v[70:73], v[48:63]
	v_mfma_f32_32x32x16_bf16 v[32:47], v[74:77], v[70:73], v[32:47]
	s_waitcnt lgkmcnt(0)
	v_mfma_f32_32x32x16_bf16 v[16:31], v[66:69], v[154:157], v[16:31]
	v_mfma_f32_32x32x16_bf16 v[0:15], v[74:77], v[154:157], v[0:15]
	ds_read_b128 v[66:69], v107
	ds_read_b128 v[70:73], v108
	ds_read_b128 v[74:77], v106
	ds_read_b128 v[150:153], v109
	s_waitcnt lgkmcnt(1)
	v_mfma_f32_32x32x16_bf16 v[48:63], v[66:69], v[70:73], v[48:63]
	v_mfma_f32_32x32x16_bf16 v[32:47], v[74:77], v[70:73], v[32:47]
	s_waitcnt lgkmcnt(0)
	v_mfma_f32_32x32x16_bf16 v[16:31], v[66:69], v[150:153], v[16:31]
	v_mfma_f32_32x32x16_bf16 v[0:15], v[74:77], v[150:153], v[0:15]
	ds_read_b128 v[66:69], v111
	ds_read_b128 v[70:73], v112
	ds_read_b128 v[74:77], v110
	ds_read_b128 v[154:157], v113
	s_waitcnt lgkmcnt(1)
	v_mfma_f32_32x32x16_bf16 v[48:63], v[66:69], v[70:73], v[48:63]
	v_mfma_f32_32x32x16_bf16 v[32:47], v[74:77], v[70:73], v[32:47]
	s_waitcnt vmcnt(0)
	s_waitcnt lgkmcnt(0)
	s_barrier
	s_waitcnt lgkmcnt(0)
	v_mfma_f32_32x32x16_bf16 v[16:31], v[66:69], v[154:157], v[16:31]
	v_mfma_f32_32x32x16_bf16 v[0:15], v[74:77], v[154:157], v[0:15]
	ds_read_b128 v[66:69], v85 offset:32768
	ds_read_b128 v[70:73], v84
	ds_read_b128 v[74:77], v85 offset:36864
	ds_read_b128 v[150:153], v84 offset:4096
	s_waitcnt lgkmcnt(1)
	v_mfma_f32_32x32x16_bf16 v[48:63], v[66:69], v[70:73], v[48:63]
	v_mfma_f32_32x32x16_bf16 v[32:47], v[74:77], v[70:73], v[32:47]
	s_waitcnt lgkmcnt(0)
	v_mfma_f32_32x32x16_bf16 v[16:31], v[66:69], v[150:153], v[16:31]
	v_mfma_f32_32x32x16_bf16 v[0:15], v[74:77], v[150:153], v[0:15]
	ds_read_b128 v[66:69], v83 offset:32768
	ds_read_b128 v[70:73], v82
	ds_read_b128 v[74:77], v83 offset:36864
	ds_read_b128 v[154:157], v82 offset:4096
	s_waitcnt lgkmcnt(1)
	v_mfma_f32_32x32x16_bf16 v[48:63], v[66:69], v[70:73], v[48:63]
	v_mfma_f32_32x32x16_bf16 v[32:47], v[74:77], v[70:73], v[32:47]
	s_waitcnt lgkmcnt(0)
	v_mfma_f32_32x32x16_bf16 v[16:31], v[66:69], v[154:157], v[16:31]
	v_mfma_f32_32x32x16_bf16 v[0:15], v[74:77], v[154:157], v[0:15]
	ds_read_b128 v[66:69], v87 offset:32768
	ds_read_b128 v[70:73], v86
	ds_read_b128 v[74:77], v87 offset:36864
	ds_read_b128 v[150:153], v86 offset:4096
	s_waitcnt lgkmcnt(1)
	v_mfma_f32_32x32x16_bf16 v[48:63], v[66:69], v[70:73], v[48:63]
	v_mfma_f32_32x32x16_bf16 v[32:47], v[74:77], v[70:73], v[32:47]
	s_waitcnt lgkmcnt(0)
	v_mfma_f32_32x32x16_bf16 v[16:31], v[66:69], v[150:153], v[16:31]
	v_mfma_f32_32x32x16_bf16 v[0:15], v[74:77], v[150:153], v[0:15]
	ds_read_b128 v[70:73], v89 offset:32768
	ds_read_b128 v[66:69], v88
	ds_read_b128 v[74:77], v89 offset:36864
	ds_read_b128 v[82:85], v88 offset:4096
	s_waitcnt lgkmcnt(0)
	s_barrier
	s_waitcnt lgkmcnt(0)
	v_mfma_f32_32x32x16_bf16 v[48:63], v[70:73], v[66:69], v[48:63]
	v_mfma_f32_32x32x16_bf16 v[32:47], v[74:77], v[66:69], v[32:47]
	v_lshl_or_b32 v69, v80, 6, v81
	v_add_u32_e32 v66, s2, v69
	v_cmp_gt_i32_e32 vcc, s69, v66
	v_ashrrev_i32_e32 v67, 31, v66
	v_mov_b32_e32 v68, 0
	v_mfma_f32_32x32x16_bf16 v[16:31], v[70:73], v[82:85], v[16:31]
	v_mov_b32_e32 v70, 0
	v_mfma_f32_32x32x16_bf16 v[0:15], v[74:77], v[82:85], v[0:15]
	s_and_saveexec_b64 s[0:1], vcc
	s_cbranch_execz .LBB0_749
	v_lshl_add_u64 v[70:71], v[66:67], 2, s[76:77]
	global_load_dword v70, v[70:71], off
	s_waitcnt vmcnt(0)
	v_fmamk_f32 v70, v70, 0x3a800000, v188
	v_mul_f32_e32 v71, 0x4b800000, v70
	v_cmp_gt_f32_e32 vcc, s82, v70
	s_nop 1
	v_cndmask_b32_e32 v70, v70, v71, vcc
	v_rsq_f32_e32 v70, v70
	s_nop 0
	v_mul_f32_e32 v71, 0x45800000, v70
	v_cndmask_b32_e32 v70, v70, v71, vcc
